# K-loops: removed the s_nop 1 pads between an LDS-DMA and the next m0 write (hipcc's own code has none); lgkmcnt(8) pacing kept
# speedup vs baseline: 1.0072x; 1.0072x over previous
; #define PG8_STAGE(bufoff, gbase, voff) do { _Pragma("unroll") for (int _i = 0; _i < 2; ++_i) \
;         __builtin_amdgcn_global_load_lds((const unsigned*)((const char*)(gbase) + (voff)[_i]), (PG8_LAS unsigned*)(lds + (bufoff) + ldsw + _i * 8192), 16, 0, 0); } while (0)
; #define PG8_LDA(dst, b, h) do { _Pragma("unroll") for (int m = 0; m < 4; ++m) _Pragma("unroll") for (int k = 0; k < 2; ++k) dst[m][k] = *(const PG8_LAS bf16x8*)(lds + PG8_SA(b, h) + aoff + m * 2048 + k * 1024); } while (0)
; #define PG8_LDB(dst, b, h) do { _Pragma("unroll") for (int n = 0; n < 2; ++n) _Pragma("unroll") for (int k = 0; k < 2; ++k) dst[n][k] = *(const PG8_LAS bf16x8*)(lds + PG8_SB(b, h) + boff + n * 2048 + k * 1024); } while (0)
; #define PG8_WAIT_V(n) asm volatile("s_waitcnt vmcnt(" #n ")" ::: "memory")
; #define PG8_WAIT_L(n) asm volatile("s_waitcnt lgkmcnt(" #n ")" ::: "memory")
; #define PG8_BAR __builtin_amdgcn_s_barrier()
; #define PG8_SCHED __builtin_amdgcn_sched_barrier(0)
; template <class Epi, class Sched>
; __device__ __forceinline__ void gemm_phase(PG8_LAS unsigned char* lds, const Gemm g, const Sched& S, const Epi& E) {
;     ...
;         const bool has_next = S.next(ui + 1, nxt);
;         const char* nA = has_next ? (const char*)g.A + (size_t)nxt.pm * tstep : cA; const char* nB = has_next ? (const char*)g.Bt + (size_t)nxt.pn * tstep : cB;
;         for (int t = 0; t < nt; t += 2) {
;             const bool last = (t == nt - 2);
;             const char* a1 = cA + (size_t)(t + 1) * kstep;
;             const char* a2 = last ? nA : cA + (size_t)(t + 2) * kstep; const char* b2 = last ? nB : cB + (size_t)(t + 2) * kstep;
;             const char* a3 = a2 + kstep; const char* b3 = b2 + kstep;
;             if (last && has_next) S.a_ready(nxt);
;             PG8_LDB(B0, 0, 0); PG8_SCHED; PG8_LDA(At, 0, 0); PG8_STAGE(PG8_SA(1, 1), a1 + hstep, voffA);
;             PG8_WAIT_L(8); PG8_BAR; PG8_WAIT_L(0); PG8_MMA(0, 0, At, B0); PG8_BAR; PG8_SCHED;
;             PG8_LDB(B1, 0, 1); PG8_STAGE(PG8_SB(0, 0), b2, voffB);
;             PG8_BAR; PG8_WAIT_L(0); PG8_MMA(0, 1, At, B1); PG8_BAR;
;             PG8_LDA(At, 0, 1); PG8_STAGE(PG8_SA(0, 0), a2, voffA);
;             PG8_BAR; PG8_WAIT_L(0); PG8_MMA(1, 0, At, B0); PG8_BAR; PG8_SCHED;
;             PG8_STAGE(PG8_SB(0, 1), b2 + hstep, voffB);
;             PG8_WAIT_V(6); PG8_BAR; PG8_MMA(1, 1, At, B1); PG8_BAR;
.LBB0_194:
	s_ashr_i32 s17, s16, 31
	v_cmp_lt_i64_e32 vcc, s[18:19], v[140:141]
	s_lshl_b64 s[18:19], s[16:17], 19
	s_add_u32 s18, s38, s18
	s_addc_u32 s19, s39, s19
	s_and_b64 s[24:25], vcc, exec
	s_cselect_b32 s17, s19, s29
	s_cselect_b32 s54, s18, s28
	s_ashr_i32 s15, s14, 31
	s_lshl_b64 s[24:25], s[14:15], 19
	s_add_u32 s24, s90, s24
	s_addc_u32 s25, s91, s25
	s_and_b64 s[34:35], vcc, exec
	s_cselect_b32 s15, s25, s31
	s_cselect_b32 s55, s24, s30
	s_add_u32 s28, s28, 0x40080
	s_addc_u32 s29, s29, 0
	s_add_u32 s56, s30, 0x100
	s_addc_u32 s57, s31, 0
	s_mov_b32 s58, -2
	ds_read_b128 v[144:147], v151
	ds_read_b128 v[156:159], v151 offset:1024
	ds_read_b128 v[160:163], v151 offset:2048
	ds_read_b128 v[166:169], v151 offset:3072
	s_add_u32 s30, s28, 0xfffc0080
	s_addc_u32 s31, s29, -1
	s_cmp_eq_u32 s58, 12
	s_cselect_b32 s35, s17, s31
	s_cselect_b32 s34, s54, s30
	s_cselect_b32 s31, s15, s57
	s_cselect_b32 s30, s55, s56
	s_add_i32 m0, s27, 0xc000
	ds_read_b128 v[170:173], v153
	ds_read_b128 v[182:185], v153 offset:1024
	ds_read_b128 v[190:193], v153 offset:2048
	ds_read_b128 v[194:197], v153 offset:3072
	ds_read_b128 v[198:201], v153 offset:4096
	ds_read_b128 v[202:205], v153 offset:5120
	ds_read_b128 v[206:209], v153 offset:6144
	ds_read_b128 v[210:213], v153 offset:7168
	global_load_lds_dwordx4 v136, s[28:29]
	s_add_i32 m0, s27, 0xe000
	s_nop 0
	global_load_lds_dwordx4 v138, s[28:29]
	s_waitcnt lgkmcnt(8)
	ds_read_b128 v[214:217], v154
	ds_read_b128 v[218:221], v154 offset:1024
	ds_read_b128 v[222:225], v154 offset:2048
	ds_read_b128 v[226:229], v154 offset:3072
	s_waitcnt vmcnt(8) lgkmcnt(0)
	s_barrier
	v_mfma_f32_16x16x32_bf16 v[124:127], v[144:147], v[170:173], 0
	v_mfma_f32_16x16x32_bf16 v[120:123], v[160:163], v[170:173], 0
	v_mfma_f32_16x16x32_bf16 v[108:111], v[144:147], v[190:193], 0
	v_mfma_f32_16x16x32_bf16 v[104:107], v[160:163], v[190:193], 0
	v_mfma_f32_16x16x32_bf16 v[92:95], v[144:147], v[198:201], 0
	v_mfma_f32_16x16x32_bf16 v[88:91], v[160:163], v[198:201], 0
	v_mfma_f32_16x16x32_bf16 v[76:79], v[144:147], v[206:209], 0
	v_mfma_f32_16x16x32_bf16 v[72:75], v[160:163], v[206:209], 0
	v_mfma_f32_16x16x32_bf16 v[124:127], v[156:159], v[182:185], v[124:127]
	v_mfma_f32_16x16x32_bf16 v[120:123], v[166:169], v[182:185], v[120:123]
	v_mfma_f32_16x16x32_bf16 v[108:111], v[156:159], v[194:197], v[108:111]
	v_mfma_f32_16x16x32_bf16 v[104:107], v[166:169], v[194:197], v[104:107]
	v_mfma_f32_16x16x32_bf16 v[92:95], v[156:159], v[202:205], v[92:95]
	v_mfma_f32_16x16x32_bf16 v[88:91], v[166:169], v[202:205], v[88:91]
	v_mfma_f32_16x16x32_bf16 v[76:79], v[156:159], v[210:213], v[76:79]
	v_mfma_f32_16x16x32_bf16 v[72:75], v[166:169], v[210:213], v[72:75]
	v_mfma_f32_16x16x32_bf16 v[116:119], v[214:217], v[170:173], 0
	v_mfma_f32_16x16x32_bf16 v[112:115], v[222:225], v[170:173], 0
	v_mfma_f32_16x16x32_bf16 v[100:103], v[214:217], v[190:193], 0
	v_mfma_f32_16x16x32_bf16 v[96:99], v[222:225], v[190:193], 0
	v_mfma_f32_16x16x32_bf16 v[84:87], v[214:217], v[198:201], 0
	v_mfma_f32_16x16x32_bf16 v[80:83], v[222:225], v[198:201], 0
	v_mfma_f32_16x16x32_bf16 v[68:71], v[214:217], v[206:209], 0
	v_mfma_f32_16x16x32_bf16 v[64:67], v[222:225], v[206:209], 0
	v_mfma_f32_16x16x32_bf16 v[116:119], v[218:221], v[182:185], v[116:119]
	v_mfma_f32_16x16x32_bf16 v[112:115], v[226:229], v[182:185], v[112:115]
	v_mfma_f32_16x16x32_bf16 v[100:103], v[218:221], v[194:197], v[100:103]
	v_mfma_f32_16x16x32_bf16 v[96:99], v[226:229], v[194:197], v[96:99]
	v_mfma_f32_16x16x32_bf16 v[84:87], v[218:221], v[202:205], v[84:87]
	v_mfma_f32_16x16x32_bf16 v[80:83], v[226:229], v[202:205], v[80:83]
	v_mfma_f32_16x16x32_bf16 v[68:71], v[218:221], v[210:213], v[68:71]
	v_mfma_f32_16x16x32_bf16 v[64:67], v[226:229], v[210:213], v[64:67]
	s_barrier
	ds_read_b128 v[170:173], v153 offset:16384
	ds_read_b128 v[182:185], v153 offset:17408
	ds_read_b128 v[190:193], v153 offset:18432
	ds_read_b128 v[194:197], v153 offset:19456
	ds_read_b128 v[198:201], v153 offset:20480
	ds_read_b128 v[202:205], v153 offset:21504
	ds_read_b128 v[206:209], v153 offset:22528
	ds_read_b128 v[210:213], v153 offset:23552
	s_add_i32 s59, s50, s40
	s_add_u32 s98, s30, s10
	s_addc_u32 s99, s31, s11
	s_mov_b32 m0, s59
	s_nop 0
	global_load_lds_dwordx4 v132, s[30:31]
	s_add_i32 m0, s59, 0x2000
	s_nop 0
	global_load_lds_dwordx4 v128, s[30:31]
	s_mov_b32 m0, s27
	s_add_u32 s100, s34, s10
	s_addc_u32 s101, s35, s11
	global_load_lds_dwordx4 v134, s[34:35]
	s_mov_b32 m0, s43
	s_nop 0
	global_load_lds_dwordx4 v130, s[34:35]
	s_add_u32 s60, s30, 0x40000
	s_addc_u32 s61, s31, 0
	s_add_i32 s59, s51, s40
	s_mov_b32 m0, s59
	s_nop 0
	global_load_lds_dwordx4 v132, s[60:61]
	s_add_i32 m0, s59, 0x2000
	s_nop 0
	global_load_lds_dwordx4 v128, s[60:61]
	s_waitcnt vmcnt(8) lgkmcnt(0)
	s_barrier
; #define PG8_STAGE(bufoff, gbase, voff) do { _Pragma("unroll") for (int _i = 0; _i < 2; ++_i) \
;         __builtin_amdgcn_global_load_lds((const unsigned*)((const char*)(gbase) + (voff)[_i]), (PG8_LAS unsigned*)(lds + (bufoff) + ldsw + _i * 8192), 16, 0, 0); } while (0)
; #define PG8_LDA(dst, b, h) do { _Pragma("unroll") for (int m = 0; m < 4; ++m) _Pragma("unroll") for (int k = 0; k < 2; ++k) dst[m][k] = *(const PG8_LAS bf16x8*)(lds + PG8_SA(b, h) + aoff + m * 2048 + k * 1024); } while (0)
; #define PG8_LDB(dst, b, h) do { _Pragma("unroll") for (int n = 0; n < 2; ++n) _Pragma("unroll") for (int k = 0; k < 2; ++k) dst[n][k] = *(const PG8_LAS bf16x8*)(lds + PG8_SB(b, h) + boff + n * 2048 + k * 1024); } while (0)
; #define PG8_MMA(ai, bj, At, Bt) do { __builtin_amdgcn_s_setprio(1); _Pragma("unroll") for (int m = 0; m < 4; ++m) _Pragma("unroll") for (int n = 0; n < 2; ++n) _Pragma("unroll") for (int k = 0; k < 2; ++k) \
;         acc[ai][bj][m][n] = __builtin_amdgcn_mfma_f32_16x16x32_bf16(Bt[n][k], At[m][k], acc[ai][bj][m][n], 0, 0, 0); __builtin_amdgcn_s_setprio(0); } while (0)
; #define PG8_WAIT_V(n) asm volatile("s_waitcnt vmcnt(" #n ")" ::: "memory")
; #define PG8_WAIT_L(n) asm volatile("s_waitcnt lgkmcnt(" #n ")" ::: "memory")
; #define PG8_BAR __builtin_amdgcn_s_barrier()
; #define PG8_SCHED __builtin_amdgcn_sched_barrier(0)
; template <class Epi, class Sched>
; __device__ __forceinline__ void gemm_phase(PG8_LAS unsigned char* lds, const Gemm g, const Sched& S, const Epi& E) {
;     ...
;             PG8_LDA(At, 0, 1); PG8_STAGE(PG8_SA(0, 0), a2, voffA);
;             PG8_BAR; PG8_WAIT_L(0); PG8_MMA(1, 0, At, B0); PG8_BAR; PG8_SCHED;
;             PG8_STAGE(PG8_SB(0, 1), b2 + hstep, voffB);
;             PG8_WAIT_V(6); PG8_BAR; PG8_MMA(1, 1, At, B1); PG8_BAR;
;             PG8_LDB(B0, 1, 0); PG8_SCHED; PG8_LDA(At, 1, 0); PG8_STAGE(PG8_SA(0, 1), a2 + hstep, voffA);
;             PG8_WAIT_L(8); PG8_BAR; PG8_WAIT_L(0); PG8_MMA(0, 0, At, B0); PG8_BAR; PG8_SCHED;
	v_mfma_f32_16x16x32_bf16 v[60:63], v[144:147], v[170:173], 0
	v_mfma_f32_16x16x32_bf16 v[56:59], v[160:163], v[170:173], 0
	v_mfma_f32_16x16x32_bf16 v[44:47], v[144:147], v[190:193], 0
	v_mfma_f32_16x16x32_bf16 v[40:43], v[160:163], v[190:193], 0
	v_mfma_f32_16x16x32_bf16 v[28:31], v[144:147], v[198:201], 0
	v_mfma_f32_16x16x32_bf16 v[24:27], v[160:163], v[198:201], 0
	v_mfma_f32_16x16x32_bf16 v[12:15], v[144:147], v[206:209], 0
	v_mfma_f32_16x16x32_bf16 v[8:11], v[160:163], v[206:209], 0
	v_mfma_f32_16x16x32_bf16 v[60:63], v[156:159], v[182:185], v[60:63]
	v_mfma_f32_16x16x32_bf16 v[56:59], v[166:169], v[182:185], v[56:59]
	v_mfma_f32_16x16x32_bf16 v[44:47], v[156:159], v[194:197], v[44:47]
	v_mfma_f32_16x16x32_bf16 v[40:43], v[166:169], v[194:197], v[40:43]
	v_mfma_f32_16x16x32_bf16 v[28:31], v[156:159], v[202:205], v[28:31]
	v_mfma_f32_16x16x32_bf16 v[24:27], v[166:169], v[202:205], v[24:27]
	v_mfma_f32_16x16x32_bf16 v[12:15], v[156:159], v[210:213], v[12:15]
	v_mfma_f32_16x16x32_bf16 v[8:11], v[166:169], v[210:213], v[8:11]
	v_mfma_f32_16x16x32_bf16 v[52:55], v[214:217], v[170:173], 0
	v_mfma_f32_16x16x32_bf16 v[48:51], v[222:225], v[170:173], 0
	v_mfma_f32_16x16x32_bf16 v[36:39], v[214:217], v[190:193], 0
	v_mfma_f32_16x16x32_bf16 v[32:35], v[222:225], v[190:193], 0
	v_mfma_f32_16x16x32_bf16 v[20:23], v[214:217], v[198:201], 0
	v_mfma_f32_16x16x32_bf16 v[16:19], v[222:225], v[198:201], 0
	v_mfma_f32_16x16x32_bf16 v[4:7], v[214:217], v[206:209], 0
	v_mfma_f32_16x16x32_bf16 v[0:3], v[222:225], v[206:209], 0
	v_mfma_f32_16x16x32_bf16 v[52:55], v[218:221], v[182:185], v[52:55]
	v_mfma_f32_16x16x32_bf16 v[48:51], v[226:229], v[182:185], v[48:51]
	v_mfma_f32_16x16x32_bf16 v[36:39], v[218:221], v[194:197], v[36:39]
	v_mfma_f32_16x16x32_bf16 v[32:35], v[226:229], v[194:197], v[32:35]
	v_mfma_f32_16x16x32_bf16 v[20:23], v[218:221], v[202:205], v[20:23]
	v_mfma_f32_16x16x32_bf16 v[16:19], v[226:229], v[202:205], v[16:19]
	v_mfma_f32_16x16x32_bf16 v[4:7], v[218:221], v[210:213], v[4:7]
	v_mfma_f32_16x16x32_bf16 v[0:3], v[226:229], v[210:213], v[0:3]
	s_barrier
	s_add_i32 s59, 0, 0x18000
	v_add_u32_e32 v155, s59, v149
	ds_read_b128 v[144:147], v155
	ds_read_b128 v[156:159], v155 offset:1024
	ds_read_b128 v[160:163], v155 offset:2048
	ds_read_b128 v[166:169], v155 offset:3072
	s_add_u32 s34, s34, 0x40000
	s_addc_u32 s35, s35, 0
	s_mov_b32 m0, s44
	ds_read_b128 v[170:173], v153 offset:32768
	ds_read_b128 v[182:185], v153 offset:33792
	ds_read_b128 v[190:193], v153 offset:34816
	ds_read_b128 v[194:197], v153 offset:35840
	ds_read_b128 v[198:201], v153 offset:36864
	ds_read_b128 v[202:205], v153 offset:37888
	ds_read_b128 v[206:209], v153 offset:38912
	ds_read_b128 v[210:213], v153 offset:39936
	global_load_lds_dwordx4 v134, s[34:35]
	s_mov_b32 m0, s45
	s_nop 0
	global_load_lds_dwordx4 v130, s[34:35]
	s_add_i32 s34, 0, 0x1c000
	v_add_u32_e32 v155, s34, v149
	s_waitcnt lgkmcnt(8)
	ds_read_b128 v[214:217], v155
	ds_read_b128 v[218:221], v155 offset:1024
	ds_read_b128 v[222:225], v155 offset:2048
	ds_read_b128 v[226:229], v155 offset:3072
	s_waitcnt vmcnt(8) lgkmcnt(0)
	s_barrier
	v_mfma_f32_16x16x32_bf16 v[124:127], v[144:147], v[170:173], v[124:127]
	v_mfma_f32_16x16x32_bf16 v[120:123], v[160:163], v[170:173], v[120:123]
	v_mfma_f32_16x16x32_bf16 v[108:111], v[144:147], v[190:193], v[108:111]
	v_mfma_f32_16x16x32_bf16 v[104:107], v[160:163], v[190:193], v[104:107]
	v_mfma_f32_16x16x32_bf16 v[92:95], v[144:147], v[198:201], v[92:95]
	v_mfma_f32_16x16x32_bf16 v[88:91], v[160:163], v[198:201], v[88:91]
	v_mfma_f32_16x16x32_bf16 v[76:79], v[144:147], v[206:209], v[76:79]
	v_mfma_f32_16x16x32_bf16 v[72:75], v[160:163], v[206:209], v[72:75]
	v_mfma_f32_16x16x32_bf16 v[124:127], v[156:159], v[182:185], v[124:127]
	v_mfma_f32_16x16x32_bf16 v[120:123], v[166:169], v[182:185], v[120:123]
	v_mfma_f32_16x16x32_bf16 v[108:111], v[156:159], v[194:197], v[108:111]
	v_mfma_f32_16x16x32_bf16 v[104:107], v[166:169], v[194:197], v[104:107]
	v_mfma_f32_16x16x32_bf16 v[92:95], v[156:159], v[202:205], v[92:95]
	v_mfma_f32_16x16x32_bf16 v[88:91], v[166:169], v[202:205], v[88:91]
	v_mfma_f32_16x16x32_bf16 v[76:79], v[156:159], v[210:213], v[76:79]
	v_mfma_f32_16x16x32_bf16 v[72:75], v[166:169], v[210:213], v[72:75]
	v_mfma_f32_16x16x32_bf16 v[116:119], v[214:217], v[170:173], v[116:119]
	v_mfma_f32_16x16x32_bf16 v[112:115], v[222:225], v[170:173], v[112:115]
	v_mfma_f32_16x16x32_bf16 v[100:103], v[214:217], v[190:193], v[100:103]
	v_mfma_f32_16x16x32_bf16 v[96:99], v[222:225], v[190:193], v[96:99]
	v_mfma_f32_16x16x32_bf16 v[84:87], v[214:217], v[198:201], v[84:87]
	v_mfma_f32_16x16x32_bf16 v[80:83], v[222:225], v[198:201], v[80:83]
	v_mfma_f32_16x16x32_bf16 v[68:71], v[214:217], v[206:209], v[68:71]
	v_mfma_f32_16x16x32_bf16 v[64:67], v[222:225], v[206:209], v[64:67]
	v_mfma_f32_16x16x32_bf16 v[116:119], v[218:221], v[182:185], v[116:119]
	v_mfma_f32_16x16x32_bf16 v[112:115], v[226:229], v[182:185], v[112:115]
	v_mfma_f32_16x16x32_bf16 v[100:103], v[218:221], v[194:197], v[100:103]
	v_mfma_f32_16x16x32_bf16 v[96:99], v[226:229], v[194:197], v[96:99]
	v_mfma_f32_16x16x32_bf16 v[84:87], v[218:221], v[202:205], v[84:87]
	v_mfma_f32_16x16x32_bf16 v[80:83], v[226:229], v[202:205], v[80:83]
	v_mfma_f32_16x16x32_bf16 v[68:71], v[218:221], v[210:213], v[68:71]
	v_mfma_f32_16x16x32_bf16 v[64:67], v[226:229], v[210:213], v[64:67]
	s_barrier
; #define PG8_STAGE(bufoff, gbase, voff) do { _Pragma("unroll") for (int _i = 0; _i < 2; ++_i) \
;         __builtin_amdgcn_global_load_lds((const unsigned*)((const char*)(gbase) + (voff)[_i]), (PG8_LAS unsigned*)(lds + (bufoff) + ldsw + _i * 8192), 16, 0, 0); } while (0)
; #define PG8_LDA(dst, b, h) do { _Pragma("unroll") for (int m = 0; m < 4; ++m) _Pragma("unroll") for (int k = 0; k < 2; ++k) dst[m][k] = *(const PG8_LAS bf16x8*)(lds + PG8_SA(b, h) + aoff + m * 2048 + k * 1024); } while (0)
; #define PG8_LDB(dst, b, h) do { _Pragma("unroll") for (int n = 0; n < 2; ++n) _Pragma("unroll") for (int k = 0; k < 2; ++k) dst[n][k] = *(const PG8_LAS bf16x8*)(lds + PG8_SB(b, h) + boff + n * 2048 + k * 1024); } while (0)
; #define PG8_MMA(ai, bj, At, Bt) do { __builtin_amdgcn_s_setprio(1); _Pragma("unroll") for (int m = 0; m < 4; ++m) _Pragma("unroll") for (int n = 0; n < 2; ++n) _Pragma("unroll") for (int k = 0; k < 2; ++k) \
;         acc[ai][bj][m][n] = __builtin_amdgcn_mfma_f32_16x16x32_bf16(Bt[n][k], At[m][k], acc[ai][bj][m][n], 0, 0, 0); __builtin_amdgcn_s_setprio(0); } while (0)
; #define PG8_WAIT_V(n) asm volatile("s_waitcnt vmcnt(" #n ")" ::: "memory")
; #define PG8_WAIT_L(n) asm volatile("s_waitcnt lgkmcnt(" #n ")" ::: "memory")
; #define PG8_BAR __builtin_amdgcn_s_barrier()
; #define PG8_SCHED __builtin_amdgcn_sched_barrier(0)
; template <class Epi, class Sched>
; __device__ __forceinline__ void gemm_phase(PG8_LAS unsigned char* lds, const Gemm g, const Sched& S, const Epi& E) {
;     ...
;         for (int t = 0; t < nt; t += 2) {
;             const bool last = (t == nt - 2);
;             const char* a1 = cA + (size_t)(t + 1) * kstep;
;             const char* a2 = last ? nA : cA + (size_t)(t + 2) * kstep; const char* b2 = last ? nB : cB + (size_t)(t + 2) * kstep;
;             const char* a3 = a2 + kstep; const char* b3 = b2 + kstep;
;             if (last && has_next) S.a_ready(nxt);
;             PG8_LDB(B0, 0, 0); PG8_SCHED; PG8_LDA(At, 0, 0); PG8_STAGE(PG8_SA(1, 1), a1 + hstep, voffA);
;             PG8_WAIT_L(8); PG8_BAR; PG8_WAIT_L(0); PG8_MMA(0, 0, At, B0); PG8_BAR; PG8_SCHED;
;     ...
;             PG8_LDA(At, 1, 1); PG8_STAGE(PG8_SA(1, 0), a3, voffA);
;             PG8_BAR; PG8_WAIT_L(0); PG8_MMA(1, 0, At, B0); PG8_BAR; PG8_SCHED;
;             PG8_STAGE(PG8_SB(1, 1), b3 + hstep, voffB);
;             PG8_WAIT_V(6); PG8_BAR; PG8_MMA(1, 1, At, B1); PG8_BAR;
	ds_read_b128 v[170:173], v153 offset:49152
	ds_read_b128 v[182:185], v153 offset:50176
	ds_read_b128 v[190:193], v153 offset:51200
	ds_read_b128 v[194:197], v153 offset:52224
	ds_read_b128 v[198:201], v153 offset:53248
	ds_read_b128 v[202:205], v153 offset:54272
	ds_read_b128 v[206:209], v153 offset:55296
	ds_read_b128 v[210:213], v153 offset:56320
	s_add_i32 s35, s59, s40
	s_mov_b32 m0, s35
	s_nop 0
	global_load_lds_dwordx4 v132, s[98:99]
	s_add_i32 m0, s35, 0x2000
	s_nop 0
	global_load_lds_dwordx4 v128, s[98:99]
	s_mov_b32 m0, s47
	s_nop 0
	global_load_lds_dwordx4 v134, s[100:101]
	s_mov_b32 m0, s48
	s_nop 0
	global_load_lds_dwordx4 v130, s[100:101]
	s_add_u32 s30, s30, 0x40080
	s_addc_u32 s31, s31, 0
	s_add_i32 s34, s34, s40
	s_mov_b32 m0, s34
	s_nop 0
	global_load_lds_dwordx4 v132, s[30:31]
	s_add_i32 m0, s34, 0x2000
	s_nop 0
	global_load_lds_dwordx4 v128, s[30:31]
	s_waitcnt vmcnt(8) lgkmcnt(0)
	s_barrier
	v_mfma_f32_16x16x32_bf16 v[60:63], v[144:147], v[170:173], v[60:63]
	v_mfma_f32_16x16x32_bf16 v[56:59], v[160:163], v[170:173], v[56:59]
	v_mfma_f32_16x16x32_bf16 v[44:47], v[144:147], v[190:193], v[44:47]
	v_mfma_f32_16x16x32_bf16 v[40:43], v[160:163], v[190:193], v[40:43]
	v_mfma_f32_16x16x32_bf16 v[28:31], v[144:147], v[198:201], v[28:31]
	v_mfma_f32_16x16x32_bf16 v[24:27], v[160:163], v[198:201], v[24:27]
	v_mfma_f32_16x16x32_bf16 v[12:15], v[144:147], v[206:209], v[12:15]
	v_mfma_f32_16x16x32_bf16 v[8:11], v[160:163], v[206:209], v[8:11]
	v_mfma_f32_16x16x32_bf16 v[60:63], v[156:159], v[182:185], v[60:63]
	v_mfma_f32_16x16x32_bf16 v[56:59], v[166:169], v[182:185], v[56:59]
	v_mfma_f32_16x16x32_bf16 v[44:47], v[156:159], v[194:197], v[44:47]
	v_mfma_f32_16x16x32_bf16 v[40:43], v[166:169], v[194:197], v[40:43]
	v_mfma_f32_16x16x32_bf16 v[28:31], v[156:159], v[202:205], v[28:31]
	v_mfma_f32_16x16x32_bf16 v[24:27], v[166:169], v[202:205], v[24:27]
	v_mfma_f32_16x16x32_bf16 v[12:15], v[156:159], v[210:213], v[12:15]
	v_mfma_f32_16x16x32_bf16 v[8:11], v[166:169], v[210:213], v[8:11]
	v_mfma_f32_16x16x32_bf16 v[52:55], v[214:217], v[170:173], v[52:55]
	v_mfma_f32_16x16x32_bf16 v[48:51], v[222:225], v[170:173], v[48:51]
	v_mfma_f32_16x16x32_bf16 v[36:39], v[214:217], v[190:193], v[36:39]
	v_mfma_f32_16x16x32_bf16 v[32:35], v[222:225], v[190:193], v[32:35]
	v_mfma_f32_16x16x32_bf16 v[20:23], v[214:217], v[198:201], v[20:23]
	v_mfma_f32_16x16x32_bf16 v[16:19], v[222:225], v[198:201], v[16:19]
	v_mfma_f32_16x16x32_bf16 v[4:7], v[214:217], v[206:209], v[4:7]
	v_mfma_f32_16x16x32_bf16 v[0:3], v[222:225], v[206:209], v[0:3]
	v_mfma_f32_16x16x32_bf16 v[52:55], v[218:221], v[182:185], v[52:55]
	v_mfma_f32_16x16x32_bf16 v[48:51], v[226:229], v[182:185], v[48:51]
	v_mfma_f32_16x16x32_bf16 v[36:39], v[218:221], v[194:197], v[36:39]
	v_mfma_f32_16x16x32_bf16 v[32:35], v[226:229], v[194:197], v[32:35]
	v_mfma_f32_16x16x32_bf16 v[20:23], v[218:221], v[202:205], v[20:23]
	v_mfma_f32_16x16x32_bf16 v[16:19], v[226:229], v[202:205], v[16:19]
	v_mfma_f32_16x16x32_bf16 v[4:7], v[218:221], v[210:213], v[4:7]
	v_mfma_f32_16x16x32_bf16 v[0:3], v[226:229], v[210:213], v[0:3]
	s_barrier
	s_add_i32 s58, s58, 2
	s_add_u32 s28, s28, 0x100
	s_addc_u32 s29, s29, 0
	s_add_u32 s56, s56, 0x100
	s_addc_u32 s57, s57, 0
	s_cmp_gt_u32 s58, 13
.LBB0_195:
	ds_read_b128 v[144:147], v151
	ds_read_b128 v[156:159], v151 offset:1024
	ds_read_b128 v[160:163], v151 offset:2048
	ds_read_b128 v[166:169], v151 offset:3072
	s_add_u32 s30, s28, 0xfffc0080
	s_addc_u32 s31, s29, -1
	s_cmp_eq_u32 s58, 12
	s_cselect_b32 s35, s17, s31
	s_cselect_b32 s34, s54, s30
	s_cselect_b32 s31, s15, s57
	s_cselect_b32 s30, s55, s56
	s_add_i32 m0, s27, 0xc000
	ds_read_b128 v[170:173], v153
	ds_read_b128 v[182:185], v153 offset:1024
	ds_read_b128 v[190:193], v153 offset:2048
	ds_read_b128 v[194:197], v153 offset:3072
	ds_read_b128 v[198:201], v153 offset:4096
	ds_read_b128 v[202:205], v153 offset:5120
	ds_read_b128 v[206:209], v153 offset:6144
	ds_read_b128 v[210:213], v153 offset:7168
	global_load_lds_dwordx4 v136, s[28:29]
	s_add_i32 m0, s27, 0xe000
	s_nop 0
	global_load_lds_dwordx4 v138, s[28:29]
	s_waitcnt lgkmcnt(8)
	ds_read_b128 v[214:217], v154
	ds_read_b128 v[218:221], v154 offset:1024
	ds_read_b128 v[222:225], v154 offset:2048
	ds_read_b128 v[226:229], v154 offset:3072
	s_waitcnt vmcnt(8) lgkmcnt(0)
	s_barrier
	v_mfma_f32_16x16x32_bf16 v[124:127], v[144:147], v[170:173], v[124:127]
	v_mfma_f32_16x16x32_bf16 v[120:123], v[160:163], v[170:173], v[120:123]
	v_mfma_f32_16x16x32_bf16 v[108:111], v[144:147], v[190:193], v[108:111]
	v_mfma_f32_16x16x32_bf16 v[104:107], v[160:163], v[190:193], v[104:107]
	v_mfma_f32_16x16x32_bf16 v[92:95], v[144:147], v[198:201], v[92:95]
	v_mfma_f32_16x16x32_bf16 v[88:91], v[160:163], v[198:201], v[88:91]
	v_mfma_f32_16x16x32_bf16 v[76:79], v[144:147], v[206:209], v[76:79]
	v_mfma_f32_16x16x32_bf16 v[72:75], v[160:163], v[206:209], v[72:75]
	v_mfma_f32_16x16x32_bf16 v[124:127], v[156:159], v[182:185], v[124:127]
	v_mfma_f32_16x16x32_bf16 v[120:123], v[166:169], v[182:185], v[120:123]
	v_mfma_f32_16x16x32_bf16 v[108:111], v[156:159], v[194:197], v[108:111]
	v_mfma_f32_16x16x32_bf16 v[104:107], v[166:169], v[194:197], v[104:107]
	v_mfma_f32_16x16x32_bf16 v[92:95], v[156:159], v[202:205], v[92:95]
	v_mfma_f32_16x16x32_bf16 v[88:91], v[166:169], v[202:205], v[88:91]
	v_mfma_f32_16x16x32_bf16 v[76:79], v[156:159], v[210:213], v[76:79]
	v_mfma_f32_16x16x32_bf16 v[72:75], v[166:169], v[210:213], v[72:75]
	v_mfma_f32_16x16x32_bf16 v[116:119], v[214:217], v[170:173], v[116:119]
	v_mfma_f32_16x16x32_bf16 v[112:115], v[222:225], v[170:173], v[112:115]
	v_mfma_f32_16x16x32_bf16 v[100:103], v[214:217], v[190:193], v[100:103]
	v_mfma_f32_16x16x32_bf16 v[96:99], v[222:225], v[190:193], v[96:99]
	v_mfma_f32_16x16x32_bf16 v[84:87], v[214:217], v[198:201], v[84:87]
	v_mfma_f32_16x16x32_bf16 v[80:83], v[222:225], v[198:201], v[80:83]
	v_mfma_f32_16x16x32_bf16 v[68:71], v[214:217], v[206:209], v[68:71]
	v_mfma_f32_16x16x32_bf16 v[64:67], v[222:225], v[206:209], v[64:67]
	v_mfma_f32_16x16x32_bf16 v[116:119], v[218:221], v[182:185], v[116:119]
	v_mfma_f32_16x16x32_bf16 v[112:115], v[226:229], v[182:185], v[112:115]
	v_mfma_f32_16x16x32_bf16 v[100:103], v[218:221], v[194:197], v[100:103]
	v_mfma_f32_16x16x32_bf16 v[96:99], v[226:229], v[194:197], v[96:99]
	v_mfma_f32_16x16x32_bf16 v[84:87], v[218:221], v[202:205], v[84:87]
	v_mfma_f32_16x16x32_bf16 v[80:83], v[226:229], v[202:205], v[80:83]
	v_mfma_f32_16x16x32_bf16 v[68:71], v[218:221], v[210:213], v[68:71]
	v_mfma_f32_16x16x32_bf16 v[64:67], v[226:229], v[210:213], v[64:67]
	s_barrier
; #define PG8_STAGE(bufoff, gbase, voff) do { _Pragma("unroll") for (int _i = 0; _i < 2; ++_i) \
;         __builtin_amdgcn_global_load_lds((const unsigned*)((const char*)(gbase) + (voff)[_i]), (PG8_LAS unsigned*)(lds + (bufoff) + ldsw + _i * 8192), 16, 0, 0); } while (0)
; #define PG8_LDA(dst, b, h) do { _Pragma("unroll") for (int m = 0; m < 4; ++m) _Pragma("unroll") for (int k = 0; k < 2; ++k) dst[m][k] = *(const PG8_LAS bf16x8*)(lds + PG8_SA(b, h) + aoff + m * 2048 + k * 1024); } while (0)
; #define PG8_LDB(dst, b, h) do { _Pragma("unroll") for (int n = 0; n < 2; ++n) _Pragma("unroll") for (int k = 0; k < 2; ++k) dst[n][k] = *(const PG8_LAS bf16x8*)(lds + PG8_SB(b, h) + boff + n * 2048 + k * 1024); } while (0)
; #define PG8_MMA(ai, bj, At, Bt) do { __builtin_amdgcn_s_setprio(1); _Pragma("unroll") for (int m = 0; m < 4; ++m) _Pragma("unroll") for (int n = 0; n < 2; ++n) _Pragma("unroll") for (int k = 0; k < 2; ++k) \
;         acc[ai][bj][m][n] = __builtin_amdgcn_mfma_f32_16x16x32_bf16(Bt[n][k], At[m][k], acc[ai][bj][m][n], 0, 0, 0); __builtin_amdgcn_s_setprio(0); } while (0)
; #define PG8_WAIT_V(n) asm volatile("s_waitcnt vmcnt(" #n ")" ::: "memory")
; #define PG8_WAIT_L(n) asm volatile("s_waitcnt lgkmcnt(" #n ")" ::: "memory")
; #define PG8_BAR __builtin_amdgcn_s_barrier()
; #define PG8_SCHED __builtin_amdgcn_sched_barrier(0)
; template <class Epi, class Sched>
; __device__ __forceinline__ void gemm_phase(PG8_LAS unsigned char* lds, const Gemm g, const Sched& S, const Epi& E) {
;     ...
;             PG8_LDB(B1, 0, 1); PG8_STAGE(PG8_SB(0, 0), b2, voffB);
;             PG8_BAR; PG8_WAIT_L(0); PG8_MMA(0, 1, At, B1); PG8_BAR;
;             PG8_LDA(At, 0, 1); PG8_STAGE(PG8_SA(0, 0), a2, voffA);
;             PG8_BAR; PG8_WAIT_L(0); PG8_MMA(1, 0, At, B0); PG8_BAR; PG8_SCHED;
;             PG8_STAGE(PG8_SB(0, 1), b2 + hstep, voffB);
;             PG8_WAIT_V(6); PG8_BAR; PG8_MMA(1, 1, At, B1); PG8_BAR;
;             PG8_LDB(B0, 1, 0); PG8_SCHED; PG8_LDA(At, 1, 0); PG8_STAGE(PG8_SA(0, 1), a2 + hstep, voffA);
;             PG8_WAIT_L(8); PG8_BAR; PG8_WAIT_L(0); PG8_MMA(0, 0, At, B0); PG8_BAR; PG8_SCHED;
;             PG8_LDB(B1, 1, 1); PG8_STAGE(PG8_SB(1, 0), b3, voffB);
;             PG8_BAR; PG8_WAIT_L(0); PG8_MMA(0, 1, At, B1); PG8_BAR;
	ds_read_b128 v[170:173], v153 offset:16384
	ds_read_b128 v[182:185], v153 offset:17408
	ds_read_b128 v[190:193], v153 offset:18432
	ds_read_b128 v[194:197], v153 offset:19456
	ds_read_b128 v[198:201], v153 offset:20480
	ds_read_b128 v[202:205], v153 offset:21504
	ds_read_b128 v[206:209], v153 offset:22528
	ds_read_b128 v[210:213], v153 offset:23552
	s_add_i32 s59, s50, s40
	s_add_u32 s98, s30, s10
	s_addc_u32 s99, s31, s11
	s_mov_b32 m0, s59
	s_nop 0
	global_load_lds_dwordx4 v132, s[30:31]
	s_add_i32 m0, s59, 0x2000
	s_nop 0
	global_load_lds_dwordx4 v128, s[30:31]
	s_mov_b32 m0, s27
	s_add_u32 s100, s34, s10
	s_addc_u32 s101, s35, s11
	global_load_lds_dwordx4 v134, s[34:35]
	s_mov_b32 m0, s43
	s_nop 0
	global_load_lds_dwordx4 v130, s[34:35]
	s_add_u32 s60, s30, 0x40000
	s_addc_u32 s61, s31, 0
	s_add_i32 s59, s51, s40
	s_mov_b32 m0, s59
	s_nop 0
	global_load_lds_dwordx4 v132, s[60:61]
	s_add_i32 m0, s59, 0x2000
	s_nop 0
	global_load_lds_dwordx4 v128, s[60:61]
	s_waitcnt vmcnt(8) lgkmcnt(0)
	s_barrier
	v_mfma_f32_16x16x32_bf16 v[60:63], v[144:147], v[170:173], v[60:63]
	v_mfma_f32_16x16x32_bf16 v[56:59], v[160:163], v[170:173], v[56:59]
	v_mfma_f32_16x16x32_bf16 v[44:47], v[144:147], v[190:193], v[44:47]
	v_mfma_f32_16x16x32_bf16 v[40:43], v[160:163], v[190:193], v[40:43]
	v_mfma_f32_16x16x32_bf16 v[28:31], v[144:147], v[198:201], v[28:31]
	v_mfma_f32_16x16x32_bf16 v[24:27], v[160:163], v[198:201], v[24:27]
	v_mfma_f32_16x16x32_bf16 v[12:15], v[144:147], v[206:209], v[12:15]
	v_mfma_f32_16x16x32_bf16 v[8:11], v[160:163], v[206:209], v[8:11]
	v_mfma_f32_16x16x32_bf16 v[60:63], v[156:159], v[182:185], v[60:63]
	v_mfma_f32_16x16x32_bf16 v[56:59], v[166:169], v[182:185], v[56:59]
	v_mfma_f32_16x16x32_bf16 v[44:47], v[156:159], v[194:197], v[44:47]
	v_mfma_f32_16x16x32_bf16 v[40:43], v[166:169], v[194:197], v[40:43]
	v_mfma_f32_16x16x32_bf16 v[28:31], v[156:159], v[202:205], v[28:31]
	v_mfma_f32_16x16x32_bf16 v[24:27], v[166:169], v[202:205], v[24:27]
	v_mfma_f32_16x16x32_bf16 v[12:15], v[156:159], v[210:213], v[12:15]
	v_mfma_f32_16x16x32_bf16 v[8:11], v[166:169], v[210:213], v[8:11]
	v_mfma_f32_16x16x32_bf16 v[52:55], v[214:217], v[170:173], v[52:55]
	v_mfma_f32_16x16x32_bf16 v[48:51], v[222:225], v[170:173], v[48:51]
	v_mfma_f32_16x16x32_bf16 v[36:39], v[214:217], v[190:193], v[36:39]
	v_mfma_f32_16x16x32_bf16 v[32:35], v[222:225], v[190:193], v[32:35]
	v_mfma_f32_16x16x32_bf16 v[20:23], v[214:217], v[198:201], v[20:23]
	v_mfma_f32_16x16x32_bf16 v[16:19], v[222:225], v[198:201], v[16:19]
	v_mfma_f32_16x16x32_bf16 v[4:7], v[214:217], v[206:209], v[4:7]
	v_mfma_f32_16x16x32_bf16 v[0:3], v[222:225], v[206:209], v[0:3]
	v_mfma_f32_16x16x32_bf16 v[52:55], v[218:221], v[182:185], v[52:55]
	v_mfma_f32_16x16x32_bf16 v[48:51], v[226:229], v[182:185], v[48:51]
	v_mfma_f32_16x16x32_bf16 v[36:39], v[218:221], v[194:197], v[36:39]
	v_mfma_f32_16x16x32_bf16 v[32:35], v[226:229], v[194:197], v[32:35]
	v_mfma_f32_16x16x32_bf16 v[20:23], v[218:221], v[202:205], v[20:23]
	v_mfma_f32_16x16x32_bf16 v[16:19], v[226:229], v[202:205], v[16:19]
	v_mfma_f32_16x16x32_bf16 v[4:7], v[218:221], v[210:213], v[4:7]
	v_mfma_f32_16x16x32_bf16 v[0:3], v[226:229], v[210:213], v[0:3]
	s_barrier
	s_add_i32 s59, 0, 0x18000
	v_add_u32_e32 v155, s59, v149
	ds_read_b128 v[144:147], v155
	ds_read_b128 v[156:159], v155 offset:1024
	ds_read_b128 v[160:163], v155 offset:2048
	ds_read_b128 v[166:169], v155 offset:3072
	s_add_u32 s34, s34, 0x40000
	s_addc_u32 s35, s35, 0
	s_mov_b32 m0, s44
	ds_read_b128 v[170:173], v153 offset:32768
	ds_read_b128 v[182:185], v153 offset:33792
	ds_read_b128 v[190:193], v153 offset:34816
	ds_read_b128 v[194:197], v153 offset:35840
	ds_read_b128 v[198:201], v153 offset:36864
	ds_read_b128 v[202:205], v153 offset:37888
	ds_read_b128 v[206:209], v153 offset:38912
	ds_read_b128 v[210:213], v153 offset:39936
	global_load_lds_dwordx4 v134, s[34:35]
	s_mov_b32 m0, s45
	s_nop 0
	global_load_lds_dwordx4 v130, s[34:35]
	s_add_i32 s34, 0, 0x1c000
	v_add_u32_e32 v155, s34, v149
	s_waitcnt lgkmcnt(8)
	ds_read_b128 v[214:217], v155
	ds_read_b128 v[218:221], v155 offset:1024
	ds_read_b128 v[222:225], v155 offset:2048
	ds_read_b128 v[226:229], v155 offset:3072
	s_waitcnt vmcnt(8) lgkmcnt(0)
	s_barrier
	v_mfma_f32_16x16x32_bf16 v[124:127], v[144:147], v[170:173], v[124:127]
	v_mfma_f32_16x16x32_bf16 v[120:123], v[160:163], v[170:173], v[120:123]
	v_mfma_f32_16x16x32_bf16 v[108:111], v[144:147], v[190:193], v[108:111]
	v_mfma_f32_16x16x32_bf16 v[104:107], v[160:163], v[190:193], v[104:107]
	v_mfma_f32_16x16x32_bf16 v[92:95], v[144:147], v[198:201], v[92:95]
	v_mfma_f32_16x16x32_bf16 v[88:91], v[160:163], v[198:201], v[88:91]
	v_mfma_f32_16x16x32_bf16 v[76:79], v[144:147], v[206:209], v[76:79]
	v_mfma_f32_16x16x32_bf16 v[72:75], v[160:163], v[206:209], v[72:75]
	v_mfma_f32_16x16x32_bf16 v[124:127], v[156:159], v[182:185], v[124:127]
	v_mfma_f32_16x16x32_bf16 v[120:123], v[166:169], v[182:185], v[120:123]
	v_mfma_f32_16x16x32_bf16 v[108:111], v[156:159], v[194:197], v[108:111]
	v_mfma_f32_16x16x32_bf16 v[104:107], v[166:169], v[194:197], v[104:107]
	v_mfma_f32_16x16x32_bf16 v[92:95], v[156:159], v[202:205], v[92:95]
	v_mfma_f32_16x16x32_bf16 v[88:91], v[166:169], v[202:205], v[88:91]
	v_mfma_f32_16x16x32_bf16 v[76:79], v[156:159], v[210:213], v[76:79]
	v_mfma_f32_16x16x32_bf16 v[72:75], v[166:169], v[210:213], v[72:75]
	v_mfma_f32_16x16x32_bf16 v[116:119], v[214:217], v[170:173], v[116:119]
	v_mfma_f32_16x16x32_bf16 v[112:115], v[222:225], v[170:173], v[112:115]
	v_mfma_f32_16x16x32_bf16 v[100:103], v[214:217], v[190:193], v[100:103]
	v_mfma_f32_16x16x32_bf16 v[96:99], v[222:225], v[190:193], v[96:99]
	v_mfma_f32_16x16x32_bf16 v[84:87], v[214:217], v[198:201], v[84:87]
	v_mfma_f32_16x16x32_bf16 v[80:83], v[222:225], v[198:201], v[80:83]
	v_mfma_f32_16x16x32_bf16 v[68:71], v[214:217], v[206:209], v[68:71]
	v_mfma_f32_16x16x32_bf16 v[64:67], v[222:225], v[206:209], v[64:67]
	v_mfma_f32_16x16x32_bf16 v[116:119], v[218:221], v[182:185], v[116:119]
	v_mfma_f32_16x16x32_bf16 v[112:115], v[226:229], v[182:185], v[112:115]
	v_mfma_f32_16x16x32_bf16 v[100:103], v[218:221], v[194:197], v[100:103]
	v_mfma_f32_16x16x32_bf16 v[96:99], v[226:229], v[194:197], v[96:99]
	v_mfma_f32_16x16x32_bf16 v[84:87], v[218:221], v[202:205], v[84:87]
	v_mfma_f32_16x16x32_bf16 v[80:83], v[226:229], v[202:205], v[80:83]
	v_mfma_f32_16x16x32_bf16 v[68:71], v[218:221], v[210:213], v[68:71]
	v_mfma_f32_16x16x32_bf16 v[64:67], v[226:229], v[210:213], v[64:67]
	s_barrier
; __device__ __forceinline__ unsigned cvt_pk_bf16(float lo, float hi) { unsigned r; asm volatile("v_cvt_pk_bf16_f32 %0, %1, %2" : "=v"(r) : "v"(lo), "v"(hi)); return r; }
; #define PG8_STAGE(bufoff, gbase, voff) do { _Pragma("unroll") for (int _i = 0; _i < 2; ++_i) \
;         __builtin_amdgcn_global_load_lds((const unsigned*)((const char*)(gbase) + (voff)[_i]), (PG8_LAS unsigned*)(lds + (bufoff) + ldsw + _i * 8192), 16, 0, 0); } while (0)
; #define PG8_LDA(dst, b, h) do { _Pragma("unroll") for (int m = 0; m < 4; ++m) _Pragma("unroll") for (int k = 0; k < 2; ++k) dst[m][k] = *(const PG8_LAS bf16x8*)(lds + PG8_SA(b, h) + aoff + m * 2048 + k * 1024); } while (0)
; #define PG8_MMA(ai, bj, At, Bt) do { __builtin_amdgcn_s_setprio(1); _Pragma("unroll") for (int m = 0; m < 4; ++m) _Pragma("unroll") for (int n = 0; n < 2; ++n) _Pragma("unroll") for (int k = 0; k < 2; ++k) \
;         acc[ai][bj][m][n] = __builtin_amdgcn_mfma_f32_16x16x32_bf16(Bt[n][k], At[m][k], acc[ai][bj][m][n], 0, 0, 0); __builtin_amdgcn_s_setprio(0); } while (0)
; #define PG8_BAR __builtin_amdgcn_s_barrier()
;     __device__ __forceinline__ void operator()(const f32x4 (&acc)[2][2][4][2], const Unit& u, int wr, int wc, int fr, int fq) const {
;         const int row0 = u.pm * BM + wr * 64 + fr, col0 = u.pn * HALF + wc * 32 + 8 * fq;
; #pragma unroll
;         for (int ai = 0; ai < 2; ++ai)
; #pragma unroll
;             for (int m = 0; m < 4; ++m) { bf16_t* rowp = O + (size_t)(row0 + ai * HALF + m * 16) * ldc + col0;
;                 f32x4 v0, v1;
; #pragma unroll
;                 for (int j = 0; j < 1; ++j) { v0 = acc[ai][0][m][0] * sigmoid4(acc[ai][0][m][0]) * acc[ai][1][m][0]; v1 = acc[ai][0][m][1] * sigmoid4(acc[ai][0][m][1]) * acc[ai][1][m][1]; }
;                 u32x4 w; w.x = cvt_pk_bf16(v0[0], v0[1]); w.y = cvt_pk_bf16(v0[2], v0[3]); w.z = cvt_pk_bf16(v1[0], v1[1]); w.w = cvt_pk_bf16(v1[2], v1[3]);
;                 *(u32x4*)rowp = w; }
; template <class Epi, class Sched>
; __device__ __forceinline__ void gemm_phase(PG8_LAS unsigned char* lds, const Gemm g, const Sched& S, const Epi& E) {
;     ...
;             PG8_LDA(At, 1, 1); PG8_STAGE(PG8_SA(1, 0), a3, voffA);
;             PG8_BAR; PG8_WAIT_L(0); PG8_MMA(1, 0, At, B0); PG8_BAR; PG8_SCHED;
;             PG8_STAGE(PG8_SB(1, 1), b3 + hstep, voffB);
;             PG8_WAIT_V(6); PG8_BAR; PG8_MMA(1, 1, At, B1); PG8_BAR;
	ds_read_b128 v[170:173], v153 offset:49152
	ds_read_b128 v[182:185], v153 offset:50176
	ds_read_b128 v[190:193], v153 offset:51200
	ds_read_b128 v[194:197], v153 offset:52224
	ds_read_b128 v[198:201], v153 offset:53248
	ds_read_b128 v[202:205], v153 offset:54272
	ds_read_b128 v[206:209], v153 offset:55296
	ds_read_b128 v[210:213], v153 offset:56320
	s_add_i32 s35, s59, s40
	s_mov_b32 m0, s35
	s_nop 0
	global_load_lds_dwordx4 v132, s[98:99]
	s_add_i32 m0, s35, 0x2000
	s_nop 0
	global_load_lds_dwordx4 v128, s[98:99]
	s_mov_b32 m0, s47
	s_nop 0
	global_load_lds_dwordx4 v134, s[100:101]
	s_mov_b32 m0, s48
	s_nop 0
	global_load_lds_dwordx4 v130, s[100:101]
	s_add_u32 s30, s30, 0x40080
	s_addc_u32 s31, s31, 0
	s_add_i32 s34, s34, s40
	s_mov_b32 m0, s34
	s_nop 0
	global_load_lds_dwordx4 v132, s[30:31]
	s_add_i32 m0, s34, 0x2000
	s_nop 0
	global_load_lds_dwordx4 v128, s[30:31]
	s_waitcnt vmcnt(8) lgkmcnt(0)
	s_barrier
	v_mfma_f32_16x16x32_bf16 v[60:63], v[144:147], v[170:173], v[60:63]
	v_mfma_f32_16x16x32_bf16 v[56:59], v[160:163], v[170:173], v[56:59]
	v_mfma_f32_16x16x32_bf16 v[44:47], v[144:147], v[190:193], v[44:47]
	v_mfma_f32_16x16x32_bf16 v[40:43], v[160:163], v[190:193], v[40:43]
	v_mfma_f32_16x16x32_bf16 v[28:31], v[144:147], v[198:201], v[28:31]
	v_mfma_f32_16x16x32_bf16 v[24:27], v[160:163], v[198:201], v[24:27]
	v_mfma_f32_16x16x32_bf16 v[12:15], v[144:147], v[206:209], v[12:15]
	v_mfma_f32_16x16x32_bf16 v[8:11], v[160:163], v[206:209], v[8:11]
	v_mfma_f32_16x16x32_bf16 v[60:63], v[156:159], v[182:185], v[60:63]
	v_mfma_f32_16x16x32_bf16 v[56:59], v[166:169], v[182:185], v[56:59]
	v_mfma_f32_16x16x32_bf16 v[44:47], v[156:159], v[194:197], v[44:47]
	v_mfma_f32_16x16x32_bf16 v[40:43], v[166:169], v[194:197], v[40:43]
	v_mfma_f32_16x16x32_bf16 v[28:31], v[156:159], v[202:205], v[28:31]
	v_mfma_f32_16x16x32_bf16 v[24:27], v[166:169], v[202:205], v[24:27]
	v_mfma_f32_16x16x32_bf16 v[12:15], v[156:159], v[210:213], v[12:15]
	v_mfma_f32_16x16x32_bf16 v[8:11], v[166:169], v[210:213], v[8:11]
	v_mfma_f32_16x16x32_bf16 v[52:55], v[214:217], v[170:173], v[52:55]
	v_mfma_f32_16x16x32_bf16 v[48:51], v[222:225], v[170:173], v[48:51]
	v_mfma_f32_16x16x32_bf16 v[36:39], v[214:217], v[190:193], v[36:39]
	v_mfma_f32_16x16x32_bf16 v[32:35], v[222:225], v[190:193], v[32:35]
	v_mfma_f32_16x16x32_bf16 v[20:23], v[214:217], v[198:201], v[20:23]
	v_mfma_f32_16x16x32_bf16 v[16:19], v[222:225], v[198:201], v[16:19]
	v_mfma_f32_16x16x32_bf16 v[4:7], v[214:217], v[206:209], v[4:7]
	v_mfma_f32_16x16x32_bf16 v[0:3], v[222:225], v[206:209], v[0:3]
	v_mfma_f32_16x16x32_bf16 v[52:55], v[218:221], v[182:185], v[52:55]
	v_mfma_f32_16x16x32_bf16 v[48:51], v[226:229], v[182:185], v[48:51]
	v_mfma_f32_16x16x32_bf16 v[36:39], v[218:221], v[194:197], v[36:39]
	v_mfma_f32_16x16x32_bf16 v[32:35], v[226:229], v[194:197], v[32:35]
	v_mfma_f32_16x16x32_bf16 v[20:23], v[218:221], v[202:205], v[20:23]
	v_mfma_f32_16x16x32_bf16 v[16:19], v[226:229], v[202:205], v[16:19]
	v_mfma_f32_16x16x32_bf16 v[4:7], v[218:221], v[210:213], v[4:7]
	v_mfma_f32_16x16x32_bf16 v[0:3], v[226:229], v[210:213], v[0:3]
	s_barrier
	s_add_i32 s58, s58, 2
	s_add_u32 s28, s28, 0x100
	s_addc_u32 s29, s29, 0
	s_add_u32 s56, s56, 0x100
	s_addc_u32 s57, s57, 0
	s_cmp_gt_u32 s58, 13
	s_cbranch_scc0 .LBB0_195
	v_max_f32_e32 v144, 0xc1a00000, v124
	v_mul_f32_e32 v144, 0xbfb8aa3b, v144
	v_exp_f32_e32 v157, v144
	v_max_f32_e32 v144, 0xc1a00000, v125
	v_mul_f32_e32 v144, 0xbfb8aa3b, v144
	v_exp_f32_e32 v156, v144
	v_max_f32_e32 v144, 0xc1a00000, v126
	v_mul_f32_e32 v144, 0xbfb8aa3b, v144
	v_exp_f32_e32 v159, v144
	v_max_f32_e32 v144, 0xc1a00000, v127
	v_mul_f32_e32 v144, 0xbfb8aa3b, v144
	v_exp_f32_e32 v158, v144
	v_pk_add_f32 v[156:157], v[156:157], 1.0 op_sel_hi:[1,0]
	v_lshl_or_b32 v146, s53, 7, v150
	v_mov_b32_e32 v160, v157
	v_pk_add_f32 v[158:159], v[158:159], 1.0 op_sel_hi:[1,0]
	v_mov_b32_e32 v162, v156
	v_mov_b32_e32 v161, v159
	v_mov_b32_e32 v163, v158
	v_pk_mul_f32 v[160:161], v[160:161], v[162:163]
	v_lshl_add_u32 v155, s26, 8, v148
	v_mul_f32_e32 v162, v160, v161
	v_rcp_f32_e32 v166, v162
	v_ashrrev_i32_e32 v147, 31, v146
	v_mov_b64_e32 v[144:145], s[4:5]
	v_mad_i64_i32 v[162:163], s[28:29], v155, s52, v[144:145]
	v_mul_f32_e32 v160, v160, v166
	v_mul_f32_e32 v164, v161, v166
	v_pk_mul_f32 v[158:159], v[158:159], v[160:161] op_sel_hi:[1,0]
	v_max_f32_e32 v160, 0xc1a00000, v120
	v_max_f32_e32 v166, 0xc1a00000, v122
	v_mul_f32_e32 v160, 0xbfb8aa3b, v160
	v_mul_f32_e32 v166, 0xbfb8aa3b, v166
	v_exp_f32_e32 v161, v160
	v_exp_f32_e32 v167, v166
	v_max_f32_e32 v160, 0xc1a00000, v121
	v_max_f32_e32 v166, 0xc1a00000, v123
	v_mul_f32_e32 v160, 0xbfb8aa3b, v160
	v_mul_f32_e32 v166, 0xbfb8aa3b, v166
	v_exp_f32_e32 v160, v160
	v_exp_f32_e32 v166, v166
	v_pk_mul_f32 v[156:157], v[156:157], v[164:165] op_sel_hi:[1,0]
	v_pk_mul_f32 v[126:127], v[126:127], v[158:159]
	v_pk_mul_f32 v[124:125], v[124:125], v[156:157]
	v_pk_add_f32 v[156:157], v[160:161], 1.0 op_sel_hi:[1,0]
	v_pk_add_f32 v[160:161], v[166:167], 1.0 op_sel_hi:[1,0]
	v_mov_b32_e32 v166, v157
	v_mov_b32_e32 v167, v161
	v_mov_b32_e32 v168, v156
	v_mov_b32_e32 v169, v160
	v_pk_mul_f32 v[166:167], v[166:167], v[168:169]
	v_pk_mul_f32 v[118:119], v[126:127], v[118:119]
	v_mul_f32_e32 v164, v166, v167
	v_rcp_f32_e32 v164, v164
	v_pk_mul_f32 v[116:117], v[124:125], v[116:117]
	v_lshlrev_b64 v[146:147], 1, v[146:147]
	v_lshl_add_u64 v[162:163], v[162:163], 0, v[146:147]
	v_mul_f32_e32 v124, v167, v164
	v_mul_f32_e32 v126, v166, v164
	v_pk_mul_f32 v[126:127], v[160:161], v[126:127] op_sel_hi:[1,0]
	v_pk_mul_f32 v[124:125], v[156:157], v[124:125] op_sel_hi:[1,0]
; __device__ __forceinline__ unsigned cvt_pk_bf16(float lo, float hi) { unsigned r; asm volatile("v_cvt_pk_bf16_f32 %0, %1, %2" : "=v"(r) : "v"(lo), "v"(hi)); return r; }
; __device__ __forceinline__ f32x4 sigmoid4(f32x4 x) {
;     f32x4 d;
; #pragma unroll
;     for (int j = 0; j < 4; ++j) d[j] = 1.0f + __expf(-fmaxf(x[j], -20.0f));
;     const float p01 = d[0] * d[1], p23 = d[2] * d[3], r = __builtin_amdgcn_rcpf(p01 * p23), r01 = r * p23, r23 = r * p01;
;     return (f32x4){r01 * d[1], r01 * d[0], r23 * d[3], r23 * d[2]};
; }
;     __device__ __forceinline__ void operator()(const f32x4 (&acc)[2][2][4][2], const Unit& u, int wr, int wc, int fr, int fq) const {
;     ...
;             for (int m = 0; m < 4; ++m) { bf16_t* rowp = O + (size_t)(row0 + ai * HALF + m * 16) * ldc + col0;
;                 f32x4 v0, v1;
; #pragma unroll
;                 for (int j = 0; j < 1; ++j) { v0 = acc[ai][0][m][0] * sigmoid4(acc[ai][0][m][0]) * acc[ai][1][m][0]; v1 = acc[ai][0][m][1] * sigmoid4(acc[ai][0][m][1]) * acc[ai][1][m][1]; }
;                 u32x4 w; w.x = cvt_pk_bf16(v0[0], v0[1]); w.y = cvt_pk_bf16(v0[2], v0[3]); w.z = cvt_pk_bf16(v1[0], v1[1]); w.w = cvt_pk_bf16(v1[2], v1[3]);
;                 *(u32x4*)rowp = w; }
	v_pk_mul_f32 v[122:123], v[122:123], v[126:127]
	v_pk_mul_f32 v[120:121], v[120:121], v[124:125]
	v_pk_mul_f32 v[122:123], v[122:123], v[114:115]
	v_pk_mul_f32 v[114:115], v[120:121], v[112:113]
	v_cvt_pk_bf16_f32 v112, v116, v117
	v_cvt_pk_bf16_f32 v113, v118, v119
	v_max_f32_e32 v116, 0xc1a00000, v108
	v_max_f32_e32 v118, 0xc1a00000, v110
	v_mul_f32_e32 v116, 0xbfb8aa3b, v116
	v_mul_f32_e32 v118, 0xbfb8aa3b, v118
	v_exp_f32_e32 v117, v116
	v_exp_f32_e32 v119, v118
	v_max_f32_e32 v116, 0xc1a00000, v109
	v_max_f32_e32 v118, 0xc1a00000, v111
	v_mul_f32_e32 v116, 0xbfb8aa3b, v116
	v_mul_f32_e32 v118, 0xbfb8aa3b, v118
	v_exp_f32_e32 v116, v116
	v_exp_f32_e32 v118, v118
	v_cvt_pk_bf16_f32 v114, v114, v115
	v_cvt_pk_bf16_f32 v115, v122, v123
	global_store_dwordx4 v[162:163], v[112:115], off
	v_or_b32_e32 v120, 16, v155
	s_and_b64 vcc, exec, s[2:3]
	v_pk_add_f32 v[112:113], v[116:117], 1.0 op_sel_hi:[1,0]
	v_pk_add_f32 v[114:115], v[118:119], 1.0 op_sel_hi:[1,0]
	v_mov_b32_e32 v116, v113
	v_mov_b32_e32 v117, v115
	v_mov_b32_e32 v118, v112
	v_mov_b32_e32 v119, v114
	v_pk_mul_f32 v[116:117], v[116:117], v[118:119]
	s_mov_b32 s53, s14
	v_mul_f32_e32 v118, v116, v117
	v_rcp_f32_e32 v121, v118
	v_mad_i64_i32 v[118:119], s[28:29], v120, s52, v[144:145]
	v_lshl_add_u64 v[118:119], v[118:119], 0, v[146:147]
	v_mul_f32_e32 v116, v116, v121
	v_mul_f32_e32 v120, v117, v121
	v_pk_mul_f32 v[114:115], v[114:115], v[116:117] op_sel_hi:[1,0]
	v_max_f32_e32 v116, 0xc1a00000, v104
	v_max_f32_e32 v121, 0xc1a00000, v106
	v_mul_f32_e32 v116, 0xbfb8aa3b, v116
	v_mul_f32_e32 v121, 0xbfb8aa3b, v121
	v_exp_f32_e32 v117, v116
	v_exp_f32_e32 v123, v121
	v_max_f32_e32 v116, 0xc1a00000, v105
	v_max_f32_e32 v121, 0xc1a00000, v107
	v_mul_f32_e32 v116, 0xbfb8aa3b, v116
	v_mul_f32_e32 v121, 0xbfb8aa3b, v121
	v_exp_f32_e32 v116, v116
	v_exp_f32_e32 v122, v121
	v_pk_mul_f32 v[112:113], v[112:113], v[120:121] op_sel_hi:[1,0]
	v_pk_mul_f32 v[110:111], v[110:111], v[114:115]
	v_pk_mul_f32 v[108:109], v[108:109], v[112:113]
	v_pk_add_f32 v[112:113], v[116:117], 1.0 op_sel_hi:[1,0]
	v_pk_add_f32 v[116:117], v[122:123], 1.0 op_sel_hi:[1,0]
	v_mov_b32_e32 v120, v113
	v_mov_b32_e32 v121, v117
	v_mov_b32_e32 v122, v112
	v_mov_b32_e32 v123, v116
	v_pk_mul_f32 v[120:121], v[120:121], v[122:123]
	v_pk_mul_f32 v[102:103], v[110:111], v[102:103]
	v_mul_f32_e32 v122, v120, v121
	v_rcp_f32_e32 v122, v122
	v_pk_mul_f32 v[100:101], v[108:109], v[100:101]
	s_mov_b32 s26, s16
	s_mov_b64 s[30:31], s[24:25]
	v_mul_f32_e32 v108, v121, v122
	v_mul_f32_e32 v110, v120, v122
	v_pk_mul_f32 v[110:111], v[116:117], v[110:111] op_sel_hi:[1,0]
	v_pk_mul_f32 v[108:109], v[112:113], v[108:109] op_sel_hi:[1,0]
	v_pk_mul_f32 v[106:107], v[106:107], v[110:111]
	v_pk_mul_f32 v[104:105], v[104:105], v[108:109]
	v_pk_mul_f32 v[106:107], v[106:107], v[98:99]
	v_pk_mul_f32 v[98:99], v[104:105], v[96:97]
	v_cvt_pk_bf16_f32 v96, v100, v101
	v_cvt_pk_bf16_f32 v97, v102, v103
	v_max_f32_e32 v100, 0xc1a00000, v92
	v_max_f32_e32 v102, 0xc1a00000, v94
	v_mul_f32_e32 v100, 0xbfb8aa3b, v100
	v_mul_f32_e32 v102, 0xbfb8aa3b, v102
	v_exp_f32_e32 v101, v100
	v_exp_f32_e32 v103, v102
	v_max_f32_e32 v100, 0xc1a00000, v93
	v_max_f32_e32 v102, 0xc1a00000, v95
	v_mul_f32_e32 v100, 0xbfb8aa3b, v100
	v_mul_f32_e32 v102, 0xbfb8aa3b, v102
	v_exp_f32_e32 v100, v100
	v_exp_f32_e32 v102, v102
	v_cvt_pk_bf16_f32 v98, v98, v99
	v_cvt_pk_bf16_f32 v99, v106, v107
	global_store_dwordx4 v[118:119], v[96:99], off
	v_or_b32_e32 v104, 32, v155
	s_nop 0
	v_pk_add_f32 v[96:97], v[100:101], 1.0 op_sel_hi:[1,0]
	v_pk_add_f32 v[98:99], v[102:103], 1.0 op_sel_hi:[1,0]
	v_mov_b32_e32 v100, v97
	v_mov_b32_e32 v101, v99
	v_mov_b32_e32 v102, v96
	v_mov_b32_e32 v103, v98
	v_pk_mul_f32 v[100:101], v[100:101], v[102:103]
	s_nop 0
	v_mul_f32_e32 v102, v100, v101
	v_rcp_f32_e32 v105, v102
	v_mad_i64_i32 v[102:103], s[28:29], v104, s52, v[144:145]
	v_lshl_add_u64 v[102:103], v[102:103], 0, v[146:147]
	v_mul_f32_e32 v100, v100, v105
	v_mul_f32_e32 v104, v101, v105
	v_pk_mul_f32 v[98:99], v[98:99], v[100:101] op_sel_hi:[1,0]
	v_max_f32_e32 v100, 0xc1a00000, v88
	v_max_f32_e32 v105, 0xc1a00000, v90
	v_mul_f32_e32 v100, 0xbfb8aa3b, v100
	v_mul_f32_e32 v105, 0xbfb8aa3b, v105
	v_exp_f32_e32 v101, v100
	v_exp_f32_e32 v107, v105
	v_max_f32_e32 v100, 0xc1a00000, v89
	v_max_f32_e32 v105, 0xc1a00000, v91
	v_mul_f32_e32 v100, 0xbfb8aa3b, v100
	v_mul_f32_e32 v105, 0xbfb8aa3b, v105
	v_exp_f32_e32 v100, v100
	v_exp_f32_e32 v106, v105
	v_pk_mul_f32 v[96:97], v[96:97], v[104:105] op_sel_hi:[1,0]
	v_pk_mul_f32 v[94:95], v[94:95], v[98:99]
	v_pk_mul_f32 v[92:93], v[92:93], v[96:97]
	v_pk_add_f32 v[96:97], v[100:101], 1.0 op_sel_hi:[1,0]
	v_pk_add_f32 v[100:101], v[106:107], 1.0 op_sel_hi:[1,0]
	v_mov_b32_e32 v104, v97
	v_mov_b32_e32 v105, v101
	v_mov_b32_e32 v106, v96
	v_mov_b32_e32 v107, v100
	v_pk_mul_f32 v[104:105], v[104:105], v[106:107]
	v_pk_mul_f32 v[86:87], v[94:95], v[86:87]
	v_mul_f32_e32 v106, v104, v105
	v_rcp_f32_e32 v106, v106
	v_pk_mul_f32 v[84:85], v[92:93], v[84:85]
	v_mul_f32_e32 v92, v105, v106
	v_mul_f32_e32 v94, v104, v106
	v_pk_mul_f32 v[94:95], v[100:101], v[94:95] op_sel_hi:[1,0]
	v_pk_mul_f32 v[92:93], v[96:97], v[92:93] op_sel_hi:[1,0]
	v_pk_mul_f32 v[90:91], v[90:91], v[94:95]
	v_pk_mul_f32 v[88:89], v[88:89], v[92:93]
	v_pk_mul_f32 v[90:91], v[90:91], v[82:83]
	v_pk_mul_f32 v[82:83], v[88:89], v[80:81]
	v_cvt_pk_bf16_f32 v80, v84, v85
	v_cvt_pk_bf16_f32 v81, v86, v87
	v_max_f32_e32 v84, 0xc1a00000, v76
	v_max_f32_e32 v86, 0xc1a00000, v78
	v_mul_f32_e32 v84, 0xbfb8aa3b, v84
	v_mul_f32_e32 v86, 0xbfb8aa3b, v86
	v_exp_f32_e32 v85, v84
	v_exp_f32_e32 v87, v86
; __device__ __forceinline__ unsigned cvt_pk_bf16(float lo, float hi) { unsigned r; asm volatile("v_cvt_pk_bf16_f32 %0, %1, %2" : "=v"(r) : "v"(lo), "v"(hi)); return r; }
; __device__ __forceinline__ f32x4 sigmoid4(f32x4 x) {
;     f32x4 d;
; #pragma unroll
;     for (int j = 0; j < 4; ++j) d[j] = 1.0f + __expf(-fmaxf(x[j], -20.0f));
;     const float p01 = d[0] * d[1], p23 = d[2] * d[3], r = __builtin_amdgcn_rcpf(p01 * p23), r01 = r * p23, r23 = r * p01;
;     return (f32x4){r01 * d[1], r01 * d[0], r23 * d[3], r23 * d[2]};
; }
;     __device__ __forceinline__ void operator()(const f32x4 (&acc)[2][2][4][2], const Unit& u, int wr, int wc, int fr, int fq) const {
;     ...
;             for (int m = 0; m < 4; ++m) { bf16_t* rowp = O + (size_t)(row0 + ai * HALF + m * 16) * ldc + col0;
;                 f32x4 v0, v1;
; #pragma unroll
;                 for (int j = 0; j < 1; ++j) { v0 = acc[ai][0][m][0] * sigmoid4(acc[ai][0][m][0]) * acc[ai][1][m][0]; v1 = acc[ai][0][m][1] * sigmoid4(acc[ai][0][m][1]) * acc[ai][1][m][1]; }
;                 u32x4 w; w.x = cvt_pk_bf16(v0[0], v0[1]); w.y = cvt_pk_bf16(v0[2], v0[3]); w.z = cvt_pk_bf16(v1[0], v1[1]); w.w = cvt_pk_bf16(v1[2], v1[3]);
;                 *(u32x4*)rowp = w; }
	v_max_f32_e32 v84, 0xc1a00000, v77
	v_max_f32_e32 v86, 0xc1a00000, v79
	v_mul_f32_e32 v84, 0xbfb8aa3b, v84
	v_mul_f32_e32 v86, 0xbfb8aa3b, v86
	v_exp_f32_e32 v84, v84
	v_exp_f32_e32 v86, v86
	v_cvt_pk_bf16_f32 v82, v82, v83
	v_cvt_pk_bf16_f32 v83, v90, v91
	global_store_dwordx4 v[102:103], v[80:83], off
	v_or_b32_e32 v88, 48, v155
	s_nop 0
	v_pk_add_f32 v[80:81], v[84:85], 1.0 op_sel_hi:[1,0]
	v_pk_add_f32 v[82:83], v[86:87], 1.0 op_sel_hi:[1,0]
	v_mov_b32_e32 v84, v81
	v_mov_b32_e32 v85, v83
	v_mov_b32_e32 v86, v80
	v_mov_b32_e32 v87, v82
	v_pk_mul_f32 v[84:85], v[84:85], v[86:87]
	s_nop 0
	v_mul_f32_e32 v86, v84, v85
	v_rcp_f32_e32 v89, v86
	v_mad_i64_i32 v[86:87], s[28:29], v88, s52, v[144:145]
	v_lshl_add_u64 v[86:87], v[86:87], 0, v[146:147]
	v_mul_f32_e32 v84, v84, v89
	v_mul_f32_e32 v88, v85, v89
	v_pk_mul_f32 v[82:83], v[82:83], v[84:85] op_sel_hi:[1,0]
	v_max_f32_e32 v84, 0xc1a00000, v72
	v_max_f32_e32 v89, 0xc1a00000, v74
	v_mul_f32_e32 v84, 0xbfb8aa3b, v84
	v_mul_f32_e32 v89, 0xbfb8aa3b, v89
	v_exp_f32_e32 v85, v84
	v_exp_f32_e32 v91, v89
	v_max_f32_e32 v84, 0xc1a00000, v73
	v_max_f32_e32 v89, 0xc1a00000, v75
	v_mul_f32_e32 v84, 0xbfb8aa3b, v84
	v_mul_f32_e32 v89, 0xbfb8aa3b, v89
	v_exp_f32_e32 v84, v84
	v_exp_f32_e32 v90, v89
	v_pk_mul_f32 v[80:81], v[80:81], v[88:89] op_sel_hi:[1,0]
	v_pk_mul_f32 v[78:79], v[78:79], v[82:83]
	v_pk_mul_f32 v[76:77], v[76:77], v[80:81]
	v_pk_add_f32 v[80:81], v[84:85], 1.0 op_sel_hi:[1,0]
	v_pk_add_f32 v[84:85], v[90:91], 1.0 op_sel_hi:[1,0]
	v_mov_b32_e32 v88, v81
	v_mov_b32_e32 v89, v85
	v_mov_b32_e32 v90, v80
	v_mov_b32_e32 v91, v84
	v_pk_mul_f32 v[88:89], v[88:89], v[90:91]
	v_pk_mul_f32 v[70:71], v[78:79], v[70:71]
	v_mul_f32_e32 v90, v88, v89
	v_rcp_f32_e32 v90, v90
	v_pk_mul_f32 v[68:69], v[76:77], v[68:69]
	v_mul_f32_e32 v76, v89, v90
	v_mul_f32_e32 v78, v88, v90
	v_pk_mul_f32 v[78:79], v[84:85], v[78:79] op_sel_hi:[1,0]
	v_pk_mul_f32 v[76:77], v[80:81], v[76:77] op_sel_hi:[1,0]
	v_pk_mul_f32 v[74:75], v[74:75], v[78:79]
	v_pk_mul_f32 v[72:73], v[72:73], v[76:77]
	v_pk_mul_f32 v[74:75], v[74:75], v[66:67]
	v_pk_mul_f32 v[66:67], v[72:73], v[64:65]
	v_cvt_pk_bf16_f32 v64, v68, v69
	v_cvt_pk_bf16_f32 v65, v70, v71
	v_max_f32_e32 v68, 0xc1a00000, v60
	v_max_f32_e32 v70, 0xc1a00000, v62
	v_mul_f32_e32 v68, 0xbfb8aa3b, v68
	v_mul_f32_e32 v70, 0xbfb8aa3b, v70
	v_exp_f32_e32 v69, v68
	v_exp_f32_e32 v71, v70
	v_max_f32_e32 v68, 0xc1a00000, v61
	v_max_f32_e32 v70, 0xc1a00000, v63
	v_mul_f32_e32 v68, 0xbfb8aa3b, v68
	v_mul_f32_e32 v70, 0xbfb8aa3b, v70
	v_exp_f32_e32 v68, v68
	v_exp_f32_e32 v70, v70
	v_cvt_pk_bf16_f32 v66, v66, v67
	v_cvt_pk_bf16_f32 v67, v74, v75
	global_store_dwordx4 v[86:87], v[64:67], off
	v_add_u32_e32 v72, 0x80, v155
	s_nop 0
	v_pk_add_f32 v[64:65], v[68:69], 1.0 op_sel_hi:[1,0]
	v_pk_add_f32 v[66:67], v[70:71], 1.0 op_sel_hi:[1,0]
	v_mov_b32_e32 v68, v65
	v_mov_b32_e32 v69, v67
	v_mov_b32_e32 v70, v64
	v_mov_b32_e32 v71, v66
	v_pk_mul_f32 v[68:69], v[68:69], v[70:71]
	s_nop 0
	v_mul_f32_e32 v70, v68, v69
	v_rcp_f32_e32 v73, v70
	v_mad_i64_i32 v[70:71], s[28:29], v72, s52, v[144:145]
	v_lshl_add_u64 v[70:71], v[70:71], 0, v[146:147]
	v_mul_f32_e32 v68, v68, v73
	v_mul_f32_e32 v72, v69, v73
	v_pk_mul_f32 v[66:67], v[66:67], v[68:69] op_sel_hi:[1,0]
	v_max_f32_e32 v68, 0xc1a00000, v56
	v_max_f32_e32 v73, 0xc1a00000, v58
	v_mul_f32_e32 v68, 0xbfb8aa3b, v68
	v_mul_f32_e32 v73, 0xbfb8aa3b, v73
	v_exp_f32_e32 v69, v68
	v_exp_f32_e32 v75, v73
	v_max_f32_e32 v68, 0xc1a00000, v57
	v_max_f32_e32 v73, 0xc1a00000, v59
	v_mul_f32_e32 v68, 0xbfb8aa3b, v68
	v_mul_f32_e32 v73, 0xbfb8aa3b, v73
	v_exp_f32_e32 v68, v68
	v_exp_f32_e32 v74, v73
	v_pk_mul_f32 v[64:65], v[64:65], v[72:73] op_sel_hi:[1,0]
	v_pk_mul_f32 v[62:63], v[62:63], v[66:67]
	v_pk_mul_f32 v[60:61], v[60:61], v[64:65]
	v_pk_add_f32 v[64:65], v[68:69], 1.0 op_sel_hi:[1,0]
	v_pk_add_f32 v[68:69], v[74:75], 1.0 op_sel_hi:[1,0]
	v_mov_b32_e32 v72, v65
	v_mov_b32_e32 v73, v69
	v_mov_b32_e32 v74, v64
	v_mov_b32_e32 v75, v68
	v_pk_mul_f32 v[72:73], v[72:73], v[74:75]
	v_pk_mul_f32 v[54:55], v[62:63], v[54:55]
	v_mul_f32_e32 v74, v72, v73
	v_rcp_f32_e32 v74, v74
	v_pk_mul_f32 v[52:53], v[60:61], v[52:53]
	v_mul_f32_e32 v60, v73, v74
	v_mul_f32_e32 v62, v72, v74
	v_pk_mul_f32 v[62:63], v[68:69], v[62:63] op_sel_hi:[1,0]
	v_pk_mul_f32 v[60:61], v[64:65], v[60:61] op_sel_hi:[1,0]
	v_pk_mul_f32 v[58:59], v[58:59], v[62:63]
	v_pk_mul_f32 v[56:57], v[56:57], v[60:61]
	v_pk_mul_f32 v[58:59], v[58:59], v[50:51]
	v_pk_mul_f32 v[50:51], v[56:57], v[48:49]
	v_cvt_pk_bf16_f32 v48, v52, v53
	v_cvt_pk_bf16_f32 v49, v54, v55
	v_max_f32_e32 v52, 0xc1a00000, v44
	v_max_f32_e32 v54, 0xc1a00000, v46
	v_mul_f32_e32 v52, 0xbfb8aa3b, v52
	v_mul_f32_e32 v54, 0xbfb8aa3b, v54
	v_exp_f32_e32 v53, v52
	v_exp_f32_e32 v55, v54
	v_max_f32_e32 v52, 0xc1a00000, v45
	v_max_f32_e32 v54, 0xc1a00000, v47
	v_mul_f32_e32 v52, 0xbfb8aa3b, v52
	v_mul_f32_e32 v54, 0xbfb8aa3b, v54
	v_exp_f32_e32 v52, v52
	v_exp_f32_e32 v54, v54
	v_cvt_pk_bf16_f32 v50, v50, v51
	v_cvt_pk_bf16_f32 v51, v58, v59
	global_store_dwordx4 v[70:71], v[48:51], off
	v_add_u32_e32 v56, 0x90, v155
	s_nop 0
	v_pk_add_f32 v[48:49], v[52:53], 1.0 op_sel_hi:[1,0]
	v_pk_add_f32 v[50:51], v[54:55], 1.0 op_sel_hi:[1,0]
	v_mov_b32_e32 v52, v49
	v_mov_b32_e32 v53, v51
	v_mov_b32_e32 v54, v48
	v_mov_b32_e32 v55, v50
	v_pk_mul_f32 v[52:53], v[52:53], v[54:55]
	s_nop 0
	v_mul_f32_e32 v54, v52, v53
	v_rcp_f32_e32 v57, v54
	v_mad_i64_i32 v[54:55], s[28:29], v56, s52, v[144:145]
	v_lshl_add_u64 v[54:55], v[54:55], 0, v[146:147]
	v_mul_f32_e32 v52, v52, v57
	v_mul_f32_e32 v56, v53, v57
	v_pk_mul_f32 v[50:51], v[50:51], v[52:53] op_sel_hi:[1,0]
; __device__ __forceinline__ unsigned cvt_pk_bf16(float lo, float hi) { unsigned r; asm volatile("v_cvt_pk_bf16_f32 %0, %1, %2" : "=v"(r) : "v"(lo), "v"(hi)); return r; }
; __device__ __forceinline__ f32x4 sigmoid4(f32x4 x) {
;     f32x4 d;
; #pragma unroll
;     for (int j = 0; j < 4; ++j) d[j] = 1.0f + __expf(-fmaxf(x[j], -20.0f));
;     const float p01 = d[0] * d[1], p23 = d[2] * d[3], r = __builtin_amdgcn_rcpf(p01 * p23), r01 = r * p23, r23 = r * p01;
;     return (f32x4){r01 * d[1], r01 * d[0], r23 * d[3], r23 * d[2]};
; }
;     __device__ __forceinline__ void operator()(const f32x4 (&acc)[2][2][4][2], const Unit& u, int wr, int wc, int fr, int fq) const {
;     ...
;             for (int m = 0; m < 4; ++m) { bf16_t* rowp = O + (size_t)(row0 + ai * HALF + m * 16) * ldc + col0;
;                 f32x4 v0, v1;
; #pragma unroll
;                 for (int j = 0; j < 1; ++j) { v0 = acc[ai][0][m][0] * sigmoid4(acc[ai][0][m][0]) * acc[ai][1][m][0]; v1 = acc[ai][0][m][1] * sigmoid4(acc[ai][0][m][1]) * acc[ai][1][m][1]; }
;                 u32x4 w; w.x = cvt_pk_bf16(v0[0], v0[1]); w.y = cvt_pk_bf16(v0[2], v0[3]); w.z = cvt_pk_bf16(v1[0], v1[1]); w.w = cvt_pk_bf16(v1[2], v1[3]);
;                 *(u32x4*)rowp = w; }
	v_max_f32_e32 v52, 0xc1a00000, v40
	v_max_f32_e32 v57, 0xc1a00000, v42
	v_mul_f32_e32 v52, 0xbfb8aa3b, v52
	v_mul_f32_e32 v57, 0xbfb8aa3b, v57
	v_exp_f32_e32 v53, v52
	v_exp_f32_e32 v59, v57
	v_max_f32_e32 v52, 0xc1a00000, v41
	v_max_f32_e32 v57, 0xc1a00000, v43
	v_mul_f32_e32 v52, 0xbfb8aa3b, v52
	v_mul_f32_e32 v57, 0xbfb8aa3b, v57
	v_exp_f32_e32 v52, v52
	v_exp_f32_e32 v58, v57
	v_pk_mul_f32 v[48:49], v[48:49], v[56:57] op_sel_hi:[1,0]
	v_pk_mul_f32 v[46:47], v[46:47], v[50:51]
	v_pk_mul_f32 v[44:45], v[44:45], v[48:49]
	v_pk_add_f32 v[48:49], v[52:53], 1.0 op_sel_hi:[1,0]
	v_pk_add_f32 v[52:53], v[58:59], 1.0 op_sel_hi:[1,0]
	v_mov_b32_e32 v56, v49
	v_mov_b32_e32 v57, v53
	v_mov_b32_e32 v58, v48
	v_mov_b32_e32 v59, v52
	v_pk_mul_f32 v[56:57], v[56:57], v[58:59]
	v_pk_mul_f32 v[38:39], v[46:47], v[38:39]
	v_mul_f32_e32 v58, v56, v57
	v_rcp_f32_e32 v58, v58
	v_pk_mul_f32 v[36:37], v[44:45], v[36:37]
	v_mul_f32_e32 v44, v57, v58
	v_mul_f32_e32 v46, v56, v58
	v_pk_mul_f32 v[46:47], v[52:53], v[46:47] op_sel_hi:[1,0]
	v_pk_mul_f32 v[44:45], v[48:49], v[44:45] op_sel_hi:[1,0]
	v_pk_mul_f32 v[42:43], v[42:43], v[46:47]
	v_pk_mul_f32 v[40:41], v[40:41], v[44:45]
	v_pk_mul_f32 v[42:43], v[42:43], v[34:35]
	v_pk_mul_f32 v[34:35], v[40:41], v[32:33]
	v_cvt_pk_bf16_f32 v32, v36, v37
	v_cvt_pk_bf16_f32 v33, v38, v39
	v_max_f32_e32 v36, 0xc1a00000, v28
	v_max_f32_e32 v38, 0xc1a00000, v30
	v_mul_f32_e32 v36, 0xbfb8aa3b, v36
	v_mul_f32_e32 v38, 0xbfb8aa3b, v38
	v_exp_f32_e32 v37, v36
	v_exp_f32_e32 v39, v38
	v_max_f32_e32 v36, 0xc1a00000, v29
	v_max_f32_e32 v38, 0xc1a00000, v31
	v_mul_f32_e32 v36, 0xbfb8aa3b, v36
	v_mul_f32_e32 v38, 0xbfb8aa3b, v38
	v_exp_f32_e32 v36, v36
	v_exp_f32_e32 v38, v38
	v_cvt_pk_bf16_f32 v34, v34, v35
	v_cvt_pk_bf16_f32 v35, v42, v43
	global_store_dwordx4 v[54:55], v[32:35], off
	v_add_u32_e32 v40, 0xa0, v155
	s_nop 0
	v_pk_add_f32 v[32:33], v[36:37], 1.0 op_sel_hi:[1,0]
	v_pk_add_f32 v[34:35], v[38:39], 1.0 op_sel_hi:[1,0]
	v_mov_b32_e32 v36, v33
	v_mov_b32_e32 v37, v35
	v_mov_b32_e32 v38, v32
	v_mov_b32_e32 v39, v34
	v_pk_mul_f32 v[36:37], v[36:37], v[38:39]
	s_nop 0
	v_mul_f32_e32 v38, v36, v37
	v_rcp_f32_e32 v41, v38
	v_mad_i64_i32 v[38:39], s[28:29], v40, s52, v[144:145]
	v_lshl_add_u64 v[38:39], v[38:39], 0, v[146:147]
	v_mul_f32_e32 v36, v36, v41
	v_mul_f32_e32 v40, v37, v41
	v_pk_mul_f32 v[34:35], v[34:35], v[36:37] op_sel_hi:[1,0]
	v_max_f32_e32 v36, 0xc1a00000, v24
	v_max_f32_e32 v41, 0xc1a00000, v26
	v_mul_f32_e32 v36, 0xbfb8aa3b, v36
	v_mul_f32_e32 v41, 0xbfb8aa3b, v41
	v_exp_f32_e32 v37, v36
	v_exp_f32_e32 v43, v41
	v_max_f32_e32 v36, 0xc1a00000, v25
	v_max_f32_e32 v41, 0xc1a00000, v27
	v_mul_f32_e32 v36, 0xbfb8aa3b, v36
	v_mul_f32_e32 v41, 0xbfb8aa3b, v41
	v_exp_f32_e32 v36, v36
	v_exp_f32_e32 v42, v41
	v_pk_mul_f32 v[32:33], v[32:33], v[40:41] op_sel_hi:[1,0]
	v_pk_mul_f32 v[30:31], v[30:31], v[34:35]
	v_pk_mul_f32 v[28:29], v[28:29], v[32:33]
	v_pk_add_f32 v[32:33], v[36:37], 1.0 op_sel_hi:[1,0]
	v_pk_add_f32 v[36:37], v[42:43], 1.0 op_sel_hi:[1,0]
	v_mov_b32_e32 v40, v33
	v_mov_b32_e32 v41, v37
	v_mov_b32_e32 v42, v32
	v_mov_b32_e32 v43, v36
	v_pk_mul_f32 v[40:41], v[40:41], v[42:43]
	v_pk_mul_f32 v[22:23], v[30:31], v[22:23]
	v_mul_f32_e32 v42, v40, v41
	v_rcp_f32_e32 v42, v42
	v_pk_mul_f32 v[20:21], v[28:29], v[20:21]
	v_mul_f32_e32 v28, v41, v42
	v_mul_f32_e32 v30, v40, v42
	v_pk_mul_f32 v[30:31], v[36:37], v[30:31] op_sel_hi:[1,0]
	v_pk_mul_f32 v[28:29], v[32:33], v[28:29] op_sel_hi:[1,0]
	v_pk_mul_f32 v[26:27], v[26:27], v[30:31]
	v_pk_mul_f32 v[24:25], v[24:25], v[28:29]
	v_pk_mul_f32 v[26:27], v[26:27], v[18:19]
	v_pk_mul_f32 v[18:19], v[24:25], v[16:17]
	v_cvt_pk_bf16_f32 v16, v20, v21
	v_cvt_pk_bf16_f32 v17, v22, v23
	v_max_f32_e32 v20, 0xc1a00000, v12
	v_max_f32_e32 v22, 0xc1a00000, v14
	v_mul_f32_e32 v20, 0xbfb8aa3b, v20
	v_mul_f32_e32 v22, 0xbfb8aa3b, v22
	v_exp_f32_e32 v21, v20
	v_exp_f32_e32 v23, v22
	v_max_f32_e32 v20, 0xc1a00000, v13
	v_max_f32_e32 v22, 0xc1a00000, v15
	v_mul_f32_e32 v20, 0xbfb8aa3b, v20
	v_mul_f32_e32 v22, 0xbfb8aa3b, v22
	v_exp_f32_e32 v20, v20
	v_exp_f32_e32 v22, v22
	v_cvt_pk_bf16_f32 v18, v18, v19
	v_cvt_pk_bf16_f32 v19, v26, v27
	global_store_dwordx4 v[38:39], v[16:19], off
	v_add_u32_e32 v24, 0xb0, v155
	s_nop 0
	v_pk_add_f32 v[16:17], v[20:21], 1.0 op_sel_hi:[1,0]
	v_pk_add_f32 v[18:19], v[22:23], 1.0 op_sel_hi:[1,0]
	v_mov_b32_e32 v20, v17
	v_mov_b32_e32 v21, v19
	v_mov_b32_e32 v22, v16
	v_mov_b32_e32 v23, v18
	v_pk_mul_f32 v[20:21], v[20:21], v[22:23]
	s_nop 0
	v_mul_f32_e32 v22, v20, v21
	v_rcp_f32_e32 v25, v22
	v_mad_i64_i32 v[22:23], s[28:29], v24, s52, v[144:145]
	v_lshl_add_u64 v[22:23], v[22:23], 0, v[146:147]
	v_mul_f32_e32 v20, v20, v25
	v_mul_f32_e32 v24, v21, v25
	v_pk_mul_f32 v[18:19], v[18:19], v[20:21] op_sel_hi:[1,0]
	v_max_f32_e32 v20, 0xc1a00000, v8
	v_max_f32_e32 v25, 0xc1a00000, v10
	v_mul_f32_e32 v20, 0xbfb8aa3b, v20
	v_mul_f32_e32 v25, 0xbfb8aa3b, v25
	v_exp_f32_e32 v21, v20
	v_exp_f32_e32 v27, v25
	v_max_f32_e32 v20, 0xc1a00000, v9
	v_max_f32_e32 v25, 0xc1a00000, v11
	v_mul_f32_e32 v20, 0xbfb8aa3b, v20
	v_mul_f32_e32 v25, 0xbfb8aa3b, v25
	v_exp_f32_e32 v20, v20
	v_exp_f32_e32 v26, v25
	v_pk_mul_f32 v[16:17], v[16:17], v[24:25] op_sel_hi:[1,0]
	v_pk_mul_f32 v[14:15], v[14:15], v[18:19]
	v_pk_mul_f32 v[12:13], v[12:13], v[16:17]
	v_pk_add_f32 v[16:17], v[20:21], 1.0 op_sel_hi:[1,0]
	v_pk_add_f32 v[20:21], v[26:27], 1.0 op_sel_hi:[1,0]
	v_mov_b32_e32 v24, v17
	v_mov_b32_e32 v25, v21
	v_mov_b32_e32 v26, v16
	v_mov_b32_e32 v27, v20
	v_pk_mul_f32 v[24:25], v[24:25], v[26:27]
	v_pk_mul_f32 v[6:7], v[14:15], v[6:7]
	v_mul_f32_e32 v26, v24, v25
	v_rcp_f32_e32 v26, v26
	v_pk_mul_f32 v[4:5], v[12:13], v[4:5]
	s_mov_b64 s[28:29], s[18:19]
	v_mul_f32_e32 v12, v25, v26
	v_mul_f32_e32 v14, v24, v26
	v_pk_mul_f32 v[14:15], v[20:21], v[14:15] op_sel_hi:[1,0]
	v_pk_mul_f32 v[12:13], v[16:17], v[12:13] op_sel_hi:[1,0]
	v_pk_mul_f32 v[10:11], v[10:11], v[14:15]
	v_pk_mul_f32 v[8:9], v[8:9], v[12:13]
	v_pk_mul_f32 v[10:11], v[10:11], v[2:3]
	v_pk_mul_f32 v[2:3], v[8:9], v[0:1]
	v_cvt_pk_bf16_f32 v0, v4, v5
	v_cvt_pk_bf16_f32 v1, v6, v7
	s_nop 0
	v_cvt_pk_bf16_f32 v2, v2, v3
	v_cvt_pk_bf16_f32 v3, v10, v11
	global_store_dwordx4 v[22:23], v[0:3], off
	s_cbranch_vccz .LBB0_192
	s_waitcnt vmcnt(0)
	s_cmpk_gt_u32 s37, 0xff
	s_cbranch_scc1 .LBB0_199
	s_barrier

; #define PG8_STAGE(bufoff, gbase, voff) do { _Pragma("unroll") for (int _i = 0; _i < 2; ++_i) \
;         __builtin_amdgcn_global_load_lds((const unsigned*)((const char*)(gbase) + (voff)[_i]), (PG8_LAS unsigned*)(lds + (bufoff) + ldsw + _i * 8192), 16, 0, 0); } while (0)
; #define PG8_LDA(dst, b, h) do { _Pragma("unroll") for (int m = 0; m < 4; ++m) _Pragma("unroll") for (int k = 0; k < 2; ++k) dst[m][k] = *(const PG8_LAS bf16x8*)(lds + PG8_SA(b, h) + aoff + m * 2048 + k * 1024); } while (0)
; #define PG8_LDB(dst, b, h) do { _Pragma("unroll") for (int n = 0; n < 2; ++n) _Pragma("unroll") for (int k = 0; k < 2; ++k) dst[n][k] = *(const PG8_LAS bf16x8*)(lds + PG8_SB(b, h) + boff + n * 2048 + k * 1024); } while (0)
; #define PG8_MMA(ai, bj, At, Bt) do { __builtin_amdgcn_s_setprio(1); _Pragma("unroll") for (int m = 0; m < 4; ++m) _Pragma("unroll") for (int n = 0; n < 2; ++n) _Pragma("unroll") for (int k = 0; k < 2; ++k) \
;         acc[ai][bj][m][n] = __builtin_amdgcn_mfma_f32_16x16x32_bf16(Bt[n][k], At[m][k], acc[ai][bj][m][n], 0, 0, 0); __builtin_amdgcn_s_setprio(0); } while (0)
; #define PG8_WAIT_V(n) asm volatile("s_waitcnt vmcnt(" #n ")" ::: "memory")
; #define PG8_WAIT_L(n) asm volatile("s_waitcnt lgkmcnt(" #n ")" ::: "memory")
; #define PG8_BAR __builtin_amdgcn_s_barrier()
; #define PG8_SCHED __builtin_amdgcn_sched_barrier(0)
; template <class Epi, class Sched>
; __device__ __forceinline__ void gemm_phase(PG8_LAS unsigned char* lds, const Gemm g, const Sched& S, const Epi& E) {
;     ...
;             PG8_LDB(B0, 0, 0); PG8_SCHED; PG8_LDA(At, 0, 0); PG8_STAGE(PG8_SA(1, 1), a1 + hstep, voffA);
;             PG8_WAIT_L(8); PG8_BAR; PG8_WAIT_L(0); PG8_MMA(0, 0, At, B0); PG8_BAR; PG8_SCHED;
;             PG8_LDB(B1, 0, 1); PG8_STAGE(PG8_SB(0, 0), b2, voffB);
;             PG8_BAR; PG8_WAIT_L(0); PG8_MMA(0, 1, At, B1); PG8_BAR;
;             PG8_LDA(At, 0, 1); PG8_STAGE(PG8_SA(0, 0), a2, voffA);
;             PG8_BAR; PG8_WAIT_L(0); PG8_MMA(1, 0, At, B0); PG8_BAR; PG8_SCHED;
;             PG8_STAGE(PG8_SB(0, 1), b2 + hstep, voffB);
;             PG8_WAIT_V(6); PG8_BAR; PG8_MMA(1, 1, At, B1); PG8_BAR;
;             PG8_LDB(B0, 1, 0); PG8_SCHED; PG8_LDA(At, 1, 0); PG8_STAGE(PG8_SA(0, 1), a2 + hstep, voffA);
;             PG8_WAIT_L(8); PG8_BAR; PG8_WAIT_L(0); PG8_MMA(0, 0, At, B0); PG8_BAR; PG8_SCHED;
.LBB0_285:
	s_add_u32 s55, s24, 0x100
	s_addc_u32 s56, s25, 0
	s_mov_b32 s57, -2
	ds_read_b128 v[154:157], v149
	ds_read_b128 v[158:161], v149 offset:1024
	ds_read_b128 v[166:169], v149 offset:2048
	ds_read_b128 v[170:173], v149 offset:3072
	s_add_u32 s24, s22, 0x100
	s_addc_u32 s25, s23, 0
	s_cmp_eq_u32 s57, 40
	s_cselect_b32 s29, s1, s25
	s_cselect_b32 s28, s0, s24
	s_cselect_b32 s27, s5, s56
	s_cselect_b32 s26, s4, s55
	s_add_i32 m0, s38, 0xc000
	ds_read_b128 v[182:185], v150
	ds_read_b128 v[190:193], v150 offset:1024
	ds_read_b128 v[194:197], v150 offset:2048
	ds_read_b128 v[198:201], v150 offset:3072
	ds_read_b128 v[202:205], v150 offset:4096
	ds_read_b128 v[206:209], v150 offset:5120
	ds_read_b128 v[210:213], v150 offset:6144
	ds_read_b128 v[214:217], v150 offset:7168
	global_load_lds_dwordx4 v136, s[22:23]
	s_add_i32 m0, s38, 0xe000
	s_nop 0
	global_load_lds_dwordx4 v138, s[22:23]
	s_waitcnt lgkmcnt(8)
	ds_read_b128 v[218:221], v151
	ds_read_b128 v[222:225], v151 offset:1024
	ds_read_b128 v[226:229], v151 offset:2048
	ds_read_b128 v[230:233], v151 offset:3072
	s_waitcnt vmcnt(8) lgkmcnt(0)
	s_barrier
	v_mfma_f32_16x16x32_bf16 v[124:127], v[154:157], v[182:185], 0
	v_mfma_f32_16x16x32_bf16 v[120:123], v[166:169], v[182:185], 0
	v_mfma_f32_16x16x32_bf16 v[108:111], v[154:157], v[194:197], 0
	v_mfma_f32_16x16x32_bf16 v[104:107], v[166:169], v[194:197], 0
	v_mfma_f32_16x16x32_bf16 v[92:95], v[154:157], v[202:205], 0
	v_mfma_f32_16x16x32_bf16 v[88:91], v[166:169], v[202:205], 0
	v_mfma_f32_16x16x32_bf16 v[76:79], v[154:157], v[210:213], 0
	v_mfma_f32_16x16x32_bf16 v[72:75], v[166:169], v[210:213], 0
	v_mfma_f32_16x16x32_bf16 v[124:127], v[158:161], v[190:193], v[124:127]
	v_mfma_f32_16x16x32_bf16 v[120:123], v[170:173], v[190:193], v[120:123]
	v_mfma_f32_16x16x32_bf16 v[108:111], v[158:161], v[198:201], v[108:111]
	v_mfma_f32_16x16x32_bf16 v[104:107], v[170:173], v[198:201], v[104:107]
	v_mfma_f32_16x16x32_bf16 v[92:95], v[158:161], v[206:209], v[92:95]
	v_mfma_f32_16x16x32_bf16 v[88:91], v[170:173], v[206:209], v[88:91]
	v_mfma_f32_16x16x32_bf16 v[76:79], v[158:161], v[214:217], v[76:79]
	v_mfma_f32_16x16x32_bf16 v[72:75], v[170:173], v[214:217], v[72:75]
	v_mfma_f32_16x16x32_bf16 v[116:119], v[218:221], v[182:185], 0
	v_mfma_f32_16x16x32_bf16 v[112:115], v[226:229], v[182:185], 0
	v_mfma_f32_16x16x32_bf16 v[100:103], v[218:221], v[194:197], 0
	v_mfma_f32_16x16x32_bf16 v[96:99], v[226:229], v[194:197], 0
	v_mfma_f32_16x16x32_bf16 v[84:87], v[218:221], v[202:205], 0
	v_mfma_f32_16x16x32_bf16 v[80:83], v[226:229], v[202:205], 0
	v_mfma_f32_16x16x32_bf16 v[68:71], v[218:221], v[210:213], 0
	v_mfma_f32_16x16x32_bf16 v[64:67], v[226:229], v[210:213], 0
	v_mfma_f32_16x16x32_bf16 v[116:119], v[222:225], v[190:193], v[116:119]
	v_mfma_f32_16x16x32_bf16 v[112:115], v[230:233], v[190:193], v[112:115]
	v_mfma_f32_16x16x32_bf16 v[100:103], v[222:225], v[198:201], v[100:103]
	v_mfma_f32_16x16x32_bf16 v[96:99], v[230:233], v[198:201], v[96:99]
	v_mfma_f32_16x16x32_bf16 v[84:87], v[222:225], v[206:209], v[84:87]
	v_mfma_f32_16x16x32_bf16 v[80:83], v[230:233], v[206:209], v[80:83]
	v_mfma_f32_16x16x32_bf16 v[68:71], v[222:225], v[214:217], v[68:71]
	v_mfma_f32_16x16x32_bf16 v[64:67], v[230:233], v[214:217], v[64:67]
	s_barrier
	ds_read_b128 v[182:185], v150 offset:16384
	ds_read_b128 v[190:193], v150 offset:17408
	ds_read_b128 v[194:197], v150 offset:18432
	ds_read_b128 v[198:201], v150 offset:19456
	ds_read_b128 v[202:205], v150 offset:20480
	ds_read_b128 v[206:209], v150 offset:21504
	ds_read_b128 v[210:213], v150 offset:22528
	ds_read_b128 v[214:217], v150 offset:23552
	s_add_i32 s22, s46, s37
	s_add_u32 s98, s26, s14
	s_addc_u32 s99, s27, s15
	s_mov_b32 m0, s22
	s_nop 0
	global_load_lds_dwordx4 v130, s[26:27]
	s_add_i32 m0, s22, 0x2000
	s_nop 0
	global_load_lds_dwordx4 v134, s[26:27]
	s_mov_b32 m0, s38
	s_add_u32 s100, s28, s14
	s_addc_u32 s101, s29, s15
	global_load_lds_dwordx4 v128, s[28:29]
	s_mov_b32 m0, s39
	s_nop 0
	global_load_lds_dwordx4 v132, s[28:29]
	s_add_u32 s22, s26, 0xb0000
	s_addc_u32 s23, s27, 0
	s_add_i32 s58, s47, s37
	s_mov_b32 m0, s58
	s_nop 0
	global_load_lds_dwordx4 v130, s[22:23]
	s_add_i32 m0, s58, 0x2000
	s_nop 0
	global_load_lds_dwordx4 v134, s[22:23]
	s_waitcnt vmcnt(8) lgkmcnt(0)
	s_barrier
	v_mfma_f32_16x16x32_bf16 v[60:63], v[154:157], v[182:185], 0
	v_mfma_f32_16x16x32_bf16 v[56:59], v[166:169], v[182:185], 0
	v_mfma_f32_16x16x32_bf16 v[48:51], v[154:157], v[194:197], 0
	v_mfma_f32_16x16x32_bf16 v[40:43], v[166:169], v[194:197], 0
	v_mfma_f32_16x16x32_bf16 v[32:35], v[154:157], v[202:205], 0
	v_mfma_f32_16x16x32_bf16 v[24:27], v[166:169], v[202:205], 0
	v_mfma_f32_16x16x32_bf16 v[16:19], v[154:157], v[210:213], 0
	v_mfma_f32_16x16x32_bf16 v[8:11], v[166:169], v[210:213], 0
	v_mfma_f32_16x16x32_bf16 v[60:63], v[158:161], v[190:193], v[60:63]
	v_mfma_f32_16x16x32_bf16 v[56:59], v[170:173], v[190:193], v[56:59]
	v_mfma_f32_16x16x32_bf16 v[48:51], v[158:161], v[198:201], v[48:51]
	v_mfma_f32_16x16x32_bf16 v[40:43], v[170:173], v[198:201], v[40:43]
	v_mfma_f32_16x16x32_bf16 v[32:35], v[158:161], v[206:209], v[32:35]
	v_mfma_f32_16x16x32_bf16 v[24:27], v[170:173], v[206:209], v[24:27]
	v_mfma_f32_16x16x32_bf16 v[16:19], v[158:161], v[214:217], v[16:19]
	v_mfma_f32_16x16x32_bf16 v[8:11], v[170:173], v[214:217], v[8:11]
	v_mfma_f32_16x16x32_bf16 v[52:55], v[218:221], v[182:185], 0
	v_mfma_f32_16x16x32_bf16 v[44:47], v[226:229], v[182:185], 0
	v_mfma_f32_16x16x32_bf16 v[36:39], v[218:221], v[194:197], 0
	v_mfma_f32_16x16x32_bf16 v[28:31], v[226:229], v[194:197], 0
	v_mfma_f32_16x16x32_bf16 v[20:23], v[218:221], v[202:205], 0
	v_mfma_f32_16x16x32_bf16 v[12:15], v[226:229], v[202:205], 0
	v_mfma_f32_16x16x32_bf16 v[4:7], v[218:221], v[210:213], 0
	v_mfma_f32_16x16x32_bf16 v[0:3], v[226:229], v[210:213], 0
	v_mfma_f32_16x16x32_bf16 v[52:55], v[222:225], v[190:193], v[52:55]
	v_mfma_f32_16x16x32_bf16 v[44:47], v[230:233], v[190:193], v[44:47]
	v_mfma_f32_16x16x32_bf16 v[36:39], v[222:225], v[198:201], v[36:39]
	v_mfma_f32_16x16x32_bf16 v[28:31], v[230:233], v[198:201], v[28:31]
	v_mfma_f32_16x16x32_bf16 v[20:23], v[222:225], v[206:209], v[20:23]
	v_mfma_f32_16x16x32_bf16 v[12:15], v[230:233], v[206:209], v[12:15]
	v_mfma_f32_16x16x32_bf16 v[4:7], v[222:225], v[214:217], v[4:7]
	v_mfma_f32_16x16x32_bf16 v[0:3], v[230:233], v[214:217], v[0:3]
	s_barrier
; #define PG8_STAGE(bufoff, gbase, voff) do { _Pragma("unroll") for (int _i = 0; _i < 2; ++_i) \
;         __builtin_amdgcn_global_load_lds((const unsigned*)((const char*)(gbase) + (voff)[_i]), (PG8_LAS unsigned*)(lds + (bufoff) + ldsw + _i * 8192), 16, 0, 0); } while (0)
; #define PG8_LDA(dst, b, h) do { _Pragma("unroll") for (int m = 0; m < 4; ++m) _Pragma("unroll") for (int k = 0; k < 2; ++k) dst[m][k] = *(const PG8_LAS bf16x8*)(lds + PG8_SA(b, h) + aoff + m * 2048 + k * 1024); } while (0)
; #define PG8_LDB(dst, b, h) do { _Pragma("unroll") for (int n = 0; n < 2; ++n) _Pragma("unroll") for (int k = 0; k < 2; ++k) dst[n][k] = *(const PG8_LAS bf16x8*)(lds + PG8_SB(b, h) + boff + n * 2048 + k * 1024); } while (0)
; #define PG8_MMA(ai, bj, At, Bt) do { __builtin_amdgcn_s_setprio(1); _Pragma("unroll") for (int m = 0; m < 4; ++m) _Pragma("unroll") for (int n = 0; n < 2; ++n) _Pragma("unroll") for (int k = 0; k < 2; ++k) \
;         acc[ai][bj][m][n] = __builtin_amdgcn_mfma_f32_16x16x32_bf16(Bt[n][k], At[m][k], acc[ai][bj][m][n], 0, 0, 0); __builtin_amdgcn_s_setprio(0); } while (0)
; #define PG8_WAIT_V(n) asm volatile("s_waitcnt vmcnt(" #n ")" ::: "memory")
; #define PG8_WAIT_L(n) asm volatile("s_waitcnt lgkmcnt(" #n ")" ::: "memory")
; #define PG8_BAR __builtin_amdgcn_s_barrier()
; #define PG8_SCHED __builtin_amdgcn_sched_barrier(0)
; template <class Epi, class Sched>
; __device__ __forceinline__ void gemm_phase(PG8_LAS unsigned char* lds, const Gemm g, const Sched& S, const Epi& E) {
;     ...
;             PG8_LDB(B0, 1, 0); PG8_SCHED; PG8_LDA(At, 1, 0); PG8_STAGE(PG8_SA(0, 1), a2 + hstep, voffA);
;             PG8_WAIT_L(8); PG8_BAR; PG8_WAIT_L(0); PG8_MMA(0, 0, At, B0); PG8_BAR; PG8_SCHED;
;             PG8_LDB(B1, 1, 1); PG8_STAGE(PG8_SB(1, 0), b3, voffB);
;             PG8_BAR; PG8_WAIT_L(0); PG8_MMA(0, 1, At, B1); PG8_BAR;
;             PG8_LDA(At, 1, 1); PG8_STAGE(PG8_SA(1, 0), a3, voffA);
;             PG8_BAR; PG8_WAIT_L(0); PG8_MMA(1, 0, At, B0); PG8_BAR; PG8_SCHED;
;             PG8_STAGE(PG8_SB(1, 1), b3 + hstep, voffB);
;             PG8_WAIT_V(6); PG8_BAR; PG8_MMA(1, 1, At, B1); PG8_BAR;
	s_add_i32 s58, 0, 0x18000
	v_add_u32_e32 v153, s58, v147
	ds_read_b128 v[154:157], v153
	ds_read_b128 v[158:161], v153 offset:1024
	ds_read_b128 v[166:169], v153 offset:2048
	ds_read_b128 v[170:173], v153 offset:3072
	s_add_u32 s22, s28, 0xb0000
	s_addc_u32 s23, s29, 0
	s_mov_b32 m0, s40
	ds_read_b128 v[182:185], v150 offset:32768
	ds_read_b128 v[190:193], v150 offset:33792
	ds_read_b128 v[194:197], v150 offset:34816
	ds_read_b128 v[198:201], v150 offset:35840
	ds_read_b128 v[202:205], v150 offset:36864
	ds_read_b128 v[206:209], v150 offset:37888
	ds_read_b128 v[210:213], v150 offset:38912
	ds_read_b128 v[214:217], v150 offset:39936
	global_load_lds_dwordx4 v128, s[22:23]
	s_mov_b32 m0, s41
	s_nop 0
	global_load_lds_dwordx4 v132, s[22:23]
	s_add_i32 s28, 0, 0x1c000
	v_add_u32_e32 v153, s28, v147
	s_waitcnt lgkmcnt(8)
	ds_read_b128 v[218:221], v153
	ds_read_b128 v[222:225], v153 offset:1024
	ds_read_b128 v[226:229], v153 offset:2048
	ds_read_b128 v[230:233], v153 offset:3072
	s_waitcnt vmcnt(8) lgkmcnt(0)
	s_barrier
	v_mfma_f32_16x16x32_bf16 v[124:127], v[154:157], v[182:185], v[124:127]
	v_mfma_f32_16x16x32_bf16 v[120:123], v[166:169], v[182:185], v[120:123]
	v_mfma_f32_16x16x32_bf16 v[108:111], v[154:157], v[194:197], v[108:111]
	v_mfma_f32_16x16x32_bf16 v[104:107], v[166:169], v[194:197], v[104:107]
	v_mfma_f32_16x16x32_bf16 v[92:95], v[154:157], v[202:205], v[92:95]
	v_mfma_f32_16x16x32_bf16 v[88:91], v[166:169], v[202:205], v[88:91]
	v_mfma_f32_16x16x32_bf16 v[76:79], v[154:157], v[210:213], v[76:79]
	v_mfma_f32_16x16x32_bf16 v[72:75], v[166:169], v[210:213], v[72:75]
	v_mfma_f32_16x16x32_bf16 v[124:127], v[158:161], v[190:193], v[124:127]
	v_mfma_f32_16x16x32_bf16 v[120:123], v[170:173], v[190:193], v[120:123]
	v_mfma_f32_16x16x32_bf16 v[108:111], v[158:161], v[198:201], v[108:111]
	v_mfma_f32_16x16x32_bf16 v[104:107], v[170:173], v[198:201], v[104:107]
	v_mfma_f32_16x16x32_bf16 v[92:95], v[158:161], v[206:209], v[92:95]
	v_mfma_f32_16x16x32_bf16 v[88:91], v[170:173], v[206:209], v[88:91]
	v_mfma_f32_16x16x32_bf16 v[76:79], v[158:161], v[214:217], v[76:79]
	v_mfma_f32_16x16x32_bf16 v[72:75], v[170:173], v[214:217], v[72:75]
	v_mfma_f32_16x16x32_bf16 v[116:119], v[218:221], v[182:185], v[116:119]
	v_mfma_f32_16x16x32_bf16 v[112:115], v[226:229], v[182:185], v[112:115]
	v_mfma_f32_16x16x32_bf16 v[100:103], v[218:221], v[194:197], v[100:103]
	v_mfma_f32_16x16x32_bf16 v[96:99], v[226:229], v[194:197], v[96:99]
	v_mfma_f32_16x16x32_bf16 v[84:87], v[218:221], v[202:205], v[84:87]
	v_mfma_f32_16x16x32_bf16 v[80:83], v[226:229], v[202:205], v[80:83]
	v_mfma_f32_16x16x32_bf16 v[68:71], v[218:221], v[210:213], v[68:71]
	v_mfma_f32_16x16x32_bf16 v[64:67], v[226:229], v[210:213], v[64:67]
	v_mfma_f32_16x16x32_bf16 v[116:119], v[222:225], v[190:193], v[116:119]
	v_mfma_f32_16x16x32_bf16 v[112:115], v[230:233], v[190:193], v[112:115]
	v_mfma_f32_16x16x32_bf16 v[100:103], v[222:225], v[198:201], v[100:103]
	v_mfma_f32_16x16x32_bf16 v[96:99], v[230:233], v[198:201], v[96:99]
	v_mfma_f32_16x16x32_bf16 v[84:87], v[222:225], v[206:209], v[84:87]
	v_mfma_f32_16x16x32_bf16 v[80:83], v[230:233], v[206:209], v[80:83]
	v_mfma_f32_16x16x32_bf16 v[68:71], v[222:225], v[214:217], v[68:71]
	v_mfma_f32_16x16x32_bf16 v[64:67], v[230:233], v[214:217], v[64:67]
	s_barrier
	ds_read_b128 v[182:185], v150 offset:49152
	ds_read_b128 v[190:193], v150 offset:50176
	ds_read_b128 v[194:197], v150 offset:51200
	ds_read_b128 v[198:201], v150 offset:52224
	ds_read_b128 v[202:205], v150 offset:53248
	ds_read_b128 v[206:209], v150 offset:54272
	ds_read_b128 v[210:213], v150 offset:55296
	ds_read_b128 v[214:217], v150 offset:56320
	s_add_i32 s22, s58, s37
	s_mov_b32 m0, s22
	s_nop 0
	global_load_lds_dwordx4 v130, s[98:99]
	s_add_i32 m0, s22, 0x2000
	s_nop 0
	global_load_lds_dwordx4 v134, s[98:99]
	s_mov_b32 m0, s43
	s_nop 0
	global_load_lds_dwordx4 v128, s[100:101]
	s_mov_b32 m0, s44
	s_nop 0
	global_load_lds_dwordx4 v132, s[100:101]
	s_add_u32 s22, s26, 0xb0080
	s_addc_u32 s23, s27, 0
	s_add_i32 s26, s28, s37
	s_mov_b32 m0, s26
	s_nop 0
	global_load_lds_dwordx4 v130, s[22:23]
	s_add_i32 m0, s26, 0x2000
	s_nop 0
	global_load_lds_dwordx4 v134, s[22:23]
	s_waitcnt vmcnt(8) lgkmcnt(0)
	s_barrier
	v_mfma_f32_16x16x32_bf16 v[60:63], v[154:157], v[182:185], v[60:63]
	v_mfma_f32_16x16x32_bf16 v[56:59], v[166:169], v[182:185], v[56:59]
	v_mfma_f32_16x16x32_bf16 v[48:51], v[154:157], v[194:197], v[48:51]
	v_mfma_f32_16x16x32_bf16 v[40:43], v[166:169], v[194:197], v[40:43]
	v_mfma_f32_16x16x32_bf16 v[32:35], v[154:157], v[202:205], v[32:35]
	v_mfma_f32_16x16x32_bf16 v[24:27], v[166:169], v[202:205], v[24:27]
	v_mfma_f32_16x16x32_bf16 v[16:19], v[154:157], v[210:213], v[16:19]
	v_mfma_f32_16x16x32_bf16 v[8:11], v[166:169], v[210:213], v[8:11]
	v_mfma_f32_16x16x32_bf16 v[60:63], v[158:161], v[190:193], v[60:63]
	v_mfma_f32_16x16x32_bf16 v[56:59], v[170:173], v[190:193], v[56:59]
	v_mfma_f32_16x16x32_bf16 v[48:51], v[158:161], v[198:201], v[48:51]
	v_mfma_f32_16x16x32_bf16 v[40:43], v[170:173], v[198:201], v[40:43]
	v_mfma_f32_16x16x32_bf16 v[32:35], v[158:161], v[206:209], v[32:35]
	v_mfma_f32_16x16x32_bf16 v[24:27], v[170:173], v[206:209], v[24:27]
	v_mfma_f32_16x16x32_bf16 v[16:19], v[158:161], v[214:217], v[16:19]
	v_mfma_f32_16x16x32_bf16 v[8:11], v[170:173], v[214:217], v[8:11]
	v_mfma_f32_16x16x32_bf16 v[52:55], v[218:221], v[182:185], v[52:55]
	v_mfma_f32_16x16x32_bf16 v[44:47], v[226:229], v[182:185], v[44:47]
	v_mfma_f32_16x16x32_bf16 v[36:39], v[218:221], v[194:197], v[36:39]
	v_mfma_f32_16x16x32_bf16 v[28:31], v[226:229], v[194:197], v[28:31]
	v_mfma_f32_16x16x32_bf16 v[20:23], v[218:221], v[202:205], v[20:23]
	v_mfma_f32_16x16x32_bf16 v[12:15], v[226:229], v[202:205], v[12:15]
	v_mfma_f32_16x16x32_bf16 v[4:7], v[218:221], v[210:213], v[4:7]
	v_mfma_f32_16x16x32_bf16 v[0:3], v[226:229], v[210:213], v[0:3]
	v_mfma_f32_16x16x32_bf16 v[52:55], v[222:225], v[190:193], v[52:55]
	v_mfma_f32_16x16x32_bf16 v[44:47], v[230:233], v[190:193], v[44:47]
	v_mfma_f32_16x16x32_bf16 v[36:39], v[222:225], v[198:201], v[36:39]
	v_mfma_f32_16x16x32_bf16 v[28:31], v[230:233], v[198:201], v[28:31]
	v_mfma_f32_16x16x32_bf16 v[20:23], v[222:225], v[206:209], v[20:23]
	v_mfma_f32_16x16x32_bf16 v[12:15], v[230:233], v[206:209], v[12:15]
	v_mfma_f32_16x16x32_bf16 v[4:7], v[222:225], v[214:217], v[4:7]
	v_mfma_f32_16x16x32_bf16 v[0:3], v[230:233], v[214:217], v[0:3]
	s_barrier
	s_add_i32 s57, s57, 2
	s_add_u32 s55, s55, 0x100
	s_addc_u32 s56, s56, 0
	s_cmp_gt_u32 s57, 41
	s_mov_b64 s[22:23], s[24:25]
; #define PG8_STAGE(bufoff, gbase, voff) do { _Pragma("unroll") for (int _i = 0; _i < 2; ++_i) \
;         __builtin_amdgcn_global_load_lds((const unsigned*)((const char*)(gbase) + (voff)[_i]), (PG8_LAS unsigned*)(lds + (bufoff) + ldsw + _i * 8192), 16, 0, 0); } while (0)
; #define PG8_LDA(dst, b, h) do { _Pragma("unroll") for (int m = 0; m < 4; ++m) _Pragma("unroll") for (int k = 0; k < 2; ++k) dst[m][k] = *(const PG8_LAS bf16x8*)(lds + PG8_SA(b, h) + aoff + m * 2048 + k * 1024); } while (0)
; #define PG8_LDB(dst, b, h) do { _Pragma("unroll") for (int n = 0; n < 2; ++n) _Pragma("unroll") for (int k = 0; k < 2; ++k) dst[n][k] = *(const PG8_LAS bf16x8*)(lds + PG8_SB(b, h) + boff + n * 2048 + k * 1024); } while (0)
; #define PG8_MMA(ai, bj, At, Bt) do { __builtin_amdgcn_s_setprio(1); _Pragma("unroll") for (int m = 0; m < 4; ++m) _Pragma("unroll") for (int n = 0; n < 2; ++n) _Pragma("unroll") for (int k = 0; k < 2; ++k) \
;         acc[ai][bj][m][n] = __builtin_amdgcn_mfma_f32_16x16x32_bf16(Bt[n][k], At[m][k], acc[ai][bj][m][n], 0, 0, 0); __builtin_amdgcn_s_setprio(0); } while (0)
; #define PG8_WAIT_V(n) asm volatile("s_waitcnt vmcnt(" #n ")" ::: "memory")
; #define PG8_WAIT_L(n) asm volatile("s_waitcnt lgkmcnt(" #n ")" ::: "memory")
; #define PG8_BAR __builtin_amdgcn_s_barrier()
; #define PG8_SCHED __builtin_amdgcn_sched_barrier(0)
; template <class Epi, class Sched>
; __device__ __forceinline__ void gemm_phase(PG8_LAS unsigned char* lds, const Gemm g, const Sched& S, const Epi& E) {
;     ...
;             PG8_LDB(B0, 0, 0); PG8_SCHED; PG8_LDA(At, 0, 0); PG8_STAGE(PG8_SA(1, 1), a1 + hstep, voffA);
;             PG8_WAIT_L(8); PG8_BAR; PG8_WAIT_L(0); PG8_MMA(0, 0, At, B0); PG8_BAR; PG8_SCHED;
;             PG8_LDB(B1, 0, 1); PG8_STAGE(PG8_SB(0, 0), b2, voffB);
;             PG8_BAR; PG8_WAIT_L(0); PG8_MMA(0, 1, At, B1); PG8_BAR;
;             PG8_LDA(At, 0, 1); PG8_STAGE(PG8_SA(0, 0), a2, voffA);
;             PG8_BAR; PG8_WAIT_L(0); PG8_MMA(1, 0, At, B0); PG8_BAR; PG8_SCHED;
;             PG8_STAGE(PG8_SB(0, 1), b2 + hstep, voffB);
;             PG8_WAIT_V(6); PG8_BAR; PG8_MMA(1, 1, At, B1); PG8_BAR;
.LBB0_286:
	ds_read_b128 v[154:157], v149
	ds_read_b128 v[158:161], v149 offset:1024
	ds_read_b128 v[166:169], v149 offset:2048
	ds_read_b128 v[170:173], v149 offset:3072
	s_add_u32 s24, s22, 0x100
	s_addc_u32 s25, s23, 0
	s_cmp_eq_u32 s57, 40
	s_cselect_b32 s29, s1, s25
	s_cselect_b32 s28, s0, s24
	s_cselect_b32 s27, s5, s56
	s_cselect_b32 s26, s4, s55
	s_add_i32 m0, s38, 0xc000
	ds_read_b128 v[182:185], v150
	ds_read_b128 v[190:193], v150 offset:1024
	ds_read_b128 v[194:197], v150 offset:2048
	ds_read_b128 v[198:201], v150 offset:3072
	ds_read_b128 v[202:205], v150 offset:4096
	ds_read_b128 v[206:209], v150 offset:5120
	ds_read_b128 v[210:213], v150 offset:6144
	ds_read_b128 v[214:217], v150 offset:7168
	global_load_lds_dwordx4 v136, s[22:23]
	s_add_i32 m0, s38, 0xe000
	s_nop 0
	global_load_lds_dwordx4 v138, s[22:23]
	s_waitcnt lgkmcnt(8)
	ds_read_b128 v[218:221], v151
	ds_read_b128 v[222:225], v151 offset:1024
	ds_read_b128 v[226:229], v151 offset:2048
	ds_read_b128 v[230:233], v151 offset:3072
	s_waitcnt vmcnt(8) lgkmcnt(0)
	s_barrier
	v_mfma_f32_16x16x32_bf16 v[124:127], v[154:157], v[182:185], v[124:127]
	v_mfma_f32_16x16x32_bf16 v[120:123], v[166:169], v[182:185], v[120:123]
	v_mfma_f32_16x16x32_bf16 v[108:111], v[154:157], v[194:197], v[108:111]
	v_mfma_f32_16x16x32_bf16 v[104:107], v[166:169], v[194:197], v[104:107]
	v_mfma_f32_16x16x32_bf16 v[92:95], v[154:157], v[202:205], v[92:95]
	v_mfma_f32_16x16x32_bf16 v[88:91], v[166:169], v[202:205], v[88:91]
	v_mfma_f32_16x16x32_bf16 v[76:79], v[154:157], v[210:213], v[76:79]
	v_mfma_f32_16x16x32_bf16 v[72:75], v[166:169], v[210:213], v[72:75]
	v_mfma_f32_16x16x32_bf16 v[124:127], v[158:161], v[190:193], v[124:127]
	v_mfma_f32_16x16x32_bf16 v[120:123], v[170:173], v[190:193], v[120:123]
	v_mfma_f32_16x16x32_bf16 v[108:111], v[158:161], v[198:201], v[108:111]
	v_mfma_f32_16x16x32_bf16 v[104:107], v[170:173], v[198:201], v[104:107]
	v_mfma_f32_16x16x32_bf16 v[92:95], v[158:161], v[206:209], v[92:95]
	v_mfma_f32_16x16x32_bf16 v[88:91], v[170:173], v[206:209], v[88:91]
	v_mfma_f32_16x16x32_bf16 v[76:79], v[158:161], v[214:217], v[76:79]
	v_mfma_f32_16x16x32_bf16 v[72:75], v[170:173], v[214:217], v[72:75]
	v_mfma_f32_16x16x32_bf16 v[116:119], v[218:221], v[182:185], v[116:119]
	v_mfma_f32_16x16x32_bf16 v[112:115], v[226:229], v[182:185], v[112:115]
	v_mfma_f32_16x16x32_bf16 v[100:103], v[218:221], v[194:197], v[100:103]
	v_mfma_f32_16x16x32_bf16 v[96:99], v[226:229], v[194:197], v[96:99]
	v_mfma_f32_16x16x32_bf16 v[84:87], v[218:221], v[202:205], v[84:87]
	v_mfma_f32_16x16x32_bf16 v[80:83], v[226:229], v[202:205], v[80:83]
	v_mfma_f32_16x16x32_bf16 v[68:71], v[218:221], v[210:213], v[68:71]
	v_mfma_f32_16x16x32_bf16 v[64:67], v[226:229], v[210:213], v[64:67]
	v_mfma_f32_16x16x32_bf16 v[116:119], v[222:225], v[190:193], v[116:119]
	v_mfma_f32_16x16x32_bf16 v[112:115], v[230:233], v[190:193], v[112:115]
	v_mfma_f32_16x16x32_bf16 v[100:103], v[222:225], v[198:201], v[100:103]
	v_mfma_f32_16x16x32_bf16 v[96:99], v[230:233], v[198:201], v[96:99]
	v_mfma_f32_16x16x32_bf16 v[84:87], v[222:225], v[206:209], v[84:87]
	v_mfma_f32_16x16x32_bf16 v[80:83], v[230:233], v[206:209], v[80:83]
	v_mfma_f32_16x16x32_bf16 v[68:71], v[222:225], v[214:217], v[68:71]
	v_mfma_f32_16x16x32_bf16 v[64:67], v[230:233], v[214:217], v[64:67]
	s_barrier
	ds_read_b128 v[182:185], v150 offset:16384
	ds_read_b128 v[190:193], v150 offset:17408
	ds_read_b128 v[194:197], v150 offset:18432
	ds_read_b128 v[198:201], v150 offset:19456
	ds_read_b128 v[202:205], v150 offset:20480
	ds_read_b128 v[206:209], v150 offset:21504
	ds_read_b128 v[210:213], v150 offset:22528
	ds_read_b128 v[214:217], v150 offset:23552
	s_add_i32 s22, s46, s37
	s_add_u32 s98, s26, s14
	s_addc_u32 s99, s27, s15
	s_mov_b32 m0, s22
	s_nop 0
	global_load_lds_dwordx4 v130, s[26:27]
	s_add_i32 m0, s22, 0x2000
	s_nop 0
	global_load_lds_dwordx4 v134, s[26:27]
	s_mov_b32 m0, s38
	s_add_u32 s100, s28, s14
	s_addc_u32 s101, s29, s15
	global_load_lds_dwordx4 v128, s[28:29]
	s_mov_b32 m0, s39
	s_nop 0
	global_load_lds_dwordx4 v132, s[28:29]
	s_add_u32 s22, s26, 0xb0000
	s_addc_u32 s23, s27, 0
	s_add_i32 s58, s47, s37
	s_mov_b32 m0, s58
	s_nop 0
	global_load_lds_dwordx4 v130, s[22:23]
	s_add_i32 m0, s58, 0x2000
	s_nop 0
	global_load_lds_dwordx4 v134, s[22:23]
	s_waitcnt vmcnt(8) lgkmcnt(0)
	s_barrier
	v_mfma_f32_16x16x32_bf16 v[60:63], v[154:157], v[182:185], v[60:63]
	v_mfma_f32_16x16x32_bf16 v[56:59], v[166:169], v[182:185], v[56:59]
	v_mfma_f32_16x16x32_bf16 v[48:51], v[154:157], v[194:197], v[48:51]
	v_mfma_f32_16x16x32_bf16 v[40:43], v[166:169], v[194:197], v[40:43]
	v_mfma_f32_16x16x32_bf16 v[32:35], v[154:157], v[202:205], v[32:35]
	v_mfma_f32_16x16x32_bf16 v[24:27], v[166:169], v[202:205], v[24:27]
	v_mfma_f32_16x16x32_bf16 v[16:19], v[154:157], v[210:213], v[16:19]
	v_mfma_f32_16x16x32_bf16 v[8:11], v[166:169], v[210:213], v[8:11]
	v_mfma_f32_16x16x32_bf16 v[60:63], v[158:161], v[190:193], v[60:63]
	v_mfma_f32_16x16x32_bf16 v[56:59], v[170:173], v[190:193], v[56:59]
	v_mfma_f32_16x16x32_bf16 v[48:51], v[158:161], v[198:201], v[48:51]
	v_mfma_f32_16x16x32_bf16 v[40:43], v[170:173], v[198:201], v[40:43]
	v_mfma_f32_16x16x32_bf16 v[32:35], v[158:161], v[206:209], v[32:35]
	v_mfma_f32_16x16x32_bf16 v[24:27], v[170:173], v[206:209], v[24:27]
	v_mfma_f32_16x16x32_bf16 v[16:19], v[158:161], v[214:217], v[16:19]
	v_mfma_f32_16x16x32_bf16 v[8:11], v[170:173], v[214:217], v[8:11]
	v_mfma_f32_16x16x32_bf16 v[52:55], v[218:221], v[182:185], v[52:55]
	v_mfma_f32_16x16x32_bf16 v[44:47], v[226:229], v[182:185], v[44:47]
	v_mfma_f32_16x16x32_bf16 v[36:39], v[218:221], v[194:197], v[36:39]
	v_mfma_f32_16x16x32_bf16 v[28:31], v[226:229], v[194:197], v[28:31]
	v_mfma_f32_16x16x32_bf16 v[20:23], v[218:221], v[202:205], v[20:23]
	v_mfma_f32_16x16x32_bf16 v[12:15], v[226:229], v[202:205], v[12:15]
	v_mfma_f32_16x16x32_bf16 v[4:7], v[218:221], v[210:213], v[4:7]
	v_mfma_f32_16x16x32_bf16 v[0:3], v[226:229], v[210:213], v[0:3]
	v_mfma_f32_16x16x32_bf16 v[52:55], v[222:225], v[190:193], v[52:55]
	v_mfma_f32_16x16x32_bf16 v[44:47], v[230:233], v[190:193], v[44:47]
	v_mfma_f32_16x16x32_bf16 v[36:39], v[222:225], v[198:201], v[36:39]
	v_mfma_f32_16x16x32_bf16 v[28:31], v[230:233], v[198:201], v[28:31]
	v_mfma_f32_16x16x32_bf16 v[20:23], v[222:225], v[206:209], v[20:23]
	v_mfma_f32_16x16x32_bf16 v[12:15], v[230:233], v[206:209], v[12:15]
	v_mfma_f32_16x16x32_bf16 v[4:7], v[222:225], v[214:217], v[4:7]
	v_mfma_f32_16x16x32_bf16 v[0:3], v[230:233], v[214:217], v[0:3]
	s_barrier
; #define PG8_STAGE(bufoff, gbase, voff) do { _Pragma("unroll") for (int _i = 0; _i < 2; ++_i) \
;         __builtin_amdgcn_global_load_lds((const unsigned*)((const char*)(gbase) + (voff)[_i]), (PG8_LAS unsigned*)(lds + (bufoff) + ldsw + _i * 8192), 16, 0, 0); } while (0)
; #define PG8_LDA(dst, b, h) do { _Pragma("unroll") for (int m = 0; m < 4; ++m) _Pragma("unroll") for (int k = 0; k < 2; ++k) dst[m][k] = *(const PG8_LAS bf16x8*)(lds + PG8_SA(b, h) + aoff + m * 2048 + k * 1024); } while (0)
; #define PG8_LDB(dst, b, h) do { _Pragma("unroll") for (int n = 0; n < 2; ++n) _Pragma("unroll") for (int k = 0; k < 2; ++k) dst[n][k] = *(const PG8_LAS bf16x8*)(lds + PG8_SB(b, h) + boff + n * 2048 + k * 1024); } while (0)
; #define PG8_MMA(ai, bj, At, Bt) do { __builtin_amdgcn_s_setprio(1); _Pragma("unroll") for (int m = 0; m < 4; ++m) _Pragma("unroll") for (int n = 0; n < 2; ++n) _Pragma("unroll") for (int k = 0; k < 2; ++k) \
;         acc[ai][bj][m][n] = __builtin_amdgcn_mfma_f32_16x16x32_bf16(Bt[n][k], At[m][k], acc[ai][bj][m][n], 0, 0, 0); __builtin_amdgcn_s_setprio(0); } while (0)
; #define PG8_WAIT_V(n) asm volatile("s_waitcnt vmcnt(" #n ")" ::: "memory")
; #define PG8_WAIT_L(n) asm volatile("s_waitcnt lgkmcnt(" #n ")" ::: "memory")
; #define PG8_BAR __builtin_amdgcn_s_barrier()
; #define PG8_SCHED __builtin_amdgcn_sched_barrier(0)
; template <class Epi, class Sched>
; __device__ __forceinline__ void gemm_phase(PG8_LAS unsigned char* lds, const Gemm g, const Sched& S, const Epi& E) {
;     ...
;             PG8_LDB(B0, 1, 0); PG8_SCHED; PG8_LDA(At, 1, 0); PG8_STAGE(PG8_SA(0, 1), a2 + hstep, voffA);
;             PG8_WAIT_L(8); PG8_BAR; PG8_WAIT_L(0); PG8_MMA(0, 0, At, B0); PG8_BAR; PG8_SCHED;
;             PG8_LDB(B1, 1, 1); PG8_STAGE(PG8_SB(1, 0), b3, voffB);
;             PG8_BAR; PG8_WAIT_L(0); PG8_MMA(0, 1, At, B1); PG8_BAR;
;             PG8_LDA(At, 1, 1); PG8_STAGE(PG8_SA(1, 0), a3, voffA);
;             PG8_BAR; PG8_WAIT_L(0); PG8_MMA(1, 0, At, B0); PG8_BAR; PG8_SCHED;
;             PG8_STAGE(PG8_SB(1, 1), b3 + hstep, voffB);
;             PG8_WAIT_V(6); PG8_BAR; PG8_MMA(1, 1, At, B1); PG8_BAR;
	s_add_i32 s58, 0, 0x18000
	v_add_u32_e32 v153, s58, v147
	ds_read_b128 v[154:157], v153
	ds_read_b128 v[158:161], v153 offset:1024
	ds_read_b128 v[166:169], v153 offset:2048
	ds_read_b128 v[170:173], v153 offset:3072
	s_add_u32 s22, s28, 0xb0000
	s_addc_u32 s23, s29, 0
	s_mov_b32 m0, s40
	ds_read_b128 v[182:185], v150 offset:32768
	ds_read_b128 v[190:193], v150 offset:33792
	ds_read_b128 v[194:197], v150 offset:34816
	ds_read_b128 v[198:201], v150 offset:35840
	ds_read_b128 v[202:205], v150 offset:36864
	ds_read_b128 v[206:209], v150 offset:37888
	ds_read_b128 v[210:213], v150 offset:38912
	ds_read_b128 v[214:217], v150 offset:39936
	global_load_lds_dwordx4 v128, s[22:23]
	s_mov_b32 m0, s41
	s_nop 0
	global_load_lds_dwordx4 v132, s[22:23]
	s_add_i32 s28, 0, 0x1c000
	v_add_u32_e32 v153, s28, v147
	s_waitcnt lgkmcnt(8)
	ds_read_b128 v[218:221], v153
	ds_read_b128 v[222:225], v153 offset:1024
	ds_read_b128 v[226:229], v153 offset:2048
	ds_read_b128 v[230:233], v153 offset:3072
	s_waitcnt vmcnt(8) lgkmcnt(0)
	s_barrier
	v_mfma_f32_16x16x32_bf16 v[124:127], v[154:157], v[182:185], v[124:127]
	v_mfma_f32_16x16x32_bf16 v[120:123], v[166:169], v[182:185], v[120:123]
	v_mfma_f32_16x16x32_bf16 v[108:111], v[154:157], v[194:197], v[108:111]
	v_mfma_f32_16x16x32_bf16 v[104:107], v[166:169], v[194:197], v[104:107]
	v_mfma_f32_16x16x32_bf16 v[92:95], v[154:157], v[202:205], v[92:95]
	v_mfma_f32_16x16x32_bf16 v[88:91], v[166:169], v[202:205], v[88:91]
	v_mfma_f32_16x16x32_bf16 v[76:79], v[154:157], v[210:213], v[76:79]
	v_mfma_f32_16x16x32_bf16 v[72:75], v[166:169], v[210:213], v[72:75]
	v_mfma_f32_16x16x32_bf16 v[124:127], v[158:161], v[190:193], v[124:127]
	v_mfma_f32_16x16x32_bf16 v[120:123], v[170:173], v[190:193], v[120:123]
	v_mfma_f32_16x16x32_bf16 v[108:111], v[158:161], v[198:201], v[108:111]
	v_mfma_f32_16x16x32_bf16 v[104:107], v[170:173], v[198:201], v[104:107]
	v_mfma_f32_16x16x32_bf16 v[92:95], v[158:161], v[206:209], v[92:95]
	v_mfma_f32_16x16x32_bf16 v[88:91], v[170:173], v[206:209], v[88:91]
	v_mfma_f32_16x16x32_bf16 v[76:79], v[158:161], v[214:217], v[76:79]
	v_mfma_f32_16x16x32_bf16 v[72:75], v[170:173], v[214:217], v[72:75]
	v_mfma_f32_16x16x32_bf16 v[116:119], v[218:221], v[182:185], v[116:119]
	v_mfma_f32_16x16x32_bf16 v[112:115], v[226:229], v[182:185], v[112:115]
	v_mfma_f32_16x16x32_bf16 v[100:103], v[218:221], v[194:197], v[100:103]
	v_mfma_f32_16x16x32_bf16 v[96:99], v[226:229], v[194:197], v[96:99]
	v_mfma_f32_16x16x32_bf16 v[84:87], v[218:221], v[202:205], v[84:87]
	v_mfma_f32_16x16x32_bf16 v[80:83], v[226:229], v[202:205], v[80:83]
	v_mfma_f32_16x16x32_bf16 v[68:71], v[218:221], v[210:213], v[68:71]
	v_mfma_f32_16x16x32_bf16 v[64:67], v[226:229], v[210:213], v[64:67]
	v_mfma_f32_16x16x32_bf16 v[116:119], v[222:225], v[190:193], v[116:119]
	v_mfma_f32_16x16x32_bf16 v[112:115], v[230:233], v[190:193], v[112:115]
	v_mfma_f32_16x16x32_bf16 v[100:103], v[222:225], v[198:201], v[100:103]
	v_mfma_f32_16x16x32_bf16 v[96:99], v[230:233], v[198:201], v[96:99]
	v_mfma_f32_16x16x32_bf16 v[84:87], v[222:225], v[206:209], v[84:87]
	v_mfma_f32_16x16x32_bf16 v[80:83], v[230:233], v[206:209], v[80:83]
	v_mfma_f32_16x16x32_bf16 v[68:71], v[222:225], v[214:217], v[68:71]
	v_mfma_f32_16x16x32_bf16 v[64:67], v[230:233], v[214:217], v[64:67]
	s_barrier
	ds_read_b128 v[182:185], v150 offset:49152
	ds_read_b128 v[190:193], v150 offset:50176
	ds_read_b128 v[194:197], v150 offset:51200
	ds_read_b128 v[198:201], v150 offset:52224
	ds_read_b128 v[202:205], v150 offset:53248
	ds_read_b128 v[206:209], v150 offset:54272
	ds_read_b128 v[210:213], v150 offset:55296
	ds_read_b128 v[214:217], v150 offset:56320
	s_add_i32 s22, s58, s37
	s_mov_b32 m0, s22
	s_nop 0
	global_load_lds_dwordx4 v130, s[98:99]
	s_add_i32 m0, s22, 0x2000
	s_nop 0
	global_load_lds_dwordx4 v134, s[98:99]
	s_mov_b32 m0, s43
	s_nop 0
	global_load_lds_dwordx4 v128, s[100:101]
	s_mov_b32 m0, s44
	s_nop 0
	global_load_lds_dwordx4 v132, s[100:101]
	s_add_u32 s22, s26, 0xb0080
	s_addc_u32 s23, s27, 0
	s_add_i32 s26, s28, s37
	s_mov_b32 m0, s26
	s_nop 0
	global_load_lds_dwordx4 v130, s[22:23]
	s_add_i32 m0, s26, 0x2000
	s_nop 0
	global_load_lds_dwordx4 v134, s[22:23]
	s_waitcnt vmcnt(8) lgkmcnt(0)
	s_barrier
	v_mfma_f32_16x16x32_bf16 v[60:63], v[154:157], v[182:185], v[60:63]
	v_mfma_f32_16x16x32_bf16 v[56:59], v[166:169], v[182:185], v[56:59]
	v_mfma_f32_16x16x32_bf16 v[48:51], v[154:157], v[194:197], v[48:51]
	v_mfma_f32_16x16x32_bf16 v[40:43], v[166:169], v[194:197], v[40:43]
	v_mfma_f32_16x16x32_bf16 v[32:35], v[154:157], v[202:205], v[32:35]
	v_mfma_f32_16x16x32_bf16 v[24:27], v[166:169], v[202:205], v[24:27]
	v_mfma_f32_16x16x32_bf16 v[16:19], v[154:157], v[210:213], v[16:19]
	v_mfma_f32_16x16x32_bf16 v[8:11], v[166:169], v[210:213], v[8:11]
	v_mfma_f32_16x16x32_bf16 v[60:63], v[158:161], v[190:193], v[60:63]
	v_mfma_f32_16x16x32_bf16 v[56:59], v[170:173], v[190:193], v[56:59]
	v_mfma_f32_16x16x32_bf16 v[48:51], v[158:161], v[198:201], v[48:51]
	v_mfma_f32_16x16x32_bf16 v[40:43], v[170:173], v[198:201], v[40:43]
	v_mfma_f32_16x16x32_bf16 v[32:35], v[158:161], v[206:209], v[32:35]
	v_mfma_f32_16x16x32_bf16 v[24:27], v[170:173], v[206:209], v[24:27]
	v_mfma_f32_16x16x32_bf16 v[16:19], v[158:161], v[214:217], v[16:19]
	v_mfma_f32_16x16x32_bf16 v[8:11], v[170:173], v[214:217], v[8:11]
	v_mfma_f32_16x16x32_bf16 v[52:55], v[218:221], v[182:185], v[52:55]
	v_mfma_f32_16x16x32_bf16 v[44:47], v[226:229], v[182:185], v[44:47]
	v_mfma_f32_16x16x32_bf16 v[36:39], v[218:221], v[194:197], v[36:39]
	v_mfma_f32_16x16x32_bf16 v[28:31], v[226:229], v[194:197], v[28:31]
	v_mfma_f32_16x16x32_bf16 v[20:23], v[218:221], v[202:205], v[20:23]
	v_mfma_f32_16x16x32_bf16 v[12:15], v[226:229], v[202:205], v[12:15]
	v_mfma_f32_16x16x32_bf16 v[4:7], v[218:221], v[210:213], v[4:7]
	v_mfma_f32_16x16x32_bf16 v[0:3], v[226:229], v[210:213], v[0:3]
	v_mfma_f32_16x16x32_bf16 v[52:55], v[222:225], v[190:193], v[52:55]
	v_mfma_f32_16x16x32_bf16 v[44:47], v[230:233], v[190:193], v[44:47]
	v_mfma_f32_16x16x32_bf16 v[36:39], v[222:225], v[198:201], v[36:39]
	v_mfma_f32_16x16x32_bf16 v[28:31], v[230:233], v[198:201], v[28:31]
	v_mfma_f32_16x16x32_bf16 v[20:23], v[222:225], v[206:209], v[20:23]
	v_mfma_f32_16x16x32_bf16 v[12:15], v[230:233], v[206:209], v[12:15]
	v_mfma_f32_16x16x32_bf16 v[4:7], v[222:225], v[214:217], v[4:7]
	v_mfma_f32_16x16x32_bf16 v[0:3], v[230:233], v[214:217], v[0:3]
	s_barrier
; __device__ __forceinline__ unsigned cvt_pk_bf16(float lo, float hi) { unsigned r; asm volatile("v_cvt_pk_bf16_f32 %0, %1, %2" : "=v"(r) : "v"(lo), "v"(hi)); return r; }
; __device__ __forceinline__ float flogsig16(float x) { return (fminf(x, 0.f) - __logf(1.0f + __expf(-fabsf(x)))) * 0.0625f; }
;     __device__ __forceinline__ void operator()(const f32x4 (&acc)[2][2][4][2], const Unit& u, int wr, int wc, int fr, int fq) const {
;     ...
;         const int row0 = u.pm * BM + wr * 64 + fr, col0 = u.pn * BM + wc * 32 + 8 * fq, bcol0 = wc * 32 + 8 * fq;
;         f32x4 bv[2][2];
; #pragma unroll
;         for (int bj = 0; bj < 2; ++bj)
; #pragma unroll
;             for (int n = 0; n < 2; ++n) bv[bj][n] = bias ? *(const f32x4*)(bias + bcol0 + bj * HALF + 4 * n) : (f32x4){0.f, 0.f, 0.f, 0.f};
; #pragma unroll
;         for (int ai = 0; ai < 2; ++ai)
; #pragma unroll
;             for (int m = 0; m < 4; ++m) { bf16_t* rowp = O + (size_t)(row0 + ai * HALF + m * 16) * ldc + col0;
; #pragma unroll
;                 for (int bj = 0; bj < 2; ++bj) { f32x4 v0 = acc[ai][bj][m][0] + bv[bj][0], v1 = acc[ai][bj][m][1] + bv[bj][1];
;                     if (act == 1) {
; #pragma unroll
;                         for (int j = 0; j < 1; ++j) { v0 = v0 * sigmoid4(v0); v1 = v1 * sigmoid4(v1); } }
;                     else if (act == 2) {
; #pragma unroll
;                         for (int j = 0; j < 1; ++j) { v0 = sigmoid4(v0); v1 = sigmoid4(v1); } }
;                     else if (act == 3) {
; #pragma unroll
;                         for (int j = 0; j < 4; ++j) { v0[j] = flogsig16(v0[j]); v1[j] = flogsig16(v1[j]); } }
;                     u32x4 w; w.x = cvt_pk_bf16(v0[0], v0[1]); w.y = cvt_pk_bf16(v0[2], v0[3]); w.z = cvt_pk_bf16(v1[0], v1[1]); w.w = cvt_pk_bf16(v1[2], v1[3]);
;                     *(u32x4*)(rowp + bj * HALF) = w; } }
	s_add_i32 s57, s57, 2
	s_add_u32 s55, s55, 0x100
	s_addc_u32 s56, s56, 0
	s_cmp_gt_u32 s57, 41
	s_mov_b64 s[22:23], s[24:25]
	s_cbranch_scc0 .LBB0_286
	v_lshl_add_u32 v154, s53, 8, v146
	v_lshl_or_b32 v144, s54, 8, v148
	v_ashrrev_i32_e32 v155, 31, v154
	v_ashrrev_i32_e32 v145, 31, v144
	v_lshlrev_b64 v[156:157], 11, v[154:155]
	v_lshl_add_u64 v[156:157], s[10:11], 0, v[156:157]
	v_lshlrev_b64 v[158:159], 1, v[144:145]
	v_lshl_add_u64 v[144:145], v[156:157], 0, v[158:159]
	v_pk_add_f32 v[126:127], v[126:127], 0 op_sel_hi:[1,0]
	v_pk_add_f32 v[124:125], v[124:125], 0 op_sel_hi:[1,0]
	v_pk_add_f32 v[156:157], v[122:123], 0 op_sel_hi:[1,0]
	v_pk_add_f32 v[122:123], v[120:121], 0 op_sel_hi:[1,0]
	v_cvt_pk_bf16_f32 v120, v124, v125
	v_cvt_pk_bf16_f32 v121, v126, v127
	v_pk_add_f32 v[116:117], v[116:117], 0 op_sel_hi:[1,0]
	v_cvt_pk_bf16_f32 v122, v122, v123
	v_cvt_pk_bf16_f32 v123, v156, v157
	global_store_dwordx4 v[144:145], v[120:123], off
	v_pk_add_f32 v[118:119], v[118:119], 0 op_sel_hi:[1,0]
	v_pk_add_f32 v[110:111], v[110:111], 0 op_sel_hi:[1,0]
	v_pk_add_f32 v[120:121], v[114:115], 0 op_sel_hi:[1,0]
	v_pk_add_f32 v[114:115], v[112:113], 0 op_sel_hi:[1,0]
	v_cvt_pk_bf16_f32 v112, v116, v117
	v_cvt_pk_bf16_f32 v113, v118, v119
	v_pk_add_f32 v[108:109], v[108:109], 0 op_sel_hi:[1,0]
	v_cvt_pk_bf16_f32 v114, v114, v115
	v_cvt_pk_bf16_f32 v115, v120, v121
	global_store_dwordx4 v[144:145], v[112:115], off offset:256
	v_pk_add_f32 v[100:101], v[100:101], 0 op_sel_hi:[1,0]
	v_pk_add_f32 v[102:103], v[102:103], 0 op_sel_hi:[1,0]
	v_or_b32_e32 v112, 16, v154
	v_ashrrev_i32_e32 v113, 31, v112
	v_lshlrev_b64 v[112:113], 11, v[112:113]
	v_lshl_add_u64 v[112:113], s[10:11], 0, v[112:113]
	v_lshl_add_u64 v[112:113], v[112:113], 0, v[158:159]
	v_pk_add_f32 v[114:115], v[106:107], 0 op_sel_hi:[1,0]
	v_pk_add_f32 v[106:107], v[104:105], 0 op_sel_hi:[1,0]
	v_cvt_pk_bf16_f32 v104, v108, v109
	v_cvt_pk_bf16_f32 v105, v110, v111
	v_pk_add_f32 v[94:95], v[94:95], 0 op_sel_hi:[1,0]
	v_cvt_pk_bf16_f32 v106, v106, v107
	v_cvt_pk_bf16_f32 v107, v114, v115
	global_store_dwordx4 v[112:113], v[104:107], off
	v_pk_add_f32 v[92:93], v[92:93], 0 op_sel_hi:[1,0]
	v_pk_add_f32 v[84:85], v[84:85], 0 op_sel_hi:[1,0]
	v_pk_add_f32 v[104:105], v[98:99], 0 op_sel_hi:[1,0]
	v_pk_add_f32 v[98:99], v[96:97], 0 op_sel_hi:[1,0]
	v_cvt_pk_bf16_f32 v96, v100, v101
	v_cvt_pk_bf16_f32 v97, v102, v103
	v_pk_add_f32 v[86:87], v[86:87], 0 op_sel_hi:[1,0]
	v_cvt_pk_bf16_f32 v98, v98, v99
	v_cvt_pk_bf16_f32 v99, v104, v105
	global_store_dwordx4 v[112:113], v[96:99], off offset:256
	v_pk_add_f32 v[78:79], v[78:79], 0 op_sel_hi:[1,0]
	v_pk_add_f32 v[76:77], v[76:77], 0 op_sel_hi:[1,0]
	v_or_b32_e32 v96, 32, v154
	v_ashrrev_i32_e32 v97, 31, v96
	v_lshlrev_b64 v[96:97], 11, v[96:97]
	v_lshl_add_u64 v[96:97], s[10:11], 0, v[96:97]
	v_lshl_add_u64 v[96:97], v[96:97], 0, v[158:159]
	v_pk_add_f32 v[98:99], v[90:91], 0 op_sel_hi:[1,0]
	v_pk_add_f32 v[90:91], v[88:89], 0 op_sel_hi:[1,0]
	v_cvt_pk_bf16_f32 v88, v92, v93
	v_cvt_pk_bf16_f32 v89, v94, v95
	v_pk_add_f32 v[70:71], v[70:71], 0 op_sel_hi:[1,0]
	v_cvt_pk_bf16_f32 v90, v90, v91
	v_cvt_pk_bf16_f32 v91, v98, v99
	global_store_dwordx4 v[96:97], v[88:91], off
	v_pk_add_f32 v[68:69], v[68:69], 0 op_sel_hi:[1,0]
	s_mov_b64 s[22:23], 0x40000
	v_pk_add_f32 v[88:89], v[82:83], 0 op_sel_hi:[1,0]
	v_pk_add_f32 v[82:83], v[80:81], 0 op_sel_hi:[1,0]
	v_cvt_pk_bf16_f32 v80, v84, v85
	v_cvt_pk_bf16_f32 v81, v86, v87
	v_pk_add_f32 v[60:61], v[60:61], 0 op_sel_hi:[1,0]
	v_cvt_pk_bf16_f32 v82, v82, v83
	v_cvt_pk_bf16_f32 v83, v88, v89
	global_store_dwordx4 v[96:97], v[80:83], off offset:256
	v_pk_add_f32 v[62:63], v[62:63], 0 op_sel_hi:[1,0]
	v_pk_add_f32 v[54:55], v[54:55], 0 op_sel_hi:[1,0]
	v_or_b32_e32 v80, 48, v154
	v_ashrrev_i32_e32 v81, 31, v80
	v_lshlrev_b64 v[80:81], 11, v[80:81]
	v_lshl_add_u64 v[80:81], s[10:11], 0, v[80:81]
	v_lshl_add_u64 v[80:81], v[80:81], 0, v[158:159]
	v_pk_add_f32 v[82:83], v[74:75], 0 op_sel_hi:[1,0]
	v_pk_add_f32 v[74:75], v[72:73], 0 op_sel_hi:[1,0]
	v_cvt_pk_bf16_f32 v72, v76, v77
	v_cvt_pk_bf16_f32 v73, v78, v79
	v_pk_add_f32 v[52:53], v[52:53], 0 op_sel_hi:[1,0]
; __device__ __forceinline__ unsigned cvt_pk_bf16(float lo, float hi) { unsigned r; asm volatile("v_cvt_pk_bf16_f32 %0, %1, %2" : "=v"(r) : "v"(lo), "v"(hi)); return r; }
; __device__ __forceinline__ float flogsig16(float x) { return (fminf(x, 0.f) - __logf(1.0f + __expf(-fabsf(x)))) * 0.0625f; }
;     __device__ __forceinline__ void operator()(const f32x4 (&acc)[2][2][4][2], const Unit& u, int wr, int wc, int fr, int fq) const {
;     ...
;             for (int m = 0; m < 4; ++m) { bf16_t* rowp = O + (size_t)(row0 + ai * HALF + m * 16) * ldc + col0;
; #pragma unroll
;                 for (int bj = 0; bj < 2; ++bj) { f32x4 v0 = acc[ai][bj][m][0] + bv[bj][0], v1 = acc[ai][bj][m][1] + bv[bj][1];
;                     if (act == 1) {
; #pragma unroll
;                         for (int j = 0; j < 1; ++j) { v0 = v0 * sigmoid4(v0); v1 = v1 * sigmoid4(v1); } }
;                     else if (act == 2) {
; #pragma unroll
;                         for (int j = 0; j < 1; ++j) { v0 = sigmoid4(v0); v1 = sigmoid4(v1); } }
;                     else if (act == 3) {
; #pragma unroll
;                         for (int j = 0; j < 4; ++j) { v0[j] = flogsig16(v0[j]); v1[j] = flogsig16(v1[j]); } }
;                     u32x4 w; w.x = cvt_pk_bf16(v0[0], v0[1]); w.y = cvt_pk_bf16(v0[2], v0[3]); w.z = cvt_pk_bf16(v1[0], v1[1]); w.w = cvt_pk_bf16(v1[2], v1[3]);
;                     *(u32x4*)(rowp + bj * HALF) = w; } }
	v_cvt_pk_bf16_f32 v74, v74, v75
	v_cvt_pk_bf16_f32 v75, v82, v83
	global_store_dwordx4 v[80:81], v[72:75], off
	v_pk_add_f32 v[48:49], v[48:49], 0 op_sel_hi:[1,0]
	v_pk_add_f32 v[38:39], v[38:39], 0 op_sel_hi:[1,0]
	v_pk_add_f32 v[72:73], v[66:67], 0 op_sel_hi:[1,0]
	v_pk_add_f32 v[66:67], v[64:65], 0 op_sel_hi:[1,0]
	v_cvt_pk_bf16_f32 v64, v68, v69
	v_cvt_pk_bf16_f32 v65, v70, v71
	v_pk_add_f32 v[36:37], v[36:37], 0 op_sel_hi:[1,0]
	v_cvt_pk_bf16_f32 v66, v66, v67
	v_cvt_pk_bf16_f32 v67, v72, v73
	global_store_dwordx4 v[80:81], v[64:67], off offset:256
	v_pk_add_f32 v[32:33], v[32:33], 0 op_sel_hi:[1,0]
	v_pk_add_f32 v[22:23], v[22:23], 0 op_sel_hi:[1,0]
	v_lshl_add_u64 v[64:65], v[144:145], 0, s[22:23]
	s_mov_b32 s22, 0x40000
	v_pk_add_f32 v[66:67], v[58:59], 0 op_sel_hi:[1,0]
	v_pk_add_f32 v[58:59], v[56:57], 0 op_sel_hi:[1,0]
	v_cvt_pk_bf16_f32 v56, v60, v61
	v_add_co_u32_e32 v60, vcc, s22, v144
	v_cvt_pk_bf16_f32 v57, v62, v63
	v_cvt_pk_bf16_f32 v58, v58, v59
	v_cvt_pk_bf16_f32 v59, v66, v67
	s_mov_b64 s[22:23], 0x48000
	s_nop 0
	v_addc_co_u32_e32 v61, vcc, 0, v145, vcc
	global_store_dwordx4 v[60:61], v[56:59], off
	v_pk_add_f32 v[20:21], v[20:21], 0 op_sel_hi:[1,0]
	v_pk_add_f32 v[16:17], v[16:17], 0 op_sel_hi:[1,0]
	v_pk_add_f32 v[56:57], v[46:47], 0 op_sel_hi:[1,0]
	v_pk_add_f32 v[46:47], v[44:45], 0 op_sel_hi:[1,0]
	v_cvt_pk_bf16_f32 v44, v52, v53
	v_cvt_pk_bf16_f32 v45, v54, v55
	s_mov_b32 s54, s51
	v_cvt_pk_bf16_f32 v46, v46, v47
	v_cvt_pk_bf16_f32 v47, v56, v57
	global_store_dwordx4 v[64:65], v[44:47], off offset:256
	s_mov_b32 s53, s52
	s_mov_b64 s[24:25], s[4:5]
	v_pk_add_f32 v[46:47], v[50:51], 0 op_sel_hi:[1,0]
	v_pk_add_f32 v[50:51], v[42:43], 0 op_sel_hi:[1,0]
	v_pk_add_f32 v[42:43], v[40:41], 0 op_sel_hi:[1,0]
	v_cvt_pk_bf16_f32 v40, v48, v49
	v_cvt_pk_bf16_f32 v41, v46, v47
	v_add_co_u32_e32 v46, vcc, s48, v144
	v_cvt_pk_bf16_f32 v42, v42, v43
	v_cvt_pk_bf16_f32 v43, v50, v51
	v_lshl_add_u64 v[44:45], v[144:145], 0, s[22:23]
	s_nop 0
	v_addc_co_u32_e32 v47, vcc, 0, v145, vcc
	global_store_dwordx4 v[46:47], v[40:43], off
	s_mov_b64 s[22:23], s[0:1]
	v_pk_add_f32 v[6:7], v[6:7], 0 op_sel_hi:[1,0]
	v_pk_add_f32 v[40:41], v[30:31], 0 op_sel_hi:[1,0]
	v_pk_add_f32 v[30:31], v[28:29], 0 op_sel_hi:[1,0]
	v_cvt_pk_bf16_f32 v28, v36, v37
	v_cvt_pk_bf16_f32 v29, v38, v39
	v_pk_add_f32 v[4:5], v[4:5], 0 op_sel_hi:[1,0]
	v_cvt_pk_bf16_f32 v30, v30, v31
	v_cvt_pk_bf16_f32 v31, v40, v41
	global_store_dwordx4 v[44:45], v[28:31], off offset:256
	s_nop 1
	v_pk_add_f32 v[30:31], v[34:35], 0 op_sel_hi:[1,0]
	v_pk_add_f32 v[34:35], v[26:27], 0 op_sel_hi:[1,0]
	v_pk_add_f32 v[26:27], v[24:25], 0 op_sel_hi:[1,0]
	v_cvt_pk_bf16_f32 v24, v32, v33
	v_cvt_pk_bf16_f32 v25, v30, v31
	v_add_co_u32_e32 v30, vcc, s49, v144
	v_cvt_pk_bf16_f32 v26, v26, v27
	v_cvt_pk_bf16_f32 v27, v34, v35
	v_lshl_add_u64 v[28:29], v[144:145], 0, s[16:17]
	s_nop 0
	v_addc_co_u32_e32 v31, vcc, 0, v145, vcc
	global_store_dwordx4 v[30:31], v[24:27], off
	s_nop 1
	v_pk_add_f32 v[24:25], v[14:15], 0 op_sel_hi:[1,0]
	v_pk_add_f32 v[14:15], v[12:13], 0 op_sel_hi:[1,0]
	v_cvt_pk_bf16_f32 v12, v20, v21
	v_cvt_pk_bf16_f32 v13, v22, v23
	s_nop 0
	v_cvt_pk_bf16_f32 v14, v14, v15
	v_cvt_pk_bf16_f32 v15, v24, v25
	global_store_dwordx4 v[28:29], v[12:15], off offset:256
	s_nop 1
	v_pk_add_f32 v[14:15], v[18:19], 0 op_sel_hi:[1,0]
	v_pk_add_f32 v[18:19], v[10:11], 0 op_sel_hi:[1,0]
	v_pk_add_f32 v[10:11], v[8:9], 0 op_sel_hi:[1,0]
	v_cvt_pk_bf16_f32 v8, v16, v17
	v_cvt_pk_bf16_f32 v9, v14, v15
	v_add_co_u32_e32 v14, vcc, s50, v144
	v_lshl_add_u64 v[12:13], v[144:145], 0, s[18:19]
	s_nop 0
	v_addc_co_u32_e32 v15, vcc, 0, v145, vcc
	v_cvt_pk_bf16_f32 v10, v10, v11
	v_cvt_pk_bf16_f32 v11, v18, v19
	global_store_dwordx4 v[14:15], v[8:11], off
	s_and_b64 vcc, exec, s[2:3]
	s_nop 0
	v_pk_add_f32 v[8:9], v[2:3], 0 op_sel_hi:[1,0]
	v_pk_add_f32 v[2:3], v[0:1], 0 op_sel_hi:[1,0]
	v_cvt_pk_bf16_f32 v0, v4, v5
	v_cvt_pk_bf16_f32 v1, v6, v7
	s_nop 0
	v_cvt_pk_bf16_f32 v2, v2, v3
	v_cvt_pk_bf16_f32 v3, v8, v9
	global_store_dwordx4 v[12:13], v[0:3], off offset:256
	s_cbranch_vccz .LBB0_275
	s_waitcnt vmcnt(0)
	s_cmpk_gt_u32 s31, 0xff
	s_cbranch_scc1 .LBB0_290
	s_barrier

; #define PG8_STAGE(bufoff, gbase, voff) do { _Pragma("unroll") for (int _i = 0; _i < 2; ++_i) \
;         __builtin_amdgcn_global_load_lds((const unsigned*)((const char*)(gbase) + (voff)[_i]), (PG8_LAS unsigned*)(lds + (bufoff) + ldsw + _i * 8192), 16, 0, 0); } while (0)
; #define PG8_LDA(dst, b, h) do { _Pragma("unroll") for (int m = 0; m < 4; ++m) _Pragma("unroll") for (int k = 0; k < 2; ++k) dst[m][k] = *(const PG8_LAS bf16x8*)(lds + PG8_SA(b, h) + aoff + m * 2048 + k * 1024); } while (0)
; #define PG8_LDB(dst, b, h) do { _Pragma("unroll") for (int n = 0; n < 2; ++n) _Pragma("unroll") for (int k = 0; k < 2; ++k) dst[n][k] = *(const PG8_LAS bf16x8*)(lds + PG8_SB(b, h) + boff + n * 2048 + k * 1024); } while (0)
; #define PG8_MMA(ai, bj, At, Bt) do { __builtin_amdgcn_s_setprio(1); _Pragma("unroll") for (int m = 0; m < 4; ++m) _Pragma("unroll") for (int n = 0; n < 2; ++n) _Pragma("unroll") for (int k = 0; k < 2; ++k) \
;         acc[ai][bj][m][n] = __builtin_amdgcn_mfma_f32_16x16x32_bf16(Bt[n][k], At[m][k], acc[ai][bj][m][n], 0, 0, 0); __builtin_amdgcn_s_setprio(0); } while (0)
; template <class Epi, class Sched>
; __device__ __forceinline__ void gemm_phase(PG8_LAS unsigned char* lds, const Gemm g, const Sched& S, const Epi& E) {
;     ...
;         const bool has_next = S.next(ui + 1, nxt);
;         const char* nA = has_next ? (const char*)g.A + (size_t)nxt.pm * tstep : cA; const char* nB = has_next ? (const char*)g.Bt + (size_t)nxt.pn * tstep : cB;
;         for (int t = 0; t < nt; t += 2) {
;             const bool last = (t == nt - 2);
;             const char* a1 = cA + (size_t)(t + 1) * kstep;
;             const char* a2 = last ? nA : cA + (size_t)(t + 2) * kstep; const char* b2 = last ? nB : cB + (size_t)(t + 2) * kstep;
;             const char* a3 = a2 + kstep; const char* b3 = b2 + kstep;
;             if (last && has_next) S.a_ready(nxt);
;             PG8_LDB(B0, 0, 0); PG8_SCHED; PG8_LDA(At, 0, 0); PG8_STAGE(PG8_SA(1, 1), a1 + hstep, voffA);
;             PG8_WAIT_L(8); PG8_BAR; PG8_WAIT_L(0); PG8_MMA(0, 0, At, B0); PG8_BAR; PG8_SCHED;
;             PG8_LDB(B1, 0, 1); PG8_STAGE(PG8_SB(0, 0), b2, voffB);
;             PG8_BAR; PG8_WAIT_L(0); PG8_MMA(0, 1, At, B1); PG8_BAR;
;             PG8_LDA(At, 0, 1); PG8_STAGE(PG8_SA(0, 0), a2, voffA);
;             PG8_BAR; PG8_WAIT_L(0); PG8_MMA(1, 0, At, B0); PG8_BAR; PG8_SCHED;
.LBB0_415:
	s_ashr_i32 s21, s20, 31
	v_cmp_lt_i64_e32 vcc, s[22:23], v[170:171]
	s_lshl_b64 s[22:23], s[20:21], 19
	s_add_u32 s22, s31, s22
	s_addc_u32 s23, s34, s23
	s_and_b64 s[24:25], vcc, exec
	s_cselect_b32 s7, s23, s1
	s_cselect_b32 s10, s22, s0
	s_ashr_i32 s19, s18, 31
	s_lshl_b64 s[24:25], s[18:19], 19
	s_add_u32 s24, s8, s24
	s_addc_u32 s25, s9, s25
	s_and_b64 s[28:29], vcc, exec
	s_cselect_b32 s19, s25, s5
	s_cselect_b32 s21, s24, s4
	s_add_u32 s0, s0, 0x40080
	s_addc_u32 s1, s1, 0
	s_add_u32 s51, s4, 0x100
	s_addc_u32 s52, s5, 0
	s_mov_b32 s53, -2
	ds_read_b128 v[24:27], v186
	ds_read_b128 v[28:31], v186 offset:1024
	ds_read_b128 v[40:43], v186 offset:2048
	ds_read_b128 v[44:47], v186 offset:3072
	s_add_u32 s4, s0, 0xfffc0080
	s_addc_u32 s5, s1, -1
	s_cmp_eq_u32 s53, 12
	s_cselect_b32 s29, s7, s5
	s_cselect_b32 s28, s10, s4
	s_cselect_b32 s5, s19, s52
	s_cselect_b32 s4, s21, s51
	s_add_i32 m0, s27, 0xc000
	ds_read_b128 v[144:147], v187
	ds_read_b128 v[148:151], v187 offset:1024
	ds_read_b128 v[182:185], v187 offset:2048
	ds_read_b128 v[192:195], v187 offset:3072
	ds_read_b128 v[196:199], v187 offset:4096
	ds_read_b128 v[200:203], v187 offset:5120
	ds_read_b128 v[204:207], v187 offset:6144
	ds_read_b128 v[208:211], v187 offset:7168
	global_load_lds_dwordx4 v166, s[0:1]
	s_add_i32 m0, s27, 0xe000
	s_nop 0
	global_load_lds_dwordx4 v168, s[0:1]
	s_waitcnt lgkmcnt(8)
	ds_read_b128 v[212:215], v189
	ds_read_b128 v[216:219], v189 offset:1024
	ds_read_b128 v[220:223], v189 offset:2048
	ds_read_b128 v[224:227], v189 offset:3072
	s_waitcnt vmcnt(8) lgkmcnt(0)
	s_barrier
	v_mfma_f32_16x16x32_bf16 v[140:143], v[24:27], v[144:147], 0
	v_mfma_f32_16x16x32_bf16 v[136:139], v[40:43], v[144:147], 0
	v_mfma_f32_16x16x32_bf16 v[124:127], v[24:27], v[182:185], 0
	v_mfma_f32_16x16x32_bf16 v[120:123], v[40:43], v[182:185], 0
	v_mfma_f32_16x16x32_bf16 v[108:111], v[24:27], v[196:199], 0
	v_mfma_f32_16x16x32_bf16 v[104:107], v[40:43], v[196:199], 0
	v_mfma_f32_16x16x32_bf16 v[92:95], v[24:27], v[204:207], 0
	v_mfma_f32_16x16x32_bf16 v[88:91], v[40:43], v[204:207], 0
	v_mfma_f32_16x16x32_bf16 v[140:143], v[28:31], v[148:151], v[140:143]
	v_mfma_f32_16x16x32_bf16 v[136:139], v[44:47], v[148:151], v[136:139]
	v_mfma_f32_16x16x32_bf16 v[124:127], v[28:31], v[192:195], v[124:127]
	v_mfma_f32_16x16x32_bf16 v[120:123], v[44:47], v[192:195], v[120:123]
	v_mfma_f32_16x16x32_bf16 v[108:111], v[28:31], v[200:203], v[108:111]
	v_mfma_f32_16x16x32_bf16 v[104:107], v[44:47], v[200:203], v[104:107]
	v_mfma_f32_16x16x32_bf16 v[92:95], v[28:31], v[208:211], v[92:95]
	v_mfma_f32_16x16x32_bf16 v[88:91], v[44:47], v[208:211], v[88:91]
	v_mfma_f32_16x16x32_bf16 v[132:135], v[212:215], v[144:147], 0
	v_mfma_f32_16x16x32_bf16 v[128:131], v[220:223], v[144:147], 0
	v_mfma_f32_16x16x32_bf16 v[116:119], v[212:215], v[182:185], 0
	v_mfma_f32_16x16x32_bf16 v[112:115], v[220:223], v[182:185], 0
	v_mfma_f32_16x16x32_bf16 v[100:103], v[212:215], v[196:199], 0
	v_mfma_f32_16x16x32_bf16 v[96:99], v[220:223], v[196:199], 0
	v_mfma_f32_16x16x32_bf16 v[84:87], v[212:215], v[204:207], 0
	v_mfma_f32_16x16x32_bf16 v[80:83], v[220:223], v[204:207], 0
	v_mfma_f32_16x16x32_bf16 v[132:135], v[216:219], v[148:151], v[132:135]
	v_mfma_f32_16x16x32_bf16 v[128:131], v[224:227], v[148:151], v[128:131]
	v_mfma_f32_16x16x32_bf16 v[116:119], v[216:219], v[192:195], v[116:119]
	v_mfma_f32_16x16x32_bf16 v[112:115], v[224:227], v[192:195], v[112:115]
	v_mfma_f32_16x16x32_bf16 v[100:103], v[216:219], v[200:203], v[100:103]
	v_mfma_f32_16x16x32_bf16 v[96:99], v[224:227], v[200:203], v[96:99]
	v_mfma_f32_16x16x32_bf16 v[84:87], v[216:219], v[208:211], v[84:87]
	v_mfma_f32_16x16x32_bf16 v[80:83], v[224:227], v[208:211], v[80:83]
	s_barrier
	ds_read_b128 v[144:147], v187 offset:16384
	ds_read_b128 v[148:151], v187 offset:17408
	ds_read_b128 v[182:185], v187 offset:18432
	ds_read_b128 v[192:195], v187 offset:19456
	ds_read_b128 v[196:199], v187 offset:20480
	ds_read_b128 v[200:203], v187 offset:21504
	ds_read_b128 v[204:207], v187 offset:22528
	ds_read_b128 v[208:211], v187 offset:23552
	s_add_i32 s54, s43, s35
	s_add_u32 s98, s4, s14
	s_addc_u32 s99, s5, s15
	s_mov_b32 m0, s54
	s_nop 0
	global_load_lds_dwordx4 v156, s[4:5]
	s_add_i32 m0, s54, 0x2000
	s_nop 0
	global_load_lds_dwordx4 v160, s[4:5]
	s_mov_b32 m0, s27
	s_add_u32 s100, s28, s14
	s_addc_u32 s101, s29, s15
	global_load_lds_dwordx4 v154, s[28:29]
	s_mov_b32 m0, s36
	s_nop 0
	global_load_lds_dwordx4 v158, s[28:29]
	s_add_u32 s54, s4, 0x40000
	s_addc_u32 s55, s5, 0
	s_add_i32 s56, s44, s35
	s_mov_b32 m0, s56
	s_nop 0
	global_load_lds_dwordx4 v156, s[54:55]
	s_add_i32 m0, s56, 0x2000
	s_nop 0
	global_load_lds_dwordx4 v160, s[54:55]
	s_waitcnt vmcnt(8) lgkmcnt(0)
	s_barrier
; #define PG8_STAGE(bufoff, gbase, voff) do { _Pragma("unroll") for (int _i = 0; _i < 2; ++_i) \
;         __builtin_amdgcn_global_load_lds((const unsigned*)((const char*)(gbase) + (voff)[_i]), (PG8_LAS unsigned*)(lds + (bufoff) + ldsw + _i * 8192), 16, 0, 0); } while (0)
; #define PG8_LDA(dst, b, h) do { _Pragma("unroll") for (int m = 0; m < 4; ++m) _Pragma("unroll") for (int k = 0; k < 2; ++k) dst[m][k] = *(const PG8_LAS bf16x8*)(lds + PG8_SA(b, h) + aoff + m * 2048 + k * 1024); } while (0)
; #define PG8_LDB(dst, b, h) do { _Pragma("unroll") for (int n = 0; n < 2; ++n) _Pragma("unroll") for (int k = 0; k < 2; ++k) dst[n][k] = *(const PG8_LAS bf16x8*)(lds + PG8_SB(b, h) + boff + n * 2048 + k * 1024); } while (0)
; #define PG8_MMA(ai, bj, At, Bt) do { __builtin_amdgcn_s_setprio(1); _Pragma("unroll") for (int m = 0; m < 4; ++m) _Pragma("unroll") for (int n = 0; n < 2; ++n) _Pragma("unroll") for (int k = 0; k < 2; ++k) \
;         acc[ai][bj][m][n] = __builtin_amdgcn_mfma_f32_16x16x32_bf16(Bt[n][k], At[m][k], acc[ai][bj][m][n], 0, 0, 0); __builtin_amdgcn_s_setprio(0); } while (0)
; #define PG8_WAIT_V(n) asm volatile("s_waitcnt vmcnt(" #n ")" ::: "memory")
; #define PG8_WAIT_L(n) asm volatile("s_waitcnt lgkmcnt(" #n ")" ::: "memory")
; #define PG8_BAR __builtin_amdgcn_s_barrier()
; #define PG8_SCHED __builtin_amdgcn_sched_barrier(0)
; template <class Epi, class Sched>
; __device__ __forceinline__ void gemm_phase(PG8_LAS unsigned char* lds, const Gemm g, const Sched& S, const Epi& E) {
;     ...
;             PG8_BAR; PG8_WAIT_L(0); PG8_MMA(1, 0, At, B0); PG8_BAR; PG8_SCHED;
;             PG8_STAGE(PG8_SB(0, 1), b2 + hstep, voffB);
;             PG8_WAIT_V(6); PG8_BAR; PG8_MMA(1, 1, At, B1); PG8_BAR;
;             PG8_LDB(B0, 1, 0); PG8_SCHED; PG8_LDA(At, 1, 0); PG8_STAGE(PG8_SA(0, 1), a2 + hstep, voffA);
;             PG8_WAIT_L(8); PG8_BAR; PG8_WAIT_L(0); PG8_MMA(0, 0, At, B0); PG8_BAR; PG8_SCHED;
;             PG8_LDB(B1, 1, 1); PG8_STAGE(PG8_SB(1, 0), b3, voffB);
;             PG8_BAR; PG8_WAIT_L(0); PG8_MMA(0, 1, At, B1); PG8_BAR;
	v_mfma_f32_16x16x32_bf16 v[76:79], v[24:27], v[144:147], 0
	v_mfma_f32_16x16x32_bf16 v[72:75], v[40:43], v[144:147], 0
	v_mfma_f32_16x16x32_bf16 v[60:63], v[24:27], v[182:185], 0
	v_mfma_f32_16x16x32_bf16 v[56:59], v[40:43], v[182:185], 0
	v_mfma_f32_16x16x32_bf16 v[36:39], v[24:27], v[196:199], 0
	v_mfma_f32_16x16x32_bf16 v[32:35], v[40:43], v[196:199], 0
	v_mfma_f32_16x16x32_bf16 v[12:15], v[24:27], v[204:207], 0
	v_mfma_f32_16x16x32_bf16 v[8:11], v[40:43], v[204:207], 0
	v_mfma_f32_16x16x32_bf16 v[76:79], v[28:31], v[148:151], v[76:79]
	v_mfma_f32_16x16x32_bf16 v[72:75], v[44:47], v[148:151], v[72:75]
	v_mfma_f32_16x16x32_bf16 v[60:63], v[28:31], v[192:195], v[60:63]
	v_mfma_f32_16x16x32_bf16 v[56:59], v[44:47], v[192:195], v[56:59]
	v_mfma_f32_16x16x32_bf16 v[36:39], v[28:31], v[200:203], v[36:39]
	v_mfma_f32_16x16x32_bf16 v[32:35], v[44:47], v[200:203], v[32:35]
	v_mfma_f32_16x16x32_bf16 v[12:15], v[28:31], v[208:211], v[12:15]
	v_mfma_f32_16x16x32_bf16 v[8:11], v[44:47], v[208:211], v[8:11]
	v_mfma_f32_16x16x32_bf16 v[20:23], v[212:215], v[196:199], 0
	v_mfma_f32_16x16x32_bf16 v[16:19], v[220:223], v[196:199], 0
	v_mfma_f32_16x16x32_bf16 v[4:7], v[212:215], v[204:207], 0
	v_mfma_f32_16x16x32_bf16 v[0:3], v[220:223], v[204:207], 0
	v_mfma_f32_16x16x32_bf16 v[24:27], v[212:215], v[144:147], 0
	v_mfma_f32_16x16x32_bf16 v[28:31], v[220:223], v[144:147], 0
	v_mfma_f32_16x16x32_bf16 v[40:43], v[212:215], v[182:185], 0
	v_mfma_f32_16x16x32_bf16 v[44:47], v[220:223], v[182:185], 0
	v_mfma_f32_16x16x32_bf16 v[20:23], v[216:219], v[200:203], v[20:23]
	v_mfma_f32_16x16x32_bf16 v[16:19], v[224:227], v[200:203], v[16:19]
	v_mfma_f32_16x16x32_bf16 v[4:7], v[216:219], v[208:211], v[4:7]
	v_mfma_f32_16x16x32_bf16 v[0:3], v[224:227], v[208:211], v[0:3]
	v_mfma_f32_16x16x32_bf16 v[24:27], v[216:219], v[148:151], v[24:27]
	v_mfma_f32_16x16x32_bf16 v[28:31], v[224:227], v[148:151], v[28:31]
	v_mfma_f32_16x16x32_bf16 v[40:43], v[216:219], v[192:195], v[40:43]
	v_mfma_f32_16x16x32_bf16 v[44:47], v[224:227], v[192:195], v[44:47]
	s_barrier
	s_add_i32 s54, 0, 0x18000
	v_add_u32_e32 v68, s54, v179
	ds_read_b128 v[48:51], v68
	ds_read_b128 v[52:55], v68 offset:1024
	ds_read_b128 v[64:67], v68 offset:2048
	ds_read_b128 v[68:71], v68 offset:3072
	s_add_u32 s28, s28, 0x40000
	s_addc_u32 s29, s29, 0
	s_mov_b32 m0, s37
	ds_read_b128 v[144:147], v187 offset:32768
	ds_read_b128 v[148:151], v187 offset:33792
	ds_read_b128 v[182:185], v187 offset:34816
	ds_read_b128 v[192:195], v187 offset:35840
	ds_read_b128 v[196:199], v187 offset:36864
	ds_read_b128 v[200:203], v187 offset:37888
	ds_read_b128 v[204:207], v187 offset:38912
	ds_read_b128 v[208:211], v187 offset:39936
	global_load_lds_dwordx4 v154, s[28:29]
	s_mov_b32 m0, s38
	s_nop 0
	global_load_lds_dwordx4 v158, s[28:29]
	s_add_i32 s28, 0, 0x1c000
	v_add_u32_e32 v162, s28, v179
	s_waitcnt lgkmcnt(8)
	ds_read_b128 v[212:215], v162
	ds_read_b128 v[216:219], v162 offset:1024
	ds_read_b128 v[220:223], v162 offset:2048
	ds_read_b128 v[224:227], v162 offset:3072
	s_waitcnt vmcnt(8) lgkmcnt(0)
	s_barrier
	v_mfma_f32_16x16x32_bf16 v[140:143], v[48:51], v[144:147], v[140:143]
	v_mfma_f32_16x16x32_bf16 v[136:139], v[64:67], v[144:147], v[136:139]
	v_mfma_f32_16x16x32_bf16 v[124:127], v[48:51], v[182:185], v[124:127]
	v_mfma_f32_16x16x32_bf16 v[120:123], v[64:67], v[182:185], v[120:123]
	v_mfma_f32_16x16x32_bf16 v[108:111], v[48:51], v[196:199], v[108:111]
	v_mfma_f32_16x16x32_bf16 v[104:107], v[64:67], v[196:199], v[104:107]
	v_mfma_f32_16x16x32_bf16 v[92:95], v[48:51], v[204:207], v[92:95]
	v_mfma_f32_16x16x32_bf16 v[88:91], v[64:67], v[204:207], v[88:91]
	v_mfma_f32_16x16x32_bf16 v[140:143], v[52:55], v[148:151], v[140:143]
	v_mfma_f32_16x16x32_bf16 v[136:139], v[68:71], v[148:151], v[136:139]
	v_mfma_f32_16x16x32_bf16 v[124:127], v[52:55], v[192:195], v[124:127]
	v_mfma_f32_16x16x32_bf16 v[120:123], v[68:71], v[192:195], v[120:123]
	v_mfma_f32_16x16x32_bf16 v[108:111], v[52:55], v[200:203], v[108:111]
	v_mfma_f32_16x16x32_bf16 v[104:107], v[68:71], v[200:203], v[104:107]
	v_mfma_f32_16x16x32_bf16 v[92:95], v[52:55], v[208:211], v[92:95]
	v_mfma_f32_16x16x32_bf16 v[88:91], v[68:71], v[208:211], v[88:91]
	v_mfma_f32_16x16x32_bf16 v[132:135], v[212:215], v[144:147], v[132:135]
	v_mfma_f32_16x16x32_bf16 v[128:131], v[220:223], v[144:147], v[128:131]
	v_mfma_f32_16x16x32_bf16 v[116:119], v[212:215], v[182:185], v[116:119]
	v_mfma_f32_16x16x32_bf16 v[112:115], v[220:223], v[182:185], v[112:115]
	v_mfma_f32_16x16x32_bf16 v[100:103], v[212:215], v[196:199], v[100:103]
	v_mfma_f32_16x16x32_bf16 v[96:99], v[220:223], v[196:199], v[96:99]
	v_mfma_f32_16x16x32_bf16 v[84:87], v[212:215], v[204:207], v[84:87]
	v_mfma_f32_16x16x32_bf16 v[80:83], v[220:223], v[204:207], v[80:83]
	v_mfma_f32_16x16x32_bf16 v[132:135], v[216:219], v[148:151], v[132:135]
	v_mfma_f32_16x16x32_bf16 v[128:131], v[224:227], v[148:151], v[128:131]
	v_mfma_f32_16x16x32_bf16 v[116:119], v[216:219], v[192:195], v[116:119]
	v_mfma_f32_16x16x32_bf16 v[112:115], v[224:227], v[192:195], v[112:115]
	v_mfma_f32_16x16x32_bf16 v[100:103], v[216:219], v[200:203], v[100:103]
	v_mfma_f32_16x16x32_bf16 v[96:99], v[224:227], v[200:203], v[96:99]
	v_mfma_f32_16x16x32_bf16 v[84:87], v[216:219], v[208:211], v[84:87]
	v_mfma_f32_16x16x32_bf16 v[80:83], v[224:227], v[208:211], v[80:83]
	s_barrier
; #define PG8_STAGE(bufoff, gbase, voff) do { _Pragma("unroll") for (int _i = 0; _i < 2; ++_i) \
;         __builtin_amdgcn_global_load_lds((const unsigned*)((const char*)(gbase) + (voff)[_i]), (PG8_LAS unsigned*)(lds + (bufoff) + ldsw + _i * 8192), 16, 0, 0); } while (0)
; #define PG8_LDA(dst, b, h) do { _Pragma("unroll") for (int m = 0; m < 4; ++m) _Pragma("unroll") for (int k = 0; k < 2; ++k) dst[m][k] = *(const PG8_LAS bf16x8*)(lds + PG8_SA(b, h) + aoff + m * 2048 + k * 1024); } while (0)
; #define PG8_LDB(dst, b, h) do { _Pragma("unroll") for (int n = 0; n < 2; ++n) _Pragma("unroll") for (int k = 0; k < 2; ++k) dst[n][k] = *(const PG8_LAS bf16x8*)(lds + PG8_SB(b, h) + boff + n * 2048 + k * 1024); } while (0)
; #define PG8_MMA(ai, bj, At, Bt) do { __builtin_amdgcn_s_setprio(1); _Pragma("unroll") for (int m = 0; m < 4; ++m) _Pragma("unroll") for (int n = 0; n < 2; ++n) _Pragma("unroll") for (int k = 0; k < 2; ++k) \
;         acc[ai][bj][m][n] = __builtin_amdgcn_mfma_f32_16x16x32_bf16(Bt[n][k], At[m][k], acc[ai][bj][m][n], 0, 0, 0); __builtin_amdgcn_s_setprio(0); } while (0)
; #define PG8_WAIT_V(n) asm volatile("s_waitcnt vmcnt(" #n ")" ::: "memory")
; #define PG8_WAIT_L(n) asm volatile("s_waitcnt lgkmcnt(" #n ")" ::: "memory")
; #define PG8_BAR __builtin_amdgcn_s_barrier()
; #define PG8_SCHED __builtin_amdgcn_sched_barrier(0)
; template <class Epi, class Sched>
; __device__ __forceinline__ void gemm_phase(PG8_LAS unsigned char* lds, const Gemm g, const Sched& S, const Epi& E) {
;     ...
;             PG8_LDB(B0, 0, 0); PG8_SCHED; PG8_LDA(At, 0, 0); PG8_STAGE(PG8_SA(1, 1), a1 + hstep, voffA);
;             PG8_WAIT_L(8); PG8_BAR; PG8_WAIT_L(0); PG8_MMA(0, 0, At, B0); PG8_BAR; PG8_SCHED;
;     ...
;             PG8_LDA(At, 1, 1); PG8_STAGE(PG8_SA(1, 0), a3, voffA);
;             PG8_BAR; PG8_WAIT_L(0); PG8_MMA(1, 0, At, B0); PG8_BAR; PG8_SCHED;
;             PG8_STAGE(PG8_SB(1, 1), b3 + hstep, voffB);
;             PG8_WAIT_V(6); PG8_BAR; PG8_MMA(1, 1, At, B1); PG8_BAR;
	ds_read_b128 v[144:147], v187 offset:49152
	ds_read_b128 v[148:151], v187 offset:50176
	ds_read_b128 v[182:185], v187 offset:51200
	ds_read_b128 v[192:195], v187 offset:52224
	ds_read_b128 v[196:199], v187 offset:53248
	ds_read_b128 v[200:203], v187 offset:54272
	ds_read_b128 v[204:207], v187 offset:55296
	ds_read_b128 v[208:211], v187 offset:56320
	s_add_i32 s29, s54, s35
	s_mov_b32 m0, s29
	s_nop 0
	global_load_lds_dwordx4 v156, s[98:99]
	s_add_i32 m0, s29, 0x2000
	s_nop 0
	global_load_lds_dwordx4 v160, s[98:99]
	s_mov_b32 m0, s39
	s_nop 0
	global_load_lds_dwordx4 v154, s[100:101]
	s_mov_b32 m0, s40
	s_nop 0
	global_load_lds_dwordx4 v158, s[100:101]
	s_add_u32 s4, s4, 0x40080
	s_addc_u32 s5, s5, 0
	s_add_i32 s28, s28, s35
	s_mov_b32 m0, s28
	s_nop 0
	global_load_lds_dwordx4 v156, s[4:5]
	s_add_i32 m0, s28, 0x2000
	s_nop 0
	global_load_lds_dwordx4 v160, s[4:5]
	s_waitcnt vmcnt(8) lgkmcnt(0)
	s_barrier
	v_mfma_f32_16x16x32_bf16 v[76:79], v[48:51], v[144:147], v[76:79]
	v_mfma_f32_16x16x32_bf16 v[72:75], v[64:67], v[144:147], v[72:75]
	v_mfma_f32_16x16x32_bf16 v[60:63], v[48:51], v[182:185], v[60:63]
	v_mfma_f32_16x16x32_bf16 v[56:59], v[64:67], v[182:185], v[56:59]
	v_mfma_f32_16x16x32_bf16 v[36:39], v[48:51], v[196:199], v[36:39]
	v_mfma_f32_16x16x32_bf16 v[32:35], v[64:67], v[196:199], v[32:35]
	v_mfma_f32_16x16x32_bf16 v[12:15], v[48:51], v[204:207], v[12:15]
	v_mfma_f32_16x16x32_bf16 v[8:11], v[64:67], v[204:207], v[8:11]
	v_mfma_f32_16x16x32_bf16 v[76:79], v[52:55], v[148:151], v[76:79]
	v_mfma_f32_16x16x32_bf16 v[72:75], v[68:71], v[148:151], v[72:75]
	v_mfma_f32_16x16x32_bf16 v[60:63], v[52:55], v[192:195], v[60:63]
	v_mfma_f32_16x16x32_bf16 v[56:59], v[68:71], v[192:195], v[56:59]
	v_mfma_f32_16x16x32_bf16 v[36:39], v[52:55], v[200:203], v[36:39]
	v_mfma_f32_16x16x32_bf16 v[32:35], v[68:71], v[200:203], v[32:35]
	v_mfma_f32_16x16x32_bf16 v[12:15], v[52:55], v[208:211], v[12:15]
	v_mfma_f32_16x16x32_bf16 v[8:11], v[68:71], v[208:211], v[8:11]
	v_mfma_f32_16x16x32_bf16 v[24:27], v[212:215], v[144:147], v[24:27]
	v_mfma_f32_16x16x32_bf16 v[68:71], v[216:219], v[148:151], v[24:27]
	v_mfma_f32_16x16x32_bf16 v[24:27], v[220:223], v[144:147], v[28:31]
	v_mfma_f32_16x16x32_bf16 v[64:67], v[224:227], v[148:151], v[24:27]
	v_mfma_f32_16x16x32_bf16 v[24:27], v[212:215], v[182:185], v[40:43]
	v_mfma_f32_16x16x32_bf16 v[52:55], v[216:219], v[192:195], v[24:27]
	v_mfma_f32_16x16x32_bf16 v[24:27], v[220:223], v[182:185], v[44:47]
	v_mfma_f32_16x16x32_bf16 v[20:23], v[212:215], v[196:199], v[20:23]
	v_mfma_f32_16x16x32_bf16 v[16:19], v[220:223], v[196:199], v[16:19]
	v_mfma_f32_16x16x32_bf16 v[4:7], v[212:215], v[204:207], v[4:7]
	v_mfma_f32_16x16x32_bf16 v[0:3], v[220:223], v[204:207], v[0:3]
	v_mfma_f32_16x16x32_bf16 v[48:51], v[224:227], v[192:195], v[24:27]
	v_mfma_f32_16x16x32_bf16 v[20:23], v[216:219], v[200:203], v[20:23]
	v_mfma_f32_16x16x32_bf16 v[16:19], v[224:227], v[200:203], v[16:19]
	v_mfma_f32_16x16x32_bf16 v[4:7], v[216:219], v[208:211], v[4:7]
	v_mfma_f32_16x16x32_bf16 v[0:3], v[224:227], v[208:211], v[0:3]
	s_barrier
	s_add_i32 s53, s53, 2
	s_add_u32 s0, s0, 0x100
	s_addc_u32 s1, s1, 0
	s_add_u32 s51, s51, 0x100
	s_addc_u32 s52, s52, 0
	s_cmp_gt_u32 s53, 13
.LBB0_416:
	ds_read_b128 v[24:27], v186
	ds_read_b128 v[28:31], v186 offset:1024
	ds_read_b128 v[40:43], v186 offset:2048
	ds_read_b128 v[44:47], v186 offset:3072
	s_add_u32 s4, s0, 0xfffc0080
	s_addc_u32 s5, s1, -1
	s_cmp_eq_u32 s53, 12
	s_cselect_b32 s29, s7, s5
	s_cselect_b32 s28, s10, s4
	s_cselect_b32 s5, s19, s52
	s_cselect_b32 s4, s21, s51
	s_add_i32 m0, s27, 0xc000
	ds_read_b128 v[144:147], v187
	ds_read_b128 v[148:151], v187 offset:1024
	ds_read_b128 v[182:185], v187 offset:2048
	ds_read_b128 v[192:195], v187 offset:3072
	ds_read_b128 v[196:199], v187 offset:4096
	ds_read_b128 v[200:203], v187 offset:5120
	ds_read_b128 v[204:207], v187 offset:6144
	ds_read_b128 v[208:211], v187 offset:7168
	global_load_lds_dwordx4 v166, s[0:1]
	s_add_i32 m0, s27, 0xe000
	s_nop 0
	global_load_lds_dwordx4 v168, s[0:1]
	s_waitcnt lgkmcnt(8)
	ds_read_b128 v[212:215], v189
	ds_read_b128 v[216:219], v189 offset:1024
	ds_read_b128 v[220:223], v189 offset:2048
	ds_read_b128 v[224:227], v189 offset:3072
	s_waitcnt vmcnt(8) lgkmcnt(0)
	s_barrier
	v_mfma_f32_16x16x32_bf16 v[140:143], v[24:27], v[144:147], v[140:143]
	v_mfma_f32_16x16x32_bf16 v[136:139], v[40:43], v[144:147], v[136:139]
	v_mfma_f32_16x16x32_bf16 v[124:127], v[24:27], v[182:185], v[124:127]
	v_mfma_f32_16x16x32_bf16 v[120:123], v[40:43], v[182:185], v[120:123]
	v_mfma_f32_16x16x32_bf16 v[108:111], v[24:27], v[196:199], v[108:111]
	v_mfma_f32_16x16x32_bf16 v[104:107], v[40:43], v[196:199], v[104:107]
	v_mfma_f32_16x16x32_bf16 v[92:95], v[24:27], v[204:207], v[92:95]
	v_mfma_f32_16x16x32_bf16 v[88:91], v[40:43], v[204:207], v[88:91]
	v_mfma_f32_16x16x32_bf16 v[140:143], v[28:31], v[148:151], v[140:143]
	v_mfma_f32_16x16x32_bf16 v[136:139], v[44:47], v[148:151], v[136:139]
	v_mfma_f32_16x16x32_bf16 v[124:127], v[28:31], v[192:195], v[124:127]
	v_mfma_f32_16x16x32_bf16 v[120:123], v[44:47], v[192:195], v[120:123]
	v_mfma_f32_16x16x32_bf16 v[108:111], v[28:31], v[200:203], v[108:111]
	v_mfma_f32_16x16x32_bf16 v[104:107], v[44:47], v[200:203], v[104:107]
	v_mfma_f32_16x16x32_bf16 v[92:95], v[28:31], v[208:211], v[92:95]
	v_mfma_f32_16x16x32_bf16 v[88:91], v[44:47], v[208:211], v[88:91]
	v_mfma_f32_16x16x32_bf16 v[132:135], v[212:215], v[144:147], v[132:135]
	v_mfma_f32_16x16x32_bf16 v[128:131], v[220:223], v[144:147], v[128:131]
	v_mfma_f32_16x16x32_bf16 v[116:119], v[212:215], v[182:185], v[116:119]
	v_mfma_f32_16x16x32_bf16 v[112:115], v[220:223], v[182:185], v[112:115]
	v_mfma_f32_16x16x32_bf16 v[100:103], v[212:215], v[196:199], v[100:103]
	v_mfma_f32_16x16x32_bf16 v[96:99], v[220:223], v[196:199], v[96:99]
	v_mfma_f32_16x16x32_bf16 v[84:87], v[212:215], v[204:207], v[84:87]
	v_mfma_f32_16x16x32_bf16 v[80:83], v[220:223], v[204:207], v[80:83]
	v_mfma_f32_16x16x32_bf16 v[132:135], v[216:219], v[148:151], v[132:135]
	v_mfma_f32_16x16x32_bf16 v[128:131], v[224:227], v[148:151], v[128:131]
	v_mfma_f32_16x16x32_bf16 v[116:119], v[216:219], v[192:195], v[116:119]
	v_mfma_f32_16x16x32_bf16 v[112:115], v[224:227], v[192:195], v[112:115]
	v_mfma_f32_16x16x32_bf16 v[100:103], v[216:219], v[200:203], v[100:103]
	v_mfma_f32_16x16x32_bf16 v[96:99], v[224:227], v[200:203], v[96:99]
	v_mfma_f32_16x16x32_bf16 v[84:87], v[216:219], v[208:211], v[84:87]
	v_mfma_f32_16x16x32_bf16 v[80:83], v[224:227], v[208:211], v[80:83]
	s_barrier
; #define PG8_STAGE(bufoff, gbase, voff) do { _Pragma("unroll") for (int _i = 0; _i < 2; ++_i) \
;         __builtin_amdgcn_global_load_lds((const unsigned*)((const char*)(gbase) + (voff)[_i]), (PG8_LAS unsigned*)(lds + (bufoff) + ldsw + _i * 8192), 16, 0, 0); } while (0)
; #define PG8_LDA(dst, b, h) do { _Pragma("unroll") for (int m = 0; m < 4; ++m) _Pragma("unroll") for (int k = 0; k < 2; ++k) dst[m][k] = *(const PG8_LAS bf16x8*)(lds + PG8_SA(b, h) + aoff + m * 2048 + k * 1024); } while (0)
; #define PG8_LDB(dst, b, h) do { _Pragma("unroll") for (int n = 0; n < 2; ++n) _Pragma("unroll") for (int k = 0; k < 2; ++k) dst[n][k] = *(const PG8_LAS bf16x8*)(lds + PG8_SB(b, h) + boff + n * 2048 + k * 1024); } while (0)
; #define PG8_MMA(ai, bj, At, Bt) do { __builtin_amdgcn_s_setprio(1); _Pragma("unroll") for (int m = 0; m < 4; ++m) _Pragma("unroll") for (int n = 0; n < 2; ++n) _Pragma("unroll") for (int k = 0; k < 2; ++k) \
;         acc[ai][bj][m][n] = __builtin_amdgcn_mfma_f32_16x16x32_bf16(Bt[n][k], At[m][k], acc[ai][bj][m][n], 0, 0, 0); __builtin_amdgcn_s_setprio(0); } while (0)
; #define PG8_WAIT_V(n) asm volatile("s_waitcnt vmcnt(" #n ")" ::: "memory")
; #define PG8_WAIT_L(n) asm volatile("s_waitcnt lgkmcnt(" #n ")" ::: "memory")
; #define PG8_BAR __builtin_amdgcn_s_barrier()
; #define PG8_SCHED __builtin_amdgcn_sched_barrier(0)
; template <class Epi, class Sched>
; __device__ __forceinline__ void gemm_phase(PG8_LAS unsigned char* lds, const Gemm g, const Sched& S, const Epi& E) {
;     ...
;             PG8_LDB(B1, 0, 1); PG8_STAGE(PG8_SB(0, 0), b2, voffB);
;             PG8_BAR; PG8_WAIT_L(0); PG8_MMA(0, 1, At, B1); PG8_BAR;
;             PG8_LDA(At, 0, 1); PG8_STAGE(PG8_SA(0, 0), a2, voffA);
;             PG8_BAR; PG8_WAIT_L(0); PG8_MMA(1, 0, At, B0); PG8_BAR; PG8_SCHED;
;             PG8_STAGE(PG8_SB(0, 1), b2 + hstep, voffB);
;             PG8_WAIT_V(6); PG8_BAR; PG8_MMA(1, 1, At, B1); PG8_BAR;
;             PG8_LDB(B0, 1, 0); PG8_SCHED; PG8_LDA(At, 1, 0); PG8_STAGE(PG8_SA(0, 1), a2 + hstep, voffA);
;             PG8_WAIT_L(8); PG8_BAR; PG8_WAIT_L(0); PG8_MMA(0, 0, At, B0); PG8_BAR; PG8_SCHED;
;             PG8_LDB(B1, 1, 1); PG8_STAGE(PG8_SB(1, 0), b3, voffB);
;             PG8_BAR; PG8_WAIT_L(0); PG8_MMA(0, 1, At, B1); PG8_BAR;
	ds_read_b128 v[144:147], v187 offset:16384
	ds_read_b128 v[148:151], v187 offset:17408
	ds_read_b128 v[182:185], v187 offset:18432
	ds_read_b128 v[192:195], v187 offset:19456
	ds_read_b128 v[196:199], v187 offset:20480
	ds_read_b128 v[200:203], v187 offset:21504
	ds_read_b128 v[204:207], v187 offset:22528
	ds_read_b128 v[208:211], v187 offset:23552
	s_add_i32 s54, s43, s35
	s_add_u32 s98, s4, s14
	s_addc_u32 s99, s5, s15
	s_mov_b32 m0, s54
	s_nop 0
	global_load_lds_dwordx4 v156, s[4:5]
	s_add_i32 m0, s54, 0x2000
	s_nop 0
	global_load_lds_dwordx4 v160, s[4:5]
	s_mov_b32 m0, s27
	s_add_u32 s100, s28, s14
	s_addc_u32 s101, s29, s15
	global_load_lds_dwordx4 v154, s[28:29]
	s_mov_b32 m0, s36
	s_nop 0
	global_load_lds_dwordx4 v158, s[28:29]
	s_add_u32 s54, s4, 0x40000
	s_addc_u32 s55, s5, 0
	s_add_i32 s56, s44, s35
	s_mov_b32 m0, s56
	s_nop 0
	global_load_lds_dwordx4 v156, s[54:55]
	s_add_i32 m0, s56, 0x2000
	s_nop 0
	global_load_lds_dwordx4 v160, s[54:55]
	s_waitcnt vmcnt(8) lgkmcnt(0)
	s_barrier
	v_mfma_f32_16x16x32_bf16 v[76:79], v[24:27], v[144:147], v[76:79]
	v_mfma_f32_16x16x32_bf16 v[72:75], v[40:43], v[144:147], v[72:75]
	v_mfma_f32_16x16x32_bf16 v[60:63], v[24:27], v[182:185], v[60:63]
	v_mfma_f32_16x16x32_bf16 v[56:59], v[40:43], v[182:185], v[56:59]
	v_mfma_f32_16x16x32_bf16 v[36:39], v[24:27], v[196:199], v[36:39]
	v_mfma_f32_16x16x32_bf16 v[32:35], v[40:43], v[196:199], v[32:35]
	v_mfma_f32_16x16x32_bf16 v[12:15], v[24:27], v[204:207], v[12:15]
	v_mfma_f32_16x16x32_bf16 v[8:11], v[40:43], v[204:207], v[8:11]
	v_mfma_f32_16x16x32_bf16 v[76:79], v[28:31], v[148:151], v[76:79]
	v_mfma_f32_16x16x32_bf16 v[72:75], v[44:47], v[148:151], v[72:75]
	v_mfma_f32_16x16x32_bf16 v[60:63], v[28:31], v[192:195], v[60:63]
	v_mfma_f32_16x16x32_bf16 v[56:59], v[44:47], v[192:195], v[56:59]
	v_mfma_f32_16x16x32_bf16 v[36:39], v[28:31], v[200:203], v[36:39]
	v_mfma_f32_16x16x32_bf16 v[32:35], v[44:47], v[200:203], v[32:35]
	v_mfma_f32_16x16x32_bf16 v[12:15], v[28:31], v[208:211], v[12:15]
	v_mfma_f32_16x16x32_bf16 v[8:11], v[44:47], v[208:211], v[8:11]
	v_mfma_f32_16x16x32_bf16 v[20:23], v[212:215], v[196:199], v[20:23]
	v_mfma_f32_16x16x32_bf16 v[16:19], v[220:223], v[196:199], v[16:19]
	v_mfma_f32_16x16x32_bf16 v[4:7], v[212:215], v[204:207], v[4:7]
	v_mfma_f32_16x16x32_bf16 v[0:3], v[220:223], v[204:207], v[0:3]
	v_mfma_f32_16x16x32_bf16 v[24:27], v[212:215], v[144:147], v[68:71]
	v_mfma_f32_16x16x32_bf16 v[28:31], v[220:223], v[144:147], v[64:67]
	v_mfma_f32_16x16x32_bf16 v[40:43], v[212:215], v[182:185], v[52:55]
	v_mfma_f32_16x16x32_bf16 v[44:47], v[220:223], v[182:185], v[48:51]
	v_mfma_f32_16x16x32_bf16 v[20:23], v[216:219], v[200:203], v[20:23]
	v_mfma_f32_16x16x32_bf16 v[16:19], v[224:227], v[200:203], v[16:19]
	v_mfma_f32_16x16x32_bf16 v[4:7], v[216:219], v[208:211], v[4:7]
	v_mfma_f32_16x16x32_bf16 v[0:3], v[224:227], v[208:211], v[0:3]
	v_mfma_f32_16x16x32_bf16 v[24:27], v[216:219], v[148:151], v[24:27]
	v_mfma_f32_16x16x32_bf16 v[28:31], v[224:227], v[148:151], v[28:31]
	v_mfma_f32_16x16x32_bf16 v[40:43], v[216:219], v[192:195], v[40:43]
	v_mfma_f32_16x16x32_bf16 v[44:47], v[224:227], v[192:195], v[44:47]
	s_barrier
	s_add_i32 s54, 0, 0x18000
	v_add_u32_e32 v68, s54, v179
	ds_read_b128 v[48:51], v68
	ds_read_b128 v[52:55], v68 offset:1024
	ds_read_b128 v[64:67], v68 offset:2048
	ds_read_b128 v[68:71], v68 offset:3072
	s_add_u32 s28, s28, 0x40000
	s_addc_u32 s29, s29, 0
	s_mov_b32 m0, s37
	ds_read_b128 v[144:147], v187 offset:32768
	ds_read_b128 v[148:151], v187 offset:33792
	ds_read_b128 v[182:185], v187 offset:34816
	ds_read_b128 v[192:195], v187 offset:35840
	ds_read_b128 v[196:199], v187 offset:36864
	ds_read_b128 v[200:203], v187 offset:37888
	ds_read_b128 v[204:207], v187 offset:38912
	ds_read_b128 v[208:211], v187 offset:39936
	global_load_lds_dwordx4 v154, s[28:29]
	s_mov_b32 m0, s38
	s_nop 0
	global_load_lds_dwordx4 v158, s[28:29]
	s_add_i32 s28, 0, 0x1c000
	v_add_u32_e32 v162, s28, v179
	s_waitcnt lgkmcnt(8)
	ds_read_b128 v[212:215], v162
	ds_read_b128 v[216:219], v162 offset:1024
	ds_read_b128 v[220:223], v162 offset:2048
	ds_read_b128 v[224:227], v162 offset:3072
	s_waitcnt vmcnt(8) lgkmcnt(0)
	s_barrier
; #define PG8_STAGE(bufoff, gbase, voff) do { _Pragma("unroll") for (int _i = 0; _i < 2; ++_i) \
;         __builtin_amdgcn_global_load_lds((const unsigned*)((const char*)(gbase) + (voff)[_i]), (PG8_LAS unsigned*)(lds + (bufoff) + ldsw + _i * 8192), 16, 0, 0); } while (0)
; #define PG8_LDA(dst, b, h) do { _Pragma("unroll") for (int m = 0; m < 4; ++m) _Pragma("unroll") for (int k = 0; k < 2; ++k) dst[m][k] = *(const PG8_LAS bf16x8*)(lds + PG8_SA(b, h) + aoff + m * 2048 + k * 1024); } while (0)
; #define PG8_MMA(ai, bj, At, Bt) do { __builtin_amdgcn_s_setprio(1); _Pragma("unroll") for (int m = 0; m < 4; ++m) _Pragma("unroll") for (int n = 0; n < 2; ++n) _Pragma("unroll") for (int k = 0; k < 2; ++k) \
;         acc[ai][bj][m][n] = __builtin_amdgcn_mfma_f32_16x16x32_bf16(Bt[n][k], At[m][k], acc[ai][bj][m][n], 0, 0, 0); __builtin_amdgcn_s_setprio(0); } while (0)
; #define PG8_WAIT_V(n) asm volatile("s_waitcnt vmcnt(" #n ")" ::: "memory")
; #define PG8_WAIT_L(n) asm volatile("s_waitcnt lgkmcnt(" #n ")" ::: "memory")
; #define PG8_BAR __builtin_amdgcn_s_barrier()
; #define PG8_SCHED __builtin_amdgcn_sched_barrier(0)
;     __device__ __forceinline__ void operator()(const f32x4 (&acc)[2][2][4][2], const Unit& u, int wr, int wc, int fr, int fq) const {
;         int act = 0; const float* bias = nullptr;
;         if (mode == 1) { if (u.pn >= 8 && u.pn < 12) act = 1; else if (u.pn >= 12) { act = 3; bias = (u.pn >= 14) ? bias_b + (u.pn - 14) * 256 : bias_f + (u.pn - 12) * 256; } }
;         else if (mode == 2) { if (u.pn >= 6) act = 2; }
;         const int row0 = u.pm * BM + wr * 64 + fr, col0 = u.pn * BM + wc * 32 + 8 * fq, bcol0 = wc * 32 + 8 * fq;
;         f32x4 bv[2][2];
; #pragma unroll
;         for (int bj = 0; bj < 2; ++bj)
; #pragma unroll
;             for (int n = 0; n < 2; ++n) bv[bj][n] = bias ? *(const f32x4*)(bias + bcol0 + bj * HALF + 4 * n) : (f32x4){0.f, 0.f, 0.f, 0.f};
; template <class Epi, class Sched>
; __device__ __forceinline__ void gemm_phase(PG8_LAS unsigned char* lds, const Gemm g, const Sched& S, const Epi& E) {
;     ...
;             PG8_LDA(At, 1, 1); PG8_STAGE(PG8_SA(1, 0), a3, voffA);
;             PG8_BAR; PG8_WAIT_L(0); PG8_MMA(1, 0, At, B0); PG8_BAR; PG8_SCHED;
;             PG8_STAGE(PG8_SB(1, 1), b3 + hstep, voffB);
;             PG8_WAIT_V(6); PG8_BAR; PG8_MMA(1, 1, At, B1); PG8_BAR;
	v_mfma_f32_16x16x32_bf16 v[140:143], v[48:51], v[144:147], v[140:143]
	v_mfma_f32_16x16x32_bf16 v[136:139], v[64:67], v[144:147], v[136:139]
	v_mfma_f32_16x16x32_bf16 v[124:127], v[48:51], v[182:185], v[124:127]
	v_mfma_f32_16x16x32_bf16 v[120:123], v[64:67], v[182:185], v[120:123]
	v_mfma_f32_16x16x32_bf16 v[108:111], v[48:51], v[196:199], v[108:111]
	v_mfma_f32_16x16x32_bf16 v[104:107], v[64:67], v[196:199], v[104:107]
	v_mfma_f32_16x16x32_bf16 v[92:95], v[48:51], v[204:207], v[92:95]
	v_mfma_f32_16x16x32_bf16 v[88:91], v[64:67], v[204:207], v[88:91]
	v_mfma_f32_16x16x32_bf16 v[140:143], v[52:55], v[148:151], v[140:143]
	v_mfma_f32_16x16x32_bf16 v[136:139], v[68:71], v[148:151], v[136:139]
	v_mfma_f32_16x16x32_bf16 v[124:127], v[52:55], v[192:195], v[124:127]
	v_mfma_f32_16x16x32_bf16 v[120:123], v[68:71], v[192:195], v[120:123]
	v_mfma_f32_16x16x32_bf16 v[108:111], v[52:55], v[200:203], v[108:111]
	v_mfma_f32_16x16x32_bf16 v[104:107], v[68:71], v[200:203], v[104:107]
	v_mfma_f32_16x16x32_bf16 v[92:95], v[52:55], v[208:211], v[92:95]
	v_mfma_f32_16x16x32_bf16 v[88:91], v[68:71], v[208:211], v[88:91]
	v_mfma_f32_16x16x32_bf16 v[132:135], v[212:215], v[144:147], v[132:135]
	v_mfma_f32_16x16x32_bf16 v[128:131], v[220:223], v[144:147], v[128:131]
	v_mfma_f32_16x16x32_bf16 v[116:119], v[212:215], v[182:185], v[116:119]
	v_mfma_f32_16x16x32_bf16 v[112:115], v[220:223], v[182:185], v[112:115]
	v_mfma_f32_16x16x32_bf16 v[100:103], v[212:215], v[196:199], v[100:103]
	v_mfma_f32_16x16x32_bf16 v[96:99], v[220:223], v[196:199], v[96:99]
	v_mfma_f32_16x16x32_bf16 v[84:87], v[212:215], v[204:207], v[84:87]
	v_mfma_f32_16x16x32_bf16 v[80:83], v[220:223], v[204:207], v[80:83]
	v_mfma_f32_16x16x32_bf16 v[132:135], v[216:219], v[148:151], v[132:135]
	v_mfma_f32_16x16x32_bf16 v[128:131], v[224:227], v[148:151], v[128:131]
	v_mfma_f32_16x16x32_bf16 v[116:119], v[216:219], v[192:195], v[116:119]
	v_mfma_f32_16x16x32_bf16 v[112:115], v[224:227], v[192:195], v[112:115]
	v_mfma_f32_16x16x32_bf16 v[100:103], v[216:219], v[200:203], v[100:103]
	v_mfma_f32_16x16x32_bf16 v[96:99], v[224:227], v[200:203], v[96:99]
	v_mfma_f32_16x16x32_bf16 v[84:87], v[216:219], v[208:211], v[84:87]
	v_mfma_f32_16x16x32_bf16 v[80:83], v[224:227], v[208:211], v[80:83]
	s_barrier
	ds_read_b128 v[144:147], v187 offset:49152
	ds_read_b128 v[148:151], v187 offset:50176
	ds_read_b128 v[182:185], v187 offset:51200
	ds_read_b128 v[192:195], v187 offset:52224
	ds_read_b128 v[196:199], v187 offset:53248
	ds_read_b128 v[200:203], v187 offset:54272
	ds_read_b128 v[204:207], v187 offset:55296
	ds_read_b128 v[208:211], v187 offset:56320
	s_add_i32 s29, s54, s35
	s_mov_b32 m0, s29
	s_nop 0
	global_load_lds_dwordx4 v156, s[98:99]
	s_add_i32 m0, s29, 0x2000
	s_nop 0
	global_load_lds_dwordx4 v160, s[98:99]
	s_mov_b32 m0, s39
	s_nop 0
	global_load_lds_dwordx4 v154, s[100:101]
	s_mov_b32 m0, s40
	s_nop 0
	global_load_lds_dwordx4 v158, s[100:101]
	s_add_u32 s4, s4, 0x40080
	s_addc_u32 s5, s5, 0
	s_add_i32 s28, s28, s35
	s_mov_b32 m0, s28
	s_nop 0
	global_load_lds_dwordx4 v156, s[4:5]
	s_add_i32 m0, s28, 0x2000
	s_nop 0
	global_load_lds_dwordx4 v160, s[4:5]
	s_waitcnt vmcnt(8) lgkmcnt(0)
	s_barrier
	v_mfma_f32_16x16x32_bf16 v[76:79], v[48:51], v[144:147], v[76:79]
	v_mfma_f32_16x16x32_bf16 v[72:75], v[64:67], v[144:147], v[72:75]
	v_mfma_f32_16x16x32_bf16 v[60:63], v[48:51], v[182:185], v[60:63]
	v_mfma_f32_16x16x32_bf16 v[56:59], v[64:67], v[182:185], v[56:59]
	v_mfma_f32_16x16x32_bf16 v[36:39], v[48:51], v[196:199], v[36:39]
	v_mfma_f32_16x16x32_bf16 v[32:35], v[64:67], v[196:199], v[32:35]
	v_mfma_f32_16x16x32_bf16 v[12:15], v[48:51], v[204:207], v[12:15]
	v_mfma_f32_16x16x32_bf16 v[8:11], v[64:67], v[204:207], v[8:11]
	v_mfma_f32_16x16x32_bf16 v[76:79], v[52:55], v[148:151], v[76:79]
	v_mfma_f32_16x16x32_bf16 v[72:75], v[68:71], v[148:151], v[72:75]
	v_mfma_f32_16x16x32_bf16 v[60:63], v[52:55], v[192:195], v[60:63]
	v_mfma_f32_16x16x32_bf16 v[56:59], v[68:71], v[192:195], v[56:59]
	v_mfma_f32_16x16x32_bf16 v[36:39], v[52:55], v[200:203], v[36:39]
	v_mfma_f32_16x16x32_bf16 v[32:35], v[68:71], v[200:203], v[32:35]
	v_mfma_f32_16x16x32_bf16 v[12:15], v[52:55], v[208:211], v[12:15]
	v_mfma_f32_16x16x32_bf16 v[8:11], v[68:71], v[208:211], v[8:11]
	v_mfma_f32_16x16x32_bf16 v[24:27], v[212:215], v[144:147], v[24:27]
	v_mfma_f32_16x16x32_bf16 v[68:71], v[216:219], v[148:151], v[24:27]
	v_mfma_f32_16x16x32_bf16 v[24:27], v[220:223], v[144:147], v[28:31]
	v_mfma_f32_16x16x32_bf16 v[64:67], v[224:227], v[148:151], v[24:27]
	v_mfma_f32_16x16x32_bf16 v[24:27], v[212:215], v[182:185], v[40:43]
	v_mfma_f32_16x16x32_bf16 v[52:55], v[216:219], v[192:195], v[24:27]
	v_mfma_f32_16x16x32_bf16 v[24:27], v[220:223], v[182:185], v[44:47]
	v_mfma_f32_16x16x32_bf16 v[20:23], v[212:215], v[196:199], v[20:23]
	v_mfma_f32_16x16x32_bf16 v[16:19], v[220:223], v[196:199], v[16:19]
	v_mfma_f32_16x16x32_bf16 v[4:7], v[212:215], v[204:207], v[4:7]
	v_mfma_f32_16x16x32_bf16 v[0:3], v[220:223], v[204:207], v[0:3]
	v_mfma_f32_16x16x32_bf16 v[48:51], v[224:227], v[192:195], v[24:27]
	v_mfma_f32_16x16x32_bf16 v[20:23], v[216:219], v[200:203], v[20:23]
	v_mfma_f32_16x16x32_bf16 v[16:19], v[224:227], v[200:203], v[16:19]
	v_mfma_f32_16x16x32_bf16 v[4:7], v[216:219], v[208:211], v[4:7]
	v_mfma_f32_16x16x32_bf16 v[0:3], v[224:227], v[208:211], v[0:3]
	s_barrier
	s_add_i32 s53, s53, 2
	s_add_u32 s0, s0, 0x100
	s_addc_u32 s1, s1, 0
	s_add_u32 s51, s51, 0x100
	s_addc_u32 s52, s52, 0
	s_cmp_gt_u32 s53, 13
	s_cbranch_scc0 .LBB0_416
	s_cmp_gt_i32 s26, 11
	s_cselect_b64 s[4:5], -1, 0
	s_cmp_lt_i32 s26, 12
	s_mov_b64 s[0:1], 0
	s_cbranch_scc1 .LBB0_422
	s_lshl_b32 s10, s26, 8
	s_cmp_lt_u32 s26, 14
	s_mov_b64 s[28:29], -1
	s_cbranch_scc0 .LBB0_420
	s_lshl_b64 s[0:1], s[10:11], 2
	v_readlane_b32 s52, v245, 0
	v_readlane_b32 s53, v245, 1
	s_add_u32 s0, s52, s0
	s_addc_u32 s1, s53, s1
	s_add_u32 s0, s0, 0xffffd000
	v_readlane_b32 s54, v245, 2
	v_readlane_b32 s55, v245, 3
	v_readlane_b32 s56, v245, 4
	v_readlane_b32 s57, v245, 5
	v_readlane_b32 s58, v245, 6
	v_readlane_b32 s59, v245, 7
	v_readlane_b32 s60, v245, 8
	v_readlane_b32 s61, v245, 9
	v_readlane_b32 s62, v245, 10
	v_readlane_b32 s63, v245, 11
	v_readlane_b32 s64, v245, 12
	v_readlane_b32 s65, v245, 13
	v_readlane_b32 s66, v245, 14
	v_readlane_b32 s67, v245, 15
	s_addc_u32 s1, s1, -1
	s_mov_b64 s[28:29], 0

; #define PG8_STAGE(bufoff, gbase, voff) do { _Pragma("unroll") for (int _i = 0; _i < 2; ++_i) \
;         __builtin_amdgcn_global_load_lds((const unsigned*)((const char*)(gbase) + (voff)[_i]), (PG8_LAS unsigned*)(lds + (bufoff) + ldsw + _i * 8192), 16, 0, 0); } while (0)
; #define PG8_LDA(dst, b, h) do { _Pragma("unroll") for (int m = 0; m < 4; ++m) _Pragma("unroll") for (int k = 0; k < 2; ++k) dst[m][k] = *(const PG8_LAS bf16x8*)(lds + PG8_SA(b, h) + aoff + m * 2048 + k * 1024); } while (0)
; #define PG8_LDB(dst, b, h) do { _Pragma("unroll") for (int n = 0; n < 2; ++n) _Pragma("unroll") for (int k = 0; k < 2; ++k) dst[n][k] = *(const PG8_LAS bf16x8*)(lds + PG8_SB(b, h) + boff + n * 2048 + k * 1024); } while (0)
; #define PG8_MMA(ai, bj, At, Bt) do { __builtin_amdgcn_s_setprio(1); _Pragma("unroll") for (int m = 0; m < 4; ++m) _Pragma("unroll") for (int n = 0; n < 2; ++n) _Pragma("unroll") for (int k = 0; k < 2; ++k) \
;         acc[ai][bj][m][n] = __builtin_amdgcn_mfma_f32_16x16x32_bf16(Bt[n][k], At[m][k], acc[ai][bj][m][n], 0, 0, 0); __builtin_amdgcn_s_setprio(0); } while (0)
; template <class Epi, class Sched>
; __device__ __forceinline__ void gemm_phase(PG8_LAS unsigned char* lds, const Gemm g, const Sched& S, const Epi& E) {
;     ...
;         const bool has_next = S.next(ui + 1, nxt);
;         const char* nA = has_next ? (const char*)g.A + (size_t)nxt.pm * tstep : cA; const char* nB = has_next ? (const char*)g.Bt + (size_t)nxt.pn * tstep : cB;
;         for (int t = 0; t < nt; t += 2) {
;             const bool last = (t == nt - 2);
;             const char* a1 = cA + (size_t)(t + 1) * kstep;
;             const char* a2 = last ? nA : cA + (size_t)(t + 2) * kstep; const char* b2 = last ? nB : cB + (size_t)(t + 2) * kstep;
;             const char* a3 = a2 + kstep; const char* b3 = b2 + kstep;
;             if (last && has_next) S.a_ready(nxt);
;             PG8_LDB(B0, 0, 0); PG8_SCHED; PG8_LDA(At, 0, 0); PG8_STAGE(PG8_SA(1, 1), a1 + hstep, voffA);
;             PG8_WAIT_L(8); PG8_BAR; PG8_WAIT_L(0); PG8_MMA(0, 0, At, B0); PG8_BAR; PG8_SCHED;
;             PG8_LDB(B1, 0, 1); PG8_STAGE(PG8_SB(0, 0), b2, voffB);
;             PG8_BAR; PG8_WAIT_L(0); PG8_MMA(0, 1, At, B1); PG8_BAR;
;             PG8_LDA(At, 0, 1); PG8_STAGE(PG8_SA(0, 0), a2, voffA);
;             PG8_BAR; PG8_WAIT_L(0); PG8_MMA(1, 0, At, B0); PG8_BAR; PG8_SCHED;
.LBB0_723:
	s_ashr_i32 s11, s10, 31
	v_cmp_lt_i64_e32 vcc, s[12:13], v[140:141]
	s_lshl_b64 s[12:13], s[10:11], 19
	s_add_u32 s12, s26, s12
	s_addc_u32 s13, s27, s13
	s_and_b64 s[14:15], vcc, exec
	s_cselect_b32 s5, s13, s19
	s_cselect_b32 s11, s12, s18
	s_ashr_i32 s9, s8, 31
	s_lshl_b64 s[14:15], s[8:9], 19
	s_add_u32 s14, s28, s14
	s_addc_u32 s15, s29, s15
	s_and_b64 s[22:23], vcc, exec
	s_cselect_b32 s9, s15, s21
	s_cselect_b32 s45, s14, s20
	s_add_u32 s18, s18, 0x40080
	s_addc_u32 s19, s19, 0
	s_add_u32 s46, s20, 0x100
	s_addc_u32 s47, s21, 0
	s_mov_b32 s48, -2
	ds_read_b128 v[144:147], v151
	ds_read_b128 v[156:159], v151 offset:1024
	ds_read_b128 v[160:163], v151 offset:2048
	ds_read_b128 v[166:169], v151 offset:3072
	s_add_u32 s20, s18, 0xfffc0080
	s_addc_u32 s21, s19, -1
	s_cmp_eq_u32 s48, 12
	s_cselect_b32 s23, s5, s21
	s_cselect_b32 s22, s11, s20
	s_cselect_b32 s21, s9, s47
	s_cselect_b32 s20, s45, s46
	s_add_i32 m0, s17, 0xc000
	ds_read_b128 v[170:173], v153
	ds_read_b128 v[182:185], v153 offset:1024
	ds_read_b128 v[190:193], v153 offset:2048
	ds_read_b128 v[194:197], v153 offset:3072
	ds_read_b128 v[198:201], v153 offset:4096
	ds_read_b128 v[202:205], v153 offset:5120
	ds_read_b128 v[206:209], v153 offset:6144
	ds_read_b128 v[210:213], v153 offset:7168
	global_load_lds_dwordx4 v136, s[18:19]
	s_add_i32 m0, s17, 0xe000
	s_nop 0
	global_load_lds_dwordx4 v138, s[18:19]
	s_waitcnt lgkmcnt(8)
	ds_read_b128 v[214:217], v154
	ds_read_b128 v[218:221], v154 offset:1024
	ds_read_b128 v[222:225], v154 offset:2048
	ds_read_b128 v[226:229], v154 offset:3072
	s_waitcnt vmcnt(8) lgkmcnt(0)
	s_barrier
	v_mfma_f32_16x16x32_bf16 v[124:127], v[144:147], v[170:173], 0
	v_mfma_f32_16x16x32_bf16 v[120:123], v[160:163], v[170:173], 0
	v_mfma_f32_16x16x32_bf16 v[108:111], v[144:147], v[190:193], 0
	v_mfma_f32_16x16x32_bf16 v[104:107], v[160:163], v[190:193], 0
	v_mfma_f32_16x16x32_bf16 v[92:95], v[144:147], v[198:201], 0
	v_mfma_f32_16x16x32_bf16 v[88:91], v[160:163], v[198:201], 0
	v_mfma_f32_16x16x32_bf16 v[76:79], v[144:147], v[206:209], 0
	v_mfma_f32_16x16x32_bf16 v[72:75], v[160:163], v[206:209], 0
	v_mfma_f32_16x16x32_bf16 v[124:127], v[156:159], v[182:185], v[124:127]
	v_mfma_f32_16x16x32_bf16 v[120:123], v[166:169], v[182:185], v[120:123]
	v_mfma_f32_16x16x32_bf16 v[108:111], v[156:159], v[194:197], v[108:111]
	v_mfma_f32_16x16x32_bf16 v[104:107], v[166:169], v[194:197], v[104:107]
	v_mfma_f32_16x16x32_bf16 v[92:95], v[156:159], v[202:205], v[92:95]
	v_mfma_f32_16x16x32_bf16 v[88:91], v[166:169], v[202:205], v[88:91]
	v_mfma_f32_16x16x32_bf16 v[76:79], v[156:159], v[210:213], v[76:79]
	v_mfma_f32_16x16x32_bf16 v[72:75], v[166:169], v[210:213], v[72:75]
	v_mfma_f32_16x16x32_bf16 v[116:119], v[214:217], v[170:173], 0
	v_mfma_f32_16x16x32_bf16 v[112:115], v[222:225], v[170:173], 0
	v_mfma_f32_16x16x32_bf16 v[100:103], v[214:217], v[190:193], 0
	v_mfma_f32_16x16x32_bf16 v[96:99], v[222:225], v[190:193], 0
	v_mfma_f32_16x16x32_bf16 v[84:87], v[214:217], v[198:201], 0
	v_mfma_f32_16x16x32_bf16 v[80:83], v[222:225], v[198:201], 0
	v_mfma_f32_16x16x32_bf16 v[68:71], v[214:217], v[206:209], 0
	v_mfma_f32_16x16x32_bf16 v[64:67], v[222:225], v[206:209], 0
	v_mfma_f32_16x16x32_bf16 v[116:119], v[218:221], v[182:185], v[116:119]
	v_mfma_f32_16x16x32_bf16 v[112:115], v[226:229], v[182:185], v[112:115]
	v_mfma_f32_16x16x32_bf16 v[100:103], v[218:221], v[194:197], v[100:103]
	v_mfma_f32_16x16x32_bf16 v[96:99], v[226:229], v[194:197], v[96:99]
	v_mfma_f32_16x16x32_bf16 v[84:87], v[218:221], v[202:205], v[84:87]
	v_mfma_f32_16x16x32_bf16 v[80:83], v[226:229], v[202:205], v[80:83]
	v_mfma_f32_16x16x32_bf16 v[68:71], v[218:221], v[210:213], v[68:71]
	v_mfma_f32_16x16x32_bf16 v[64:67], v[226:229], v[210:213], v[64:67]
	s_barrier
	ds_read_b128 v[170:173], v153 offset:16384
	ds_read_b128 v[182:185], v153 offset:17408
	ds_read_b128 v[190:193], v153 offset:18432
	ds_read_b128 v[194:197], v153 offset:19456
	ds_read_b128 v[198:201], v153 offset:20480
	ds_read_b128 v[202:205], v153 offset:21504
	ds_read_b128 v[206:209], v153 offset:22528
	ds_read_b128 v[210:213], v153 offset:23552
	s_add_i32 s49, s42, s30
	s_add_u32 s98, s20, s6
	s_addc_u32 s99, s21, s7
	s_mov_b32 m0, s49
	s_nop 0
	global_load_lds_dwordx4 v130, s[20:21]
	s_add_i32 m0, s49, 0x2000
	s_nop 0
	global_load_lds_dwordx4 v134, s[20:21]
	s_mov_b32 m0, s17
	s_add_u32 s100, s22, s6
	s_addc_u32 s101, s23, s7
	global_load_lds_dwordx4 v128, s[22:23]
	s_mov_b32 m0, s31
	s_nop 0
	global_load_lds_dwordx4 v132, s[22:23]
	s_add_u32 s50, s20, 0x40000
	s_addc_u32 s51, s21, 0
	s_add_i32 s49, s43, s30
	s_mov_b32 m0, s49
	s_nop 0
	global_load_lds_dwordx4 v130, s[50:51]
	s_add_i32 m0, s49, 0x2000
	s_nop 0
	global_load_lds_dwordx4 v134, s[50:51]
	s_waitcnt vmcnt(8) lgkmcnt(0)
	s_barrier
; #define PG8_STAGE(bufoff, gbase, voff) do { _Pragma("unroll") for (int _i = 0; _i < 2; ++_i) \
;         __builtin_amdgcn_global_load_lds((const unsigned*)((const char*)(gbase) + (voff)[_i]), (PG8_LAS unsigned*)(lds + (bufoff) + ldsw + _i * 8192), 16, 0, 0); } while (0)
; #define PG8_LDA(dst, b, h) do { _Pragma("unroll") for (int m = 0; m < 4; ++m) _Pragma("unroll") for (int k = 0; k < 2; ++k) dst[m][k] = *(const PG8_LAS bf16x8*)(lds + PG8_SA(b, h) + aoff + m * 2048 + k * 1024); } while (0)
; #define PG8_LDB(dst, b, h) do { _Pragma("unroll") for (int n = 0; n < 2; ++n) _Pragma("unroll") for (int k = 0; k < 2; ++k) dst[n][k] = *(const PG8_LAS bf16x8*)(lds + PG8_SB(b, h) + boff + n * 2048 + k * 1024); } while (0)
; #define PG8_MMA(ai, bj, At, Bt) do { __builtin_amdgcn_s_setprio(1); _Pragma("unroll") for (int m = 0; m < 4; ++m) _Pragma("unroll") for (int n = 0; n < 2; ++n) _Pragma("unroll") for (int k = 0; k < 2; ++k) \
;         acc[ai][bj][m][n] = __builtin_amdgcn_mfma_f32_16x16x32_bf16(Bt[n][k], At[m][k], acc[ai][bj][m][n], 0, 0, 0); __builtin_amdgcn_s_setprio(0); } while (0)
; #define PG8_WAIT_V(n) asm volatile("s_waitcnt vmcnt(" #n ")" ::: "memory")
; #define PG8_WAIT_L(n) asm volatile("s_waitcnt lgkmcnt(" #n ")" ::: "memory")
; #define PG8_BAR __builtin_amdgcn_s_barrier()
; #define PG8_SCHED __builtin_amdgcn_sched_barrier(0)
; template <class Epi, class Sched>
; __device__ __forceinline__ void gemm_phase(PG8_LAS unsigned char* lds, const Gemm g, const Sched& S, const Epi& E) {
;     ...
;             PG8_BAR; PG8_WAIT_L(0); PG8_MMA(1, 0, At, B0); PG8_BAR; PG8_SCHED;
;             PG8_STAGE(PG8_SB(0, 1), b2 + hstep, voffB);
;             PG8_WAIT_V(6); PG8_BAR; PG8_MMA(1, 1, At, B1); PG8_BAR;
;             PG8_LDB(B0, 1, 0); PG8_SCHED; PG8_LDA(At, 1, 0); PG8_STAGE(PG8_SA(0, 1), a2 + hstep, voffA);
;             PG8_WAIT_L(8); PG8_BAR; PG8_WAIT_L(0); PG8_MMA(0, 0, At, B0); PG8_BAR; PG8_SCHED;
;             PG8_LDB(B1, 1, 1); PG8_STAGE(PG8_SB(1, 0), b3, voffB);
;             PG8_BAR; PG8_WAIT_L(0); PG8_MMA(0, 1, At, B1); PG8_BAR;
	v_mfma_f32_16x16x32_bf16 v[60:63], v[144:147], v[170:173], 0
	v_mfma_f32_16x16x32_bf16 v[56:59], v[160:163], v[170:173], 0
	v_mfma_f32_16x16x32_bf16 v[44:47], v[144:147], v[190:193], 0
	v_mfma_f32_16x16x32_bf16 v[40:43], v[160:163], v[190:193], 0
	v_mfma_f32_16x16x32_bf16 v[28:31], v[144:147], v[198:201], 0
	v_mfma_f32_16x16x32_bf16 v[24:27], v[160:163], v[198:201], 0
	v_mfma_f32_16x16x32_bf16 v[12:15], v[144:147], v[206:209], 0
	v_mfma_f32_16x16x32_bf16 v[8:11], v[160:163], v[206:209], 0
	v_mfma_f32_16x16x32_bf16 v[60:63], v[156:159], v[182:185], v[60:63]
	v_mfma_f32_16x16x32_bf16 v[56:59], v[166:169], v[182:185], v[56:59]
	v_mfma_f32_16x16x32_bf16 v[44:47], v[156:159], v[194:197], v[44:47]
	v_mfma_f32_16x16x32_bf16 v[40:43], v[166:169], v[194:197], v[40:43]
	v_mfma_f32_16x16x32_bf16 v[28:31], v[156:159], v[202:205], v[28:31]
	v_mfma_f32_16x16x32_bf16 v[24:27], v[166:169], v[202:205], v[24:27]
	v_mfma_f32_16x16x32_bf16 v[12:15], v[156:159], v[210:213], v[12:15]
	v_mfma_f32_16x16x32_bf16 v[8:11], v[166:169], v[210:213], v[8:11]
	v_mfma_f32_16x16x32_bf16 v[52:55], v[214:217], v[170:173], 0
	v_mfma_f32_16x16x32_bf16 v[48:51], v[222:225], v[170:173], 0
	v_mfma_f32_16x16x32_bf16 v[36:39], v[214:217], v[190:193], 0
	v_mfma_f32_16x16x32_bf16 v[32:35], v[222:225], v[190:193], 0
	v_mfma_f32_16x16x32_bf16 v[20:23], v[214:217], v[198:201], 0
	v_mfma_f32_16x16x32_bf16 v[16:19], v[222:225], v[198:201], 0
	v_mfma_f32_16x16x32_bf16 v[4:7], v[214:217], v[206:209], 0
	v_mfma_f32_16x16x32_bf16 v[0:3], v[222:225], v[206:209], 0
	v_mfma_f32_16x16x32_bf16 v[52:55], v[218:221], v[182:185], v[52:55]
	v_mfma_f32_16x16x32_bf16 v[48:51], v[226:229], v[182:185], v[48:51]
	v_mfma_f32_16x16x32_bf16 v[36:39], v[218:221], v[194:197], v[36:39]
	v_mfma_f32_16x16x32_bf16 v[32:35], v[226:229], v[194:197], v[32:35]
	v_mfma_f32_16x16x32_bf16 v[20:23], v[218:221], v[202:205], v[20:23]
	v_mfma_f32_16x16x32_bf16 v[16:19], v[226:229], v[202:205], v[16:19]
	v_mfma_f32_16x16x32_bf16 v[4:7], v[218:221], v[210:213], v[4:7]
	v_mfma_f32_16x16x32_bf16 v[0:3], v[226:229], v[210:213], v[0:3]
	s_barrier
	s_add_i32 s49, 0, 0x18000
	v_add_u32_e32 v155, s49, v149
	ds_read_b128 v[144:147], v155
	ds_read_b128 v[156:159], v155 offset:1024
	ds_read_b128 v[160:163], v155 offset:2048
	ds_read_b128 v[166:169], v155 offset:3072
	s_add_u32 s22, s22, 0x40000
	s_addc_u32 s23, s23, 0
	s_mov_b32 m0, s34
	ds_read_b128 v[170:173], v153 offset:32768
	ds_read_b128 v[182:185], v153 offset:33792
	ds_read_b128 v[190:193], v153 offset:34816
	ds_read_b128 v[194:197], v153 offset:35840
	ds_read_b128 v[198:201], v153 offset:36864
	ds_read_b128 v[202:205], v153 offset:37888
	ds_read_b128 v[206:209], v153 offset:38912
	ds_read_b128 v[210:213], v153 offset:39936
	global_load_lds_dwordx4 v128, s[22:23]
	s_mov_b32 m0, s35
	s_nop 0
	global_load_lds_dwordx4 v132, s[22:23]
	s_add_i32 s22, 0, 0x1c000
	v_add_u32_e32 v155, s22, v149
	s_waitcnt lgkmcnt(8)
	ds_read_b128 v[214:217], v155
	ds_read_b128 v[218:221], v155 offset:1024
	ds_read_b128 v[222:225], v155 offset:2048
	ds_read_b128 v[226:229], v155 offset:3072
	s_waitcnt vmcnt(8) lgkmcnt(0)
	s_barrier
	v_mfma_f32_16x16x32_bf16 v[124:127], v[144:147], v[170:173], v[124:127]
	v_mfma_f32_16x16x32_bf16 v[120:123], v[160:163], v[170:173], v[120:123]
	v_mfma_f32_16x16x32_bf16 v[108:111], v[144:147], v[190:193], v[108:111]
	v_mfma_f32_16x16x32_bf16 v[104:107], v[160:163], v[190:193], v[104:107]
	v_mfma_f32_16x16x32_bf16 v[92:95], v[144:147], v[198:201], v[92:95]
	v_mfma_f32_16x16x32_bf16 v[88:91], v[160:163], v[198:201], v[88:91]
	v_mfma_f32_16x16x32_bf16 v[76:79], v[144:147], v[206:209], v[76:79]
	v_mfma_f32_16x16x32_bf16 v[72:75], v[160:163], v[206:209], v[72:75]
	v_mfma_f32_16x16x32_bf16 v[124:127], v[156:159], v[182:185], v[124:127]
	v_mfma_f32_16x16x32_bf16 v[120:123], v[166:169], v[182:185], v[120:123]
	v_mfma_f32_16x16x32_bf16 v[108:111], v[156:159], v[194:197], v[108:111]
	v_mfma_f32_16x16x32_bf16 v[104:107], v[166:169], v[194:197], v[104:107]
	v_mfma_f32_16x16x32_bf16 v[92:95], v[156:159], v[202:205], v[92:95]
	v_mfma_f32_16x16x32_bf16 v[88:91], v[166:169], v[202:205], v[88:91]
	v_mfma_f32_16x16x32_bf16 v[76:79], v[156:159], v[210:213], v[76:79]
	v_mfma_f32_16x16x32_bf16 v[72:75], v[166:169], v[210:213], v[72:75]
	v_mfma_f32_16x16x32_bf16 v[116:119], v[214:217], v[170:173], v[116:119]
	v_mfma_f32_16x16x32_bf16 v[112:115], v[222:225], v[170:173], v[112:115]
	v_mfma_f32_16x16x32_bf16 v[100:103], v[214:217], v[190:193], v[100:103]
	v_mfma_f32_16x16x32_bf16 v[96:99], v[222:225], v[190:193], v[96:99]
	v_mfma_f32_16x16x32_bf16 v[84:87], v[214:217], v[198:201], v[84:87]
	v_mfma_f32_16x16x32_bf16 v[80:83], v[222:225], v[198:201], v[80:83]
	v_mfma_f32_16x16x32_bf16 v[68:71], v[214:217], v[206:209], v[68:71]
	v_mfma_f32_16x16x32_bf16 v[64:67], v[222:225], v[206:209], v[64:67]
	v_mfma_f32_16x16x32_bf16 v[116:119], v[218:221], v[182:185], v[116:119]
	v_mfma_f32_16x16x32_bf16 v[112:115], v[226:229], v[182:185], v[112:115]
	v_mfma_f32_16x16x32_bf16 v[100:103], v[218:221], v[194:197], v[100:103]
	v_mfma_f32_16x16x32_bf16 v[96:99], v[226:229], v[194:197], v[96:99]
	v_mfma_f32_16x16x32_bf16 v[84:87], v[218:221], v[202:205], v[84:87]
	v_mfma_f32_16x16x32_bf16 v[80:83], v[226:229], v[202:205], v[80:83]
	v_mfma_f32_16x16x32_bf16 v[68:71], v[218:221], v[210:213], v[68:71]
	v_mfma_f32_16x16x32_bf16 v[64:67], v[226:229], v[210:213], v[64:67]
	s_barrier
; #define PG8_STAGE(bufoff, gbase, voff) do { _Pragma("unroll") for (int _i = 0; _i < 2; ++_i) \
;         __builtin_amdgcn_global_load_lds((const unsigned*)((const char*)(gbase) + (voff)[_i]), (PG8_LAS unsigned*)(lds + (bufoff) + ldsw + _i * 8192), 16, 0, 0); } while (0)
; #define PG8_LDA(dst, b, h) do { _Pragma("unroll") for (int m = 0; m < 4; ++m) _Pragma("unroll") for (int k = 0; k < 2; ++k) dst[m][k] = *(const PG8_LAS bf16x8*)(lds + PG8_SA(b, h) + aoff + m * 2048 + k * 1024); } while (0)
; #define PG8_LDB(dst, b, h) do { _Pragma("unroll") for (int n = 0; n < 2; ++n) _Pragma("unroll") for (int k = 0; k < 2; ++k) dst[n][k] = *(const PG8_LAS bf16x8*)(lds + PG8_SB(b, h) + boff + n * 2048 + k * 1024); } while (0)
; #define PG8_MMA(ai, bj, At, Bt) do { __builtin_amdgcn_s_setprio(1); _Pragma("unroll") for (int m = 0; m < 4; ++m) _Pragma("unroll") for (int n = 0; n < 2; ++n) _Pragma("unroll") for (int k = 0; k < 2; ++k) \
;         acc[ai][bj][m][n] = __builtin_amdgcn_mfma_f32_16x16x32_bf16(Bt[n][k], At[m][k], acc[ai][bj][m][n], 0, 0, 0); __builtin_amdgcn_s_setprio(0); } while (0)
; #define PG8_WAIT_V(n) asm volatile("s_waitcnt vmcnt(" #n ")" ::: "memory")
; #define PG8_WAIT_L(n) asm volatile("s_waitcnt lgkmcnt(" #n ")" ::: "memory")
; #define PG8_BAR __builtin_amdgcn_s_barrier()
; #define PG8_SCHED __builtin_amdgcn_sched_barrier(0)
; template <class Epi, class Sched>
; __device__ __forceinline__ void gemm_phase(PG8_LAS unsigned char* lds, const Gemm g, const Sched& S, const Epi& E) {
;     ...
;             PG8_LDB(B0, 0, 0); PG8_SCHED; PG8_LDA(At, 0, 0); PG8_STAGE(PG8_SA(1, 1), a1 + hstep, voffA);
;             PG8_WAIT_L(8); PG8_BAR; PG8_WAIT_L(0); PG8_MMA(0, 0, At, B0); PG8_BAR; PG8_SCHED;
;     ...
;             PG8_LDA(At, 1, 1); PG8_STAGE(PG8_SA(1, 0), a3, voffA);
;             PG8_BAR; PG8_WAIT_L(0); PG8_MMA(1, 0, At, B0); PG8_BAR; PG8_SCHED;
;             PG8_STAGE(PG8_SB(1, 1), b3 + hstep, voffB);
;             PG8_WAIT_V(6); PG8_BAR; PG8_MMA(1, 1, At, B1); PG8_BAR;
	ds_read_b128 v[170:173], v153 offset:49152
	ds_read_b128 v[182:185], v153 offset:50176
	ds_read_b128 v[190:193], v153 offset:51200
	ds_read_b128 v[194:197], v153 offset:52224
	ds_read_b128 v[198:201], v153 offset:53248
	ds_read_b128 v[202:205], v153 offset:54272
	ds_read_b128 v[206:209], v153 offset:55296
	ds_read_b128 v[210:213], v153 offset:56320
	s_add_i32 s23, s49, s30
	s_mov_b32 m0, s23
	s_nop 0
	global_load_lds_dwordx4 v130, s[98:99]
	s_add_i32 m0, s23, 0x2000
	s_nop 0
	global_load_lds_dwordx4 v134, s[98:99]
	s_mov_b32 m0, s37
	s_nop 0
	global_load_lds_dwordx4 v128, s[100:101]
	s_mov_b32 m0, s38
	s_nop 0
	global_load_lds_dwordx4 v132, s[100:101]
	s_add_u32 s20, s20, 0x40080
	s_addc_u32 s21, s21, 0
	s_add_i32 s22, s22, s30
	s_mov_b32 m0, s22
	s_nop 0
	global_load_lds_dwordx4 v130, s[20:21]
	s_add_i32 m0, s22, 0x2000
	s_nop 0
	global_load_lds_dwordx4 v134, s[20:21]
	s_waitcnt vmcnt(8) lgkmcnt(0)
	s_barrier
	v_mfma_f32_16x16x32_bf16 v[60:63], v[144:147], v[170:173], v[60:63]
	v_mfma_f32_16x16x32_bf16 v[56:59], v[160:163], v[170:173], v[56:59]
	v_mfma_f32_16x16x32_bf16 v[44:47], v[144:147], v[190:193], v[44:47]
	v_mfma_f32_16x16x32_bf16 v[40:43], v[160:163], v[190:193], v[40:43]
	v_mfma_f32_16x16x32_bf16 v[28:31], v[144:147], v[198:201], v[28:31]
	v_mfma_f32_16x16x32_bf16 v[24:27], v[160:163], v[198:201], v[24:27]
	v_mfma_f32_16x16x32_bf16 v[12:15], v[144:147], v[206:209], v[12:15]
	v_mfma_f32_16x16x32_bf16 v[8:11], v[160:163], v[206:209], v[8:11]
	v_mfma_f32_16x16x32_bf16 v[60:63], v[156:159], v[182:185], v[60:63]
	v_mfma_f32_16x16x32_bf16 v[56:59], v[166:169], v[182:185], v[56:59]
	v_mfma_f32_16x16x32_bf16 v[44:47], v[156:159], v[194:197], v[44:47]
	v_mfma_f32_16x16x32_bf16 v[40:43], v[166:169], v[194:197], v[40:43]
	v_mfma_f32_16x16x32_bf16 v[28:31], v[156:159], v[202:205], v[28:31]
	v_mfma_f32_16x16x32_bf16 v[24:27], v[166:169], v[202:205], v[24:27]
	v_mfma_f32_16x16x32_bf16 v[12:15], v[156:159], v[210:213], v[12:15]
	v_mfma_f32_16x16x32_bf16 v[8:11], v[166:169], v[210:213], v[8:11]
	v_mfma_f32_16x16x32_bf16 v[52:55], v[214:217], v[170:173], v[52:55]
	v_mfma_f32_16x16x32_bf16 v[48:51], v[222:225], v[170:173], v[48:51]
	v_mfma_f32_16x16x32_bf16 v[36:39], v[214:217], v[190:193], v[36:39]
	v_mfma_f32_16x16x32_bf16 v[32:35], v[222:225], v[190:193], v[32:35]
	v_mfma_f32_16x16x32_bf16 v[20:23], v[214:217], v[198:201], v[20:23]
	v_mfma_f32_16x16x32_bf16 v[16:19], v[222:225], v[198:201], v[16:19]
	v_mfma_f32_16x16x32_bf16 v[4:7], v[214:217], v[206:209], v[4:7]
	v_mfma_f32_16x16x32_bf16 v[0:3], v[222:225], v[206:209], v[0:3]
	v_mfma_f32_16x16x32_bf16 v[52:55], v[218:221], v[182:185], v[52:55]
	v_mfma_f32_16x16x32_bf16 v[48:51], v[226:229], v[182:185], v[48:51]
	v_mfma_f32_16x16x32_bf16 v[36:39], v[218:221], v[194:197], v[36:39]
	v_mfma_f32_16x16x32_bf16 v[32:35], v[226:229], v[194:197], v[32:35]
	v_mfma_f32_16x16x32_bf16 v[20:23], v[218:221], v[202:205], v[20:23]
	v_mfma_f32_16x16x32_bf16 v[16:19], v[226:229], v[202:205], v[16:19]
	v_mfma_f32_16x16x32_bf16 v[4:7], v[218:221], v[210:213], v[4:7]
	v_mfma_f32_16x16x32_bf16 v[0:3], v[226:229], v[210:213], v[0:3]
	s_barrier
	s_add_i32 s48, s48, 2
	s_add_u32 s18, s18, 0x100
	s_addc_u32 s19, s19, 0
	s_add_u32 s46, s46, 0x100
	s_addc_u32 s47, s47, 0
	s_cmp_gt_u32 s48, 13
.LBB0_724:
	ds_read_b128 v[144:147], v151
	ds_read_b128 v[156:159], v151 offset:1024
	ds_read_b128 v[160:163], v151 offset:2048
	ds_read_b128 v[166:169], v151 offset:3072
	s_add_u32 s20, s18, 0xfffc0080
	s_addc_u32 s21, s19, -1
	s_cmp_eq_u32 s48, 12
	s_cselect_b32 s23, s5, s21
	s_cselect_b32 s22, s11, s20
	s_cselect_b32 s21, s9, s47
	s_cselect_b32 s20, s45, s46
	s_add_i32 m0, s17, 0xc000
	ds_read_b128 v[170:173], v153
	ds_read_b128 v[182:185], v153 offset:1024
	ds_read_b128 v[190:193], v153 offset:2048
	ds_read_b128 v[194:197], v153 offset:3072
	ds_read_b128 v[198:201], v153 offset:4096
	ds_read_b128 v[202:205], v153 offset:5120
	ds_read_b128 v[206:209], v153 offset:6144
	ds_read_b128 v[210:213], v153 offset:7168
	global_load_lds_dwordx4 v136, s[18:19]
	s_add_i32 m0, s17, 0xe000
	s_nop 0
	global_load_lds_dwordx4 v138, s[18:19]
	s_waitcnt lgkmcnt(8)
	ds_read_b128 v[214:217], v154
	ds_read_b128 v[218:221], v154 offset:1024
	ds_read_b128 v[222:225], v154 offset:2048
	ds_read_b128 v[226:229], v154 offset:3072
	s_waitcnt vmcnt(8) lgkmcnt(0)
	s_barrier
	v_mfma_f32_16x16x32_bf16 v[124:127], v[144:147], v[170:173], v[124:127]
	v_mfma_f32_16x16x32_bf16 v[120:123], v[160:163], v[170:173], v[120:123]
	v_mfma_f32_16x16x32_bf16 v[108:111], v[144:147], v[190:193], v[108:111]
	v_mfma_f32_16x16x32_bf16 v[104:107], v[160:163], v[190:193], v[104:107]
	v_mfma_f32_16x16x32_bf16 v[92:95], v[144:147], v[198:201], v[92:95]
	v_mfma_f32_16x16x32_bf16 v[88:91], v[160:163], v[198:201], v[88:91]
	v_mfma_f32_16x16x32_bf16 v[76:79], v[144:147], v[206:209], v[76:79]
	v_mfma_f32_16x16x32_bf16 v[72:75], v[160:163], v[206:209], v[72:75]
	v_mfma_f32_16x16x32_bf16 v[124:127], v[156:159], v[182:185], v[124:127]
	v_mfma_f32_16x16x32_bf16 v[120:123], v[166:169], v[182:185], v[120:123]
	v_mfma_f32_16x16x32_bf16 v[108:111], v[156:159], v[194:197], v[108:111]
	v_mfma_f32_16x16x32_bf16 v[104:107], v[166:169], v[194:197], v[104:107]
	v_mfma_f32_16x16x32_bf16 v[92:95], v[156:159], v[202:205], v[92:95]
	v_mfma_f32_16x16x32_bf16 v[88:91], v[166:169], v[202:205], v[88:91]
	v_mfma_f32_16x16x32_bf16 v[76:79], v[156:159], v[210:213], v[76:79]
	v_mfma_f32_16x16x32_bf16 v[72:75], v[166:169], v[210:213], v[72:75]
	v_mfma_f32_16x16x32_bf16 v[116:119], v[214:217], v[170:173], v[116:119]
	v_mfma_f32_16x16x32_bf16 v[112:115], v[222:225], v[170:173], v[112:115]
	v_mfma_f32_16x16x32_bf16 v[100:103], v[214:217], v[190:193], v[100:103]
	v_mfma_f32_16x16x32_bf16 v[96:99], v[222:225], v[190:193], v[96:99]
	v_mfma_f32_16x16x32_bf16 v[84:87], v[214:217], v[198:201], v[84:87]
	v_mfma_f32_16x16x32_bf16 v[80:83], v[222:225], v[198:201], v[80:83]
	v_mfma_f32_16x16x32_bf16 v[68:71], v[214:217], v[206:209], v[68:71]
	v_mfma_f32_16x16x32_bf16 v[64:67], v[222:225], v[206:209], v[64:67]
	v_mfma_f32_16x16x32_bf16 v[116:119], v[218:221], v[182:185], v[116:119]
	v_mfma_f32_16x16x32_bf16 v[112:115], v[226:229], v[182:185], v[112:115]
	v_mfma_f32_16x16x32_bf16 v[100:103], v[218:221], v[194:197], v[100:103]
	v_mfma_f32_16x16x32_bf16 v[96:99], v[226:229], v[194:197], v[96:99]
	v_mfma_f32_16x16x32_bf16 v[84:87], v[218:221], v[202:205], v[84:87]
	v_mfma_f32_16x16x32_bf16 v[80:83], v[226:229], v[202:205], v[80:83]
	v_mfma_f32_16x16x32_bf16 v[68:71], v[218:221], v[210:213], v[68:71]
	v_mfma_f32_16x16x32_bf16 v[64:67], v[226:229], v[210:213], v[64:67]
	s_barrier
; #define PG8_STAGE(bufoff, gbase, voff) do { _Pragma("unroll") for (int _i = 0; _i < 2; ++_i) \
;         __builtin_amdgcn_global_load_lds((const unsigned*)((const char*)(gbase) + (voff)[_i]), (PG8_LAS unsigned*)(lds + (bufoff) + ldsw + _i * 8192), 16, 0, 0); } while (0)
; #define PG8_LDA(dst, b, h) do { _Pragma("unroll") for (int m = 0; m < 4; ++m) _Pragma("unroll") for (int k = 0; k < 2; ++k) dst[m][k] = *(const PG8_LAS bf16x8*)(lds + PG8_SA(b, h) + aoff + m * 2048 + k * 1024); } while (0)
; #define PG8_LDB(dst, b, h) do { _Pragma("unroll") for (int n = 0; n < 2; ++n) _Pragma("unroll") for (int k = 0; k < 2; ++k) dst[n][k] = *(const PG8_LAS bf16x8*)(lds + PG8_SB(b, h) + boff + n * 2048 + k * 1024); } while (0)
; #define PG8_MMA(ai, bj, At, Bt) do { __builtin_amdgcn_s_setprio(1); _Pragma("unroll") for (int m = 0; m < 4; ++m) _Pragma("unroll") for (int n = 0; n < 2; ++n) _Pragma("unroll") for (int k = 0; k < 2; ++k) \
;         acc[ai][bj][m][n] = __builtin_amdgcn_mfma_f32_16x16x32_bf16(Bt[n][k], At[m][k], acc[ai][bj][m][n], 0, 0, 0); __builtin_amdgcn_s_setprio(0); } while (0)
; #define PG8_WAIT_V(n) asm volatile("s_waitcnt vmcnt(" #n ")" ::: "memory")
; #define PG8_WAIT_L(n) asm volatile("s_waitcnt lgkmcnt(" #n ")" ::: "memory")
; #define PG8_BAR __builtin_amdgcn_s_barrier()
; template <class Epi, class Sched>
; __device__ __forceinline__ void gemm_phase(PG8_LAS unsigned char* lds, const Gemm g, const Sched& S, const Epi& E) {
;     ...
;             PG8_LDA(At, 0, 1); PG8_STAGE(PG8_SA(0, 0), a2, voffA);
;             PG8_BAR; PG8_WAIT_L(0); PG8_MMA(1, 0, At, B0); PG8_BAR; PG8_SCHED;
;             PG8_STAGE(PG8_SB(0, 1), b2 + hstep, voffB);
;             PG8_WAIT_V(6); PG8_BAR; PG8_MMA(1, 1, At, B1); PG8_BAR;
;             PG8_LDB(B0, 1, 0); PG8_SCHED; PG8_LDA(At, 1, 0); PG8_STAGE(PG8_SA(0, 1), a2 + hstep, voffA);
;             PG8_WAIT_L(8); PG8_BAR; PG8_WAIT_L(0); PG8_MMA(0, 0, At, B0); PG8_BAR; PG8_SCHED;
;             PG8_LDB(B1, 1, 1); PG8_STAGE(PG8_SB(1, 0), b3, voffB);
;             PG8_BAR; PG8_WAIT_L(0); PG8_MMA(0, 1, At, B1); PG8_BAR;
;             PG8_LDA(At, 1, 1); PG8_STAGE(PG8_SA(1, 0), a3, voffA);
;             PG8_BAR; PG8_WAIT_L(0); PG8_MMA(1, 0, At, B0); PG8_BAR; PG8_SCHED;
;             PG8_STAGE(PG8_SB(1, 1), b3 + hstep, voffB);
;             PG8_WAIT_V(6); PG8_BAR; PG8_MMA(1, 1, At, B1); PG8_BAR;
	ds_read_b128 v[170:173], v153 offset:16384
	ds_read_b128 v[182:185], v153 offset:17408
	ds_read_b128 v[190:193], v153 offset:18432
	ds_read_b128 v[194:197], v153 offset:19456
	ds_read_b128 v[198:201], v153 offset:20480
	ds_read_b128 v[202:205], v153 offset:21504
	ds_read_b128 v[206:209], v153 offset:22528
	ds_read_b128 v[210:213], v153 offset:23552
	s_add_i32 s49, s42, s30
	s_add_u32 s98, s20, s6
	s_addc_u32 s99, s21, s7
	s_mov_b32 m0, s49
	s_nop 0
	global_load_lds_dwordx4 v130, s[20:21]
	s_add_i32 m0, s49, 0x2000
	s_nop 0
	global_load_lds_dwordx4 v134, s[20:21]
	s_mov_b32 m0, s17
	s_add_u32 s100, s22, s6
	s_addc_u32 s101, s23, s7
	global_load_lds_dwordx4 v128, s[22:23]
	s_mov_b32 m0, s31
	s_nop 0
	global_load_lds_dwordx4 v132, s[22:23]
	s_add_u32 s50, s20, 0x40000
	s_addc_u32 s51, s21, 0
	s_add_i32 s49, s43, s30
	s_mov_b32 m0, s49
	s_nop 0
	global_load_lds_dwordx4 v130, s[50:51]
	s_add_i32 m0, s49, 0x2000
	s_nop 0
	global_load_lds_dwordx4 v134, s[50:51]
	s_waitcnt vmcnt(8) lgkmcnt(0)
	s_barrier
	v_mfma_f32_16x16x32_bf16 v[60:63], v[144:147], v[170:173], v[60:63]
	v_mfma_f32_16x16x32_bf16 v[56:59], v[160:163], v[170:173], v[56:59]
	v_mfma_f32_16x16x32_bf16 v[44:47], v[144:147], v[190:193], v[44:47]
	v_mfma_f32_16x16x32_bf16 v[40:43], v[160:163], v[190:193], v[40:43]
	v_mfma_f32_16x16x32_bf16 v[28:31], v[144:147], v[198:201], v[28:31]
	v_mfma_f32_16x16x32_bf16 v[24:27], v[160:163], v[198:201], v[24:27]
	v_mfma_f32_16x16x32_bf16 v[12:15], v[144:147], v[206:209], v[12:15]
	v_mfma_f32_16x16x32_bf16 v[8:11], v[160:163], v[206:209], v[8:11]
	v_mfma_f32_16x16x32_bf16 v[60:63], v[156:159], v[182:185], v[60:63]
	v_mfma_f32_16x16x32_bf16 v[56:59], v[166:169], v[182:185], v[56:59]
	v_mfma_f32_16x16x32_bf16 v[44:47], v[156:159], v[194:197], v[44:47]
	v_mfma_f32_16x16x32_bf16 v[40:43], v[166:169], v[194:197], v[40:43]
	v_mfma_f32_16x16x32_bf16 v[28:31], v[156:159], v[202:205], v[28:31]
	v_mfma_f32_16x16x32_bf16 v[24:27], v[166:169], v[202:205], v[24:27]
	v_mfma_f32_16x16x32_bf16 v[12:15], v[156:159], v[210:213], v[12:15]
	v_mfma_f32_16x16x32_bf16 v[8:11], v[166:169], v[210:213], v[8:11]
	v_mfma_f32_16x16x32_bf16 v[52:55], v[214:217], v[170:173], v[52:55]
	v_mfma_f32_16x16x32_bf16 v[48:51], v[222:225], v[170:173], v[48:51]
	v_mfma_f32_16x16x32_bf16 v[36:39], v[214:217], v[190:193], v[36:39]
	v_mfma_f32_16x16x32_bf16 v[32:35], v[222:225], v[190:193], v[32:35]
	v_mfma_f32_16x16x32_bf16 v[20:23], v[214:217], v[198:201], v[20:23]
	v_mfma_f32_16x16x32_bf16 v[16:19], v[222:225], v[198:201], v[16:19]
	v_mfma_f32_16x16x32_bf16 v[4:7], v[214:217], v[206:209], v[4:7]
	v_mfma_f32_16x16x32_bf16 v[0:3], v[222:225], v[206:209], v[0:3]
	v_mfma_f32_16x16x32_bf16 v[52:55], v[218:221], v[182:185], v[52:55]
	v_mfma_f32_16x16x32_bf16 v[48:51], v[226:229], v[182:185], v[48:51]
	v_mfma_f32_16x16x32_bf16 v[36:39], v[218:221], v[194:197], v[36:39]
	v_mfma_f32_16x16x32_bf16 v[32:35], v[226:229], v[194:197], v[32:35]
	v_mfma_f32_16x16x32_bf16 v[20:23], v[218:221], v[202:205], v[20:23]
	v_mfma_f32_16x16x32_bf16 v[16:19], v[226:229], v[202:205], v[16:19]
	v_mfma_f32_16x16x32_bf16 v[4:7], v[218:221], v[210:213], v[4:7]
	v_mfma_f32_16x16x32_bf16 v[0:3], v[226:229], v[210:213], v[0:3]
	s_barrier
	s_add_i32 s49, 0, 0x18000
	v_add_u32_e32 v155, s49, v149
	ds_read_b128 v[144:147], v155
	ds_read_b128 v[156:159], v155 offset:1024
	ds_read_b128 v[160:163], v155 offset:2048
	ds_read_b128 v[166:169], v155 offset:3072
	s_add_u32 s22, s22, 0x40000
	s_addc_u32 s23, s23, 0
	s_mov_b32 m0, s34
	ds_read_b128 v[170:173], v153 offset:32768
	ds_read_b128 v[182:185], v153 offset:33792
	ds_read_b128 v[190:193], v153 offset:34816
	ds_read_b128 v[194:197], v153 offset:35840
	ds_read_b128 v[198:201], v153 offset:36864
	ds_read_b128 v[202:205], v153 offset:37888
	ds_read_b128 v[206:209], v153 offset:38912
	ds_read_b128 v[210:213], v153 offset:39936
	global_load_lds_dwordx4 v128, s[22:23]
	s_mov_b32 m0, s35
	s_nop 0
	global_load_lds_dwordx4 v132, s[22:23]
	s_add_i32 s22, 0, 0x1c000
	v_add_u32_e32 v155, s22, v149
	s_waitcnt lgkmcnt(8)
	ds_read_b128 v[214:217], v155
	ds_read_b128 v[218:221], v155 offset:1024
	ds_read_b128 v[222:225], v155 offset:2048
	ds_read_b128 v[226:229], v155 offset:3072
	s_waitcnt vmcnt(8) lgkmcnt(0)
	s_barrier
	v_mfma_f32_16x16x32_bf16 v[124:127], v[144:147], v[170:173], v[124:127]
	v_mfma_f32_16x16x32_bf16 v[120:123], v[160:163], v[170:173], v[120:123]
	v_mfma_f32_16x16x32_bf16 v[108:111], v[144:147], v[190:193], v[108:111]
	v_mfma_f32_16x16x32_bf16 v[104:107], v[160:163], v[190:193], v[104:107]
	v_mfma_f32_16x16x32_bf16 v[92:95], v[144:147], v[198:201], v[92:95]
	v_mfma_f32_16x16x32_bf16 v[88:91], v[160:163], v[198:201], v[88:91]
	v_mfma_f32_16x16x32_bf16 v[76:79], v[144:147], v[206:209], v[76:79]
	v_mfma_f32_16x16x32_bf16 v[72:75], v[160:163], v[206:209], v[72:75]
	v_mfma_f32_16x16x32_bf16 v[124:127], v[156:159], v[182:185], v[124:127]
	v_mfma_f32_16x16x32_bf16 v[120:123], v[166:169], v[182:185], v[120:123]
	v_mfma_f32_16x16x32_bf16 v[108:111], v[156:159], v[194:197], v[108:111]
	v_mfma_f32_16x16x32_bf16 v[104:107], v[166:169], v[194:197], v[104:107]
	v_mfma_f32_16x16x32_bf16 v[92:95], v[156:159], v[202:205], v[92:95]
	v_mfma_f32_16x16x32_bf16 v[88:91], v[166:169], v[202:205], v[88:91]
	v_mfma_f32_16x16x32_bf16 v[76:79], v[156:159], v[210:213], v[76:79]
	v_mfma_f32_16x16x32_bf16 v[72:75], v[166:169], v[210:213], v[72:75]
	v_mfma_f32_16x16x32_bf16 v[116:119], v[214:217], v[170:173], v[116:119]
	v_mfma_f32_16x16x32_bf16 v[112:115], v[222:225], v[170:173], v[112:115]
	v_mfma_f32_16x16x32_bf16 v[100:103], v[214:217], v[190:193], v[100:103]
	v_mfma_f32_16x16x32_bf16 v[96:99], v[222:225], v[190:193], v[96:99]
	v_mfma_f32_16x16x32_bf16 v[84:87], v[214:217], v[198:201], v[84:87]
	v_mfma_f32_16x16x32_bf16 v[80:83], v[222:225], v[198:201], v[80:83]
	v_mfma_f32_16x16x32_bf16 v[68:71], v[214:217], v[206:209], v[68:71]
	v_mfma_f32_16x16x32_bf16 v[64:67], v[222:225], v[206:209], v[64:67]
	v_mfma_f32_16x16x32_bf16 v[116:119], v[218:221], v[182:185], v[116:119]
	v_mfma_f32_16x16x32_bf16 v[112:115], v[226:229], v[182:185], v[112:115]
	v_mfma_f32_16x16x32_bf16 v[100:103], v[218:221], v[194:197], v[100:103]
	v_mfma_f32_16x16x32_bf16 v[96:99], v[226:229], v[194:197], v[96:99]
	v_mfma_f32_16x16x32_bf16 v[84:87], v[218:221], v[202:205], v[84:87]
	v_mfma_f32_16x16x32_bf16 v[80:83], v[226:229], v[202:205], v[80:83]
	v_mfma_f32_16x16x32_bf16 v[68:71], v[218:221], v[210:213], v[68:71]
	v_mfma_f32_16x16x32_bf16 v[64:67], v[226:229], v[210:213], v[64:67]
	s_barrier
; #define PG8_STAGE(bufoff, gbase, voff) do { _Pragma("unroll") for (int _i = 0; _i < 2; ++_i) \
;         __builtin_amdgcn_global_load_lds((const unsigned*)((const char*)(gbase) + (voff)[_i]), (PG8_LAS unsigned*)(lds + (bufoff) + ldsw + _i * 8192), 16, 0, 0); } while (0)
; #define PG8_LDA(dst, b, h) do { _Pragma("unroll") for (int m = 0; m < 4; ++m) _Pragma("unroll") for (int k = 0; k < 2; ++k) dst[m][k] = *(const PG8_LAS bf16x8*)(lds + PG8_SA(b, h) + aoff + m * 2048 + k * 1024); } while (0)
; #define PG8_MMA(ai, bj, At, Bt) do { __builtin_amdgcn_s_setprio(1); _Pragma("unroll") for (int m = 0; m < 4; ++m) _Pragma("unroll") for (int n = 0; n < 2; ++n) _Pragma("unroll") for (int k = 0; k < 2; ++k) \
;         acc[ai][bj][m][n] = __builtin_amdgcn_mfma_f32_16x16x32_bf16(Bt[n][k], At[m][k], acc[ai][bj][m][n], 0, 0, 0); __builtin_amdgcn_s_setprio(0); } while (0)
; #define PG8_WAIT_V(n) asm volatile("s_waitcnt vmcnt(" #n ")" ::: "memory")
; #define PG8_WAIT_L(n) asm volatile("s_waitcnt lgkmcnt(" #n ")" ::: "memory")
; #define PG8_BAR __builtin_amdgcn_s_barrier()
; #define PG8_SCHED __builtin_amdgcn_sched_barrier(0)
; __device__ __forceinline__ f32x4 sigmoid4(f32x4 x) {
;     f32x4 d;
; #pragma unroll
;     for (int j = 0; j < 4; ++j) d[j] = 1.0f + __expf(-fmaxf(x[j], -20.0f));
;     const float p01 = d[0] * d[1], p23 = d[2] * d[3], r = __builtin_amdgcn_rcpf(p01 * p23), r01 = r * p23, r23 = r * p01;
;     return (f32x4){r01 * d[1], r01 * d[0], r23 * d[3], r23 * d[2]};
; }
; template <class Epi, class Sched>
; __device__ __forceinline__ void gemm_phase(PG8_LAS unsigned char* lds, const Gemm g, const Sched& S, const Epi& E) {
;     ...
;             PG8_LDA(At, 1, 1); PG8_STAGE(PG8_SA(1, 0), a3, voffA);
;             PG8_BAR; PG8_WAIT_L(0); PG8_MMA(1, 0, At, B0); PG8_BAR; PG8_SCHED;
;             PG8_STAGE(PG8_SB(1, 1), b3 + hstep, voffB);
;             PG8_WAIT_V(6); PG8_BAR; PG8_MMA(1, 1, At, B1); PG8_BAR;
	ds_read_b128 v[170:173], v153 offset:49152
	ds_read_b128 v[182:185], v153 offset:50176
	ds_read_b128 v[190:193], v153 offset:51200
	ds_read_b128 v[194:197], v153 offset:52224
	ds_read_b128 v[198:201], v153 offset:53248
	ds_read_b128 v[202:205], v153 offset:54272
	ds_read_b128 v[206:209], v153 offset:55296
	ds_read_b128 v[210:213], v153 offset:56320
	s_add_i32 s23, s49, s30
	s_mov_b32 m0, s23
	s_nop 0
	global_load_lds_dwordx4 v130, s[98:99]
	s_add_i32 m0, s23, 0x2000
	s_nop 0
	global_load_lds_dwordx4 v134, s[98:99]
	s_mov_b32 m0, s37
	s_nop 0
	global_load_lds_dwordx4 v128, s[100:101]
	s_mov_b32 m0, s38
	s_nop 0
	global_load_lds_dwordx4 v132, s[100:101]
	s_add_u32 s20, s20, 0x40080
	s_addc_u32 s21, s21, 0
	s_add_i32 s22, s22, s30
	s_mov_b32 m0, s22
	s_nop 0
	global_load_lds_dwordx4 v130, s[20:21]
	s_add_i32 m0, s22, 0x2000
	s_nop 0
	global_load_lds_dwordx4 v134, s[20:21]
	s_waitcnt vmcnt(8) lgkmcnt(0)
	s_barrier
	v_mfma_f32_16x16x32_bf16 v[60:63], v[144:147], v[170:173], v[60:63]
	v_mfma_f32_16x16x32_bf16 v[56:59], v[160:163], v[170:173], v[56:59]
	v_mfma_f32_16x16x32_bf16 v[44:47], v[144:147], v[190:193], v[44:47]
	v_mfma_f32_16x16x32_bf16 v[40:43], v[160:163], v[190:193], v[40:43]
	v_mfma_f32_16x16x32_bf16 v[28:31], v[144:147], v[198:201], v[28:31]
	v_mfma_f32_16x16x32_bf16 v[24:27], v[160:163], v[198:201], v[24:27]
	v_mfma_f32_16x16x32_bf16 v[12:15], v[144:147], v[206:209], v[12:15]
	v_mfma_f32_16x16x32_bf16 v[8:11], v[160:163], v[206:209], v[8:11]
	v_mfma_f32_16x16x32_bf16 v[60:63], v[156:159], v[182:185], v[60:63]
	v_mfma_f32_16x16x32_bf16 v[56:59], v[166:169], v[182:185], v[56:59]
	v_mfma_f32_16x16x32_bf16 v[44:47], v[156:159], v[194:197], v[44:47]
	v_mfma_f32_16x16x32_bf16 v[40:43], v[166:169], v[194:197], v[40:43]
	v_mfma_f32_16x16x32_bf16 v[28:31], v[156:159], v[202:205], v[28:31]
	v_mfma_f32_16x16x32_bf16 v[24:27], v[166:169], v[202:205], v[24:27]
	v_mfma_f32_16x16x32_bf16 v[12:15], v[156:159], v[210:213], v[12:15]
	v_mfma_f32_16x16x32_bf16 v[8:11], v[166:169], v[210:213], v[8:11]
	v_mfma_f32_16x16x32_bf16 v[52:55], v[214:217], v[170:173], v[52:55]
	v_mfma_f32_16x16x32_bf16 v[48:51], v[222:225], v[170:173], v[48:51]
	v_mfma_f32_16x16x32_bf16 v[36:39], v[214:217], v[190:193], v[36:39]
	v_mfma_f32_16x16x32_bf16 v[32:35], v[222:225], v[190:193], v[32:35]
	v_mfma_f32_16x16x32_bf16 v[20:23], v[214:217], v[198:201], v[20:23]
	v_mfma_f32_16x16x32_bf16 v[16:19], v[222:225], v[198:201], v[16:19]
	v_mfma_f32_16x16x32_bf16 v[4:7], v[214:217], v[206:209], v[4:7]
	v_mfma_f32_16x16x32_bf16 v[0:3], v[222:225], v[206:209], v[0:3]
	v_mfma_f32_16x16x32_bf16 v[52:55], v[218:221], v[182:185], v[52:55]
	v_mfma_f32_16x16x32_bf16 v[48:51], v[226:229], v[182:185], v[48:51]
	v_mfma_f32_16x16x32_bf16 v[36:39], v[218:221], v[194:197], v[36:39]
	v_mfma_f32_16x16x32_bf16 v[32:35], v[226:229], v[194:197], v[32:35]
	v_mfma_f32_16x16x32_bf16 v[20:23], v[218:221], v[202:205], v[20:23]
	v_mfma_f32_16x16x32_bf16 v[16:19], v[226:229], v[202:205], v[16:19]
	v_mfma_f32_16x16x32_bf16 v[4:7], v[218:221], v[210:213], v[4:7]
	v_mfma_f32_16x16x32_bf16 v[0:3], v[226:229], v[210:213], v[0:3]
	s_barrier
	s_add_i32 s48, s48, 2
	s_add_u32 s18, s18, 0x100
	s_addc_u32 s19, s19, 0
	s_add_u32 s46, s46, 0x100
	s_addc_u32 s47, s47, 0
	s_cmp_gt_u32 s48, 13
	s_cbranch_scc0 .LBB0_724
	s_cmp_gt_i32 s4, 5
	s_cselect_b64 s[18:19], -1, 0
	s_cmp_lt_i32 s4, 6
	v_pk_add_f32 v[144:145], v[126:127], 0 op_sel_hi:[1,0]
	v_pk_add_f32 v[146:147], v[124:125], 0 op_sel_hi:[1,0]
	v_pk_add_f32 v[124:125], v[122:123], 0 op_sel_hi:[1,0]
	v_pk_add_f32 v[126:127], v[120:121], 0 op_sel_hi:[1,0]
	s_cbranch_scc1 .LBB0_727
	v_max_f32_e32 v122, 0xc1a00000, v144
	v_mul_f32_e32 v122, 0xbfb8aa3b, v122
	v_exp_f32_e32 v123, v122
	v_max_f32_e32 v120, 0xc1a00000, v146
	v_max_f32_e32 v121, 0xc1a00000, v147
	v_max_f32_e32 v122, 0xc1a00000, v145
	v_mul_f32_e32 v120, 0xbfb8aa3b, v120
	v_mul_f32_e32 v121, 0xbfb8aa3b, v121
	v_mul_f32_e32 v122, 0xbfb8aa3b, v122
	v_exp_f32_e32 v120, v120
	v_exp_f32_e32 v121, v121
	v_exp_f32_e32 v122, v122
	v_max_f32_e32 v124, 0xc1a00000, v124
	v_pk_add_f32 v[120:121], v[120:121], 1.0 op_sel_hi:[1,0]
	v_pk_add_f32 v[122:123], v[122:123], 1.0 op_sel_hi:[1,0]
	v_mov_b32_e32 v144, v120
	v_mov_b32_e32 v145, v123
	v_pk_mov_b32 v[146:147], v[120:121], v[122:123] op_sel:[1,0]
	v_mul_f32_e32 v124, 0xbfb8aa3b, v124
	v_pk_mul_f32 v[144:145], v[144:145], v[146:147]
	v_exp_f32_e32 v147, v124
	v_max_f32_e32 v126, 0xc1a00000, v126
	v_max_f32_e32 v127, 0xc1a00000, v127
	v_max_f32_e32 v124, 0xc1a00000, v125
	v_mul_f32_e32 v146, v144, v145
	v_mul_f32_e32 v126, 0xbfb8aa3b, v126
	v_mul_f32_e32 v127, 0xbfb8aa3b, v127
	v_mul_f32_e32 v124, 0xbfb8aa3b, v124
	v_rcp_f32_e32 v155, v146
	v_exp_f32_e32 v126, v126
	v_exp_f32_e32 v127, v127
	v_exp_f32_e32 v146, v124
	v_mul_f32_e32 v124, v145, v155
	v_mul_f32_e32 v144, v144, v155
	v_pk_add_f32 v[126:127], v[126:127], 1.0 op_sel_hi:[1,0]
	v_pk_add_f32 v[156:157], v[146:147], 1.0 op_sel_hi:[1,0]
	v_mov_b32_e32 v146, v126
	v_mov_b32_e32 v147, v157
	v_pk_mov_b32 v[158:159], v[126:127], v[156:157] op_sel:[1,0]
	v_pk_mul_f32 v[144:145], v[122:123], v[144:145] op_sel_hi:[1,0]
	v_pk_mul_f32 v[158:159], v[146:147], v[158:159]
	s_nop 0
	v_mul_f32_e32 v125, v158, v159
	v_rcp_f32_e32 v125, v125
	s_nop 0
	v_pk_mul_f32 v[146:147], v[120:121], v[124:125] op_sel:[1,0] op_sel_hi:[0,0]
	v_mul_f32_e32 v120, v159, v125
	v_mul_f32_e32 v122, v158, v125
	v_pk_mul_f32 v[124:125], v[156:157], v[122:123] op_sel_hi:[1,0]
	v_pk_mul_f32 v[126:127], v[126:127], v[120:121] op_sel:[1,0] op_sel_hi:[0,0]

; #define PG8_STAGE(bufoff, gbase, voff) do { _Pragma("unroll") for (int _i = 0; _i < 2; ++_i) \
;         __builtin_amdgcn_global_load_lds((const unsigned*)((const char*)(gbase) + (voff)[_i]), (PG8_LAS unsigned*)(lds + (bufoff) + ldsw + _i * 8192), 16, 0, 0); } while (0)
; #define PG8_LDA(dst, b, h) do { _Pragma("unroll") for (int m = 0; m < 4; ++m) _Pragma("unroll") for (int k = 0; k < 2; ++k) dst[m][k] = *(const PG8_LAS bf16x8*)(lds + PG8_SA(b, h) + aoff + m * 2048 + k * 1024); } while (0)
; #define PG8_LDB(dst, b, h) do { _Pragma("unroll") for (int n = 0; n < 2; ++n) _Pragma("unroll") for (int k = 0; k < 2; ++k) dst[n][k] = *(const PG8_LAS bf16x8*)(lds + PG8_SB(b, h) + boff + n * 2048 + k * 1024); } while (0)
; #define PG8_MMA(ai, bj, At, Bt) do { __builtin_amdgcn_s_setprio(1); _Pragma("unroll") for (int m = 0; m < 4; ++m) _Pragma("unroll") for (int n = 0; n < 2; ++n) _Pragma("unroll") for (int k = 0; k < 2; ++k) \
;         acc[ai][bj][m][n] = __builtin_amdgcn_mfma_f32_16x16x32_bf16(Bt[n][k], At[m][k], acc[ai][bj][m][n], 0, 0, 0); __builtin_amdgcn_s_setprio(0); } while (0)
; template <class Epi, class Sched>
; __device__ __forceinline__ void gemm_phase(PG8_LAS unsigned char* lds, const Gemm g, const Sched& S, const Epi& E) {
;     ...
;         const bool has_next = S.next(ui + 1, nxt);
;         const char* nA = has_next ? (const char*)g.A + (size_t)nxt.pm * tstep : cA; const char* nB = has_next ? (const char*)g.Bt + (size_t)nxt.pn * tstep : cB;
;         for (int t = 0; t < nt; t += 2) {
;             const bool last = (t == nt - 2);
;             const char* a1 = cA + (size_t)(t + 1) * kstep;
;             const char* a2 = last ? nA : cA + (size_t)(t + 2) * kstep; const char* b2 = last ? nB : cB + (size_t)(t + 2) * kstep;
;             const char* a3 = a2 + kstep; const char* b3 = b2 + kstep;
;             if (last && has_next) S.a_ready(nxt);
;             PG8_LDB(B0, 0, 0); PG8_SCHED; PG8_LDA(At, 0, 0); PG8_STAGE(PG8_SA(1, 1), a1 + hstep, voffA);
;             PG8_WAIT_L(8); PG8_BAR; PG8_WAIT_L(0); PG8_MMA(0, 0, At, B0); PG8_BAR; PG8_SCHED;
;             PG8_LDB(B1, 0, 1); PG8_STAGE(PG8_SB(0, 0), b2, voffB);
;             PG8_BAR; PG8_WAIT_L(0); PG8_MMA(0, 1, At, B1); PG8_BAR;
;             PG8_LDA(At, 0, 1); PG8_STAGE(PG8_SA(0, 0), a2, voffA);
;             PG8_BAR; PG8_WAIT_L(0); PG8_MMA(1, 0, At, B0); PG8_BAR; PG8_SCHED;
.LBB0_990:
	s_ashr_i32 s11, s10, 31
	v_cmp_lt_i64_e32 vcc, s[12:13], v[140:141]
	s_lshl_b64 s[12:13], s[10:11], 19
	s_add_u32 s12, s27, s12
	s_addc_u32 s13, s28, s13
	s_and_b64 s[14:15], vcc, exec
	s_cselect_b32 s11, s13, s19
	s_cselect_b32 s43, s12, s18
	s_ashr_i32 s9, s8, 31
	s_lshl_b64 s[14:15], s[8:9], 19
	s_add_u32 s14, s96, s14
	s_addc_u32 s15, s97, s15
	s_and_b64 s[22:23], vcc, exec
	s_cselect_b32 s9, s15, s21
	s_cselect_b32 s44, s14, s20
	s_add_u32 s18, s18, 0x40080
	s_addc_u32 s19, s19, 0
	s_add_u32 s45, s20, 0x100
	s_addc_u32 s46, s21, 0
	s_mov_b32 s47, -2
	ds_read_b128 v[144:147], v153
	ds_read_b128 v[156:159], v153 offset:1024
	ds_read_b128 v[160:163], v153 offset:2048
	ds_read_b128 v[164:167], v153 offset:3072
	s_add_u32 s20, s18, 0xfffc0080
	s_addc_u32 s21, s19, -1
	s_cmp_eq_u32 s47, 12
	s_cselect_b32 s23, s11, s21
	s_cselect_b32 s22, s43, s20
	s_cselect_b32 s21, s9, s46
	s_cselect_b32 s20, s44, s45
	s_add_i32 m0, s17, 0xc000
	ds_read_b128 v[168:171], v154
	ds_read_b128 v[172:175], v154 offset:1024
	ds_read_b128 v[182:185], v154 offset:2048
	ds_read_b128 v[190:193], v154 offset:3072
	ds_read_b128 v[194:197], v154 offset:4096
	ds_read_b128 v[198:201], v154 offset:5120
	ds_read_b128 v[202:205], v154 offset:6144
	ds_read_b128 v[206:209], v154 offset:7168
	global_load_lds_dwordx4 v136, s[18:19]
	s_add_i32 m0, s17, 0xe000
	s_nop 0
	global_load_lds_dwordx4 v138, s[18:19]
	s_waitcnt lgkmcnt(8)
	ds_read_b128 v[210:213], v155
	ds_read_b128 v[214:217], v155 offset:1024
	ds_read_b128 v[218:221], v155 offset:2048
	ds_read_b128 v[222:225], v155 offset:3072
	s_waitcnt vmcnt(8) lgkmcnt(0)
	s_barrier
	v_mfma_f32_16x16x32_bf16 v[124:127], v[144:147], v[168:171], 0
	v_mfma_f32_16x16x32_bf16 v[120:123], v[160:163], v[168:171], 0
	v_mfma_f32_16x16x32_bf16 v[112:115], v[144:147], v[182:185], 0
	v_mfma_f32_16x16x32_bf16 v[104:107], v[160:163], v[182:185], 0
	v_mfma_f32_16x16x32_bf16 v[96:99], v[144:147], v[194:197], 0
	v_mfma_f32_16x16x32_bf16 v[88:91], v[160:163], v[194:197], 0
	v_mfma_f32_16x16x32_bf16 v[80:83], v[144:147], v[202:205], 0
	v_mfma_f32_16x16x32_bf16 v[72:75], v[160:163], v[202:205], 0
	v_mfma_f32_16x16x32_bf16 v[124:127], v[156:159], v[172:175], v[124:127]
	v_mfma_f32_16x16x32_bf16 v[120:123], v[164:167], v[172:175], v[120:123]
	v_mfma_f32_16x16x32_bf16 v[112:115], v[156:159], v[190:193], v[112:115]
	v_mfma_f32_16x16x32_bf16 v[104:107], v[164:167], v[190:193], v[104:107]
	v_mfma_f32_16x16x32_bf16 v[96:99], v[156:159], v[198:201], v[96:99]
	v_mfma_f32_16x16x32_bf16 v[88:91], v[164:167], v[198:201], v[88:91]
	v_mfma_f32_16x16x32_bf16 v[80:83], v[156:159], v[206:209], v[80:83]
	v_mfma_f32_16x16x32_bf16 v[72:75], v[164:167], v[206:209], v[72:75]
	v_mfma_f32_16x16x32_bf16 v[116:119], v[210:213], v[168:171], 0
	v_mfma_f32_16x16x32_bf16 v[108:111], v[218:221], v[168:171], 0
	v_mfma_f32_16x16x32_bf16 v[100:103], v[210:213], v[182:185], 0
	v_mfma_f32_16x16x32_bf16 v[92:95], v[218:221], v[182:185], 0
	v_mfma_f32_16x16x32_bf16 v[84:87], v[210:213], v[194:197], 0
	v_mfma_f32_16x16x32_bf16 v[76:79], v[218:221], v[194:197], 0
	v_mfma_f32_16x16x32_bf16 v[68:71], v[210:213], v[202:205], 0
	v_mfma_f32_16x16x32_bf16 v[64:67], v[218:221], v[202:205], 0
	v_mfma_f32_16x16x32_bf16 v[116:119], v[214:217], v[172:175], v[116:119]
	v_mfma_f32_16x16x32_bf16 v[108:111], v[222:225], v[172:175], v[108:111]
	v_mfma_f32_16x16x32_bf16 v[100:103], v[214:217], v[190:193], v[100:103]
	v_mfma_f32_16x16x32_bf16 v[92:95], v[222:225], v[190:193], v[92:95]
	v_mfma_f32_16x16x32_bf16 v[84:87], v[214:217], v[198:201], v[84:87]
	v_mfma_f32_16x16x32_bf16 v[76:79], v[222:225], v[198:201], v[76:79]
	v_mfma_f32_16x16x32_bf16 v[68:71], v[214:217], v[206:209], v[68:71]
	v_mfma_f32_16x16x32_bf16 v[64:67], v[222:225], v[206:209], v[64:67]
	s_barrier
	ds_read_b128 v[168:171], v154 offset:16384
	ds_read_b128 v[172:175], v154 offset:17408
	ds_read_b128 v[182:185], v154 offset:18432
	ds_read_b128 v[190:193], v154 offset:19456
	ds_read_b128 v[194:197], v154 offset:20480
	ds_read_b128 v[198:201], v154 offset:21504
	ds_read_b128 v[202:205], v154 offset:22528
	ds_read_b128 v[206:209], v154 offset:23552
	s_add_i32 s48, s39, s29
	s_add_u32 s98, s20, s6
	s_addc_u32 s99, s21, s7
	s_mov_b32 m0, s48
	s_nop 0
	global_load_lds_dwordx4 v130, s[20:21]
	s_add_i32 m0, s48, 0x2000
	s_nop 0
	global_load_lds_dwordx4 v134, s[20:21]
	s_mov_b32 m0, s17
	s_add_u32 s100, s22, s6
	s_addc_u32 s101, s23, s7
	global_load_lds_dwordx4 v128, s[22:23]
	s_mov_b32 m0, s30
	s_nop 0
	global_load_lds_dwordx4 v132, s[22:23]
	s_add_u32 s48, s20, 0x40000
	s_addc_u32 s49, s21, 0
	s_add_i32 s50, s40, s29
	s_mov_b32 m0, s50
	s_nop 0
	global_load_lds_dwordx4 v130, s[48:49]
	s_add_i32 m0, s50, 0x2000
	s_nop 0
	global_load_lds_dwordx4 v134, s[48:49]
	s_waitcnt vmcnt(8) lgkmcnt(0)
	s_barrier
; #define PG8_STAGE(bufoff, gbase, voff) do { _Pragma("unroll") for (int _i = 0; _i < 2; ++_i) \
;         __builtin_amdgcn_global_load_lds((const unsigned*)((const char*)(gbase) + (voff)[_i]), (PG8_LAS unsigned*)(lds + (bufoff) + ldsw + _i * 8192), 16, 0, 0); } while (0)
; #define PG8_LDA(dst, b, h) do { _Pragma("unroll") for (int m = 0; m < 4; ++m) _Pragma("unroll") for (int k = 0; k < 2; ++k) dst[m][k] = *(const PG8_LAS bf16x8*)(lds + PG8_SA(b, h) + aoff + m * 2048 + k * 1024); } while (0)
; #define PG8_LDB(dst, b, h) do { _Pragma("unroll") for (int n = 0; n < 2; ++n) _Pragma("unroll") for (int k = 0; k < 2; ++k) dst[n][k] = *(const PG8_LAS bf16x8*)(lds + PG8_SB(b, h) + boff + n * 2048 + k * 1024); } while (0)
; #define PG8_MMA(ai, bj, At, Bt) do { __builtin_amdgcn_s_setprio(1); _Pragma("unroll") for (int m = 0; m < 4; ++m) _Pragma("unroll") for (int n = 0; n < 2; ++n) _Pragma("unroll") for (int k = 0; k < 2; ++k) \
;         acc[ai][bj][m][n] = __builtin_amdgcn_mfma_f32_16x16x32_bf16(Bt[n][k], At[m][k], acc[ai][bj][m][n], 0, 0, 0); __builtin_amdgcn_s_setprio(0); } while (0)
; #define PG8_WAIT_V(n) asm volatile("s_waitcnt vmcnt(" #n ")" ::: "memory")
; #define PG8_WAIT_L(n) asm volatile("s_waitcnt lgkmcnt(" #n ")" ::: "memory")
; #define PG8_BAR __builtin_amdgcn_s_barrier()
; #define PG8_SCHED __builtin_amdgcn_sched_barrier(0)
; template <class Epi, class Sched>
; __device__ __forceinline__ void gemm_phase(PG8_LAS unsigned char* lds, const Gemm g, const Sched& S, const Epi& E) {
;     ...
;             PG8_BAR; PG8_WAIT_L(0); PG8_MMA(1, 0, At, B0); PG8_BAR; PG8_SCHED;
;             PG8_STAGE(PG8_SB(0, 1), b2 + hstep, voffB);
;             PG8_WAIT_V(6); PG8_BAR; PG8_MMA(1, 1, At, B1); PG8_BAR;
;             PG8_LDB(B0, 1, 0); PG8_SCHED; PG8_LDA(At, 1, 0); PG8_STAGE(PG8_SA(0, 1), a2 + hstep, voffA);
;             PG8_WAIT_L(8); PG8_BAR; PG8_WAIT_L(0); PG8_MMA(0, 0, At, B0); PG8_BAR; PG8_SCHED;
	v_mfma_f32_16x16x32_bf16 v[60:63], v[144:147], v[168:171], 0
	v_mfma_f32_16x16x32_bf16 v[56:59], v[160:163], v[168:171], 0
	v_mfma_f32_16x16x32_bf16 v[48:51], v[144:147], v[182:185], 0
	v_mfma_f32_16x16x32_bf16 v[40:43], v[160:163], v[182:185], 0
	v_mfma_f32_16x16x32_bf16 v[32:35], v[144:147], v[194:197], 0
	v_mfma_f32_16x16x32_bf16 v[24:27], v[160:163], v[194:197], 0
	v_mfma_f32_16x16x32_bf16 v[16:19], v[144:147], v[202:205], 0
	v_mfma_f32_16x16x32_bf16 v[8:11], v[160:163], v[202:205], 0
	v_mfma_f32_16x16x32_bf16 v[60:63], v[156:159], v[172:175], v[60:63]
	v_mfma_f32_16x16x32_bf16 v[56:59], v[164:167], v[172:175], v[56:59]
	v_mfma_f32_16x16x32_bf16 v[48:51], v[156:159], v[190:193], v[48:51]
	v_mfma_f32_16x16x32_bf16 v[40:43], v[164:167], v[190:193], v[40:43]
	v_mfma_f32_16x16x32_bf16 v[32:35], v[156:159], v[198:201], v[32:35]
	v_mfma_f32_16x16x32_bf16 v[24:27], v[164:167], v[198:201], v[24:27]
	v_mfma_f32_16x16x32_bf16 v[16:19], v[156:159], v[206:209], v[16:19]
	v_mfma_f32_16x16x32_bf16 v[8:11], v[164:167], v[206:209], v[8:11]
	v_mfma_f32_16x16x32_bf16 v[52:55], v[210:213], v[168:171], 0
	v_mfma_f32_16x16x32_bf16 v[44:47], v[218:221], v[168:171], 0
	v_mfma_f32_16x16x32_bf16 v[36:39], v[210:213], v[182:185], 0
	v_mfma_f32_16x16x32_bf16 v[28:31], v[218:221], v[182:185], 0
	v_mfma_f32_16x16x32_bf16 v[20:23], v[210:213], v[194:197], 0
	v_mfma_f32_16x16x32_bf16 v[12:15], v[218:221], v[194:197], 0
	v_mfma_f32_16x16x32_bf16 v[4:7], v[210:213], v[202:205], 0
	v_mfma_f32_16x16x32_bf16 v[0:3], v[218:221], v[202:205], 0
	v_mfma_f32_16x16x32_bf16 v[52:55], v[214:217], v[172:175], v[52:55]
	v_mfma_f32_16x16x32_bf16 v[44:47], v[222:225], v[172:175], v[44:47]
	v_mfma_f32_16x16x32_bf16 v[36:39], v[214:217], v[190:193], v[36:39]
	v_mfma_f32_16x16x32_bf16 v[28:31], v[222:225], v[190:193], v[28:31]
	v_mfma_f32_16x16x32_bf16 v[20:23], v[214:217], v[198:201], v[20:23]
	v_mfma_f32_16x16x32_bf16 v[12:15], v[222:225], v[198:201], v[12:15]
	v_mfma_f32_16x16x32_bf16 v[4:7], v[214:217], v[206:209], v[4:7]
	v_mfma_f32_16x16x32_bf16 v[0:3], v[222:225], v[206:209], v[0:3]
	s_barrier
	s_add_i32 s48, 0, 0x18000
	v_add_u32_e32 v164, s48, v151
	ds_read_b128 v[144:147], v164
	ds_read_b128 v[156:159], v164 offset:1024
	ds_read_b128 v[160:163], v164 offset:2048
	ds_read_b128 v[164:167], v164 offset:3072
	s_add_u32 s22, s22, 0x40000
	s_addc_u32 s23, s23, 0
	s_mov_b32 m0, s31
	ds_read_b128 v[168:171], v154 offset:32768
	ds_read_b128 v[172:175], v154 offset:33792
	ds_read_b128 v[182:185], v154 offset:34816
	ds_read_b128 v[190:193], v154 offset:35840
	ds_read_b128 v[194:197], v154 offset:36864
	ds_read_b128 v[198:201], v154 offset:37888
	ds_read_b128 v[202:205], v154 offset:38912
	ds_read_b128 v[206:209], v154 offset:39936
	global_load_lds_dwordx4 v128, s[22:23]
	s_mov_b32 m0, s34
	s_nop 0
	global_load_lds_dwordx4 v132, s[22:23]
	s_add_i32 s22, 0, 0x1c000
	v_add_u32_e32 v179, s22, v151
	s_waitcnt lgkmcnt(8)
	ds_read_b128 v[210:213], v179
	ds_read_b128 v[214:217], v179 offset:1024
	ds_read_b128 v[218:221], v179 offset:2048
	ds_read_b128 v[222:225], v179 offset:3072
	s_waitcnt vmcnt(8) lgkmcnt(0)
	s_barrier
	v_mfma_f32_16x16x32_bf16 v[124:127], v[144:147], v[168:171], v[124:127]
	v_mfma_f32_16x16x32_bf16 v[120:123], v[160:163], v[168:171], v[120:123]
	v_mfma_f32_16x16x32_bf16 v[112:115], v[144:147], v[182:185], v[112:115]
	v_mfma_f32_16x16x32_bf16 v[104:107], v[160:163], v[182:185], v[104:107]
	v_mfma_f32_16x16x32_bf16 v[96:99], v[144:147], v[194:197], v[96:99]
	v_mfma_f32_16x16x32_bf16 v[88:91], v[160:163], v[194:197], v[88:91]
	v_mfma_f32_16x16x32_bf16 v[80:83], v[144:147], v[202:205], v[80:83]
	v_mfma_f32_16x16x32_bf16 v[72:75], v[160:163], v[202:205], v[72:75]
	v_mfma_f32_16x16x32_bf16 v[124:127], v[156:159], v[172:175], v[124:127]
	v_mfma_f32_16x16x32_bf16 v[120:123], v[164:167], v[172:175], v[120:123]
	v_mfma_f32_16x16x32_bf16 v[112:115], v[156:159], v[190:193], v[112:115]
	v_mfma_f32_16x16x32_bf16 v[104:107], v[164:167], v[190:193], v[104:107]
	v_mfma_f32_16x16x32_bf16 v[96:99], v[156:159], v[198:201], v[96:99]
	v_mfma_f32_16x16x32_bf16 v[88:91], v[164:167], v[198:201], v[88:91]
	v_mfma_f32_16x16x32_bf16 v[80:83], v[156:159], v[206:209], v[80:83]
	v_mfma_f32_16x16x32_bf16 v[72:75], v[164:167], v[206:209], v[72:75]
	v_mfma_f32_16x16x32_bf16 v[116:119], v[210:213], v[168:171], v[116:119]
	v_mfma_f32_16x16x32_bf16 v[108:111], v[218:221], v[168:171], v[108:111]
	v_mfma_f32_16x16x32_bf16 v[100:103], v[210:213], v[182:185], v[100:103]
	v_mfma_f32_16x16x32_bf16 v[92:95], v[218:221], v[182:185], v[92:95]
	v_mfma_f32_16x16x32_bf16 v[84:87], v[210:213], v[194:197], v[84:87]
	v_mfma_f32_16x16x32_bf16 v[76:79], v[218:221], v[194:197], v[76:79]
	v_mfma_f32_16x16x32_bf16 v[68:71], v[210:213], v[202:205], v[68:71]
	v_mfma_f32_16x16x32_bf16 v[64:67], v[218:221], v[202:205], v[64:67]
	v_mfma_f32_16x16x32_bf16 v[116:119], v[214:217], v[172:175], v[116:119]
	v_mfma_f32_16x16x32_bf16 v[108:111], v[222:225], v[172:175], v[108:111]
	v_mfma_f32_16x16x32_bf16 v[100:103], v[214:217], v[190:193], v[100:103]
	v_mfma_f32_16x16x32_bf16 v[92:95], v[222:225], v[190:193], v[92:95]
	v_mfma_f32_16x16x32_bf16 v[84:87], v[214:217], v[198:201], v[84:87]
	v_mfma_f32_16x16x32_bf16 v[76:79], v[222:225], v[198:201], v[76:79]
	v_mfma_f32_16x16x32_bf16 v[68:71], v[214:217], v[206:209], v[68:71]
	v_mfma_f32_16x16x32_bf16 v[64:67], v[222:225], v[206:209], v[64:67]
	s_barrier
; #define PG8_STAGE(bufoff, gbase, voff) do { _Pragma("unroll") for (int _i = 0; _i < 2; ++_i) \
;         __builtin_amdgcn_global_load_lds((const unsigned*)((const char*)(gbase) + (voff)[_i]), (PG8_LAS unsigned*)(lds + (bufoff) + ldsw + _i * 8192), 16, 0, 0); } while (0)
; #define PG8_LDA(dst, b, h) do { _Pragma("unroll") for (int m = 0; m < 4; ++m) _Pragma("unroll") for (int k = 0; k < 2; ++k) dst[m][k] = *(const PG8_LAS bf16x8*)(lds + PG8_SA(b, h) + aoff + m * 2048 + k * 1024); } while (0)
; #define PG8_LDB(dst, b, h) do { _Pragma("unroll") for (int n = 0; n < 2; ++n) _Pragma("unroll") for (int k = 0; k < 2; ++k) dst[n][k] = *(const PG8_LAS bf16x8*)(lds + PG8_SB(b, h) + boff + n * 2048 + k * 1024); } while (0)
; #define PG8_MMA(ai, bj, At, Bt) do { __builtin_amdgcn_s_setprio(1); _Pragma("unroll") for (int m = 0; m < 4; ++m) _Pragma("unroll") for (int n = 0; n < 2; ++n) _Pragma("unroll") for (int k = 0; k < 2; ++k) \
;         acc[ai][bj][m][n] = __builtin_amdgcn_mfma_f32_16x16x32_bf16(Bt[n][k], At[m][k], acc[ai][bj][m][n], 0, 0, 0); __builtin_amdgcn_s_setprio(0); } while (0)
; #define PG8_WAIT_V(n) asm volatile("s_waitcnt vmcnt(" #n ")" ::: "memory")
; #define PG8_WAIT_L(n) asm volatile("s_waitcnt lgkmcnt(" #n ")" ::: "memory")
; #define PG8_BAR __builtin_amdgcn_s_barrier()
; #define PG8_SCHED __builtin_amdgcn_sched_barrier(0)
; template <class Epi, class Sched>
; __device__ __forceinline__ void gemm_phase(PG8_LAS unsigned char* lds, const Gemm g, const Sched& S, const Epi& E) {
;     ...
;         for (int t = 0; t < nt; t += 2) {
;             const bool last = (t == nt - 2);
;             const char* a1 = cA + (size_t)(t + 1) * kstep;
;             const char* a2 = last ? nA : cA + (size_t)(t + 2) * kstep; const char* b2 = last ? nB : cB + (size_t)(t + 2) * kstep;
;             const char* a3 = a2 + kstep; const char* b3 = b2 + kstep;
;             if (last && has_next) S.a_ready(nxt);
;             PG8_LDB(B0, 0, 0); PG8_SCHED; PG8_LDA(At, 0, 0); PG8_STAGE(PG8_SA(1, 1), a1 + hstep, voffA);
;             PG8_WAIT_L(8); PG8_BAR; PG8_WAIT_L(0); PG8_MMA(0, 0, At, B0); PG8_BAR; PG8_SCHED;
;     ...
;             PG8_LDA(At, 1, 1); PG8_STAGE(PG8_SA(1, 0), a3, voffA);
;             PG8_BAR; PG8_WAIT_L(0); PG8_MMA(1, 0, At, B0); PG8_BAR; PG8_SCHED;
;             PG8_STAGE(PG8_SB(1, 1), b3 + hstep, voffB);
;             PG8_WAIT_V(6); PG8_BAR; PG8_MMA(1, 1, At, B1); PG8_BAR;
	ds_read_b128 v[168:171], v154 offset:49152
	ds_read_b128 v[172:175], v154 offset:50176
	ds_read_b128 v[182:185], v154 offset:51200
	ds_read_b128 v[190:193], v154 offset:52224
	ds_read_b128 v[194:197], v154 offset:53248
	ds_read_b128 v[198:201], v154 offset:54272
	ds_read_b128 v[202:205], v154 offset:55296
	ds_read_b128 v[206:209], v154 offset:56320
	s_add_i32 s23, s48, s29
	s_mov_b32 m0, s23
	s_nop 0
	global_load_lds_dwordx4 v130, s[98:99]
	s_add_i32 m0, s23, 0x2000
	s_nop 0
	global_load_lds_dwordx4 v134, s[98:99]
	s_mov_b32 m0, s36
	s_nop 0
	global_load_lds_dwordx4 v128, s[100:101]
	s_mov_b32 m0, s37
	s_nop 0
	global_load_lds_dwordx4 v132, s[100:101]
	s_add_u32 s20, s20, 0x40080
	s_addc_u32 s21, s21, 0
	s_add_i32 s22, s22, s29
	s_mov_b32 m0, s22
	s_nop 0
	global_load_lds_dwordx4 v130, s[20:21]
	s_add_i32 m0, s22, 0x2000
	s_nop 0
	global_load_lds_dwordx4 v134, s[20:21]
	s_waitcnt vmcnt(8) lgkmcnt(0)
	s_barrier
	v_mfma_f32_16x16x32_bf16 v[60:63], v[144:147], v[168:171], v[60:63]
	v_mfma_f32_16x16x32_bf16 v[56:59], v[160:163], v[168:171], v[56:59]
	v_mfma_f32_16x16x32_bf16 v[48:51], v[144:147], v[182:185], v[48:51]
	v_mfma_f32_16x16x32_bf16 v[40:43], v[160:163], v[182:185], v[40:43]
	v_mfma_f32_16x16x32_bf16 v[32:35], v[144:147], v[194:197], v[32:35]
	v_mfma_f32_16x16x32_bf16 v[24:27], v[160:163], v[194:197], v[24:27]
	v_mfma_f32_16x16x32_bf16 v[16:19], v[144:147], v[202:205], v[16:19]
	v_mfma_f32_16x16x32_bf16 v[8:11], v[160:163], v[202:205], v[8:11]
	v_mfma_f32_16x16x32_bf16 v[60:63], v[156:159], v[172:175], v[60:63]
	v_mfma_f32_16x16x32_bf16 v[56:59], v[164:167], v[172:175], v[56:59]
	v_mfma_f32_16x16x32_bf16 v[48:51], v[156:159], v[190:193], v[48:51]
	v_mfma_f32_16x16x32_bf16 v[40:43], v[164:167], v[190:193], v[40:43]
	v_mfma_f32_16x16x32_bf16 v[32:35], v[156:159], v[198:201], v[32:35]
	v_mfma_f32_16x16x32_bf16 v[24:27], v[164:167], v[198:201], v[24:27]
	v_mfma_f32_16x16x32_bf16 v[16:19], v[156:159], v[206:209], v[16:19]
	v_mfma_f32_16x16x32_bf16 v[8:11], v[164:167], v[206:209], v[8:11]
	v_mfma_f32_16x16x32_bf16 v[52:55], v[210:213], v[168:171], v[52:55]
	v_mfma_f32_16x16x32_bf16 v[44:47], v[218:221], v[168:171], v[44:47]
	v_mfma_f32_16x16x32_bf16 v[36:39], v[210:213], v[182:185], v[36:39]
	v_mfma_f32_16x16x32_bf16 v[28:31], v[218:221], v[182:185], v[28:31]
	v_mfma_f32_16x16x32_bf16 v[20:23], v[210:213], v[194:197], v[20:23]
	v_mfma_f32_16x16x32_bf16 v[12:15], v[218:221], v[194:197], v[12:15]
	v_mfma_f32_16x16x32_bf16 v[4:7], v[210:213], v[202:205], v[4:7]
	v_mfma_f32_16x16x32_bf16 v[0:3], v[218:221], v[202:205], v[0:3]
	v_mfma_f32_16x16x32_bf16 v[52:55], v[214:217], v[172:175], v[52:55]
	v_mfma_f32_16x16x32_bf16 v[44:47], v[222:225], v[172:175], v[44:47]
	v_mfma_f32_16x16x32_bf16 v[36:39], v[214:217], v[190:193], v[36:39]
	v_mfma_f32_16x16x32_bf16 v[28:31], v[222:225], v[190:193], v[28:31]
	v_mfma_f32_16x16x32_bf16 v[20:23], v[214:217], v[198:201], v[20:23]
	v_mfma_f32_16x16x32_bf16 v[12:15], v[222:225], v[198:201], v[12:15]
	v_mfma_f32_16x16x32_bf16 v[4:7], v[214:217], v[206:209], v[4:7]
	v_mfma_f32_16x16x32_bf16 v[0:3], v[222:225], v[206:209], v[0:3]
	s_barrier
	s_add_i32 s47, s47, 2
	s_add_u32 s18, s18, 0x100
	s_addc_u32 s19, s19, 0
	s_add_u32 s45, s45, 0x100
	s_addc_u32 s46, s46, 0
	s_cmp_gt_u32 s47, 13
.LBB0_991:
	ds_read_b128 v[144:147], v153
	ds_read_b128 v[156:159], v153 offset:1024
	ds_read_b128 v[160:163], v153 offset:2048
	ds_read_b128 v[164:167], v153 offset:3072
	s_add_u32 s20, s18, 0xfffc0080
	s_addc_u32 s21, s19, -1
	s_cmp_eq_u32 s47, 12
	s_cselect_b32 s23, s11, s21
	s_cselect_b32 s22, s43, s20
	s_cselect_b32 s21, s9, s46
	s_cselect_b32 s20, s44, s45
	s_add_i32 m0, s17, 0xc000
	ds_read_b128 v[168:171], v154
	ds_read_b128 v[172:175], v154 offset:1024
	ds_read_b128 v[182:185], v154 offset:2048
	ds_read_b128 v[190:193], v154 offset:3072
	ds_read_b128 v[194:197], v154 offset:4096
	ds_read_b128 v[198:201], v154 offset:5120
	ds_read_b128 v[202:205], v154 offset:6144
	ds_read_b128 v[206:209], v154 offset:7168
	global_load_lds_dwordx4 v136, s[18:19]
	s_add_i32 m0, s17, 0xe000
	s_nop 0
	global_load_lds_dwordx4 v138, s[18:19]
	s_waitcnt lgkmcnt(8)
	ds_read_b128 v[210:213], v155
	ds_read_b128 v[214:217], v155 offset:1024
	ds_read_b128 v[218:221], v155 offset:2048
	ds_read_b128 v[222:225], v155 offset:3072
	s_waitcnt vmcnt(8) lgkmcnt(0)
	s_barrier
	v_mfma_f32_16x16x32_bf16 v[124:127], v[144:147], v[168:171], v[124:127]
	v_mfma_f32_16x16x32_bf16 v[120:123], v[160:163], v[168:171], v[120:123]
	v_mfma_f32_16x16x32_bf16 v[112:115], v[144:147], v[182:185], v[112:115]
	v_mfma_f32_16x16x32_bf16 v[104:107], v[160:163], v[182:185], v[104:107]
	v_mfma_f32_16x16x32_bf16 v[96:99], v[144:147], v[194:197], v[96:99]
	v_mfma_f32_16x16x32_bf16 v[88:91], v[160:163], v[194:197], v[88:91]
	v_mfma_f32_16x16x32_bf16 v[80:83], v[144:147], v[202:205], v[80:83]
	v_mfma_f32_16x16x32_bf16 v[72:75], v[160:163], v[202:205], v[72:75]
	v_mfma_f32_16x16x32_bf16 v[124:127], v[156:159], v[172:175], v[124:127]
	v_mfma_f32_16x16x32_bf16 v[120:123], v[164:167], v[172:175], v[120:123]
	v_mfma_f32_16x16x32_bf16 v[112:115], v[156:159], v[190:193], v[112:115]
	v_mfma_f32_16x16x32_bf16 v[104:107], v[164:167], v[190:193], v[104:107]
	v_mfma_f32_16x16x32_bf16 v[96:99], v[156:159], v[198:201], v[96:99]
	v_mfma_f32_16x16x32_bf16 v[88:91], v[164:167], v[198:201], v[88:91]
	v_mfma_f32_16x16x32_bf16 v[80:83], v[156:159], v[206:209], v[80:83]
	v_mfma_f32_16x16x32_bf16 v[72:75], v[164:167], v[206:209], v[72:75]
	v_mfma_f32_16x16x32_bf16 v[116:119], v[210:213], v[168:171], v[116:119]
	v_mfma_f32_16x16x32_bf16 v[108:111], v[218:221], v[168:171], v[108:111]
	v_mfma_f32_16x16x32_bf16 v[100:103], v[210:213], v[182:185], v[100:103]
	v_mfma_f32_16x16x32_bf16 v[92:95], v[218:221], v[182:185], v[92:95]
	v_mfma_f32_16x16x32_bf16 v[84:87], v[210:213], v[194:197], v[84:87]
	v_mfma_f32_16x16x32_bf16 v[76:79], v[218:221], v[194:197], v[76:79]
	v_mfma_f32_16x16x32_bf16 v[68:71], v[210:213], v[202:205], v[68:71]
	v_mfma_f32_16x16x32_bf16 v[64:67], v[218:221], v[202:205], v[64:67]
	v_mfma_f32_16x16x32_bf16 v[116:119], v[214:217], v[172:175], v[116:119]
	v_mfma_f32_16x16x32_bf16 v[108:111], v[222:225], v[172:175], v[108:111]
	v_mfma_f32_16x16x32_bf16 v[100:103], v[214:217], v[190:193], v[100:103]
	v_mfma_f32_16x16x32_bf16 v[92:95], v[222:225], v[190:193], v[92:95]
	v_mfma_f32_16x16x32_bf16 v[84:87], v[214:217], v[198:201], v[84:87]
	v_mfma_f32_16x16x32_bf16 v[76:79], v[222:225], v[198:201], v[76:79]
	v_mfma_f32_16x16x32_bf16 v[68:71], v[214:217], v[206:209], v[68:71]
	v_mfma_f32_16x16x32_bf16 v[64:67], v[222:225], v[206:209], v[64:67]
	s_barrier
; #define PG8_STAGE(bufoff, gbase, voff) do { _Pragma("unroll") for (int _i = 0; _i < 2; ++_i) \
;         __builtin_amdgcn_global_load_lds((const unsigned*)((const char*)(gbase) + (voff)[_i]), (PG8_LAS unsigned*)(lds + (bufoff) + ldsw + _i * 8192), 16, 0, 0); } while (0)
; #define PG8_LDA(dst, b, h) do { _Pragma("unroll") for (int m = 0; m < 4; ++m) _Pragma("unroll") for (int k = 0; k < 2; ++k) dst[m][k] = *(const PG8_LAS bf16x8*)(lds + PG8_SA(b, h) + aoff + m * 2048 + k * 1024); } while (0)
; #define PG8_LDB(dst, b, h) do { _Pragma("unroll") for (int n = 0; n < 2; ++n) _Pragma("unroll") for (int k = 0; k < 2; ++k) dst[n][k] = *(const PG8_LAS bf16x8*)(lds + PG8_SB(b, h) + boff + n * 2048 + k * 1024); } while (0)
; #define PG8_MMA(ai, bj, At, Bt) do { __builtin_amdgcn_s_setprio(1); _Pragma("unroll") for (int m = 0; m < 4; ++m) _Pragma("unroll") for (int n = 0; n < 2; ++n) _Pragma("unroll") for (int k = 0; k < 2; ++k) \
;         acc[ai][bj][m][n] = __builtin_amdgcn_mfma_f32_16x16x32_bf16(Bt[n][k], At[m][k], acc[ai][bj][m][n], 0, 0, 0); __builtin_amdgcn_s_setprio(0); } while (0)
; #define PG8_WAIT_V(n) asm volatile("s_waitcnt vmcnt(" #n ")" ::: "memory")
; #define PG8_WAIT_L(n) asm volatile("s_waitcnt lgkmcnt(" #n ")" ::: "memory")
; #define PG8_BAR __builtin_amdgcn_s_barrier()
; #define PG8_SCHED __builtin_amdgcn_sched_barrier(0)
; template <class Epi, class Sched>
; __device__ __forceinline__ void gemm_phase(PG8_LAS unsigned char* lds, const Gemm g, const Sched& S, const Epi& E) {
;     ...
;             PG8_LDB(B1, 0, 1); PG8_STAGE(PG8_SB(0, 0), b2, voffB);
;             PG8_BAR; PG8_WAIT_L(0); PG8_MMA(0, 1, At, B1); PG8_BAR;
;             PG8_LDA(At, 0, 1); PG8_STAGE(PG8_SA(0, 0), a2, voffA);
;             PG8_BAR; PG8_WAIT_L(0); PG8_MMA(1, 0, At, B0); PG8_BAR; PG8_SCHED;
;             PG8_STAGE(PG8_SB(0, 1), b2 + hstep, voffB);
;             PG8_WAIT_V(6); PG8_BAR; PG8_MMA(1, 1, At, B1); PG8_BAR;
;             PG8_LDB(B0, 1, 0); PG8_SCHED; PG8_LDA(At, 1, 0); PG8_STAGE(PG8_SA(0, 1), a2 + hstep, voffA);
;             PG8_WAIT_L(8); PG8_BAR; PG8_WAIT_L(0); PG8_MMA(0, 0, At, B0); PG8_BAR; PG8_SCHED;
	ds_read_b128 v[168:171], v154 offset:16384
	ds_read_b128 v[172:175], v154 offset:17408
	ds_read_b128 v[182:185], v154 offset:18432
	ds_read_b128 v[190:193], v154 offset:19456
	ds_read_b128 v[194:197], v154 offset:20480
	ds_read_b128 v[198:201], v154 offset:21504
	ds_read_b128 v[202:205], v154 offset:22528
	ds_read_b128 v[206:209], v154 offset:23552
	s_add_i32 s48, s39, s29
	s_add_u32 s98, s20, s6
	s_addc_u32 s99, s21, s7
	s_mov_b32 m0, s48
	s_nop 0
	global_load_lds_dwordx4 v130, s[20:21]
	s_add_i32 m0, s48, 0x2000
	s_nop 0
	global_load_lds_dwordx4 v134, s[20:21]
	s_mov_b32 m0, s17
	s_add_u32 s100, s22, s6
	s_addc_u32 s101, s23, s7
	global_load_lds_dwordx4 v128, s[22:23]
	s_mov_b32 m0, s30
	s_nop 0
	global_load_lds_dwordx4 v132, s[22:23]
	s_add_u32 s48, s20, 0x40000
	s_addc_u32 s49, s21, 0
	s_add_i32 s50, s40, s29
	s_mov_b32 m0, s50
	s_nop 0
	global_load_lds_dwordx4 v130, s[48:49]
	s_add_i32 m0, s50, 0x2000
	s_nop 0
	global_load_lds_dwordx4 v134, s[48:49]
	s_waitcnt vmcnt(8) lgkmcnt(0)
	s_barrier
	v_mfma_f32_16x16x32_bf16 v[60:63], v[144:147], v[168:171], v[60:63]
	v_mfma_f32_16x16x32_bf16 v[56:59], v[160:163], v[168:171], v[56:59]
	v_mfma_f32_16x16x32_bf16 v[48:51], v[144:147], v[182:185], v[48:51]
	v_mfma_f32_16x16x32_bf16 v[40:43], v[160:163], v[182:185], v[40:43]
	v_mfma_f32_16x16x32_bf16 v[32:35], v[144:147], v[194:197], v[32:35]
	v_mfma_f32_16x16x32_bf16 v[24:27], v[160:163], v[194:197], v[24:27]
	v_mfma_f32_16x16x32_bf16 v[16:19], v[144:147], v[202:205], v[16:19]
	v_mfma_f32_16x16x32_bf16 v[8:11], v[160:163], v[202:205], v[8:11]
	v_mfma_f32_16x16x32_bf16 v[60:63], v[156:159], v[172:175], v[60:63]
	v_mfma_f32_16x16x32_bf16 v[56:59], v[164:167], v[172:175], v[56:59]
	v_mfma_f32_16x16x32_bf16 v[48:51], v[156:159], v[190:193], v[48:51]
	v_mfma_f32_16x16x32_bf16 v[40:43], v[164:167], v[190:193], v[40:43]
	v_mfma_f32_16x16x32_bf16 v[32:35], v[156:159], v[198:201], v[32:35]
	v_mfma_f32_16x16x32_bf16 v[24:27], v[164:167], v[198:201], v[24:27]
	v_mfma_f32_16x16x32_bf16 v[16:19], v[156:159], v[206:209], v[16:19]
	v_mfma_f32_16x16x32_bf16 v[8:11], v[164:167], v[206:209], v[8:11]
	v_mfma_f32_16x16x32_bf16 v[52:55], v[210:213], v[168:171], v[52:55]
	v_mfma_f32_16x16x32_bf16 v[44:47], v[218:221], v[168:171], v[44:47]
	v_mfma_f32_16x16x32_bf16 v[36:39], v[210:213], v[182:185], v[36:39]
	v_mfma_f32_16x16x32_bf16 v[28:31], v[218:221], v[182:185], v[28:31]
	v_mfma_f32_16x16x32_bf16 v[20:23], v[210:213], v[194:197], v[20:23]
	v_mfma_f32_16x16x32_bf16 v[12:15], v[218:221], v[194:197], v[12:15]
	v_mfma_f32_16x16x32_bf16 v[4:7], v[210:213], v[202:205], v[4:7]
	v_mfma_f32_16x16x32_bf16 v[0:3], v[218:221], v[202:205], v[0:3]
	v_mfma_f32_16x16x32_bf16 v[52:55], v[214:217], v[172:175], v[52:55]
	v_mfma_f32_16x16x32_bf16 v[44:47], v[222:225], v[172:175], v[44:47]
	v_mfma_f32_16x16x32_bf16 v[36:39], v[214:217], v[190:193], v[36:39]
	v_mfma_f32_16x16x32_bf16 v[28:31], v[222:225], v[190:193], v[28:31]
	v_mfma_f32_16x16x32_bf16 v[20:23], v[214:217], v[198:201], v[20:23]
	v_mfma_f32_16x16x32_bf16 v[12:15], v[222:225], v[198:201], v[12:15]
	v_mfma_f32_16x16x32_bf16 v[4:7], v[214:217], v[206:209], v[4:7]
	v_mfma_f32_16x16x32_bf16 v[0:3], v[222:225], v[206:209], v[0:3]
	s_barrier
	s_add_i32 s48, 0, 0x18000
	v_add_u32_e32 v164, s48, v151
	ds_read_b128 v[144:147], v164
	ds_read_b128 v[156:159], v164 offset:1024
	ds_read_b128 v[160:163], v164 offset:2048
	ds_read_b128 v[164:167], v164 offset:3072
	s_add_u32 s22, s22, 0x40000
	s_addc_u32 s23, s23, 0
	s_mov_b32 m0, s31
	ds_read_b128 v[168:171], v154 offset:32768
	ds_read_b128 v[172:175], v154 offset:33792
	ds_read_b128 v[182:185], v154 offset:34816
	ds_read_b128 v[190:193], v154 offset:35840
	ds_read_b128 v[194:197], v154 offset:36864
	ds_read_b128 v[198:201], v154 offset:37888
	ds_read_b128 v[202:205], v154 offset:38912
	ds_read_b128 v[206:209], v154 offset:39936
	global_load_lds_dwordx4 v128, s[22:23]
	s_mov_b32 m0, s34
	s_nop 0
	global_load_lds_dwordx4 v132, s[22:23]
	s_add_i32 s22, 0, 0x1c000
	v_add_u32_e32 v179, s22, v151
	s_waitcnt lgkmcnt(8)
	ds_read_b128 v[210:213], v179
	ds_read_b128 v[214:217], v179 offset:1024
	ds_read_b128 v[218:221], v179 offset:2048
	ds_read_b128 v[222:225], v179 offset:3072
	s_waitcnt vmcnt(8) lgkmcnt(0)
	s_barrier
	v_mfma_f32_16x16x32_bf16 v[124:127], v[144:147], v[168:171], v[124:127]
	v_mfma_f32_16x16x32_bf16 v[120:123], v[160:163], v[168:171], v[120:123]
	v_mfma_f32_16x16x32_bf16 v[112:115], v[144:147], v[182:185], v[112:115]
	v_mfma_f32_16x16x32_bf16 v[104:107], v[160:163], v[182:185], v[104:107]
	v_mfma_f32_16x16x32_bf16 v[96:99], v[144:147], v[194:197], v[96:99]
	v_mfma_f32_16x16x32_bf16 v[88:91], v[160:163], v[194:197], v[88:91]
	v_mfma_f32_16x16x32_bf16 v[80:83], v[144:147], v[202:205], v[80:83]
	v_mfma_f32_16x16x32_bf16 v[72:75], v[160:163], v[202:205], v[72:75]
	v_mfma_f32_16x16x32_bf16 v[124:127], v[156:159], v[172:175], v[124:127]
	v_mfma_f32_16x16x32_bf16 v[120:123], v[164:167], v[172:175], v[120:123]
	v_mfma_f32_16x16x32_bf16 v[112:115], v[156:159], v[190:193], v[112:115]
	v_mfma_f32_16x16x32_bf16 v[104:107], v[164:167], v[190:193], v[104:107]
	v_mfma_f32_16x16x32_bf16 v[96:99], v[156:159], v[198:201], v[96:99]
	v_mfma_f32_16x16x32_bf16 v[88:91], v[164:167], v[198:201], v[88:91]
	v_mfma_f32_16x16x32_bf16 v[80:83], v[156:159], v[206:209], v[80:83]
	v_mfma_f32_16x16x32_bf16 v[72:75], v[164:167], v[206:209], v[72:75]
	v_mfma_f32_16x16x32_bf16 v[116:119], v[210:213], v[168:171], v[116:119]
	v_mfma_f32_16x16x32_bf16 v[108:111], v[218:221], v[168:171], v[108:111]
	v_mfma_f32_16x16x32_bf16 v[100:103], v[210:213], v[182:185], v[100:103]
	v_mfma_f32_16x16x32_bf16 v[92:95], v[218:221], v[182:185], v[92:95]
	v_mfma_f32_16x16x32_bf16 v[84:87], v[210:213], v[194:197], v[84:87]
	v_mfma_f32_16x16x32_bf16 v[76:79], v[218:221], v[194:197], v[76:79]
	v_mfma_f32_16x16x32_bf16 v[68:71], v[210:213], v[202:205], v[68:71]
	v_mfma_f32_16x16x32_bf16 v[64:67], v[218:221], v[202:205], v[64:67]
	v_mfma_f32_16x16x32_bf16 v[116:119], v[214:217], v[172:175], v[116:119]
	v_mfma_f32_16x16x32_bf16 v[108:111], v[222:225], v[172:175], v[108:111]
	v_mfma_f32_16x16x32_bf16 v[100:103], v[214:217], v[190:193], v[100:103]
	v_mfma_f32_16x16x32_bf16 v[92:95], v[222:225], v[190:193], v[92:95]
	v_mfma_f32_16x16x32_bf16 v[84:87], v[214:217], v[198:201], v[84:87]
	v_mfma_f32_16x16x32_bf16 v[76:79], v[222:225], v[198:201], v[76:79]
	v_mfma_f32_16x16x32_bf16 v[68:71], v[214:217], v[206:209], v[68:71]
	v_mfma_f32_16x16x32_bf16 v[64:67], v[222:225], v[206:209], v[64:67]
	s_barrier
; __device__ __forceinline__ unsigned cvt_pk_bf16(float lo, float hi) { unsigned r; asm volatile("v_cvt_pk_bf16_f32 %0, %1, %2" : "=v"(r) : "v"(lo), "v"(hi)); return r; }
; __device__ __forceinline__ float bf_lo(unsigned u) { return __uint_as_float(u << 16); }
; __device__ __forceinline__ float bf_hi(unsigned u) { return __uint_as_float(u & 0xffff0000u); }
; #define PG8_WAIT_V(n) asm volatile("s_waitcnt vmcnt(" #n ")" ::: "memory")
; #define PG8_WAIT_L(n) asm volatile("s_waitcnt lgkmcnt(" #n ")" ::: "memory")
;     __device__ __forceinline__ void operator()(const f32x4 (&acc)[2][2][4][2], const Unit& u, int wr, int wc, int fr, int fq) const {
;         const int row0 = u.pm * BM + wr * 64 + fr, col0 = u.pn * BM + wc * 32 + 8 * fq;
; #pragma unroll
;         for (int ai = 0; ai < 2; ++ai)
; #pragma unroll
;             for (int m = 0; m < 4; ++m) { const size_t r = (size_t)(row0 + ai * HALF + m * 16); bf16_t* rowp = O + r * ldc + col0; const bf16_t* gp = G + r * ldg + col0;
; #pragma unroll
;                 for (int bj = 0; bj < 2; ++bj) { const u32x4 gw = *(const u32x4*)(gp + bj * HALF);
;                     f32x4 v0 = acc[ai][bj][m][0], v1 = acc[ai][bj][m][1];
;                     v0[0] *= bf_lo(gw.x); v0[1] *= bf_hi(gw.x); v0[2] *= bf_lo(gw.y); v0[3] *= bf_hi(gw.y);
;                     v1[0] *= bf_lo(gw.z); v1[1] *= bf_hi(gw.z); v1[2] *= bf_lo(gw.w); v1[3] *= bf_hi(gw.w);
;                     if (ACCUM) { const u32x4 pw = *(const u32x4*)(rowp + bj * HALF);
;                         v0[0] += bf_lo(pw.x); v0[1] += bf_hi(pw.x); v0[2] += bf_lo(pw.y); v0[3] += bf_hi(pw.y);
;                         v1[0] += bf_lo(pw.z); v1[1] += bf_hi(pw.z); v1[2] += bf_lo(pw.w); v1[3] += bf_hi(pw.w); }
;                     u32x4 w; w.x = cvt_pk_bf16(v0[0], v0[1]); w.y = cvt_pk_bf16(v0[2], v0[3]); w.z = cvt_pk_bf16(v1[0], v1[1]); w.w = cvt_pk_bf16(v1[2], v1[3]);
;                     *(u32x4*)(rowp + bj * HALF) = w; } }
; template <class Epi, class Sched>
; __device__ __forceinline__ void gemm_phase(PG8_LAS unsigned char* lds, const Gemm g, const Sched& S, const Epi& E) {
;     ...
;             PG8_LDA(At, 1, 1); PG8_STAGE(PG8_SA(1, 0), a3, voffA);
;             PG8_BAR; PG8_WAIT_L(0); PG8_MMA(1, 0, At, B0); PG8_BAR; PG8_SCHED;
;             PG8_STAGE(PG8_SB(1, 1), b3 + hstep, voffB);
;             PG8_WAIT_V(6); PG8_BAR; PG8_MMA(1, 1, At, B1); PG8_BAR;
	ds_read_b128 v[168:171], v154 offset:49152
	ds_read_b128 v[172:175], v154 offset:50176
	ds_read_b128 v[182:185], v154 offset:51200
	ds_read_b128 v[190:193], v154 offset:52224
	ds_read_b128 v[194:197], v154 offset:53248
	ds_read_b128 v[198:201], v154 offset:54272
	ds_read_b128 v[202:205], v154 offset:55296
	ds_read_b128 v[206:209], v154 offset:56320
	s_add_i32 s23, s48, s29
	s_mov_b32 m0, s23
	s_nop 0
	global_load_lds_dwordx4 v130, s[98:99]
	s_add_i32 m0, s23, 0x2000
	s_nop 0
	global_load_lds_dwordx4 v134, s[98:99]
	s_mov_b32 m0, s36
	s_nop 0
	global_load_lds_dwordx4 v128, s[100:101]
	s_mov_b32 m0, s37
	s_nop 0
	global_load_lds_dwordx4 v132, s[100:101]
	s_add_u32 s20, s20, 0x40080
	s_addc_u32 s21, s21, 0
	s_add_i32 s22, s22, s29
	s_mov_b32 m0, s22
	s_nop 0
	global_load_lds_dwordx4 v130, s[20:21]
	s_add_i32 m0, s22, 0x2000
	s_nop 0
	global_load_lds_dwordx4 v134, s[20:21]
	s_waitcnt vmcnt(8) lgkmcnt(0)
	s_barrier
	v_mfma_f32_16x16x32_bf16 v[60:63], v[144:147], v[168:171], v[60:63]
	v_mfma_f32_16x16x32_bf16 v[56:59], v[160:163], v[168:171], v[56:59]
	v_mfma_f32_16x16x32_bf16 v[48:51], v[144:147], v[182:185], v[48:51]
	v_mfma_f32_16x16x32_bf16 v[40:43], v[160:163], v[182:185], v[40:43]
	v_mfma_f32_16x16x32_bf16 v[32:35], v[144:147], v[194:197], v[32:35]
	v_mfma_f32_16x16x32_bf16 v[24:27], v[160:163], v[194:197], v[24:27]
	v_mfma_f32_16x16x32_bf16 v[16:19], v[144:147], v[202:205], v[16:19]
	v_mfma_f32_16x16x32_bf16 v[8:11], v[160:163], v[202:205], v[8:11]
	v_mfma_f32_16x16x32_bf16 v[60:63], v[156:159], v[172:175], v[60:63]
	v_mfma_f32_16x16x32_bf16 v[56:59], v[164:167], v[172:175], v[56:59]
	v_mfma_f32_16x16x32_bf16 v[48:51], v[156:159], v[190:193], v[48:51]
	v_mfma_f32_16x16x32_bf16 v[40:43], v[164:167], v[190:193], v[40:43]
	v_mfma_f32_16x16x32_bf16 v[32:35], v[156:159], v[198:201], v[32:35]
	v_mfma_f32_16x16x32_bf16 v[24:27], v[164:167], v[198:201], v[24:27]
	v_mfma_f32_16x16x32_bf16 v[16:19], v[156:159], v[206:209], v[16:19]
	v_mfma_f32_16x16x32_bf16 v[8:11], v[164:167], v[206:209], v[8:11]
	v_mfma_f32_16x16x32_bf16 v[52:55], v[210:213], v[168:171], v[52:55]
	v_mfma_f32_16x16x32_bf16 v[44:47], v[218:221], v[168:171], v[44:47]
	v_mfma_f32_16x16x32_bf16 v[36:39], v[210:213], v[182:185], v[36:39]
	v_mfma_f32_16x16x32_bf16 v[28:31], v[218:221], v[182:185], v[28:31]
	v_mfma_f32_16x16x32_bf16 v[20:23], v[210:213], v[194:197], v[20:23]
	v_mfma_f32_16x16x32_bf16 v[12:15], v[218:221], v[194:197], v[12:15]
	v_mfma_f32_16x16x32_bf16 v[4:7], v[210:213], v[202:205], v[4:7]
	v_mfma_f32_16x16x32_bf16 v[0:3], v[218:221], v[202:205], v[0:3]
	v_mfma_f32_16x16x32_bf16 v[52:55], v[214:217], v[172:175], v[52:55]
	v_mfma_f32_16x16x32_bf16 v[44:47], v[222:225], v[172:175], v[44:47]
	v_mfma_f32_16x16x32_bf16 v[36:39], v[214:217], v[190:193], v[36:39]
	v_mfma_f32_16x16x32_bf16 v[28:31], v[222:225], v[190:193], v[28:31]
	v_mfma_f32_16x16x32_bf16 v[20:23], v[214:217], v[198:201], v[20:23]
	v_mfma_f32_16x16x32_bf16 v[12:15], v[222:225], v[198:201], v[12:15]
	v_mfma_f32_16x16x32_bf16 v[4:7], v[214:217], v[206:209], v[4:7]
	v_mfma_f32_16x16x32_bf16 v[0:3], v[222:225], v[206:209], v[0:3]
	s_barrier
	s_add_i32 s47, s47, 2
	s_add_u32 s18, s18, 0x100
	s_addc_u32 s19, s19, 0
	s_add_u32 s45, s45, 0x100
	s_addc_u32 s46, s46, 0
	s_cmp_gt_u32 s47, 13
	s_cbranch_scc0 .LBB0_991
	v_lshl_or_b32 v144, s42, 8, v152
	v_lshl_add_u32 v146, s16, 8, v150
	v_ashrrev_i32_e32 v145, 31, v144
	v_mov_b64_e32 v[148:149], s[4:5]
	v_lshlrev_b64 v[144:145], 1, v[144:145]
	v_mad_i64_i32 v[156:157], s[18:19], v146, s41, v[148:149]
	v_lshl_add_u64 v[160:161], v[156:157], 0, v[144:145]
	global_load_dwordx4 v[166:169], v[160:161], off offset:3072
	global_load_dwordx4 v[170:173], v[160:161], off offset:3328
	s_mul_i32 s98, s41, 16
	s_mov_b32 s99, 0
	v_lshl_add_u64 v[224:225], v[160:161], 0, s[98:99]
	global_load_dwordx4 v[182:185], v[224:225], off offset:3072
	global_load_dwordx4 v[190:193], v[224:225], off offset:3328
	s_mul_i32 s98, s41, 32
	s_mov_b32 s99, 0
	v_lshl_add_u64 v[174:175], v[160:161], 0, s[98:99]
	global_load_dwordx4 v[194:197], v[174:175], off offset:3072
	global_load_dwordx4 v[198:201], v[174:175], off offset:3328
	s_mul_i32 s98, s41, 48
	s_mov_b32 s99, 0
	v_lshl_add_u64 v[224:225], v[160:161], 0, s[98:99]
	global_load_dwordx4 v[202:205], v[224:225], off offset:3072
	global_load_dwordx4 v[206:209], v[224:225], off offset:3328
	s_mul_i32 s98, s41, 128
	s_mov_b32 s99, 0
	v_lshl_add_u64 v[174:175], v[160:161], 0, s[98:99]
	global_load_dwordx4 v[210:213], v[174:175], off offset:3072
	global_load_dwordx4 v[214:217], v[174:175], off offset:3328
	s_mul_i32 s98, s41, 144
	s_mov_b32 s99, 0
	v_lshl_add_u64 v[218:219], v[160:161], 0, s[98:99]
	s_mul_i32 s98, s41, 160
	s_mov_b32 s99, 0
	v_lshl_add_u64 v[220:221], v[160:161], 0, s[98:99]
	s_mul_i32 s98, s41, 176
	s_mov_b32 s99, 0
	v_lshl_add_u64 v[222:223], v[160:161], 0, s[98:99]
	s_and_b64 vcc, exec, s[2:3]
	s_mov_b32 s42, s8
	s_mov_b32 s16, s10
	s_mov_b64 s[20:21], s[14:15]
	s_waitcnt vmcnt(9)
	v_mov_b32_e32 v156, v166
	v_mov_b32_e32 v157, v167
	v_mov_b32_e32 v158, v168
	v_mov_b32_e32 v159, v169
	global_load_dwordx4 v[166:169], v[218:219], off offset:3072
	v_lshlrev_b32_e32 v147, 16, v156
	v_and_b32_e32 v156, 0xffff0000, v156
	v_lshlrev_b32_e32 v162, 16, v157
	v_and_b32_e32 v157, 0xffff0000, v157
	v_lshlrev_b32_e32 v164, 16, v159
	v_and_b32_e32 v159, 0xffff0000, v159
	v_lshlrev_b32_e32 v163, 16, v158
	v_and_b32_e32 v158, 0xffff0000, v158
	v_mul_f32_e32 v124, v124, v147
	v_mul_f32_e32 v125, v125, v156
	v_mul_f32_e32 v126, v126, v162
	v_mul_f32_e32 v127, v127, v157
	v_mul_f32_e32 v123, v123, v159
	v_mul_f32_e32 v147, v120, v163
	v_mul_f32_e32 v156, v121, v158
	v_mul_f32_e32 v157, v122, v164
	v_cvt_pk_bf16_f32 v120, v124, v125
	v_cvt_pk_bf16_f32 v121, v126, v127
	v_cvt_pk_bf16_f32 v122, v147, v156
	v_cvt_pk_bf16_f32 v123, v157, v123
	v_ashrrev_i32_e32 v147, 31, v146
	v_lshlrev_b64 v[158:159], 11, v[146:147]
	v_lshl_add_u64 v[158:159], s[0:1], 0, v[158:159]
	v_or_b32_e32 v156, 16, v146
	v_lshl_add_u64 v[158:159], v[158:159], 0, v[144:145]
	v_mad_i64_i32 v[160:161], s[18:19], v156, s41, v[148:149]
	global_store_dwordx4 v[158:159], v[120:123], off
	v_lshl_add_u64 v[160:161], v[160:161], 0, v[144:145]
	v_ashrrev_i32_e32 v157, 31, v156
	s_waitcnt vmcnt(10)
; __device__ __forceinline__ unsigned cvt_pk_bf16(float lo, float hi) { unsigned r; asm volatile("v_cvt_pk_bf16_f32 %0, %1, %2" : "=v"(r) : "v"(lo), "v"(hi)); return r; }
; __device__ __forceinline__ float bf_lo(unsigned u) { return __uint_as_float(u << 16); }
; __device__ __forceinline__ float bf_hi(unsigned u) { return __uint_as_float(u & 0xffff0000u); }
;     __device__ __forceinline__ void operator()(const f32x4 (&acc)[2][2][4][2], const Unit& u, int wr, int wc, int fr, int fq) const {
;     ...
;             for (int m = 0; m < 4; ++m) { const size_t r = (size_t)(row0 + ai * HALF + m * 16); bf16_t* rowp = O + r * ldc + col0; const bf16_t* gp = G + r * ldg + col0;
; #pragma unroll
;                 for (int bj = 0; bj < 2; ++bj) { const u32x4 gw = *(const u32x4*)(gp + bj * HALF);
;                     f32x4 v0 = acc[ai][bj][m][0], v1 = acc[ai][bj][m][1];
;                     v0[0] *= bf_lo(gw.x); v0[1] *= bf_hi(gw.x); v0[2] *= bf_lo(gw.y); v0[3] *= bf_hi(gw.y);
;                     v1[0] *= bf_lo(gw.z); v1[1] *= bf_hi(gw.z); v1[2] *= bf_lo(gw.w); v1[3] *= bf_hi(gw.w);
;                     if (ACCUM) { const u32x4 pw = *(const u32x4*)(rowp + bj * HALF);
;                         v0[0] += bf_lo(pw.x); v0[1] += bf_hi(pw.x); v0[2] += bf_lo(pw.y); v0[3] += bf_hi(pw.y);
;                         v1[0] += bf_lo(pw.z); v1[1] += bf_hi(pw.z); v1[2] += bf_lo(pw.w); v1[3] += bf_hi(pw.w); }
;                     u32x4 w; w.x = cvt_pk_bf16(v0[0], v0[1]); w.y = cvt_pk_bf16(v0[2], v0[3]); w.z = cvt_pk_bf16(v1[0], v1[1]); w.w = cvt_pk_bf16(v1[2], v1[3]);
;                     *(u32x4*)(rowp + bj * HALF) = w; } }
	v_mov_b32_e32 v124, v170
	v_mov_b32_e32 v125, v171
	v_mov_b32_e32 v126, v172
	v_mov_b32_e32 v127, v173
	global_load_dwordx4 v[170:173], v[218:219], off offset:3328
	v_lshlrev_b32_e32 v120, 16, v124
	v_and_b32_e32 v121, 0xffff0000, v124
	v_lshlrev_b32_e32 v122, 16, v125
	v_and_b32_e32 v123, 0xffff0000, v125
	v_lshlrev_b32_e32 v124, 16, v126
	v_and_b32_e32 v125, 0xffff0000, v126
	v_lshlrev_b32_e32 v126, 16, v127
	v_and_b32_e32 v127, 0xffff0000, v127
	v_mul_f32_e32 v116, v116, v120
	v_mul_f32_e32 v117, v117, v121
	v_mul_f32_e32 v118, v118, v122
	v_mul_f32_e32 v119, v119, v123
	v_mul_f32_e32 v111, v111, v127
	v_mul_f32_e32 v120, v108, v124
	v_mul_f32_e32 v121, v109, v125
	v_mul_f32_e32 v122, v110, v126
	v_cvt_pk_bf16_f32 v108, v116, v117
	v_cvt_pk_bf16_f32 v109, v118, v119
	v_cvt_pk_bf16_f32 v110, v120, v121
	v_cvt_pk_bf16_f32 v111, v122, v111
	s_nop 0
	global_store_dwordx4 v[158:159], v[108:111], off offset:256
	s_waitcnt vmcnt(11)
	v_mov_b32_e32 v116, v182
	v_mov_b32_e32 v117, v183
	v_mov_b32_e32 v118, v184
	v_mov_b32_e32 v119, v185
	global_load_dwordx4 v[182:185], v[220:221], off offset:3072
	s_nop 0
	v_lshlrev_b32_e32 v108, 16, v116
	v_and_b32_e32 v109, 0xffff0000, v116
	v_lshlrev_b32_e32 v110, 16, v117
	v_and_b32_e32 v111, 0xffff0000, v117
	v_lshlrev_b32_e32 v116, 16, v118
	v_and_b32_e32 v117, 0xffff0000, v118
	v_lshlrev_b32_e32 v118, 16, v119
	v_and_b32_e32 v119, 0xffff0000, v119
	v_mul_f32_e32 v108, v112, v108
	v_mul_f32_e32 v109, v113, v109
	v_mul_f32_e32 v110, v114, v110
	v_mul_f32_e32 v111, v115, v111
	v_mul_f32_e32 v107, v107, v119
	v_mul_f32_e32 v112, v104, v116
	v_mul_f32_e32 v113, v105, v117
	v_mul_f32_e32 v114, v106, v118
	v_cvt_pk_bf16_f32 v104, v108, v109
	v_cvt_pk_bf16_f32 v105, v110, v111
	v_cvt_pk_bf16_f32 v106, v112, v113
	v_cvt_pk_bf16_f32 v107, v114, v107
	v_lshlrev_b64 v[116:117], 11, v[156:157]
	v_lshl_add_u64 v[116:117], s[0:1], 0, v[116:117]
	v_or_b32_e32 v112, 32, v146
	v_lshl_add_u64 v[116:117], v[116:117], 0, v[144:145]
	v_mad_i64_i32 v[114:115], s[18:19], v112, s41, v[148:149]
	global_store_dwordx4 v[116:117], v[104:107], off
	v_lshl_add_u64 v[114:115], v[114:115], 0, v[144:145]
	v_ashrrev_i32_e32 v113, 31, v112
	s_waitcnt vmcnt(12)
	v_mov_b32_e32 v108, v190
	v_mov_b32_e32 v109, v191
	v_mov_b32_e32 v110, v192
	v_mov_b32_e32 v111, v193
	global_load_dwordx4 v[190:193], v[220:221], off offset:3328
	v_lshlrev_b32_e32 v104, 16, v108
	v_and_b32_e32 v105, 0xffff0000, v108
	v_lshlrev_b32_e32 v106, 16, v109
	v_and_b32_e32 v107, 0xffff0000, v109
	v_lshlrev_b32_e32 v108, 16, v110
	v_and_b32_e32 v109, 0xffff0000, v110
	v_lshlrev_b32_e32 v110, 16, v111
	v_and_b32_e32 v111, 0xffff0000, v111
	v_mul_f32_e32 v100, v100, v104
	v_mul_f32_e32 v101, v101, v105
	v_mul_f32_e32 v102, v102, v106
	v_mul_f32_e32 v103, v103, v107
	v_mul_f32_e32 v95, v95, v111
	v_mul_f32_e32 v104, v92, v108
	v_mul_f32_e32 v105, v93, v109
	v_mul_f32_e32 v106, v94, v110
	v_cvt_pk_bf16_f32 v92, v100, v101
	v_cvt_pk_bf16_f32 v93, v102, v103
	v_cvt_pk_bf16_f32 v94, v104, v105
	v_cvt_pk_bf16_f32 v95, v106, v95
	s_nop 0
	global_store_dwordx4 v[116:117], v[92:95], off offset:256
	s_waitcnt vmcnt(13)
	v_mov_b32_e32 v100, v194
	v_mov_b32_e32 v101, v195
	v_mov_b32_e32 v102, v196
	v_mov_b32_e32 v103, v197
	global_load_dwordx4 v[194:197], v[222:223], off offset:3072
	s_nop 0
	v_lshlrev_b32_e32 v92, 16, v100
	v_and_b32_e32 v93, 0xffff0000, v100
	v_lshlrev_b32_e32 v94, 16, v101
	v_and_b32_e32 v95, 0xffff0000, v101
	v_lshlrev_b32_e32 v100, 16, v102
	v_and_b32_e32 v101, 0xffff0000, v102
	v_lshlrev_b32_e32 v102, 16, v103
	v_and_b32_e32 v103, 0xffff0000, v103
	v_mul_f32_e32 v92, v96, v92
	v_mul_f32_e32 v93, v97, v93
	v_mul_f32_e32 v94, v98, v94
	v_mul_f32_e32 v95, v99, v95
	v_mul_f32_e32 v91, v91, v103
	v_mul_f32_e32 v96, v88, v100
	v_mul_f32_e32 v97, v89, v101
	v_mul_f32_e32 v98, v90, v102
	v_cvt_pk_bf16_f32 v88, v92, v93
	v_cvt_pk_bf16_f32 v89, v94, v95
	v_cvt_pk_bf16_f32 v90, v96, v97
	v_cvt_pk_bf16_f32 v91, v98, v91
	v_lshlrev_b64 v[100:101], 11, v[112:113]
	v_lshl_add_u64 v[100:101], s[0:1], 0, v[100:101]
	v_or_b32_e32 v96, 48, v146
	v_lshl_add_u64 v[100:101], v[100:101], 0, v[144:145]
	v_mad_i64_i32 v[98:99], s[18:19], v96, s41, v[148:149]
	global_store_dwordx4 v[100:101], v[88:91], off
	v_lshl_add_u64 v[98:99], v[98:99], 0, v[144:145]
	v_ashrrev_i32_e32 v97, 31, v96
	s_waitcnt vmcnt(14)
	v_mov_b32_e32 v92, v198
	v_mov_b32_e32 v93, v199
	v_mov_b32_e32 v94, v200
	v_mov_b32_e32 v95, v201
	global_load_dwordx4 v[198:201], v[222:223], off offset:3328
	v_lshlrev_b32_e32 v88, 16, v92
	v_and_b32_e32 v89, 0xffff0000, v92
	v_lshlrev_b32_e32 v90, 16, v93
	v_and_b32_e32 v91, 0xffff0000, v93
	v_lshlrev_b32_e32 v92, 16, v94
	v_and_b32_e32 v93, 0xffff0000, v94
	v_lshlrev_b32_e32 v94, 16, v95
	v_and_b32_e32 v95, 0xffff0000, v95
	v_mul_f32_e32 v84, v84, v88
	v_mul_f32_e32 v85, v85, v89
	v_mul_f32_e32 v86, v86, v90
	v_mul_f32_e32 v87, v87, v91
	v_mul_f32_e32 v79, v79, v95
	v_mul_f32_e32 v88, v76, v92
	v_mul_f32_e32 v89, v77, v93
	v_mul_f32_e32 v90, v78, v94
	v_cvt_pk_bf16_f32 v76, v84, v85
	v_cvt_pk_bf16_f32 v77, v86, v87
	v_cvt_pk_bf16_f32 v78, v88, v89
	v_cvt_pk_bf16_f32 v79, v90, v79
	s_nop 0
	global_store_dwordx4 v[100:101], v[76:79], off offset:256
	s_waitcnt vmcnt(15)
; __device__ __forceinline__ unsigned cvt_pk_bf16(float lo, float hi) { unsigned r; asm volatile("v_cvt_pk_bf16_f32 %0, %1, %2" : "=v"(r) : "v"(lo), "v"(hi)); return r; }
; __device__ __forceinline__ float bf_lo(unsigned u) { return __uint_as_float(u << 16); }
; __device__ __forceinline__ float bf_hi(unsigned u) { return __uint_as_float(u & 0xffff0000u); }
;     __device__ __forceinline__ void operator()(const f32x4 (&acc)[2][2][4][2], const Unit& u, int wr, int wc, int fr, int fq) const {
;     ...
;             for (int m = 0; m < 4; ++m) { const size_t r = (size_t)(row0 + ai * HALF + m * 16); bf16_t* rowp = O + r * ldc + col0; const bf16_t* gp = G + r * ldg + col0;
; #pragma unroll
;                 for (int bj = 0; bj < 2; ++bj) { const u32x4 gw = *(const u32x4*)(gp + bj * HALF);
;                     f32x4 v0 = acc[ai][bj][m][0], v1 = acc[ai][bj][m][1];
;                     v0[0] *= bf_lo(gw.x); v0[1] *= bf_hi(gw.x); v0[2] *= bf_lo(gw.y); v0[3] *= bf_hi(gw.y);
;                     v1[0] *= bf_lo(gw.z); v1[1] *= bf_hi(gw.z); v1[2] *= bf_lo(gw.w); v1[3] *= bf_hi(gw.w);
;                     if (ACCUM) { const u32x4 pw = *(const u32x4*)(rowp + bj * HALF);
;                         v0[0] += bf_lo(pw.x); v0[1] += bf_hi(pw.x); v0[2] += bf_lo(pw.y); v0[3] += bf_hi(pw.y);
;                         v1[0] += bf_lo(pw.z); v1[1] += bf_hi(pw.z); v1[2] += bf_lo(pw.w); v1[3] += bf_hi(pw.w); }
;                     u32x4 w; w.x = cvt_pk_bf16(v0[0], v0[1]); w.y = cvt_pk_bf16(v0[2], v0[3]); w.z = cvt_pk_bf16(v1[0], v1[1]); w.w = cvt_pk_bf16(v1[2], v1[3]);
;                     *(u32x4*)(rowp + bj * HALF) = w; } }
	v_mov_b32_e32 v84, v202
	v_mov_b32_e32 v85, v203
	v_mov_b32_e32 v86, v204
	v_mov_b32_e32 v87, v205
	s_nop 0
	v_lshlrev_b32_e32 v76, 16, v84
	v_and_b32_e32 v77, 0xffff0000, v84
	v_lshlrev_b32_e32 v78, 16, v85
	v_and_b32_e32 v79, 0xffff0000, v85
	v_lshlrev_b32_e32 v84, 16, v86
	v_and_b32_e32 v85, 0xffff0000, v86
	v_lshlrev_b32_e32 v86, 16, v87
	v_and_b32_e32 v87, 0xffff0000, v87
	v_mul_f32_e32 v76, v80, v76
	v_mul_f32_e32 v77, v81, v77
	v_mul_f32_e32 v78, v82, v78
	v_mul_f32_e32 v79, v83, v79
	v_mul_f32_e32 v75, v75, v87
	v_mul_f32_e32 v80, v72, v84
	v_mul_f32_e32 v81, v73, v85
	v_mul_f32_e32 v82, v74, v86
	v_cvt_pk_bf16_f32 v72, v76, v77
	v_cvt_pk_bf16_f32 v73, v78, v79
	v_cvt_pk_bf16_f32 v74, v80, v81
	v_cvt_pk_bf16_f32 v75, v82, v75
	v_lshlrev_b64 v[84:85], 11, v[96:97]
	v_lshl_add_u64 v[84:85], s[0:1], 0, v[84:85]
	v_add_u32_e32 v80, 0x80, v146
	v_lshl_add_u64 v[84:85], v[84:85], 0, v[144:145]
	v_mad_i64_i32 v[82:83], s[18:19], v80, s41, v[148:149]
	global_store_dwordx4 v[84:85], v[72:75], off
	v_lshl_add_u64 v[82:83], v[82:83], 0, v[144:145]
	v_ashrrev_i32_e32 v81, 31, v80
	s_waitcnt vmcnt(15)
	v_mov_b32_e32 v76, v206
	v_mov_b32_e32 v77, v207
	v_mov_b32_e32 v78, v208
	v_mov_b32_e32 v79, v209
	v_lshlrev_b32_e32 v72, 16, v76
	v_and_b32_e32 v73, 0xffff0000, v76
	v_lshlrev_b32_e32 v74, 16, v77
	v_and_b32_e32 v75, 0xffff0000, v77
	v_lshlrev_b32_e32 v76, 16, v78
	v_and_b32_e32 v77, 0xffff0000, v78
	v_lshlrev_b32_e32 v78, 16, v79
	v_and_b32_e32 v79, 0xffff0000, v79
	v_mul_f32_e32 v68, v68, v72
	v_mul_f32_e32 v69, v69, v73
	v_mul_f32_e32 v70, v70, v74
	v_mul_f32_e32 v71, v71, v75
	v_mul_f32_e32 v67, v67, v79
	v_mul_f32_e32 v72, v64, v76
	v_mul_f32_e32 v73, v65, v77
	v_mul_f32_e32 v74, v66, v78
	v_cvt_pk_bf16_f32 v64, v68, v69
	v_cvt_pk_bf16_f32 v65, v70, v71
	v_cvt_pk_bf16_f32 v66, v72, v73
	v_cvt_pk_bf16_f32 v67, v74, v67
	s_nop 0
	global_store_dwordx4 v[84:85], v[64:67], off offset:256
	s_waitcnt vmcnt(15)
	v_mov_b32_e32 v68, v210
	v_mov_b32_e32 v69, v211
	v_mov_b32_e32 v70, v212
	v_mov_b32_e32 v71, v213
	s_nop 0
	v_lshlrev_b32_e32 v64, 16, v68
	v_and_b32_e32 v65, 0xffff0000, v68
	v_lshlrev_b32_e32 v66, 16, v69
	v_and_b32_e32 v67, 0xffff0000, v69
	v_lshlrev_b32_e32 v68, 16, v70
	v_and_b32_e32 v69, 0xffff0000, v70
	v_lshlrev_b32_e32 v70, 16, v71
	v_and_b32_e32 v71, 0xffff0000, v71
	v_mul_f32_e32 v60, v60, v64
	v_mul_f32_e32 v61, v61, v65
	v_mul_f32_e32 v62, v62, v66
	v_mul_f32_e32 v63, v63, v67
	v_mul_f32_e32 v59, v59, v71
	v_mul_f32_e32 v64, v56, v68
	v_mul_f32_e32 v65, v57, v69
	v_mul_f32_e32 v66, v58, v70
	v_cvt_pk_bf16_f32 v56, v60, v61
	v_cvt_pk_bf16_f32 v57, v62, v63
	v_cvt_pk_bf16_f32 v58, v64, v65
	v_cvt_pk_bf16_f32 v59, v66, v59
	v_lshlrev_b64 v[68:69], 11, v[80:81]
	v_lshl_add_u64 v[68:69], s[0:1], 0, v[68:69]
	v_add_u32_e32 v64, 0x90, v146
	v_lshl_add_u64 v[68:69], v[68:69], 0, v[144:145]
	v_mad_i64_i32 v[66:67], s[18:19], v64, s41, v[148:149]
	global_store_dwordx4 v[68:69], v[56:59], off
	v_lshl_add_u64 v[66:67], v[66:67], 0, v[144:145]
	v_ashrrev_i32_e32 v65, 31, v64
	s_waitcnt vmcnt(15)
	v_mov_b32_e32 v60, v214
	v_mov_b32_e32 v61, v215
	v_mov_b32_e32 v62, v216
	v_mov_b32_e32 v63, v217
	v_lshlrev_b32_e32 v56, 16, v60
	v_and_b32_e32 v57, 0xffff0000, v60
	v_lshlrev_b32_e32 v58, 16, v61
	v_and_b32_e32 v59, 0xffff0000, v61
	v_lshlrev_b32_e32 v60, 16, v62
	v_and_b32_e32 v61, 0xffff0000, v62
	v_lshlrev_b32_e32 v62, 16, v63
	v_and_b32_e32 v63, 0xffff0000, v63
	v_mul_f32_e32 v52, v52, v56
	v_mul_f32_e32 v53, v53, v57
	v_mul_f32_e32 v54, v54, v58
	v_mul_f32_e32 v55, v55, v59
	v_mul_f32_e32 v47, v47, v63
	v_mul_f32_e32 v56, v44, v60
	v_mul_f32_e32 v57, v45, v61
	v_mul_f32_e32 v58, v46, v62
	v_cvt_pk_bf16_f32 v44, v52, v53
	v_cvt_pk_bf16_f32 v45, v54, v55
	v_cvt_pk_bf16_f32 v46, v56, v57
	v_cvt_pk_bf16_f32 v47, v58, v47
	s_nop 0
	global_store_dwordx4 v[68:69], v[44:47], off offset:256
	s_waitcnt vmcnt(15)
	v_mov_b32_e32 v52, v166
	v_mov_b32_e32 v53, v167
	v_mov_b32_e32 v54, v168
	v_mov_b32_e32 v55, v169
	s_nop 0
	v_lshlrev_b32_e32 v44, 16, v52
	v_and_b32_e32 v45, 0xffff0000, v52
	v_lshlrev_b32_e32 v46, 16, v53
	v_and_b32_e32 v47, 0xffff0000, v53
	v_lshlrev_b32_e32 v52, 16, v54
	v_and_b32_e32 v53, 0xffff0000, v54
	v_lshlrev_b32_e32 v54, 16, v55
	v_and_b32_e32 v55, 0xffff0000, v55
	v_mul_f32_e32 v44, v48, v44
	v_mul_f32_e32 v45, v49, v45
	v_mul_f32_e32 v46, v50, v46
	v_mul_f32_e32 v47, v51, v47
	v_mul_f32_e32 v43, v43, v55
	v_mul_f32_e32 v48, v40, v52
	v_mul_f32_e32 v49, v41, v53
	v_mul_f32_e32 v50, v42, v54
	v_cvt_pk_bf16_f32 v40, v44, v45
	v_cvt_pk_bf16_f32 v41, v46, v47
	v_cvt_pk_bf16_f32 v42, v48, v49
	v_cvt_pk_bf16_f32 v43, v50, v43
	v_lshlrev_b64 v[52:53], 11, v[64:65]
	v_lshl_add_u64 v[52:53], s[0:1], 0, v[52:53]
	v_add_u32_e32 v48, 0xa0, v146
	v_lshl_add_u64 v[52:53], v[52:53], 0, v[144:145]
	v_mad_i64_i32 v[50:51], s[18:19], v48, s41, v[148:149]
	global_store_dwordx4 v[52:53], v[40:43], off
	v_lshl_add_u64 v[50:51], v[50:51], 0, v[144:145]
	v_ashrrev_i32_e32 v49, 31, v48
	s_waitcnt vmcnt(14)
; __device__ __forceinline__ unsigned cvt_pk_bf16(float lo, float hi) { unsigned r; asm volatile("v_cvt_pk_bf16_f32 %0, %1, %2" : "=v"(r) : "v"(lo), "v"(hi)); return r; }
; __device__ __forceinline__ float bf_lo(unsigned u) { return __uint_as_float(u << 16); }
; __device__ __forceinline__ float bf_hi(unsigned u) { return __uint_as_float(u & 0xffff0000u); }
; #define PG8_WAIT_V(n) asm volatile("s_waitcnt vmcnt(" #n ")" ::: "memory")
; #define PG8_BAR __builtin_amdgcn_s_barrier()
;     __device__ __forceinline__ void operator()(const f32x4 (&acc)[2][2][4][2], const Unit& u, int wr, int wc, int fr, int fq) const {
;     ...
;             for (int m = 0; m < 4; ++m) { const size_t r = (size_t)(row0 + ai * HALF + m * 16); bf16_t* rowp = O + r * ldc + col0; const bf16_t* gp = G + r * ldg + col0;
; #pragma unroll
;                 for (int bj = 0; bj < 2; ++bj) { const u32x4 gw = *(const u32x4*)(gp + bj * HALF);
;                     f32x4 v0 = acc[ai][bj][m][0], v1 = acc[ai][bj][m][1];
;                     v0[0] *= bf_lo(gw.x); v0[1] *= bf_hi(gw.x); v0[2] *= bf_lo(gw.y); v0[3] *= bf_hi(gw.y);
;                     v1[0] *= bf_lo(gw.z); v1[1] *= bf_hi(gw.z); v1[2] *= bf_lo(gw.w); v1[3] *= bf_hi(gw.w);
;                     if (ACCUM) { const u32x4 pw = *(const u32x4*)(rowp + bj * HALF);
;                         v0[0] += bf_lo(pw.x); v0[1] += bf_hi(pw.x); v0[2] += bf_lo(pw.y); v0[3] += bf_hi(pw.y);
;                         v1[0] += bf_lo(pw.z); v1[1] += bf_hi(pw.z); v1[2] += bf_lo(pw.w); v1[3] += bf_hi(pw.w); }
;                     u32x4 w; w.x = cvt_pk_bf16(v0[0], v0[1]); w.y = cvt_pk_bf16(v0[2], v0[3]); w.z = cvt_pk_bf16(v1[0], v1[1]); w.w = cvt_pk_bf16(v1[2], v1[3]);
;                     *(u32x4*)(rowp + bj * HALF) = w; } }
; template <class Epi, class Sched>
; __device__ __forceinline__ void gemm_phase(PG8_LAS unsigned char* lds, const Gemm g, const Sched& S, const Epi& E) {
;     ...
;     PG8_WAIT_V(0);
;     if (wr == 0) PG8_BAR;
;     PG8_BAR;
	v_mov_b32_e32 v44, v170
	v_mov_b32_e32 v45, v171
	v_mov_b32_e32 v46, v172
	v_mov_b32_e32 v47, v173
	v_lshlrev_b32_e32 v40, 16, v44
	v_and_b32_e32 v41, 0xffff0000, v44
	v_lshlrev_b32_e32 v42, 16, v45
	v_and_b32_e32 v43, 0xffff0000, v45
	v_lshlrev_b32_e32 v44, 16, v46
	v_and_b32_e32 v45, 0xffff0000, v46
	v_lshlrev_b32_e32 v46, 16, v47
	v_and_b32_e32 v47, 0xffff0000, v47
	v_mul_f32_e32 v36, v36, v40
	v_mul_f32_e32 v37, v37, v41
	v_mul_f32_e32 v38, v38, v42
	v_mul_f32_e32 v39, v39, v43
	v_mul_f32_e32 v31, v31, v47
	v_mul_f32_e32 v40, v28, v44
	v_mul_f32_e32 v41, v29, v45
	v_mul_f32_e32 v42, v30, v46
	v_cvt_pk_bf16_f32 v28, v36, v37
	v_cvt_pk_bf16_f32 v29, v38, v39
	v_cvt_pk_bf16_f32 v30, v40, v41
	v_cvt_pk_bf16_f32 v31, v42, v31
	s_nop 0
	global_store_dwordx4 v[52:53], v[28:31], off offset:256
	s_waitcnt vmcnt(13)
	v_mov_b32_e32 v36, v182
	v_mov_b32_e32 v37, v183
	v_mov_b32_e32 v38, v184
	v_mov_b32_e32 v39, v185
	s_nop 0
	v_lshlrev_b32_e32 v28, 16, v36
	v_and_b32_e32 v29, 0xffff0000, v36
	v_lshlrev_b32_e32 v30, 16, v37
	v_and_b32_e32 v31, 0xffff0000, v37
	v_lshlrev_b32_e32 v36, 16, v38
	v_and_b32_e32 v37, 0xffff0000, v38
	v_lshlrev_b32_e32 v38, 16, v39
	v_and_b32_e32 v39, 0xffff0000, v39
	v_mul_f32_e32 v28, v32, v28
	v_mul_f32_e32 v29, v33, v29
	v_mul_f32_e32 v30, v34, v30
	v_mul_f32_e32 v31, v35, v31
	v_mul_f32_e32 v27, v27, v39
	v_mul_f32_e32 v32, v24, v36
	v_mul_f32_e32 v33, v25, v37
	v_mul_f32_e32 v34, v26, v38
	v_cvt_pk_bf16_f32 v24, v28, v29
	v_cvt_pk_bf16_f32 v25, v30, v31
	v_cvt_pk_bf16_f32 v26, v32, v33
	v_cvt_pk_bf16_f32 v27, v34, v27
	v_lshlrev_b64 v[36:37], 11, v[48:49]
	v_lshl_add_u64 v[36:37], s[0:1], 0, v[36:37]
	v_add_u32_e32 v32, 0xb0, v146
	v_lshl_add_u64 v[36:37], v[36:37], 0, v[144:145]
	v_mad_i64_i32 v[34:35], s[18:19], v32, s41, v[148:149]
	global_store_dwordx4 v[36:37], v[24:27], off
	v_lshl_add_u64 v[34:35], v[34:35], 0, v[144:145]
	v_ashrrev_i32_e32 v33, 31, v32
	s_mov_b64 s[18:19], s[12:13]
	s_waitcnt vmcnt(12)
	v_mov_b32_e32 v28, v190
	v_mov_b32_e32 v29, v191
	v_mov_b32_e32 v30, v192
	v_mov_b32_e32 v31, v193
	v_lshlrev_b32_e32 v24, 16, v28
	v_and_b32_e32 v25, 0xffff0000, v28
	v_lshlrev_b32_e32 v26, 16, v29
	v_and_b32_e32 v27, 0xffff0000, v29
	v_lshlrev_b32_e32 v28, 16, v30
	v_and_b32_e32 v29, 0xffff0000, v30
	v_lshlrev_b32_e32 v30, 16, v31
	v_and_b32_e32 v31, 0xffff0000, v31
	v_mul_f32_e32 v20, v20, v24
	v_mul_f32_e32 v21, v21, v25
	v_mul_f32_e32 v22, v22, v26
	v_mul_f32_e32 v23, v23, v27
	v_mul_f32_e32 v15, v15, v31
	v_mul_f32_e32 v24, v12, v28
	v_mul_f32_e32 v25, v13, v29
	v_mul_f32_e32 v26, v14, v30
	v_cvt_pk_bf16_f32 v12, v20, v21
	v_cvt_pk_bf16_f32 v13, v22, v23
	v_cvt_pk_bf16_f32 v14, v24, v25
	v_cvt_pk_bf16_f32 v15, v26, v15
	s_nop 0
	global_store_dwordx4 v[36:37], v[12:15], off offset:256
	s_waitcnt vmcnt(11)
	v_mov_b32_e32 v20, v194
	v_mov_b32_e32 v21, v195
	v_mov_b32_e32 v22, v196
	v_mov_b32_e32 v23, v197
	s_nop 0
	v_lshlrev_b32_e32 v12, 16, v20
	v_and_b32_e32 v13, 0xffff0000, v20
	v_lshlrev_b32_e32 v14, 16, v21
	v_and_b32_e32 v15, 0xffff0000, v21
	v_lshlrev_b32_e32 v20, 16, v22
	v_and_b32_e32 v21, 0xffff0000, v22
	v_lshlrev_b32_e32 v22, 16, v23
	v_and_b32_e32 v23, 0xffff0000, v23
	v_mul_f32_e32 v12, v16, v12
	v_mul_f32_e32 v13, v17, v13
	v_mul_f32_e32 v14, v18, v14
	v_mul_f32_e32 v15, v19, v15
	v_mul_f32_e32 v11, v11, v23
	v_mul_f32_e32 v16, v8, v20
	v_mul_f32_e32 v17, v9, v21
	v_mul_f32_e32 v18, v10, v22
	v_cvt_pk_bf16_f32 v8, v12, v13
	v_cvt_pk_bf16_f32 v9, v14, v15
	v_cvt_pk_bf16_f32 v10, v16, v17
	v_cvt_pk_bf16_f32 v11, v18, v11
	v_lshlrev_b64 v[16:17], 11, v[32:33]
	v_lshl_add_u64 v[16:17], s[0:1], 0, v[16:17]
	v_lshl_add_u64 v[16:17], v[16:17], 0, v[144:145]
	global_store_dwordx4 v[16:17], v[8:11], off
	s_waitcnt vmcnt(10)
	v_mov_b32_e32 v12, v198
	v_mov_b32_e32 v13, v199
	v_mov_b32_e32 v14, v200
	v_mov_b32_e32 v15, v201
	s_nop 0
	v_lshlrev_b32_e32 v8, 16, v12
	v_and_b32_e32 v9, 0xffff0000, v12
	v_lshlrev_b32_e32 v10, 16, v13
	v_and_b32_e32 v11, 0xffff0000, v13
	v_lshlrev_b32_e32 v12, 16, v14
	v_and_b32_e32 v13, 0xffff0000, v14
	v_lshlrev_b32_e32 v14, 16, v15
	v_and_b32_e32 v15, 0xffff0000, v15
	v_mul_f32_e32 v3, v3, v15
	v_mul_f32_e32 v4, v4, v8
	v_mul_f32_e32 v5, v5, v9
	v_mul_f32_e32 v6, v6, v10
	v_mul_f32_e32 v7, v7, v11
	v_mul_f32_e32 v8, v0, v12
	v_mul_f32_e32 v9, v1, v13
	v_mul_f32_e32 v10, v2, v14
	v_cvt_pk_bf16_f32 v0, v4, v5
	v_cvt_pk_bf16_f32 v1, v6, v7
	v_cvt_pk_bf16_f32 v2, v8, v9
	v_cvt_pk_bf16_f32 v3, v10, v3
	global_store_dwordx4 v[16:17], v[0:3], off offset:256
	s_cbranch_vccz .LBB0_984
	s_waitcnt vmcnt(0)
	s_cmpk_gt_u32 s25, 0xff
	s_cbranch_scc1 .LBB0_995
	s_barrier

; #define PG8_STAGE(bufoff, gbase, voff) do { _Pragma("unroll") for (int _i = 0; _i < 2; ++_i) \
;         __builtin_amdgcn_global_load_lds((const unsigned*)((const char*)(gbase) + (voff)[_i]), (PG8_LAS unsigned*)(lds + (bufoff) + ldsw + _i * 8192), 16, 0, 0); } while (0)
; #define PG8_LDA(dst, b, h) do { _Pragma("unroll") for (int m = 0; m < 4; ++m) _Pragma("unroll") for (int k = 0; k < 2; ++k) dst[m][k] = *(const PG8_LAS bf16x8*)(lds + PG8_SA(b, h) + aoff + m * 2048 + k * 1024); } while (0)
; #define PG8_LDB(dst, b, h) do { _Pragma("unroll") for (int n = 0; n < 2; ++n) _Pragma("unroll") for (int k = 0; k < 2; ++k) dst[n][k] = *(const PG8_LAS bf16x8*)(lds + PG8_SB(b, h) + boff + n * 2048 + k * 1024); } while (0)
; #define PG8_MMA(ai, bj, At, Bt) do { __builtin_amdgcn_s_setprio(1); _Pragma("unroll") for (int m = 0; m < 4; ++m) _Pragma("unroll") for (int n = 0; n < 2; ++n) _Pragma("unroll") for (int k = 0; k < 2; ++k) \
;         acc[ai][bj][m][n] = __builtin_amdgcn_mfma_f32_16x16x32_bf16(Bt[n][k], At[m][k], acc[ai][bj][m][n], 0, 0, 0); __builtin_amdgcn_s_setprio(0); } while (0)
; template <class Epi, class Sched>
; __device__ __forceinline__ void gemm_phase(PG8_LAS unsigned char* lds, const Gemm g, const Sched& S, const Epi& E) {
;     ...
;         const bool has_next = S.next(ui + 1, nxt);
;         const char* nA = has_next ? (const char*)g.A + (size_t)nxt.pm * tstep : cA; const char* nB = has_next ? (const char*)g.Bt + (size_t)nxt.pn * tstep : cB;
;         for (int t = 0; t < nt; t += 2) {
;             const bool last = (t == nt - 2);
;             const char* a1 = cA + (size_t)(t + 1) * kstep;
;             const char* a2 = last ? nA : cA + (size_t)(t + 2) * kstep; const char* b2 = last ? nB : cB + (size_t)(t + 2) * kstep;
;             const char* a3 = a2 + kstep; const char* b3 = b2 + kstep;
;             if (last && has_next) S.a_ready(nxt);
;             PG8_LDB(B0, 0, 0); PG8_SCHED; PG8_LDA(At, 0, 0); PG8_STAGE(PG8_SA(1, 1), a1 + hstep, voffA);
;             PG8_WAIT_L(8); PG8_BAR; PG8_WAIT_L(0); PG8_MMA(0, 0, At, B0); PG8_BAR; PG8_SCHED;
;             PG8_LDB(B1, 0, 1); PG8_STAGE(PG8_SB(0, 0), b2, voffB);
;             PG8_BAR; PG8_WAIT_L(0); PG8_MMA(0, 1, At, B1); PG8_BAR;
;             PG8_LDA(At, 0, 1); PG8_STAGE(PG8_SA(0, 0), a2, voffA);
;             PG8_BAR; PG8_WAIT_L(0); PG8_MMA(1, 0, At, B0); PG8_BAR; PG8_SCHED;
.LBB0_1010:
	s_ashr_i32 s11, s10, 31
	v_cmp_lt_i64_e32 vcc, s[12:13], v[140:141]
	s_lshl_b64 s[12:13], s[10:11], 19
	s_add_u32 s12, s27, s12
	s_addc_u32 s13, s28, s13
	s_and_b64 s[14:15], vcc, exec
	s_cselect_b32 s11, s13, s19
	s_cselect_b32 s43, s12, s18
	s_ashr_i32 s9, s8, 31
	s_lshl_b64 s[14:15], s[8:9], 19
	s_add_u32 s14, s94, s14
	s_addc_u32 s15, s95, s15
	s_and_b64 s[22:23], vcc, exec
	s_cselect_b32 s9, s15, s21
	s_cselect_b32 s44, s14, s20
	s_add_u32 s18, s18, 0x40080
	s_addc_u32 s19, s19, 0
	s_add_u32 s45, s20, 0x100
	s_addc_u32 s46, s21, 0
	s_mov_b32 s47, -2
	ds_read_b128 v[144:147], v153
	ds_read_b128 v[156:159], v153 offset:1024
	ds_read_b128 v[160:163], v153 offset:2048
	ds_read_b128 v[164:167], v153 offset:3072
	s_add_u32 s20, s18, 0xfffc0080
	s_addc_u32 s21, s19, -1
	s_cmp_eq_u32 s47, 12
	s_cselect_b32 s23, s11, s21
	s_cselect_b32 s22, s43, s20
	s_cselect_b32 s21, s9, s46
	s_cselect_b32 s20, s44, s45
	s_add_i32 m0, s17, 0xc000
	ds_read_b128 v[168:171], v154
	ds_read_b128 v[172:175], v154 offset:1024
	ds_read_b128 v[182:185], v154 offset:2048
	ds_read_b128 v[190:193], v154 offset:3072
	ds_read_b128 v[194:197], v154 offset:4096
	ds_read_b128 v[198:201], v154 offset:5120
	ds_read_b128 v[202:205], v154 offset:6144
	ds_read_b128 v[206:209], v154 offset:7168
	global_load_lds_dwordx4 v136, s[18:19]
	s_add_i32 m0, s17, 0xe000
	s_nop 0
	global_load_lds_dwordx4 v138, s[18:19]
	s_waitcnt lgkmcnt(8)
	ds_read_b128 v[210:213], v155
	ds_read_b128 v[214:217], v155 offset:1024
	ds_read_b128 v[218:221], v155 offset:2048
	ds_read_b128 v[222:225], v155 offset:3072
	s_waitcnt vmcnt(8) lgkmcnt(0)
	s_barrier
	v_mfma_f32_16x16x32_bf16 v[124:127], v[144:147], v[168:171], 0
	v_mfma_f32_16x16x32_bf16 v[120:123], v[160:163], v[168:171], 0
	v_mfma_f32_16x16x32_bf16 v[108:111], v[144:147], v[182:185], 0
	v_mfma_f32_16x16x32_bf16 v[104:107], v[160:163], v[182:185], 0
	v_mfma_f32_16x16x32_bf16 v[92:95], v[144:147], v[194:197], 0
	v_mfma_f32_16x16x32_bf16 v[88:91], v[160:163], v[194:197], 0
	v_mfma_f32_16x16x32_bf16 v[76:79], v[144:147], v[202:205], 0
	v_mfma_f32_16x16x32_bf16 v[72:75], v[160:163], v[202:205], 0
	v_mfma_f32_16x16x32_bf16 v[124:127], v[156:159], v[172:175], v[124:127]
	v_mfma_f32_16x16x32_bf16 v[120:123], v[164:167], v[172:175], v[120:123]
	v_mfma_f32_16x16x32_bf16 v[108:111], v[156:159], v[190:193], v[108:111]
	v_mfma_f32_16x16x32_bf16 v[104:107], v[164:167], v[190:193], v[104:107]
	v_mfma_f32_16x16x32_bf16 v[92:95], v[156:159], v[198:201], v[92:95]
	v_mfma_f32_16x16x32_bf16 v[88:91], v[164:167], v[198:201], v[88:91]
	v_mfma_f32_16x16x32_bf16 v[76:79], v[156:159], v[206:209], v[76:79]
	v_mfma_f32_16x16x32_bf16 v[72:75], v[164:167], v[206:209], v[72:75]
	v_mfma_f32_16x16x32_bf16 v[116:119], v[210:213], v[168:171], 0
	v_mfma_f32_16x16x32_bf16 v[112:115], v[218:221], v[168:171], 0
	v_mfma_f32_16x16x32_bf16 v[100:103], v[210:213], v[182:185], 0
	v_mfma_f32_16x16x32_bf16 v[96:99], v[218:221], v[182:185], 0
	v_mfma_f32_16x16x32_bf16 v[84:87], v[210:213], v[194:197], 0
	v_mfma_f32_16x16x32_bf16 v[80:83], v[218:221], v[194:197], 0
	v_mfma_f32_16x16x32_bf16 v[68:71], v[210:213], v[202:205], 0
	v_mfma_f32_16x16x32_bf16 v[64:67], v[218:221], v[202:205], 0
	v_mfma_f32_16x16x32_bf16 v[116:119], v[214:217], v[172:175], v[116:119]
	v_mfma_f32_16x16x32_bf16 v[112:115], v[222:225], v[172:175], v[112:115]
	v_mfma_f32_16x16x32_bf16 v[100:103], v[214:217], v[190:193], v[100:103]
	v_mfma_f32_16x16x32_bf16 v[96:99], v[222:225], v[190:193], v[96:99]
	v_mfma_f32_16x16x32_bf16 v[84:87], v[214:217], v[198:201], v[84:87]
	v_mfma_f32_16x16x32_bf16 v[80:83], v[222:225], v[198:201], v[80:83]
	v_mfma_f32_16x16x32_bf16 v[68:71], v[214:217], v[206:209], v[68:71]
	v_mfma_f32_16x16x32_bf16 v[64:67], v[222:225], v[206:209], v[64:67]
	s_barrier
	ds_read_b128 v[168:171], v154 offset:16384
	ds_read_b128 v[172:175], v154 offset:17408
	ds_read_b128 v[182:185], v154 offset:18432
	ds_read_b128 v[190:193], v154 offset:19456
	ds_read_b128 v[194:197], v154 offset:20480
	ds_read_b128 v[198:201], v154 offset:21504
	ds_read_b128 v[202:205], v154 offset:22528
	ds_read_b128 v[206:209], v154 offset:23552
	s_add_i32 s48, s39, s29
	s_add_u32 s98, s20, s6
	s_addc_u32 s99, s21, s7
	s_mov_b32 m0, s48
	s_nop 0
	global_load_lds_dwordx4 v130, s[20:21]
	s_add_i32 m0, s48, 0x2000
	s_nop 0
	global_load_lds_dwordx4 v134, s[20:21]
	s_mov_b32 m0, s17
	s_add_u32 s100, s22, s6
	s_addc_u32 s101, s23, s7
	global_load_lds_dwordx4 v128, s[22:23]
	s_mov_b32 m0, s30
	s_nop 0
	global_load_lds_dwordx4 v132, s[22:23]
	s_add_u32 s48, s20, 0x40000
	s_addc_u32 s49, s21, 0
	s_add_i32 s50, s40, s29
	s_mov_b32 m0, s50
	s_nop 0
	global_load_lds_dwordx4 v130, s[48:49]
	s_add_i32 m0, s50, 0x2000
	s_nop 0
	global_load_lds_dwordx4 v134, s[48:49]
	s_waitcnt vmcnt(8) lgkmcnt(0)
	s_barrier
; #define PG8_STAGE(bufoff, gbase, voff) do { _Pragma("unroll") for (int _i = 0; _i < 2; ++_i) \
;         __builtin_amdgcn_global_load_lds((const unsigned*)((const char*)(gbase) + (voff)[_i]), (PG8_LAS unsigned*)(lds + (bufoff) + ldsw + _i * 8192), 16, 0, 0); } while (0)
; #define PG8_LDA(dst, b, h) do { _Pragma("unroll") for (int m = 0; m < 4; ++m) _Pragma("unroll") for (int k = 0; k < 2; ++k) dst[m][k] = *(const PG8_LAS bf16x8*)(lds + PG8_SA(b, h) + aoff + m * 2048 + k * 1024); } while (0)
; #define PG8_LDB(dst, b, h) do { _Pragma("unroll") for (int n = 0; n < 2; ++n) _Pragma("unroll") for (int k = 0; k < 2; ++k) dst[n][k] = *(const PG8_LAS bf16x8*)(lds + PG8_SB(b, h) + boff + n * 2048 + k * 1024); } while (0)
; #define PG8_MMA(ai, bj, At, Bt) do { __builtin_amdgcn_s_setprio(1); _Pragma("unroll") for (int m = 0; m < 4; ++m) _Pragma("unroll") for (int n = 0; n < 2; ++n) _Pragma("unroll") for (int k = 0; k < 2; ++k) \
;         acc[ai][bj][m][n] = __builtin_amdgcn_mfma_f32_16x16x32_bf16(Bt[n][k], At[m][k], acc[ai][bj][m][n], 0, 0, 0); __builtin_amdgcn_s_setprio(0); } while (0)
; #define PG8_WAIT_V(n) asm volatile("s_waitcnt vmcnt(" #n ")" ::: "memory")
; #define PG8_WAIT_L(n) asm volatile("s_waitcnt lgkmcnt(" #n ")" ::: "memory")
; #define PG8_BAR __builtin_amdgcn_s_barrier()
; #define PG8_SCHED __builtin_amdgcn_sched_barrier(0)
; template <class Epi, class Sched>
; __device__ __forceinline__ void gemm_phase(PG8_LAS unsigned char* lds, const Gemm g, const Sched& S, const Epi& E) {
;     ...
;             PG8_BAR; PG8_WAIT_L(0); PG8_MMA(1, 0, At, B0); PG8_BAR; PG8_SCHED;
;             PG8_STAGE(PG8_SB(0, 1), b2 + hstep, voffB);
;             PG8_WAIT_V(6); PG8_BAR; PG8_MMA(1, 1, At, B1); PG8_BAR;
;             PG8_LDB(B0, 1, 0); PG8_SCHED; PG8_LDA(At, 1, 0); PG8_STAGE(PG8_SA(0, 1), a2 + hstep, voffA);
;             PG8_WAIT_L(8); PG8_BAR; PG8_WAIT_L(0); PG8_MMA(0, 0, At, B0); PG8_BAR; PG8_SCHED;
	v_mfma_f32_16x16x32_bf16 v[60:63], v[144:147], v[168:171], 0
	v_mfma_f32_16x16x32_bf16 v[56:59], v[160:163], v[168:171], 0
	v_mfma_f32_16x16x32_bf16 v[44:47], v[144:147], v[182:185], 0
	v_mfma_f32_16x16x32_bf16 v[40:43], v[160:163], v[182:185], 0
	v_mfma_f32_16x16x32_bf16 v[28:31], v[144:147], v[194:197], 0
	v_mfma_f32_16x16x32_bf16 v[24:27], v[160:163], v[194:197], 0
	v_mfma_f32_16x16x32_bf16 v[12:15], v[144:147], v[202:205], 0
	v_mfma_f32_16x16x32_bf16 v[8:11], v[160:163], v[202:205], 0
	v_mfma_f32_16x16x32_bf16 v[60:63], v[156:159], v[172:175], v[60:63]
	v_mfma_f32_16x16x32_bf16 v[56:59], v[164:167], v[172:175], v[56:59]
	v_mfma_f32_16x16x32_bf16 v[44:47], v[156:159], v[190:193], v[44:47]
	v_mfma_f32_16x16x32_bf16 v[40:43], v[164:167], v[190:193], v[40:43]
	v_mfma_f32_16x16x32_bf16 v[28:31], v[156:159], v[198:201], v[28:31]
	v_mfma_f32_16x16x32_bf16 v[24:27], v[164:167], v[198:201], v[24:27]
	v_mfma_f32_16x16x32_bf16 v[12:15], v[156:159], v[206:209], v[12:15]
	v_mfma_f32_16x16x32_bf16 v[8:11], v[164:167], v[206:209], v[8:11]
	v_mfma_f32_16x16x32_bf16 v[52:55], v[210:213], v[168:171], 0
	v_mfma_f32_16x16x32_bf16 v[48:51], v[218:221], v[168:171], 0
	v_mfma_f32_16x16x32_bf16 v[36:39], v[210:213], v[182:185], 0
	v_mfma_f32_16x16x32_bf16 v[32:35], v[218:221], v[182:185], 0
	v_mfma_f32_16x16x32_bf16 v[20:23], v[210:213], v[194:197], 0
	v_mfma_f32_16x16x32_bf16 v[16:19], v[218:221], v[194:197], 0
	v_mfma_f32_16x16x32_bf16 v[4:7], v[210:213], v[202:205], 0
	v_mfma_f32_16x16x32_bf16 v[0:3], v[218:221], v[202:205], 0
	v_mfma_f32_16x16x32_bf16 v[52:55], v[214:217], v[172:175], v[52:55]
	v_mfma_f32_16x16x32_bf16 v[48:51], v[222:225], v[172:175], v[48:51]
	v_mfma_f32_16x16x32_bf16 v[36:39], v[214:217], v[190:193], v[36:39]
	v_mfma_f32_16x16x32_bf16 v[32:35], v[222:225], v[190:193], v[32:35]
	v_mfma_f32_16x16x32_bf16 v[20:23], v[214:217], v[198:201], v[20:23]
	v_mfma_f32_16x16x32_bf16 v[16:19], v[222:225], v[198:201], v[16:19]
	v_mfma_f32_16x16x32_bf16 v[4:7], v[214:217], v[206:209], v[4:7]
	v_mfma_f32_16x16x32_bf16 v[0:3], v[222:225], v[206:209], v[0:3]
	s_barrier
	s_add_i32 s48, 0, 0x18000
	v_add_u32_e32 v164, s48, v151
	ds_read_b128 v[144:147], v164
	ds_read_b128 v[156:159], v164 offset:1024
	ds_read_b128 v[160:163], v164 offset:2048
	ds_read_b128 v[164:167], v164 offset:3072
	s_add_u32 s22, s22, 0x40000
	s_addc_u32 s23, s23, 0
	s_mov_b32 m0, s31
	ds_read_b128 v[168:171], v154 offset:32768
	ds_read_b128 v[172:175], v154 offset:33792
	ds_read_b128 v[182:185], v154 offset:34816
	ds_read_b128 v[190:193], v154 offset:35840
	ds_read_b128 v[194:197], v154 offset:36864
	ds_read_b128 v[198:201], v154 offset:37888
	ds_read_b128 v[202:205], v154 offset:38912
	ds_read_b128 v[206:209], v154 offset:39936
	global_load_lds_dwordx4 v128, s[22:23]
	s_mov_b32 m0, s34
	s_nop 0
	global_load_lds_dwordx4 v132, s[22:23]
	s_add_i32 s22, 0, 0x1c000
	v_add_u32_e32 v179, s22, v151
	s_waitcnt lgkmcnt(8)
	ds_read_b128 v[210:213], v179
	ds_read_b128 v[214:217], v179 offset:1024
	ds_read_b128 v[218:221], v179 offset:2048
	ds_read_b128 v[222:225], v179 offset:3072
	s_waitcnt vmcnt(8) lgkmcnt(0)
	s_barrier
	v_mfma_f32_16x16x32_bf16 v[124:127], v[144:147], v[168:171], v[124:127]
	v_mfma_f32_16x16x32_bf16 v[120:123], v[160:163], v[168:171], v[120:123]
	v_mfma_f32_16x16x32_bf16 v[108:111], v[144:147], v[182:185], v[108:111]
	v_mfma_f32_16x16x32_bf16 v[104:107], v[160:163], v[182:185], v[104:107]
	v_mfma_f32_16x16x32_bf16 v[92:95], v[144:147], v[194:197], v[92:95]
	v_mfma_f32_16x16x32_bf16 v[88:91], v[160:163], v[194:197], v[88:91]
	v_mfma_f32_16x16x32_bf16 v[76:79], v[144:147], v[202:205], v[76:79]
	v_mfma_f32_16x16x32_bf16 v[72:75], v[160:163], v[202:205], v[72:75]
	v_mfma_f32_16x16x32_bf16 v[124:127], v[156:159], v[172:175], v[124:127]
	v_mfma_f32_16x16x32_bf16 v[120:123], v[164:167], v[172:175], v[120:123]
	v_mfma_f32_16x16x32_bf16 v[108:111], v[156:159], v[190:193], v[108:111]
	v_mfma_f32_16x16x32_bf16 v[104:107], v[164:167], v[190:193], v[104:107]
	v_mfma_f32_16x16x32_bf16 v[92:95], v[156:159], v[198:201], v[92:95]
	v_mfma_f32_16x16x32_bf16 v[88:91], v[164:167], v[198:201], v[88:91]
	v_mfma_f32_16x16x32_bf16 v[76:79], v[156:159], v[206:209], v[76:79]
	v_mfma_f32_16x16x32_bf16 v[72:75], v[164:167], v[206:209], v[72:75]
	v_mfma_f32_16x16x32_bf16 v[116:119], v[210:213], v[168:171], v[116:119]
	v_mfma_f32_16x16x32_bf16 v[112:115], v[218:221], v[168:171], v[112:115]
	v_mfma_f32_16x16x32_bf16 v[100:103], v[210:213], v[182:185], v[100:103]
	v_mfma_f32_16x16x32_bf16 v[96:99], v[218:221], v[182:185], v[96:99]
	v_mfma_f32_16x16x32_bf16 v[84:87], v[210:213], v[194:197], v[84:87]
	v_mfma_f32_16x16x32_bf16 v[80:83], v[218:221], v[194:197], v[80:83]
	v_mfma_f32_16x16x32_bf16 v[68:71], v[210:213], v[202:205], v[68:71]
	v_mfma_f32_16x16x32_bf16 v[64:67], v[218:221], v[202:205], v[64:67]
	v_mfma_f32_16x16x32_bf16 v[116:119], v[214:217], v[172:175], v[116:119]
	v_mfma_f32_16x16x32_bf16 v[112:115], v[222:225], v[172:175], v[112:115]
	v_mfma_f32_16x16x32_bf16 v[100:103], v[214:217], v[190:193], v[100:103]
	v_mfma_f32_16x16x32_bf16 v[96:99], v[222:225], v[190:193], v[96:99]
	v_mfma_f32_16x16x32_bf16 v[84:87], v[214:217], v[198:201], v[84:87]
	v_mfma_f32_16x16x32_bf16 v[80:83], v[222:225], v[198:201], v[80:83]
	v_mfma_f32_16x16x32_bf16 v[68:71], v[214:217], v[206:209], v[68:71]
	v_mfma_f32_16x16x32_bf16 v[64:67], v[222:225], v[206:209], v[64:67]
	s_barrier
; #define PG8_STAGE(bufoff, gbase, voff) do { _Pragma("unroll") for (int _i = 0; _i < 2; ++_i) \
;         __builtin_amdgcn_global_load_lds((const unsigned*)((const char*)(gbase) + (voff)[_i]), (PG8_LAS unsigned*)(lds + (bufoff) + ldsw + _i * 8192), 16, 0, 0); } while (0)
; #define PG8_LDA(dst, b, h) do { _Pragma("unroll") for (int m = 0; m < 4; ++m) _Pragma("unroll") for (int k = 0; k < 2; ++k) dst[m][k] = *(const PG8_LAS bf16x8*)(lds + PG8_SA(b, h) + aoff + m * 2048 + k * 1024); } while (0)
; #define PG8_LDB(dst, b, h) do { _Pragma("unroll") for (int n = 0; n < 2; ++n) _Pragma("unroll") for (int k = 0; k < 2; ++k) dst[n][k] = *(const PG8_LAS bf16x8*)(lds + PG8_SB(b, h) + boff + n * 2048 + k * 1024); } while (0)
; #define PG8_MMA(ai, bj, At, Bt) do { __builtin_amdgcn_s_setprio(1); _Pragma("unroll") for (int m = 0; m < 4; ++m) _Pragma("unroll") for (int n = 0; n < 2; ++n) _Pragma("unroll") for (int k = 0; k < 2; ++k) \
;         acc[ai][bj][m][n] = __builtin_amdgcn_mfma_f32_16x16x32_bf16(Bt[n][k], At[m][k], acc[ai][bj][m][n], 0, 0, 0); __builtin_amdgcn_s_setprio(0); } while (0)
; #define PG8_WAIT_V(n) asm volatile("s_waitcnt vmcnt(" #n ")" ::: "memory")
; #define PG8_WAIT_L(n) asm volatile("s_waitcnt lgkmcnt(" #n ")" ::: "memory")
; #define PG8_BAR __builtin_amdgcn_s_barrier()
; #define PG8_SCHED __builtin_amdgcn_sched_barrier(0)
; template <class Epi, class Sched>
; __device__ __forceinline__ void gemm_phase(PG8_LAS unsigned char* lds, const Gemm g, const Sched& S, const Epi& E) {
;     ...
;         for (int t = 0; t < nt; t += 2) {
;             const bool last = (t == nt - 2);
;             const char* a1 = cA + (size_t)(t + 1) * kstep;
;             const char* a2 = last ? nA : cA + (size_t)(t + 2) * kstep; const char* b2 = last ? nB : cB + (size_t)(t + 2) * kstep;
;             const char* a3 = a2 + kstep; const char* b3 = b2 + kstep;
;             if (last && has_next) S.a_ready(nxt);
;             PG8_LDB(B0, 0, 0); PG8_SCHED; PG8_LDA(At, 0, 0); PG8_STAGE(PG8_SA(1, 1), a1 + hstep, voffA);
;             PG8_WAIT_L(8); PG8_BAR; PG8_WAIT_L(0); PG8_MMA(0, 0, At, B0); PG8_BAR; PG8_SCHED;
;     ...
;             PG8_LDA(At, 1, 1); PG8_STAGE(PG8_SA(1, 0), a3, voffA);
;             PG8_BAR; PG8_WAIT_L(0); PG8_MMA(1, 0, At, B0); PG8_BAR; PG8_SCHED;
;             PG8_STAGE(PG8_SB(1, 1), b3 + hstep, voffB);
;             PG8_WAIT_V(6); PG8_BAR; PG8_MMA(1, 1, At, B1); PG8_BAR;
	ds_read_b128 v[168:171], v154 offset:49152
	ds_read_b128 v[172:175], v154 offset:50176
	ds_read_b128 v[182:185], v154 offset:51200
	ds_read_b128 v[190:193], v154 offset:52224
	ds_read_b128 v[194:197], v154 offset:53248
	ds_read_b128 v[198:201], v154 offset:54272
	ds_read_b128 v[202:205], v154 offset:55296
	ds_read_b128 v[206:209], v154 offset:56320
	s_add_i32 s23, s48, s29
	s_mov_b32 m0, s23
	s_nop 0
	global_load_lds_dwordx4 v130, s[98:99]
	s_add_i32 m0, s23, 0x2000
	s_nop 0
	global_load_lds_dwordx4 v134, s[98:99]
	s_mov_b32 m0, s36
	s_nop 0
	global_load_lds_dwordx4 v128, s[100:101]
	s_mov_b32 m0, s37
	s_nop 0
	global_load_lds_dwordx4 v132, s[100:101]
	s_add_u32 s20, s20, 0x40080
	s_addc_u32 s21, s21, 0
	s_add_i32 s22, s22, s29
	s_mov_b32 m0, s22
	s_nop 0
	global_load_lds_dwordx4 v130, s[20:21]
	s_add_i32 m0, s22, 0x2000
	s_nop 0
	global_load_lds_dwordx4 v134, s[20:21]
	s_waitcnt vmcnt(8) lgkmcnt(0)
	s_barrier
	v_mfma_f32_16x16x32_bf16 v[60:63], v[144:147], v[168:171], v[60:63]
	v_mfma_f32_16x16x32_bf16 v[56:59], v[160:163], v[168:171], v[56:59]
	v_mfma_f32_16x16x32_bf16 v[44:47], v[144:147], v[182:185], v[44:47]
	v_mfma_f32_16x16x32_bf16 v[40:43], v[160:163], v[182:185], v[40:43]
	v_mfma_f32_16x16x32_bf16 v[28:31], v[144:147], v[194:197], v[28:31]
	v_mfma_f32_16x16x32_bf16 v[24:27], v[160:163], v[194:197], v[24:27]
	v_mfma_f32_16x16x32_bf16 v[12:15], v[144:147], v[202:205], v[12:15]
	v_mfma_f32_16x16x32_bf16 v[8:11], v[160:163], v[202:205], v[8:11]
	v_mfma_f32_16x16x32_bf16 v[60:63], v[156:159], v[172:175], v[60:63]
	v_mfma_f32_16x16x32_bf16 v[56:59], v[164:167], v[172:175], v[56:59]
	v_mfma_f32_16x16x32_bf16 v[44:47], v[156:159], v[190:193], v[44:47]
	v_mfma_f32_16x16x32_bf16 v[40:43], v[164:167], v[190:193], v[40:43]
	v_mfma_f32_16x16x32_bf16 v[28:31], v[156:159], v[198:201], v[28:31]
	v_mfma_f32_16x16x32_bf16 v[24:27], v[164:167], v[198:201], v[24:27]
	v_mfma_f32_16x16x32_bf16 v[12:15], v[156:159], v[206:209], v[12:15]
	v_mfma_f32_16x16x32_bf16 v[8:11], v[164:167], v[206:209], v[8:11]
	v_mfma_f32_16x16x32_bf16 v[52:55], v[210:213], v[168:171], v[52:55]
	v_mfma_f32_16x16x32_bf16 v[48:51], v[218:221], v[168:171], v[48:51]
	v_mfma_f32_16x16x32_bf16 v[36:39], v[210:213], v[182:185], v[36:39]
	v_mfma_f32_16x16x32_bf16 v[32:35], v[218:221], v[182:185], v[32:35]
	v_mfma_f32_16x16x32_bf16 v[20:23], v[210:213], v[194:197], v[20:23]
	v_mfma_f32_16x16x32_bf16 v[16:19], v[218:221], v[194:197], v[16:19]
	v_mfma_f32_16x16x32_bf16 v[4:7], v[210:213], v[202:205], v[4:7]
	v_mfma_f32_16x16x32_bf16 v[0:3], v[218:221], v[202:205], v[0:3]
	v_mfma_f32_16x16x32_bf16 v[52:55], v[214:217], v[172:175], v[52:55]
	v_mfma_f32_16x16x32_bf16 v[48:51], v[222:225], v[172:175], v[48:51]
	v_mfma_f32_16x16x32_bf16 v[36:39], v[214:217], v[190:193], v[36:39]
	v_mfma_f32_16x16x32_bf16 v[32:35], v[222:225], v[190:193], v[32:35]
	v_mfma_f32_16x16x32_bf16 v[20:23], v[214:217], v[198:201], v[20:23]
	v_mfma_f32_16x16x32_bf16 v[16:19], v[222:225], v[198:201], v[16:19]
	v_mfma_f32_16x16x32_bf16 v[4:7], v[214:217], v[206:209], v[4:7]
	v_mfma_f32_16x16x32_bf16 v[0:3], v[222:225], v[206:209], v[0:3]
	s_barrier
	s_add_i32 s47, s47, 2
	s_add_u32 s18, s18, 0x100
	s_addc_u32 s19, s19, 0
	s_add_u32 s45, s45, 0x100
	s_addc_u32 s46, s46, 0
	s_cmp_gt_u32 s47, 13
.LBB0_1011:
	ds_read_b128 v[144:147], v153
	ds_read_b128 v[156:159], v153 offset:1024
	ds_read_b128 v[160:163], v153 offset:2048
	ds_read_b128 v[164:167], v153 offset:3072
	s_add_u32 s20, s18, 0xfffc0080
	s_addc_u32 s21, s19, -1
	s_cmp_eq_u32 s47, 12
	s_cselect_b32 s23, s11, s21
	s_cselect_b32 s22, s43, s20
	s_cselect_b32 s21, s9, s46
	s_cselect_b32 s20, s44, s45
	s_add_i32 m0, s17, 0xc000
	ds_read_b128 v[168:171], v154
	ds_read_b128 v[172:175], v154 offset:1024
	ds_read_b128 v[182:185], v154 offset:2048
	ds_read_b128 v[190:193], v154 offset:3072
	ds_read_b128 v[194:197], v154 offset:4096
	ds_read_b128 v[198:201], v154 offset:5120
	ds_read_b128 v[202:205], v154 offset:6144
	ds_read_b128 v[206:209], v154 offset:7168
	global_load_lds_dwordx4 v136, s[18:19]
	s_add_i32 m0, s17, 0xe000
	s_nop 0
	global_load_lds_dwordx4 v138, s[18:19]
	s_waitcnt lgkmcnt(8)
	ds_read_b128 v[210:213], v155
	ds_read_b128 v[214:217], v155 offset:1024
	ds_read_b128 v[218:221], v155 offset:2048
	ds_read_b128 v[222:225], v155 offset:3072
	s_waitcnt vmcnt(8) lgkmcnt(0)
	s_barrier
	v_mfma_f32_16x16x32_bf16 v[124:127], v[144:147], v[168:171], v[124:127]
	v_mfma_f32_16x16x32_bf16 v[120:123], v[160:163], v[168:171], v[120:123]
	v_mfma_f32_16x16x32_bf16 v[108:111], v[144:147], v[182:185], v[108:111]
	v_mfma_f32_16x16x32_bf16 v[104:107], v[160:163], v[182:185], v[104:107]
	v_mfma_f32_16x16x32_bf16 v[92:95], v[144:147], v[194:197], v[92:95]
	v_mfma_f32_16x16x32_bf16 v[88:91], v[160:163], v[194:197], v[88:91]
	v_mfma_f32_16x16x32_bf16 v[76:79], v[144:147], v[202:205], v[76:79]
	v_mfma_f32_16x16x32_bf16 v[72:75], v[160:163], v[202:205], v[72:75]
	v_mfma_f32_16x16x32_bf16 v[124:127], v[156:159], v[172:175], v[124:127]
	v_mfma_f32_16x16x32_bf16 v[120:123], v[164:167], v[172:175], v[120:123]
	v_mfma_f32_16x16x32_bf16 v[108:111], v[156:159], v[190:193], v[108:111]
	v_mfma_f32_16x16x32_bf16 v[104:107], v[164:167], v[190:193], v[104:107]
	v_mfma_f32_16x16x32_bf16 v[92:95], v[156:159], v[198:201], v[92:95]
	v_mfma_f32_16x16x32_bf16 v[88:91], v[164:167], v[198:201], v[88:91]
	v_mfma_f32_16x16x32_bf16 v[76:79], v[156:159], v[206:209], v[76:79]
	v_mfma_f32_16x16x32_bf16 v[72:75], v[164:167], v[206:209], v[72:75]
	v_mfma_f32_16x16x32_bf16 v[116:119], v[210:213], v[168:171], v[116:119]
	v_mfma_f32_16x16x32_bf16 v[112:115], v[218:221], v[168:171], v[112:115]
	v_mfma_f32_16x16x32_bf16 v[100:103], v[210:213], v[182:185], v[100:103]
	v_mfma_f32_16x16x32_bf16 v[96:99], v[218:221], v[182:185], v[96:99]
	v_mfma_f32_16x16x32_bf16 v[84:87], v[210:213], v[194:197], v[84:87]
	v_mfma_f32_16x16x32_bf16 v[80:83], v[218:221], v[194:197], v[80:83]
	v_mfma_f32_16x16x32_bf16 v[68:71], v[210:213], v[202:205], v[68:71]
	v_mfma_f32_16x16x32_bf16 v[64:67], v[218:221], v[202:205], v[64:67]
	v_mfma_f32_16x16x32_bf16 v[116:119], v[214:217], v[172:175], v[116:119]
	v_mfma_f32_16x16x32_bf16 v[112:115], v[222:225], v[172:175], v[112:115]
	v_mfma_f32_16x16x32_bf16 v[100:103], v[214:217], v[190:193], v[100:103]
	v_mfma_f32_16x16x32_bf16 v[96:99], v[222:225], v[190:193], v[96:99]
	v_mfma_f32_16x16x32_bf16 v[84:87], v[214:217], v[198:201], v[84:87]
	v_mfma_f32_16x16x32_bf16 v[80:83], v[222:225], v[198:201], v[80:83]
	v_mfma_f32_16x16x32_bf16 v[68:71], v[214:217], v[206:209], v[68:71]
	v_mfma_f32_16x16x32_bf16 v[64:67], v[222:225], v[206:209], v[64:67]
	s_barrier
; #define PG8_STAGE(bufoff, gbase, voff) do { _Pragma("unroll") for (int _i = 0; _i < 2; ++_i) \
;         __builtin_amdgcn_global_load_lds((const unsigned*)((const char*)(gbase) + (voff)[_i]), (PG8_LAS unsigned*)(lds + (bufoff) + ldsw + _i * 8192), 16, 0, 0); } while (0)
; #define PG8_LDA(dst, b, h) do { _Pragma("unroll") for (int m = 0; m < 4; ++m) _Pragma("unroll") for (int k = 0; k < 2; ++k) dst[m][k] = *(const PG8_LAS bf16x8*)(lds + PG8_SA(b, h) + aoff + m * 2048 + k * 1024); } while (0)
; #define PG8_LDB(dst, b, h) do { _Pragma("unroll") for (int n = 0; n < 2; ++n) _Pragma("unroll") for (int k = 0; k < 2; ++k) dst[n][k] = *(const PG8_LAS bf16x8*)(lds + PG8_SB(b, h) + boff + n * 2048 + k * 1024); } while (0)
; #define PG8_MMA(ai, bj, At, Bt) do { __builtin_amdgcn_s_setprio(1); _Pragma("unroll") for (int m = 0; m < 4; ++m) _Pragma("unroll") for (int n = 0; n < 2; ++n) _Pragma("unroll") for (int k = 0; k < 2; ++k) \
;         acc[ai][bj][m][n] = __builtin_amdgcn_mfma_f32_16x16x32_bf16(Bt[n][k], At[m][k], acc[ai][bj][m][n], 0, 0, 0); __builtin_amdgcn_s_setprio(0); } while (0)
; #define PG8_WAIT_V(n) asm volatile("s_waitcnt vmcnt(" #n ")" ::: "memory")
; #define PG8_WAIT_L(n) asm volatile("s_waitcnt lgkmcnt(" #n ")" ::: "memory")
; #define PG8_BAR __builtin_amdgcn_s_barrier()
; #define PG8_SCHED __builtin_amdgcn_sched_barrier(0)
; template <class Epi, class Sched>
; __device__ __forceinline__ void gemm_phase(PG8_LAS unsigned char* lds, const Gemm g, const Sched& S, const Epi& E) {
;     ...
;             PG8_LDB(B1, 0, 1); PG8_STAGE(PG8_SB(0, 0), b2, voffB);
;             PG8_BAR; PG8_WAIT_L(0); PG8_MMA(0, 1, At, B1); PG8_BAR;
;             PG8_LDA(At, 0, 1); PG8_STAGE(PG8_SA(0, 0), a2, voffA);
;             PG8_BAR; PG8_WAIT_L(0); PG8_MMA(1, 0, At, B0); PG8_BAR; PG8_SCHED;
;             PG8_STAGE(PG8_SB(0, 1), b2 + hstep, voffB);
;             PG8_WAIT_V(6); PG8_BAR; PG8_MMA(1, 1, At, B1); PG8_BAR;
;             PG8_LDB(B0, 1, 0); PG8_SCHED; PG8_LDA(At, 1, 0); PG8_STAGE(PG8_SA(0, 1), a2 + hstep, voffA);
;             PG8_WAIT_L(8); PG8_BAR; PG8_WAIT_L(0); PG8_MMA(0, 0, At, B0); PG8_BAR; PG8_SCHED;
	ds_read_b128 v[168:171], v154 offset:16384
	ds_read_b128 v[172:175], v154 offset:17408
	ds_read_b128 v[182:185], v154 offset:18432
	ds_read_b128 v[190:193], v154 offset:19456
	ds_read_b128 v[194:197], v154 offset:20480
	ds_read_b128 v[198:201], v154 offset:21504
	ds_read_b128 v[202:205], v154 offset:22528
	ds_read_b128 v[206:209], v154 offset:23552
	s_add_i32 s48, s39, s29
	s_add_u32 s98, s20, s6
	s_addc_u32 s99, s21, s7
	s_mov_b32 m0, s48
	s_nop 0
	global_load_lds_dwordx4 v130, s[20:21]
	s_add_i32 m0, s48, 0x2000
	s_nop 0
	global_load_lds_dwordx4 v134, s[20:21]
	s_mov_b32 m0, s17
	s_add_u32 s100, s22, s6
	s_addc_u32 s101, s23, s7
	global_load_lds_dwordx4 v128, s[22:23]
	s_mov_b32 m0, s30
	s_nop 0
	global_load_lds_dwordx4 v132, s[22:23]
	s_add_u32 s48, s20, 0x40000
	s_addc_u32 s49, s21, 0
	s_add_i32 s50, s40, s29
	s_mov_b32 m0, s50
	s_nop 0
	global_load_lds_dwordx4 v130, s[48:49]
	s_add_i32 m0, s50, 0x2000
	s_nop 0
	global_load_lds_dwordx4 v134, s[48:49]
	s_waitcnt vmcnt(8) lgkmcnt(0)
	s_barrier
	v_mfma_f32_16x16x32_bf16 v[60:63], v[144:147], v[168:171], v[60:63]
	v_mfma_f32_16x16x32_bf16 v[56:59], v[160:163], v[168:171], v[56:59]
	v_mfma_f32_16x16x32_bf16 v[44:47], v[144:147], v[182:185], v[44:47]
	v_mfma_f32_16x16x32_bf16 v[40:43], v[160:163], v[182:185], v[40:43]
	v_mfma_f32_16x16x32_bf16 v[28:31], v[144:147], v[194:197], v[28:31]
	v_mfma_f32_16x16x32_bf16 v[24:27], v[160:163], v[194:197], v[24:27]
	v_mfma_f32_16x16x32_bf16 v[12:15], v[144:147], v[202:205], v[12:15]
	v_mfma_f32_16x16x32_bf16 v[8:11], v[160:163], v[202:205], v[8:11]
	v_mfma_f32_16x16x32_bf16 v[60:63], v[156:159], v[172:175], v[60:63]
	v_mfma_f32_16x16x32_bf16 v[56:59], v[164:167], v[172:175], v[56:59]
	v_mfma_f32_16x16x32_bf16 v[44:47], v[156:159], v[190:193], v[44:47]
	v_mfma_f32_16x16x32_bf16 v[40:43], v[164:167], v[190:193], v[40:43]
	v_mfma_f32_16x16x32_bf16 v[28:31], v[156:159], v[198:201], v[28:31]
	v_mfma_f32_16x16x32_bf16 v[24:27], v[164:167], v[198:201], v[24:27]
	v_mfma_f32_16x16x32_bf16 v[12:15], v[156:159], v[206:209], v[12:15]
	v_mfma_f32_16x16x32_bf16 v[8:11], v[164:167], v[206:209], v[8:11]
	v_mfma_f32_16x16x32_bf16 v[52:55], v[210:213], v[168:171], v[52:55]
	v_mfma_f32_16x16x32_bf16 v[48:51], v[218:221], v[168:171], v[48:51]
	v_mfma_f32_16x16x32_bf16 v[36:39], v[210:213], v[182:185], v[36:39]
	v_mfma_f32_16x16x32_bf16 v[32:35], v[218:221], v[182:185], v[32:35]
	v_mfma_f32_16x16x32_bf16 v[20:23], v[210:213], v[194:197], v[20:23]
	v_mfma_f32_16x16x32_bf16 v[16:19], v[218:221], v[194:197], v[16:19]
	v_mfma_f32_16x16x32_bf16 v[4:7], v[210:213], v[202:205], v[4:7]
	v_mfma_f32_16x16x32_bf16 v[0:3], v[218:221], v[202:205], v[0:3]
	v_mfma_f32_16x16x32_bf16 v[52:55], v[214:217], v[172:175], v[52:55]
	v_mfma_f32_16x16x32_bf16 v[48:51], v[222:225], v[172:175], v[48:51]
	v_mfma_f32_16x16x32_bf16 v[36:39], v[214:217], v[190:193], v[36:39]
	v_mfma_f32_16x16x32_bf16 v[32:35], v[222:225], v[190:193], v[32:35]
	v_mfma_f32_16x16x32_bf16 v[20:23], v[214:217], v[198:201], v[20:23]
	v_mfma_f32_16x16x32_bf16 v[16:19], v[222:225], v[198:201], v[16:19]
	v_mfma_f32_16x16x32_bf16 v[4:7], v[214:217], v[206:209], v[4:7]
	v_mfma_f32_16x16x32_bf16 v[0:3], v[222:225], v[206:209], v[0:3]
	s_barrier
	s_add_i32 s48, 0, 0x18000
	v_add_u32_e32 v164, s48, v151
	ds_read_b128 v[144:147], v164
	ds_read_b128 v[156:159], v164 offset:1024
	ds_read_b128 v[160:163], v164 offset:2048
	ds_read_b128 v[164:167], v164 offset:3072
	s_add_u32 s22, s22, 0x40000
	s_addc_u32 s23, s23, 0
	s_mov_b32 m0, s31
	ds_read_b128 v[168:171], v154 offset:32768
	ds_read_b128 v[172:175], v154 offset:33792
	ds_read_b128 v[182:185], v154 offset:34816
	ds_read_b128 v[190:193], v154 offset:35840
	ds_read_b128 v[194:197], v154 offset:36864
	ds_read_b128 v[198:201], v154 offset:37888
	ds_read_b128 v[202:205], v154 offset:38912
	ds_read_b128 v[206:209], v154 offset:39936
	global_load_lds_dwordx4 v128, s[22:23]
	s_mov_b32 m0, s34
	s_nop 0
	global_load_lds_dwordx4 v132, s[22:23]
	s_add_i32 s22, 0, 0x1c000
	v_add_u32_e32 v179, s22, v151
	s_waitcnt lgkmcnt(8)
	ds_read_b128 v[210:213], v179
	ds_read_b128 v[214:217], v179 offset:1024
	ds_read_b128 v[218:221], v179 offset:2048
	ds_read_b128 v[222:225], v179 offset:3072
	s_waitcnt vmcnt(8) lgkmcnt(0)
	s_barrier
	v_mfma_f32_16x16x32_bf16 v[124:127], v[144:147], v[168:171], v[124:127]
	v_mfma_f32_16x16x32_bf16 v[120:123], v[160:163], v[168:171], v[120:123]
	v_mfma_f32_16x16x32_bf16 v[108:111], v[144:147], v[182:185], v[108:111]
	v_mfma_f32_16x16x32_bf16 v[104:107], v[160:163], v[182:185], v[104:107]
	v_mfma_f32_16x16x32_bf16 v[92:95], v[144:147], v[194:197], v[92:95]
	v_mfma_f32_16x16x32_bf16 v[88:91], v[160:163], v[194:197], v[88:91]
	v_mfma_f32_16x16x32_bf16 v[76:79], v[144:147], v[202:205], v[76:79]
	v_mfma_f32_16x16x32_bf16 v[72:75], v[160:163], v[202:205], v[72:75]
	v_mfma_f32_16x16x32_bf16 v[124:127], v[156:159], v[172:175], v[124:127]
	v_mfma_f32_16x16x32_bf16 v[120:123], v[164:167], v[172:175], v[120:123]
	v_mfma_f32_16x16x32_bf16 v[108:111], v[156:159], v[190:193], v[108:111]
	v_mfma_f32_16x16x32_bf16 v[104:107], v[164:167], v[190:193], v[104:107]
	v_mfma_f32_16x16x32_bf16 v[92:95], v[156:159], v[198:201], v[92:95]
	v_mfma_f32_16x16x32_bf16 v[88:91], v[164:167], v[198:201], v[88:91]
	v_mfma_f32_16x16x32_bf16 v[76:79], v[156:159], v[206:209], v[76:79]
	v_mfma_f32_16x16x32_bf16 v[72:75], v[164:167], v[206:209], v[72:75]
	v_mfma_f32_16x16x32_bf16 v[116:119], v[210:213], v[168:171], v[116:119]
	v_mfma_f32_16x16x32_bf16 v[112:115], v[218:221], v[168:171], v[112:115]
	v_mfma_f32_16x16x32_bf16 v[100:103], v[210:213], v[182:185], v[100:103]
	v_mfma_f32_16x16x32_bf16 v[96:99], v[218:221], v[182:185], v[96:99]
	v_mfma_f32_16x16x32_bf16 v[84:87], v[210:213], v[194:197], v[84:87]
	v_mfma_f32_16x16x32_bf16 v[80:83], v[218:221], v[194:197], v[80:83]
	v_mfma_f32_16x16x32_bf16 v[68:71], v[210:213], v[202:205], v[68:71]
	v_mfma_f32_16x16x32_bf16 v[64:67], v[218:221], v[202:205], v[64:67]
	v_mfma_f32_16x16x32_bf16 v[116:119], v[214:217], v[172:175], v[116:119]
	v_mfma_f32_16x16x32_bf16 v[112:115], v[222:225], v[172:175], v[112:115]
	v_mfma_f32_16x16x32_bf16 v[100:103], v[214:217], v[190:193], v[100:103]
	v_mfma_f32_16x16x32_bf16 v[96:99], v[222:225], v[190:193], v[96:99]
	v_mfma_f32_16x16x32_bf16 v[84:87], v[214:217], v[198:201], v[84:87]
	v_mfma_f32_16x16x32_bf16 v[80:83], v[222:225], v[198:201], v[80:83]
	v_mfma_f32_16x16x32_bf16 v[68:71], v[214:217], v[206:209], v[68:71]
	v_mfma_f32_16x16x32_bf16 v[64:67], v[222:225], v[206:209], v[64:67]
	s_barrier
; __device__ __forceinline__ float bf_lo(unsigned u) { return __uint_as_float(u << 16); }
; __device__ __forceinline__ float bf_hi(unsigned u) { return __uint_as_float(u & 0xffff0000u); }
; #define PG8_STAGE(bufoff, gbase, voff) do { _Pragma("unroll") for (int _i = 0; _i < 2; ++_i) \
;         __builtin_amdgcn_global_load_lds((const unsigned*)((const char*)(gbase) + (voff)[_i]), (PG8_LAS unsigned*)(lds + (bufoff) + ldsw + _i * 8192), 16, 0, 0); } while (0)
; #define PG8_LDA(dst, b, h) do { _Pragma("unroll") for (int m = 0; m < 4; ++m) _Pragma("unroll") for (int k = 0; k < 2; ++k) dst[m][k] = *(const PG8_LAS bf16x8*)(lds + PG8_SA(b, h) + aoff + m * 2048 + k * 1024); } while (0)
; #define PG8_WAIT_V(n) asm volatile("s_waitcnt vmcnt(" #n ")" ::: "memory")
;     __device__ __forceinline__ void operator()(const f32x4 (&acc)[2][2][4][2], const Unit& u, int wr, int wc, int fr, int fq) const {
;         const int row0 = u.pm * BM + wr * 64 + fr, col0 = u.pn * BM + wc * 32 + 8 * fq;
; #pragma unroll
;         for (int ai = 0; ai < 2; ++ai)
; #pragma unroll
;             for (int m = 0; m < 4; ++m) { const size_t r = (size_t)(row0 + ai * HALF + m * 16); bf16_t* rowp = O + r * ldc + col0; const bf16_t* gp = G + r * ldg + col0;
; #pragma unroll
;                 for (int bj = 0; bj < 2; ++bj) { const u32x4 gw = *(const u32x4*)(gp + bj * HALF);
;                     f32x4 v0 = acc[ai][bj][m][0], v1 = acc[ai][bj][m][1];
;                     v0[0] *= bf_lo(gw.x); v0[1] *= bf_hi(gw.x); v0[2] *= bf_lo(gw.y); v0[3] *= bf_hi(gw.y);
;                     v1[0] *= bf_lo(gw.z); v1[1] *= bf_hi(gw.z); v1[2] *= bf_lo(gw.w); v1[3] *= bf_hi(gw.w);
;                     if (ACCUM) { const u32x4 pw = *(const u32x4*)(rowp + bj * HALF);
;                         v0[0] += bf_lo(pw.x); v0[1] += bf_hi(pw.x); v0[2] += bf_lo(pw.y); v0[3] += bf_hi(pw.y);
;                         v1[0] += bf_lo(pw.z); v1[1] += bf_hi(pw.z); v1[2] += bf_lo(pw.w); v1[3] += bf_hi(pw.w); }
; template <class Epi, class Sched>
; __device__ __forceinline__ void gemm_phase(PG8_LAS unsigned char* lds, const Gemm g, const Sched& S, const Epi& E) {
;     ...
;             PG8_LDA(At, 1, 1); PG8_STAGE(PG8_SA(1, 0), a3, voffA);
;             PG8_BAR; PG8_WAIT_L(0); PG8_MMA(1, 0, At, B0); PG8_BAR; PG8_SCHED;
;             PG8_STAGE(PG8_SB(1, 1), b3 + hstep, voffB);
;             PG8_WAIT_V(6); PG8_BAR; PG8_MMA(1, 1, At, B1); PG8_BAR;
	ds_read_b128 v[168:171], v154 offset:49152
	ds_read_b128 v[172:175], v154 offset:50176
	ds_read_b128 v[182:185], v154 offset:51200
	ds_read_b128 v[190:193], v154 offset:52224
	ds_read_b128 v[194:197], v154 offset:53248
	ds_read_b128 v[198:201], v154 offset:54272
	ds_read_b128 v[202:205], v154 offset:55296
	ds_read_b128 v[206:209], v154 offset:56320
	s_add_i32 s23, s48, s29
	s_mov_b32 m0, s23
	s_nop 0
	global_load_lds_dwordx4 v130, s[98:99]
	s_add_i32 m0, s23, 0x2000
	s_nop 0
	global_load_lds_dwordx4 v134, s[98:99]
	s_mov_b32 m0, s36
	s_nop 0
	global_load_lds_dwordx4 v128, s[100:101]
	s_mov_b32 m0, s37
	s_nop 0
	global_load_lds_dwordx4 v132, s[100:101]
	s_add_u32 s20, s20, 0x40080
	s_addc_u32 s21, s21, 0
	s_add_i32 s22, s22, s29
	s_mov_b32 m0, s22
	s_nop 0
	global_load_lds_dwordx4 v130, s[20:21]
	s_add_i32 m0, s22, 0x2000
	s_nop 0
	global_load_lds_dwordx4 v134, s[20:21]
	s_waitcnt vmcnt(8) lgkmcnt(0)
	s_barrier
	v_mfma_f32_16x16x32_bf16 v[60:63], v[144:147], v[168:171], v[60:63]
	v_mfma_f32_16x16x32_bf16 v[56:59], v[160:163], v[168:171], v[56:59]
	v_mfma_f32_16x16x32_bf16 v[44:47], v[144:147], v[182:185], v[44:47]
	v_mfma_f32_16x16x32_bf16 v[40:43], v[160:163], v[182:185], v[40:43]
	v_mfma_f32_16x16x32_bf16 v[28:31], v[144:147], v[194:197], v[28:31]
	v_mfma_f32_16x16x32_bf16 v[24:27], v[160:163], v[194:197], v[24:27]
	v_mfma_f32_16x16x32_bf16 v[12:15], v[144:147], v[202:205], v[12:15]
	v_mfma_f32_16x16x32_bf16 v[8:11], v[160:163], v[202:205], v[8:11]
	v_mfma_f32_16x16x32_bf16 v[60:63], v[156:159], v[172:175], v[60:63]
	v_mfma_f32_16x16x32_bf16 v[56:59], v[164:167], v[172:175], v[56:59]
	v_mfma_f32_16x16x32_bf16 v[44:47], v[156:159], v[190:193], v[44:47]
	v_mfma_f32_16x16x32_bf16 v[40:43], v[164:167], v[190:193], v[40:43]
	v_mfma_f32_16x16x32_bf16 v[28:31], v[156:159], v[198:201], v[28:31]
	v_mfma_f32_16x16x32_bf16 v[24:27], v[164:167], v[198:201], v[24:27]
	v_mfma_f32_16x16x32_bf16 v[12:15], v[156:159], v[206:209], v[12:15]
	v_mfma_f32_16x16x32_bf16 v[8:11], v[164:167], v[206:209], v[8:11]
	v_mfma_f32_16x16x32_bf16 v[52:55], v[210:213], v[168:171], v[52:55]
	v_mfma_f32_16x16x32_bf16 v[48:51], v[218:221], v[168:171], v[48:51]
	v_mfma_f32_16x16x32_bf16 v[36:39], v[210:213], v[182:185], v[36:39]
	v_mfma_f32_16x16x32_bf16 v[32:35], v[218:221], v[182:185], v[32:35]
	v_mfma_f32_16x16x32_bf16 v[20:23], v[210:213], v[194:197], v[20:23]
	v_mfma_f32_16x16x32_bf16 v[16:19], v[218:221], v[194:197], v[16:19]
	v_mfma_f32_16x16x32_bf16 v[4:7], v[210:213], v[202:205], v[4:7]
	v_mfma_f32_16x16x32_bf16 v[0:3], v[218:221], v[202:205], v[0:3]
	v_mfma_f32_16x16x32_bf16 v[52:55], v[214:217], v[172:175], v[52:55]
	v_mfma_f32_16x16x32_bf16 v[48:51], v[222:225], v[172:175], v[48:51]
	v_mfma_f32_16x16x32_bf16 v[36:39], v[214:217], v[190:193], v[36:39]
	v_mfma_f32_16x16x32_bf16 v[32:35], v[222:225], v[190:193], v[32:35]
	v_mfma_f32_16x16x32_bf16 v[20:23], v[214:217], v[198:201], v[20:23]
	v_mfma_f32_16x16x32_bf16 v[16:19], v[222:225], v[198:201], v[16:19]
	v_mfma_f32_16x16x32_bf16 v[4:7], v[214:217], v[206:209], v[4:7]
	v_mfma_f32_16x16x32_bf16 v[0:3], v[222:225], v[206:209], v[0:3]
	s_barrier
	s_add_i32 s47, s47, 2
	s_add_u32 s18, s18, 0x100
	s_addc_u32 s19, s19, 0
	s_add_u32 s45, s45, 0x100
	s_addc_u32 s46, s46, 0
	s_cmp_gt_u32 s47, 13
	s_cbranch_scc0 .LBB0_1011
	v_lshl_add_u32 v146, s16, 8, v150
	v_lshl_or_b32 v144, s42, 8, v152
	v_ashrrev_i32_e32 v147, 31, v146
	v_ashrrev_i32_e32 v145, 31, v144
	v_mov_b64_e32 v[148:149], s[4:5]
	v_lshlrev_b64 v[160:161], 11, v[146:147]
	v_lshlrev_b64 v[144:145], 1, v[144:145]
	v_mad_i64_i32 v[156:157], s[18:19], v146, s41, v[148:149]
	v_lshl_add_u64 v[160:161], s[0:1], 0, v[160:161]
	v_lshl_add_u64 v[164:165], v[156:157], 0, v[144:145]
	v_lshl_add_u64 v[166:167], v[160:161], 0, v[144:145]
	v_mov_b64_e32 v[218:219], v[164:165]
	v_mov_b64_e32 v[220:221], v[166:167]
	s_mul_i32 s98, s41, 0
	s_mov_b32 s99, 0
	v_lshl_add_u64 v[222:223], v[218:219], 0, s[98:99]
	global_load_dwordx4 v[182:185], v[222:223], off
	s_mov_b32 s98, 0
	v_lshl_add_u64 v[224:225], v[220:221], 0, s[98:99]
	global_load_dwordx4 v[190:193], v[224:225], off
	s_mul_i32 s98, s41, 0
	s_mov_b32 s99, 0
	v_lshl_add_u64 v[222:223], v[218:219], 0, s[98:99]
	global_load_dwordx4 v[194:197], v[222:223], off offset:256
	s_mov_b32 s98, 0
	v_lshl_add_u64 v[224:225], v[220:221], 0, s[98:99]
	global_load_dwordx4 v[198:201], v[224:225], off offset:256
	s_mul_i32 s98, s41, 16
	s_mov_b32 s99, 0
	v_lshl_add_u64 v[222:223], v[218:219], 0, s[98:99]
	global_load_dwordx4 v[202:205], v[222:223], off
	s_mov_b32 s98, 32768
	v_lshl_add_u64 v[224:225], v[220:221], 0, s[98:99]
	global_load_dwordx4 v[206:209], v[224:225], off
	s_mul_i32 s98, s41, 16
	s_mov_b32 s99, 0
	v_lshl_add_u64 v[222:223], v[218:219], 0, s[98:99]
	global_load_dwordx4 v[210:213], v[222:223], off offset:256
	s_mov_b32 s98, 32768
	v_lshl_add_u64 v[224:225], v[220:221], 0, s[98:99]
	global_load_dwordx4 v[214:217], v[224:225], off offset:256
	s_and_b64 vcc, exec, s[2:3]
	s_mov_b32 s42, s8
	s_mov_b32 s16, s10
	s_mov_b64 s[20:21], s[14:15]
	s_waitcnt vmcnt(6)
; __device__ __forceinline__ unsigned cvt_pk_bf16(float lo, float hi) { unsigned r; asm volatile("v_cvt_pk_bf16_f32 %0, %1, %2" : "=v"(r) : "v"(lo), "v"(hi)); return r; }
; __device__ __forceinline__ float bf_lo(unsigned u) { return __uint_as_float(u << 16); }
; __device__ __forceinline__ float bf_hi(unsigned u) { return __uint_as_float(u & 0xffff0000u); }
;     __device__ __forceinline__ void operator()(const f32x4 (&acc)[2][2][4][2], const Unit& u, int wr, int wc, int fr, int fq) const {
;     ...
;             for (int m = 0; m < 4; ++m) { const size_t r = (size_t)(row0 + ai * HALF + m * 16); bf16_t* rowp = O + r * ldc + col0; const bf16_t* gp = G + r * ldg + col0;
; #pragma unroll
;                 for (int bj = 0; bj < 2; ++bj) { const u32x4 gw = *(const u32x4*)(gp + bj * HALF);
;                     f32x4 v0 = acc[ai][bj][m][0], v1 = acc[ai][bj][m][1];
;                     v0[0] *= bf_lo(gw.x); v0[1] *= bf_hi(gw.x); v0[2] *= bf_lo(gw.y); v0[3] *= bf_hi(gw.y);
;                     v1[0] *= bf_lo(gw.z); v1[1] *= bf_hi(gw.z); v1[2] *= bf_lo(gw.w); v1[3] *= bf_hi(gw.w);
;                     if (ACCUM) { const u32x4 pw = *(const u32x4*)(rowp + bj * HALF);
;                         v0[0] += bf_lo(pw.x); v0[1] += bf_hi(pw.x); v0[2] += bf_lo(pw.y); v0[3] += bf_hi(pw.y);
;                         v1[0] += bf_lo(pw.z); v1[1] += bf_hi(pw.z); v1[2] += bf_lo(pw.w); v1[3] += bf_hi(pw.w); }
;                     u32x4 w; w.x = cvt_pk_bf16(v0[0], v0[1]); w.y = cvt_pk_bf16(v0[2], v0[3]); w.z = cvt_pk_bf16(v1[0], v1[1]); w.w = cvt_pk_bf16(v1[2], v1[3]);
;                     *(u32x4*)(rowp + bj * HALF) = w; } }
	v_mov_b32_e32 v156, v182
	v_mov_b32_e32 v157, v183
	v_mov_b32_e32 v158, v184
	v_mov_b32_e32 v159, v185
	v_mov_b32_e32 v160, v190
	v_mov_b32_e32 v161, v191
	v_mov_b32_e32 v162, v192
	v_mov_b32_e32 v163, v193
	s_mul_i32 s98, s41, 32
	s_mov_b32 s99, 0
	v_lshl_add_u64 v[222:223], v[218:219], 0, s[98:99]
	global_load_dwordx4 v[182:185], v[222:223], off
	s_mov_b32 s98, 65536
	v_lshl_add_u64 v[224:225], v[220:221], 0, s[98:99]
	global_load_dwordx4 v[190:193], v[224:225], off
	v_lshlrev_b32_e32 v147, 16, v156
	v_and_b32_e32 v156, 0xffff0000, v156
	v_lshlrev_b32_e32 v168, 16, v157
	v_and_b32_e32 v157, 0xffff0000, v157
	v_lshlrev_b32_e32 v169, 16, v158
	v_and_b32_e32 v158, 0xffff0000, v158
	v_lshlrev_b32_e32 v170, 16, v159
	v_and_b32_e32 v159, 0xffff0000, v159
	v_lshlrev_b32_e32 v171, 16, v160
	v_and_b32_e32 v160, 0xffff0000, v160
	v_lshlrev_b32_e32 v172, 16, v161
	v_and_b32_e32 v161, 0xffff0000, v161
	v_lshlrev_b32_e32 v173, 16, v162
	v_and_b32_e32 v162, 0xffff0000, v162
	v_lshlrev_b32_e32 v174, 16, v163
	v_and_b32_e32 v163, 0xffff0000, v163
	v_fmac_f32_e32 v171, v124, v147
	v_fmac_f32_e32 v160, v125, v156
	v_fmac_f32_e32 v172, v126, v168
	v_fmac_f32_e32 v161, v127, v157
	v_fmac_f32_e32 v173, v120, v169
	v_fmac_f32_e32 v162, v121, v158
	v_fmac_f32_e32 v174, v122, v170
	v_fmac_f32_e32 v163, v123, v159
	v_cvt_pk_bf16_f32 v120, v171, v160
	v_cvt_pk_bf16_f32 v121, v172, v161
	v_cvt_pk_bf16_f32 v122, v173, v162
	v_cvt_pk_bf16_f32 v123, v174, v163
	v_or_b32_e32 v160, 16, v146
	global_store_dwordx4 v[166:167], v[120:123], off
	v_mad_i64_i32 v[162:163], s[18:19], v160, s41, v[148:149]
	v_lshl_add_u64 v[162:163], v[162:163], 0, v[144:145]
	s_waitcnt vmcnt(7)
	v_mov_b32_e32 v124, v194
	v_mov_b32_e32 v125, v195
	v_mov_b32_e32 v126, v196
	v_mov_b32_e32 v127, v197
	v_mov_b32_e32 v156, v198
	v_mov_b32_e32 v157, v199
	v_mov_b32_e32 v158, v200
	v_mov_b32_e32 v159, v201
	s_mul_i32 s98, s41, 32
	s_mov_b32 s99, 0
	v_lshl_add_u64 v[222:223], v[218:219], 0, s[98:99]
	global_load_dwordx4 v[194:197], v[222:223], off offset:256
	s_mov_b32 s98, 65536
	v_lshl_add_u64 v[224:225], v[220:221], 0, s[98:99]
	global_load_dwordx4 v[198:201], v[224:225], off offset:256
	v_lshlrev_b32_e32 v122, 16, v125
	v_lshlrev_b32_e32 v161, 16, v157
	v_lshlrev_b32_e32 v120, 16, v124
	v_and_b32_e32 v121, 0xffff0000, v124
	v_and_b32_e32 v123, 0xffff0000, v125
	v_lshlrev_b32_e32 v124, 16, v126
	v_and_b32_e32 v125, 0xffff0000, v126
	v_lshlrev_b32_e32 v147, 16, v156
	v_and_b32_e32 v156, 0xffff0000, v156
	v_and_b32_e32 v157, 0xffff0000, v157
	v_lshlrev_b32_e32 v164, 16, v158
	v_and_b32_e32 v158, 0xffff0000, v158
	v_fmac_f32_e32 v161, v118, v122
	v_fmac_f32_e32 v147, v116, v120
	v_fmac_f32_e32 v156, v117, v121
	v_fmac_f32_e32 v157, v119, v123
	v_fmac_f32_e32 v164, v112, v124
	v_fmac_f32_e32 v158, v113, v125
	v_cvt_pk_bf16_f32 v112, v147, v156
	v_cvt_pk_bf16_f32 v113, v161, v157
	v_ashrrev_i32_e32 v161, 31, v160
	v_lshlrev_b64 v[120:121], 11, v[160:161]
	v_lshl_add_u64 v[120:121], s[0:1], 0, v[120:121]
	v_lshlrev_b32_e32 v126, 16, v127
	v_and_b32_e32 v127, 0xffff0000, v127
	v_lshlrev_b32_e32 v165, 16, v159
	v_and_b32_e32 v159, 0xffff0000, v159
	v_lshl_add_u64 v[124:125], v[120:121], 0, v[144:145]
	v_fmac_f32_e32 v165, v114, v126
	v_fmac_f32_e32 v159, v115, v127
	v_cvt_pk_bf16_f32 v114, v164, v158
	v_cvt_pk_bf16_f32 v115, v165, v159
	s_waitcnt vmcnt(7)
	v_mov_b32_e32 v116, v202
	v_mov_b32_e32 v117, v203
	v_mov_b32_e32 v118, v204
	v_mov_b32_e32 v119, v205
	v_mov_b32_e32 v120, v206
	v_mov_b32_e32 v121, v207
	v_mov_b32_e32 v122, v208
	v_mov_b32_e32 v123, v209
	s_mul_i32 s98, s41, 48
	s_mov_b32 s99, 0
	v_lshl_add_u64 v[222:223], v[218:219], 0, s[98:99]
	global_load_dwordx4 v[202:205], v[222:223], off
	s_mov_b32 s98, 98304
	v_lshl_add_u64 v[224:225], v[220:221], 0, s[98:99]
	global_load_dwordx4 v[206:209], v[224:225], off
	v_lshlrev_b32_e32 v126, 16, v120
	global_store_dwordx4 v[166:167], v[112:115], off offset:256
	v_and_b32_e32 v120, 0xffff0000, v120
	v_lshlrev_b32_e32 v127, 16, v121
	v_lshlrev_b32_e32 v112, 16, v116
	v_and_b32_e32 v113, 0xffff0000, v116
	v_lshlrev_b32_e32 v114, 16, v117
	v_and_b32_e32 v115, 0xffff0000, v117
	v_lshlrev_b32_e32 v116, 16, v118
	v_and_b32_e32 v117, 0xffff0000, v118
	v_lshlrev_b32_e32 v118, 16, v119
	v_and_b32_e32 v119, 0xffff0000, v119
	v_and_b32_e32 v121, 0xffff0000, v121
	v_lshlrev_b32_e32 v147, 16, v122
	v_and_b32_e32 v122, 0xffff0000, v122
	v_lshlrev_b32_e32 v156, 16, v123
	v_and_b32_e32 v123, 0xffff0000, v123
	v_fmac_f32_e32 v126, v108, v112
	v_fmac_f32_e32 v120, v109, v113
	v_fmac_f32_e32 v127, v110, v114
	v_fmac_f32_e32 v121, v111, v115
	v_fmac_f32_e32 v147, v104, v116
	v_fmac_f32_e32 v122, v105, v117
	v_fmac_f32_e32 v156, v106, v118
	v_fmac_f32_e32 v123, v107, v119
	v_cvt_pk_bf16_f32 v104, v126, v120
	v_cvt_pk_bf16_f32 v105, v127, v121
	v_cvt_pk_bf16_f32 v106, v147, v122
	v_cvt_pk_bf16_f32 v107, v156, v123
	v_or_b32_e32 v116, 32, v146
	global_store_dwordx4 v[124:125], v[104:107], off
	v_mad_i64_i32 v[118:119], s[18:19], v116, s41, v[148:149]
	v_lshl_add_u64 v[118:119], v[118:119], 0, v[144:145]
	s_waitcnt vmcnt(9)
; __device__ __forceinline__ unsigned cvt_pk_bf16(float lo, float hi) { unsigned r; asm volatile("v_cvt_pk_bf16_f32 %0, %1, %2" : "=v"(r) : "v"(lo), "v"(hi)); return r; }
; __device__ __forceinline__ float bf_lo(unsigned u) { return __uint_as_float(u << 16); }
; __device__ __forceinline__ float bf_hi(unsigned u) { return __uint_as_float(u & 0xffff0000u); }
;     __device__ __forceinline__ void operator()(const f32x4 (&acc)[2][2][4][2], const Unit& u, int wr, int wc, int fr, int fq) const {
;     ...
;             for (int m = 0; m < 4; ++m) { const size_t r = (size_t)(row0 + ai * HALF + m * 16); bf16_t* rowp = O + r * ldc + col0; const bf16_t* gp = G + r * ldg + col0;
; #pragma unroll
;                 for (int bj = 0; bj < 2; ++bj) { const u32x4 gw = *(const u32x4*)(gp + bj * HALF);
;                     f32x4 v0 = acc[ai][bj][m][0], v1 = acc[ai][bj][m][1];
;                     v0[0] *= bf_lo(gw.x); v0[1] *= bf_hi(gw.x); v0[2] *= bf_lo(gw.y); v0[3] *= bf_hi(gw.y);
;                     v1[0] *= bf_lo(gw.z); v1[1] *= bf_hi(gw.z); v1[2] *= bf_lo(gw.w); v1[3] *= bf_hi(gw.w);
;                     if (ACCUM) { const u32x4 pw = *(const u32x4*)(rowp + bj * HALF);
;                         v0[0] += bf_lo(pw.x); v0[1] += bf_hi(pw.x); v0[2] += bf_lo(pw.y); v0[3] += bf_hi(pw.y);
;                         v1[0] += bf_lo(pw.z); v1[1] += bf_hi(pw.z); v1[2] += bf_lo(pw.w); v1[3] += bf_hi(pw.w); }
;                     u32x4 w; w.x = cvt_pk_bf16(v0[0], v0[1]); w.y = cvt_pk_bf16(v0[2], v0[3]); w.z = cvt_pk_bf16(v1[0], v1[1]); w.w = cvt_pk_bf16(v1[2], v1[3]);
;                     *(u32x4*)(rowp + bj * HALF) = w; } }
	v_mov_b32_e32 v108, v210
	v_mov_b32_e32 v109, v211
	v_mov_b32_e32 v110, v212
	v_mov_b32_e32 v111, v213
	v_mov_b32_e32 v112, v214
	v_mov_b32_e32 v113, v215
	v_mov_b32_e32 v114, v216
	v_mov_b32_e32 v115, v217
	s_mul_i32 s98, s41, 48
	s_mov_b32 s99, 0
	v_lshl_add_u64 v[222:223], v[218:219], 0, s[98:99]
	global_load_dwordx4 v[210:213], v[222:223], off offset:256
	s_mov_b32 s98, 98304
	v_lshl_add_u64 v[224:225], v[220:221], 0, s[98:99]
	global_load_dwordx4 v[214:217], v[224:225], off offset:256
	v_lshlrev_b32_e32 v104, 16, v108
	v_lshlrev_b32_e32 v117, 16, v112
	v_and_b32_e32 v105, 0xffff0000, v108
	v_lshlrev_b32_e32 v108, 16, v110
	v_and_b32_e32 v112, 0xffff0000, v112
	v_lshlrev_b32_e32 v121, 16, v114
	v_fmac_f32_e32 v117, v100, v104
	v_fmac_f32_e32 v112, v101, v105
	v_fmac_f32_e32 v121, v96, v108
	v_cvt_pk_bf16_f32 v96, v117, v112
	v_ashrrev_i32_e32 v117, 31, v116
	v_lshlrev_b64 v[104:105], 11, v[116:117]
	v_lshlrev_b32_e32 v106, 16, v109
	v_and_b32_e32 v107, 0xffff0000, v109
	v_and_b32_e32 v109, 0xffff0000, v110
	v_and_b32_e32 v114, 0xffff0000, v114
	v_lshl_add_u64 v[104:105], s[0:1], 0, v[104:105]
	v_lshlrev_b32_e32 v110, 16, v111
	v_and_b32_e32 v111, 0xffff0000, v111
	v_lshlrev_b32_e32 v120, 16, v113
	v_and_b32_e32 v113, 0xffff0000, v113
	v_lshlrev_b32_e32 v122, 16, v115
	v_and_b32_e32 v115, 0xffff0000, v115
	v_fmac_f32_e32 v114, v97, v109
	v_lshl_add_u64 v[108:109], v[104:105], 0, v[144:145]
	v_fmac_f32_e32 v120, v102, v106
	v_fmac_f32_e32 v113, v103, v107
	v_fmac_f32_e32 v122, v98, v110
	v_fmac_f32_e32 v115, v99, v111
	v_cvt_pk_bf16_f32 v97, v120, v113
	v_cvt_pk_bf16_f32 v98, v121, v114
	v_cvt_pk_bf16_f32 v99, v122, v115
	s_waitcnt vmcnt(9)
	v_mov_b32_e32 v100, v182
	v_mov_b32_e32 v101, v183
	v_mov_b32_e32 v102, v184
	v_mov_b32_e32 v103, v185
	v_mov_b32_e32 v104, v190
	v_mov_b32_e32 v105, v191
	v_mov_b32_e32 v106, v192
	v_mov_b32_e32 v107, v193
	s_mul_i32 s98, s41, 128
	s_mov_b32 s99, 0
	v_lshl_add_u64 v[222:223], v[218:219], 0, s[98:99]
	global_load_dwordx4 v[182:185], v[222:223], off
	s_mov_b32 s98, 262144
	v_lshl_add_u64 v[224:225], v[220:221], 0, s[98:99]
	global_load_dwordx4 v[190:193], v[224:225], off
	v_lshlrev_b32_e32 v110, 16, v104
	global_store_dwordx4 v[124:125], v[96:99], off offset:256
	v_and_b32_e32 v104, 0xffff0000, v104
	v_lshlrev_b32_e32 v111, 16, v105
	v_lshlrev_b32_e32 v96, 16, v100
	v_and_b32_e32 v97, 0xffff0000, v100
	v_lshlrev_b32_e32 v98, 16, v101
	v_and_b32_e32 v99, 0xffff0000, v101
	v_lshlrev_b32_e32 v100, 16, v102
	v_and_b32_e32 v101, 0xffff0000, v102
	v_lshlrev_b32_e32 v102, 16, v103
	v_and_b32_e32 v103, 0xffff0000, v103
	v_and_b32_e32 v105, 0xffff0000, v105
	v_lshlrev_b32_e32 v112, 16, v106
	v_and_b32_e32 v106, 0xffff0000, v106
	v_lshlrev_b32_e32 v113, 16, v107
	v_and_b32_e32 v107, 0xffff0000, v107
	v_fmac_f32_e32 v110, v92, v96
	v_fmac_f32_e32 v104, v93, v97
	v_fmac_f32_e32 v111, v94, v98
	v_fmac_f32_e32 v105, v95, v99
	v_fmac_f32_e32 v112, v88, v100
	v_fmac_f32_e32 v106, v89, v101
	v_fmac_f32_e32 v113, v90, v102
	v_fmac_f32_e32 v107, v91, v103
	v_cvt_pk_bf16_f32 v88, v110, v104
	v_cvt_pk_bf16_f32 v89, v111, v105
	v_cvt_pk_bf16_f32 v90, v112, v106
	v_cvt_pk_bf16_f32 v91, v113, v107
	v_or_b32_e32 v100, 48, v146
	global_store_dwordx4 v[108:109], v[88:91], off
	v_mad_i64_i32 v[102:103], s[18:19], v100, s41, v[148:149]
	v_lshl_add_u64 v[102:103], v[102:103], 0, v[144:145]
	s_waitcnt vmcnt(10)
	v_mov_b32_e32 v92, v194
	v_mov_b32_e32 v93, v195
	v_mov_b32_e32 v94, v196
	v_mov_b32_e32 v95, v197
	v_mov_b32_e32 v96, v198
	v_mov_b32_e32 v97, v199
	v_mov_b32_e32 v98, v200
	v_mov_b32_e32 v99, v201
	s_mul_i32 s98, s41, 128
	s_mov_b32 s99, 0
	v_lshl_add_u64 v[222:223], v[218:219], 0, s[98:99]
	global_load_dwordx4 v[194:197], v[222:223], off offset:256
	s_mov_b32 s98, 262144
	v_lshl_add_u64 v[224:225], v[220:221], 0, s[98:99]
	global_load_dwordx4 v[198:201], v[224:225], off offset:256
	v_lshlrev_b32_e32 v88, 16, v92
	v_lshlrev_b32_e32 v101, 16, v96
	v_and_b32_e32 v89, 0xffff0000, v92
	v_lshlrev_b32_e32 v92, 16, v94
	v_and_b32_e32 v96, 0xffff0000, v96
	v_lshlrev_b32_e32 v105, 16, v98
	v_fmac_f32_e32 v101, v84, v88
	v_fmac_f32_e32 v96, v85, v89
	v_fmac_f32_e32 v105, v80, v92
	v_cvt_pk_bf16_f32 v80, v101, v96
	v_ashrrev_i32_e32 v101, 31, v100
	v_lshlrev_b64 v[88:89], 11, v[100:101]
	v_lshlrev_b32_e32 v90, 16, v93
	v_and_b32_e32 v91, 0xffff0000, v93
	v_and_b32_e32 v93, 0xffff0000, v94
	v_and_b32_e32 v98, 0xffff0000, v98
	v_lshl_add_u64 v[88:89], s[0:1], 0, v[88:89]
	v_lshlrev_b32_e32 v94, 16, v95
	v_and_b32_e32 v95, 0xffff0000, v95
	v_lshlrev_b32_e32 v104, 16, v97
	v_and_b32_e32 v97, 0xffff0000, v97
	v_lshlrev_b32_e32 v106, 16, v99
	v_and_b32_e32 v99, 0xffff0000, v99
	v_fmac_f32_e32 v98, v81, v93
	v_lshl_add_u64 v[92:93], v[88:89], 0, v[144:145]
	v_fmac_f32_e32 v104, v86, v90
	v_fmac_f32_e32 v97, v87, v91
	v_fmac_f32_e32 v106, v82, v94
	v_fmac_f32_e32 v99, v83, v95
	v_cvt_pk_bf16_f32 v81, v104, v97
	v_cvt_pk_bf16_f32 v82, v105, v98
	v_cvt_pk_bf16_f32 v83, v106, v99
	s_waitcnt vmcnt(10)
; __device__ __forceinline__ unsigned cvt_pk_bf16(float lo, float hi) { unsigned r; asm volatile("v_cvt_pk_bf16_f32 %0, %1, %2" : "=v"(r) : "v"(lo), "v"(hi)); return r; }
; __device__ __forceinline__ float bf_lo(unsigned u) { return __uint_as_float(u << 16); }
; __device__ __forceinline__ float bf_hi(unsigned u) { return __uint_as_float(u & 0xffff0000u); }
;     __device__ __forceinline__ void operator()(const f32x4 (&acc)[2][2][4][2], const Unit& u, int wr, int wc, int fr, int fq) const {
;     ...
;             for (int m = 0; m < 4; ++m) { const size_t r = (size_t)(row0 + ai * HALF + m * 16); bf16_t* rowp = O + r * ldc + col0; const bf16_t* gp = G + r * ldg + col0;
; #pragma unroll
;                 for (int bj = 0; bj < 2; ++bj) { const u32x4 gw = *(const u32x4*)(gp + bj * HALF);
;                     f32x4 v0 = acc[ai][bj][m][0], v1 = acc[ai][bj][m][1];
;                     v0[0] *= bf_lo(gw.x); v0[1] *= bf_hi(gw.x); v0[2] *= bf_lo(gw.y); v0[3] *= bf_hi(gw.y);
;                     v1[0] *= bf_lo(gw.z); v1[1] *= bf_hi(gw.z); v1[2] *= bf_lo(gw.w); v1[3] *= bf_hi(gw.w);
;                     if (ACCUM) { const u32x4 pw = *(const u32x4*)(rowp + bj * HALF);
;                         v0[0] += bf_lo(pw.x); v0[1] += bf_hi(pw.x); v0[2] += bf_lo(pw.y); v0[3] += bf_hi(pw.y);
;                         v1[0] += bf_lo(pw.z); v1[1] += bf_hi(pw.z); v1[2] += bf_lo(pw.w); v1[3] += bf_hi(pw.w); }
;                     u32x4 w; w.x = cvt_pk_bf16(v0[0], v0[1]); w.y = cvt_pk_bf16(v0[2], v0[3]); w.z = cvt_pk_bf16(v1[0], v1[1]); w.w = cvt_pk_bf16(v1[2], v1[3]);
;                     *(u32x4*)(rowp + bj * HALF) = w; } }
	v_mov_b32_e32 v84, v202
	v_mov_b32_e32 v85, v203
	v_mov_b32_e32 v86, v204
	v_mov_b32_e32 v87, v205
	v_mov_b32_e32 v88, v206
	v_mov_b32_e32 v89, v207
	v_mov_b32_e32 v90, v208
	v_mov_b32_e32 v91, v209
	s_mul_i32 s98, s41, 144
	s_mov_b32 s99, 0
	v_lshl_add_u64 v[222:223], v[218:219], 0, s[98:99]
	global_load_dwordx4 v[202:205], v[222:223], off
	s_mov_b32 s98, 294912
	v_lshl_add_u64 v[224:225], v[220:221], 0, s[98:99]
	global_load_dwordx4 v[206:209], v[224:225], off
	v_lshlrev_b32_e32 v94, 16, v88
	global_store_dwordx4 v[108:109], v[80:83], off offset:256
	v_and_b32_e32 v88, 0xffff0000, v88
	v_lshlrev_b32_e32 v95, 16, v89
	v_lshlrev_b32_e32 v80, 16, v84
	v_and_b32_e32 v81, 0xffff0000, v84
	v_lshlrev_b32_e32 v82, 16, v85
	v_and_b32_e32 v83, 0xffff0000, v85
	v_lshlrev_b32_e32 v84, 16, v86
	v_and_b32_e32 v85, 0xffff0000, v86
	v_lshlrev_b32_e32 v86, 16, v87
	v_and_b32_e32 v87, 0xffff0000, v87
	v_and_b32_e32 v89, 0xffff0000, v89
	v_lshlrev_b32_e32 v96, 16, v90
	v_and_b32_e32 v90, 0xffff0000, v90
	v_lshlrev_b32_e32 v97, 16, v91
	v_and_b32_e32 v91, 0xffff0000, v91
	v_fmac_f32_e32 v94, v76, v80
	v_fmac_f32_e32 v88, v77, v81
	v_fmac_f32_e32 v95, v78, v82
	v_fmac_f32_e32 v89, v79, v83
	v_fmac_f32_e32 v96, v72, v84
	v_fmac_f32_e32 v90, v73, v85
	v_fmac_f32_e32 v97, v74, v86
	v_fmac_f32_e32 v91, v75, v87
	v_cvt_pk_bf16_f32 v72, v94, v88
	v_cvt_pk_bf16_f32 v73, v95, v89
	v_cvt_pk_bf16_f32 v74, v96, v90
	v_cvt_pk_bf16_f32 v75, v97, v91
	v_add_u32_e32 v84, 0x80, v146
	global_store_dwordx4 v[92:93], v[72:75], off
	v_mad_i64_i32 v[86:87], s[18:19], v84, s41, v[148:149]
	v_lshl_add_u64 v[86:87], v[86:87], 0, v[144:145]
	s_waitcnt vmcnt(10)
	v_mov_b32_e32 v76, v210
	v_mov_b32_e32 v77, v211
	v_mov_b32_e32 v78, v212
	v_mov_b32_e32 v79, v213
	v_mov_b32_e32 v80, v214
	v_mov_b32_e32 v81, v215
	v_mov_b32_e32 v82, v216
	v_mov_b32_e32 v83, v217
	s_mul_i32 s98, s41, 144
	s_mov_b32 s99, 0
	v_lshl_add_u64 v[222:223], v[218:219], 0, s[98:99]
	global_load_dwordx4 v[210:213], v[222:223], off offset:256
	s_mov_b32 s98, 294912
	v_lshl_add_u64 v[224:225], v[220:221], 0, s[98:99]
	global_load_dwordx4 v[214:217], v[224:225], off offset:256
	v_lshlrev_b32_e32 v72, 16, v76
	v_lshlrev_b32_e32 v85, 16, v80
	v_and_b32_e32 v73, 0xffff0000, v76
	v_lshlrev_b32_e32 v76, 16, v78
	v_and_b32_e32 v80, 0xffff0000, v80
	v_lshlrev_b32_e32 v89, 16, v82
	v_fmac_f32_e32 v85, v68, v72
	v_fmac_f32_e32 v80, v69, v73
	v_fmac_f32_e32 v89, v64, v76
	v_cvt_pk_bf16_f32 v64, v85, v80
	v_ashrrev_i32_e32 v85, 31, v84
	v_lshlrev_b64 v[72:73], 11, v[84:85]
	v_lshlrev_b32_e32 v74, 16, v77
	v_and_b32_e32 v75, 0xffff0000, v77
	v_and_b32_e32 v77, 0xffff0000, v78
	v_and_b32_e32 v82, 0xffff0000, v82
	v_lshl_add_u64 v[72:73], s[0:1], 0, v[72:73]
	v_lshlrev_b32_e32 v78, 16, v79
	v_and_b32_e32 v79, 0xffff0000, v79
	v_lshlrev_b32_e32 v88, 16, v81
	v_and_b32_e32 v81, 0xffff0000, v81
	v_lshlrev_b32_e32 v90, 16, v83
	v_and_b32_e32 v83, 0xffff0000, v83
	v_fmac_f32_e32 v82, v65, v77
	v_lshl_add_u64 v[76:77], v[72:73], 0, v[144:145]
	v_fmac_f32_e32 v88, v70, v74
	v_fmac_f32_e32 v81, v71, v75
	v_fmac_f32_e32 v90, v66, v78
	v_fmac_f32_e32 v83, v67, v79
	v_cvt_pk_bf16_f32 v65, v88, v81
	v_cvt_pk_bf16_f32 v66, v89, v82
	v_cvt_pk_bf16_f32 v67, v90, v83
	s_waitcnt vmcnt(10)
	v_mov_b32_e32 v68, v182
	v_mov_b32_e32 v69, v183
	v_mov_b32_e32 v70, v184
	v_mov_b32_e32 v71, v185
	v_mov_b32_e32 v72, v190
	v_mov_b32_e32 v73, v191
	v_mov_b32_e32 v74, v192
	v_mov_b32_e32 v75, v193
	s_mul_i32 s98, s41, 160
	s_mov_b32 s99, 0
	v_lshl_add_u64 v[222:223], v[218:219], 0, s[98:99]
	global_load_dwordx4 v[182:185], v[222:223], off
	s_mov_b32 s98, 327680
	v_lshl_add_u64 v[224:225], v[220:221], 0, s[98:99]
	global_load_dwordx4 v[190:193], v[224:225], off
	v_lshlrev_b32_e32 v78, 16, v72
	global_store_dwordx4 v[92:93], v[64:67], off offset:256
	v_and_b32_e32 v72, 0xffff0000, v72
	v_lshlrev_b32_e32 v79, 16, v73
	v_lshlrev_b32_e32 v64, 16, v68
	v_and_b32_e32 v65, 0xffff0000, v68
	v_lshlrev_b32_e32 v66, 16, v69
	v_and_b32_e32 v67, 0xffff0000, v69
	v_lshlrev_b32_e32 v68, 16, v70
	v_and_b32_e32 v69, 0xffff0000, v70
	v_lshlrev_b32_e32 v70, 16, v71
	v_and_b32_e32 v71, 0xffff0000, v71
	v_and_b32_e32 v73, 0xffff0000, v73
	v_lshlrev_b32_e32 v80, 16, v74
	v_and_b32_e32 v74, 0xffff0000, v74
	v_lshlrev_b32_e32 v81, 16, v75
	v_and_b32_e32 v75, 0xffff0000, v75
	v_fmac_f32_e32 v78, v60, v64
	v_fmac_f32_e32 v72, v61, v65
	v_fmac_f32_e32 v79, v62, v66
	v_fmac_f32_e32 v73, v63, v67
	v_fmac_f32_e32 v80, v56, v68
	v_fmac_f32_e32 v74, v57, v69
	v_fmac_f32_e32 v81, v58, v70
	v_fmac_f32_e32 v75, v59, v71
	v_cvt_pk_bf16_f32 v56, v78, v72
	v_cvt_pk_bf16_f32 v57, v79, v73
	v_cvt_pk_bf16_f32 v58, v80, v74
	v_cvt_pk_bf16_f32 v59, v81, v75
	v_add_u32_e32 v68, 0x90, v146
	global_store_dwordx4 v[76:77], v[56:59], off
	v_mad_i64_i32 v[70:71], s[18:19], v68, s41, v[148:149]
	v_lshl_add_u64 v[70:71], v[70:71], 0, v[144:145]
	s_waitcnt vmcnt(10)
; __device__ __forceinline__ unsigned cvt_pk_bf16(float lo, float hi) { unsigned r; asm volatile("v_cvt_pk_bf16_f32 %0, %1, %2" : "=v"(r) : "v"(lo), "v"(hi)); return r; }
; __device__ __forceinline__ float bf_lo(unsigned u) { return __uint_as_float(u << 16); }
; __device__ __forceinline__ float bf_hi(unsigned u) { return __uint_as_float(u & 0xffff0000u); }
;     __device__ __forceinline__ void operator()(const f32x4 (&acc)[2][2][4][2], const Unit& u, int wr, int wc, int fr, int fq) const {
;     ...
;             for (int m = 0; m < 4; ++m) { const size_t r = (size_t)(row0 + ai * HALF + m * 16); bf16_t* rowp = O + r * ldc + col0; const bf16_t* gp = G + r * ldg + col0;
; #pragma unroll
;                 for (int bj = 0; bj < 2; ++bj) { const u32x4 gw = *(const u32x4*)(gp + bj * HALF);
;                     f32x4 v0 = acc[ai][bj][m][0], v1 = acc[ai][bj][m][1];
;                     v0[0] *= bf_lo(gw.x); v0[1] *= bf_hi(gw.x); v0[2] *= bf_lo(gw.y); v0[3] *= bf_hi(gw.y);
;                     v1[0] *= bf_lo(gw.z); v1[1] *= bf_hi(gw.z); v1[2] *= bf_lo(gw.w); v1[3] *= bf_hi(gw.w);
;                     if (ACCUM) { const u32x4 pw = *(const u32x4*)(rowp + bj * HALF);
;                         v0[0] += bf_lo(pw.x); v0[1] += bf_hi(pw.x); v0[2] += bf_lo(pw.y); v0[3] += bf_hi(pw.y);
;                         v1[0] += bf_lo(pw.z); v1[1] += bf_hi(pw.z); v1[2] += bf_lo(pw.w); v1[3] += bf_hi(pw.w); }
;                     u32x4 w; w.x = cvt_pk_bf16(v0[0], v0[1]); w.y = cvt_pk_bf16(v0[2], v0[3]); w.z = cvt_pk_bf16(v1[0], v1[1]); w.w = cvt_pk_bf16(v1[2], v1[3]);
;                     *(u32x4*)(rowp + bj * HALF) = w; } }
	v_mov_b32_e32 v60, v194
	v_mov_b32_e32 v61, v195
	v_mov_b32_e32 v62, v196
	v_mov_b32_e32 v63, v197
	v_mov_b32_e32 v64, v198
	v_mov_b32_e32 v65, v199
	v_mov_b32_e32 v66, v200
	v_mov_b32_e32 v67, v201
	s_mul_i32 s98, s41, 160
	s_mov_b32 s99, 0
	v_lshl_add_u64 v[222:223], v[218:219], 0, s[98:99]
	global_load_dwordx4 v[194:197], v[222:223], off offset:256
	s_mov_b32 s98, 327680
	v_lshl_add_u64 v[224:225], v[220:221], 0, s[98:99]
	global_load_dwordx4 v[198:201], v[224:225], off offset:256
	v_lshlrev_b32_e32 v56, 16, v60
	v_lshlrev_b32_e32 v69, 16, v64
	v_and_b32_e32 v57, 0xffff0000, v60
	v_lshlrev_b32_e32 v60, 16, v62
	v_and_b32_e32 v64, 0xffff0000, v64
	v_lshlrev_b32_e32 v73, 16, v66
	v_fmac_f32_e32 v69, v52, v56
	v_fmac_f32_e32 v64, v53, v57
	v_fmac_f32_e32 v73, v48, v60
	v_cvt_pk_bf16_f32 v48, v69, v64
	v_ashrrev_i32_e32 v69, 31, v68
	v_lshlrev_b64 v[56:57], 11, v[68:69]
	v_lshlrev_b32_e32 v58, 16, v61
	v_and_b32_e32 v59, 0xffff0000, v61
	v_and_b32_e32 v61, 0xffff0000, v62
	v_and_b32_e32 v66, 0xffff0000, v66
	v_lshl_add_u64 v[56:57], s[0:1], 0, v[56:57]
	v_lshlrev_b32_e32 v62, 16, v63
	v_and_b32_e32 v63, 0xffff0000, v63
	v_lshlrev_b32_e32 v72, 16, v65
	v_and_b32_e32 v65, 0xffff0000, v65
	v_lshlrev_b32_e32 v74, 16, v67
	v_and_b32_e32 v67, 0xffff0000, v67
	v_fmac_f32_e32 v66, v49, v61
	v_lshl_add_u64 v[60:61], v[56:57], 0, v[144:145]
	v_fmac_f32_e32 v72, v54, v58
	v_fmac_f32_e32 v65, v55, v59
	v_fmac_f32_e32 v74, v50, v62
	v_fmac_f32_e32 v67, v51, v63
	v_cvt_pk_bf16_f32 v49, v72, v65
	v_cvt_pk_bf16_f32 v50, v73, v66
	v_cvt_pk_bf16_f32 v51, v74, v67
	s_waitcnt vmcnt(10)
	v_mov_b32_e32 v52, v202
	v_mov_b32_e32 v53, v203
	v_mov_b32_e32 v54, v204
	v_mov_b32_e32 v55, v205
	v_mov_b32_e32 v56, v206
	v_mov_b32_e32 v57, v207
	v_mov_b32_e32 v58, v208
	v_mov_b32_e32 v59, v209
	s_mul_i32 s98, s41, 176
	s_mov_b32 s99, 0
	v_lshl_add_u64 v[222:223], v[218:219], 0, s[98:99]
	global_load_dwordx4 v[202:205], v[222:223], off
	s_mov_b32 s98, 360448
	v_lshl_add_u64 v[224:225], v[220:221], 0, s[98:99]
	global_load_dwordx4 v[206:209], v[224:225], off
	v_lshlrev_b32_e32 v62, 16, v56
	global_store_dwordx4 v[76:77], v[48:51], off offset:256
	v_and_b32_e32 v56, 0xffff0000, v56
	v_lshlrev_b32_e32 v63, 16, v57
	v_lshlrev_b32_e32 v48, 16, v52
	v_and_b32_e32 v49, 0xffff0000, v52
	v_lshlrev_b32_e32 v50, 16, v53
	v_and_b32_e32 v51, 0xffff0000, v53
	v_lshlrev_b32_e32 v52, 16, v54
	v_and_b32_e32 v53, 0xffff0000, v54
	v_lshlrev_b32_e32 v54, 16, v55
	v_and_b32_e32 v55, 0xffff0000, v55
	v_and_b32_e32 v57, 0xffff0000, v57
	v_lshlrev_b32_e32 v64, 16, v58
	v_and_b32_e32 v58, 0xffff0000, v58
	v_lshlrev_b32_e32 v65, 16, v59
	v_and_b32_e32 v59, 0xffff0000, v59
	v_fmac_f32_e32 v62, v44, v48
	v_fmac_f32_e32 v56, v45, v49
	v_fmac_f32_e32 v63, v46, v50
	v_fmac_f32_e32 v57, v47, v51
	v_fmac_f32_e32 v64, v40, v52
	v_fmac_f32_e32 v58, v41, v53
	v_fmac_f32_e32 v65, v42, v54
	v_fmac_f32_e32 v59, v43, v55
	v_cvt_pk_bf16_f32 v40, v62, v56
	v_cvt_pk_bf16_f32 v41, v63, v57
	v_cvt_pk_bf16_f32 v42, v64, v58
	v_cvt_pk_bf16_f32 v43, v65, v59
	v_add_u32_e32 v52, 0xa0, v146
	global_store_dwordx4 v[60:61], v[40:43], off
	v_mad_i64_i32 v[54:55], s[18:19], v52, s41, v[148:149]
	v_lshl_add_u64 v[54:55], v[54:55], 0, v[144:145]
	s_waitcnt vmcnt(10)
	v_mov_b32_e32 v44, v210
	v_mov_b32_e32 v45, v211
	v_mov_b32_e32 v46, v212
	v_mov_b32_e32 v47, v213
	v_mov_b32_e32 v48, v214
	v_mov_b32_e32 v49, v215
	v_mov_b32_e32 v50, v216
	v_mov_b32_e32 v51, v217
	s_mul_i32 s98, s41, 176
	s_mov_b32 s99, 0
	v_lshl_add_u64 v[222:223], v[218:219], 0, s[98:99]
	global_load_dwordx4 v[210:213], v[222:223], off offset:256
	s_mov_b32 s98, 360448
	v_lshl_add_u64 v[224:225], v[220:221], 0, s[98:99]
	global_load_dwordx4 v[214:217], v[224:225], off offset:256
	v_lshlrev_b32_e32 v40, 16, v44
	v_lshlrev_b32_e32 v53, 16, v48
	v_and_b32_e32 v41, 0xffff0000, v44
	v_lshlrev_b32_e32 v44, 16, v46
	v_and_b32_e32 v48, 0xffff0000, v48
	v_lshlrev_b32_e32 v57, 16, v50
	v_fmac_f32_e32 v53, v36, v40
	v_fmac_f32_e32 v48, v37, v41
	v_fmac_f32_e32 v57, v32, v44
	v_cvt_pk_bf16_f32 v32, v53, v48
	v_ashrrev_i32_e32 v53, 31, v52
	v_lshlrev_b64 v[40:41], 11, v[52:53]
	v_lshlrev_b32_e32 v42, 16, v45
	v_and_b32_e32 v43, 0xffff0000, v45
	v_and_b32_e32 v45, 0xffff0000, v46
	v_and_b32_e32 v50, 0xffff0000, v50
	v_lshl_add_u64 v[40:41], s[0:1], 0, v[40:41]
	v_lshlrev_b32_e32 v46, 16, v47
	v_and_b32_e32 v47, 0xffff0000, v47
	v_lshlrev_b32_e32 v56, 16, v49
	v_and_b32_e32 v49, 0xffff0000, v49
	v_lshlrev_b32_e32 v58, 16, v51
	v_and_b32_e32 v51, 0xffff0000, v51
	v_fmac_f32_e32 v50, v33, v45
	v_lshl_add_u64 v[44:45], v[40:41], 0, v[144:145]
	v_fmac_f32_e32 v56, v38, v42
	v_fmac_f32_e32 v49, v39, v43
	v_fmac_f32_e32 v58, v34, v46
	v_fmac_f32_e32 v51, v35, v47
	v_cvt_pk_bf16_f32 v33, v56, v49
	v_cvt_pk_bf16_f32 v34, v57, v50
	v_cvt_pk_bf16_f32 v35, v58, v51
	s_waitcnt vmcnt(10)
; __device__ __forceinline__ unsigned cvt_pk_bf16(float lo, float hi) { unsigned r; asm volatile("v_cvt_pk_bf16_f32 %0, %1, %2" : "=v"(r) : "v"(lo), "v"(hi)); return r; }
; __device__ __forceinline__ float bf_lo(unsigned u) { return __uint_as_float(u << 16); }
; __device__ __forceinline__ float bf_hi(unsigned u) { return __uint_as_float(u & 0xffff0000u); }
; #define PG8_WAIT_V(n) asm volatile("s_waitcnt vmcnt(" #n ")" ::: "memory")
; #define PG8_BAR __builtin_amdgcn_s_barrier()
;     __device__ __forceinline__ void operator()(const f32x4 (&acc)[2][2][4][2], const Unit& u, int wr, int wc, int fr, int fq) const {
;     ...
;             for (int m = 0; m < 4; ++m) { const size_t r = (size_t)(row0 + ai * HALF + m * 16); bf16_t* rowp = O + r * ldc + col0; const bf16_t* gp = G + r * ldg + col0;
; #pragma unroll
;                 for (int bj = 0; bj < 2; ++bj) { const u32x4 gw = *(const u32x4*)(gp + bj * HALF);
;                     f32x4 v0 = acc[ai][bj][m][0], v1 = acc[ai][bj][m][1];
;                     v0[0] *= bf_lo(gw.x); v0[1] *= bf_hi(gw.x); v0[2] *= bf_lo(gw.y); v0[3] *= bf_hi(gw.y);
;                     v1[0] *= bf_lo(gw.z); v1[1] *= bf_hi(gw.z); v1[2] *= bf_lo(gw.w); v1[3] *= bf_hi(gw.w);
;                     if (ACCUM) { const u32x4 pw = *(const u32x4*)(rowp + bj * HALF);
;                         v0[0] += bf_lo(pw.x); v0[1] += bf_hi(pw.x); v0[2] += bf_lo(pw.y); v0[3] += bf_hi(pw.y);
;                         v1[0] += bf_lo(pw.z); v1[1] += bf_hi(pw.z); v1[2] += bf_lo(pw.w); v1[3] += bf_hi(pw.w); }
;                     u32x4 w; w.x = cvt_pk_bf16(v0[0], v0[1]); w.y = cvt_pk_bf16(v0[2], v0[3]); w.z = cvt_pk_bf16(v1[0], v1[1]); w.w = cvt_pk_bf16(v1[2], v1[3]);
;                     *(u32x4*)(rowp + bj * HALF) = w; } }
; template <class Epi, class Sched>
; __device__ __forceinline__ void gemm_phase(PG8_LAS unsigned char* lds, const Gemm g, const Sched& S, const Epi& E) {
;     ...
;     PG8_WAIT_V(0);
;     if (wr == 0) PG8_BAR;
;     PG8_BAR;
	v_mov_b32_e32 v36, v182
	v_mov_b32_e32 v37, v183
	v_mov_b32_e32 v38, v184
	v_mov_b32_e32 v39, v185
	v_mov_b32_e32 v40, v190
	v_mov_b32_e32 v41, v191
	v_mov_b32_e32 v42, v192
	v_mov_b32_e32 v43, v193
	v_lshlrev_b32_e32 v46, 16, v40
	global_store_dwordx4 v[60:61], v[32:35], off offset:256
	v_and_b32_e32 v40, 0xffff0000, v40
	v_lshlrev_b32_e32 v47, 16, v41
	v_lshlrev_b32_e32 v32, 16, v36
	v_and_b32_e32 v33, 0xffff0000, v36
	v_lshlrev_b32_e32 v34, 16, v37
	v_and_b32_e32 v35, 0xffff0000, v37
	v_lshlrev_b32_e32 v36, 16, v38
	v_and_b32_e32 v37, 0xffff0000, v38
	v_lshlrev_b32_e32 v38, 16, v39
	v_and_b32_e32 v39, 0xffff0000, v39
	v_and_b32_e32 v41, 0xffff0000, v41
	v_lshlrev_b32_e32 v48, 16, v42
	v_and_b32_e32 v42, 0xffff0000, v42
	v_lshlrev_b32_e32 v49, 16, v43
	v_and_b32_e32 v43, 0xffff0000, v43
	v_fmac_f32_e32 v46, v28, v32
	v_fmac_f32_e32 v40, v29, v33
	v_fmac_f32_e32 v47, v30, v34
	v_fmac_f32_e32 v41, v31, v35
	v_fmac_f32_e32 v48, v24, v36
	v_fmac_f32_e32 v42, v25, v37
	v_fmac_f32_e32 v49, v26, v38
	v_fmac_f32_e32 v43, v27, v39
	v_cvt_pk_bf16_f32 v24, v46, v40
	v_cvt_pk_bf16_f32 v25, v47, v41
	v_cvt_pk_bf16_f32 v26, v48, v42
	v_cvt_pk_bf16_f32 v27, v49, v43
	v_add_u32_e32 v36, 0xb0, v146
	global_store_dwordx4 v[44:45], v[24:27], off
	v_mad_i64_i32 v[38:39], s[18:19], v36, s41, v[148:149]
	v_lshl_add_u64 v[38:39], v[38:39], 0, v[144:145]
	s_mov_b64 s[18:19], s[12:13]
	s_waitcnt vmcnt(8)
	v_mov_b32_e32 v28, v194
	v_mov_b32_e32 v29, v195
	v_mov_b32_e32 v30, v196
	v_mov_b32_e32 v31, v197
	v_mov_b32_e32 v32, v198
	v_mov_b32_e32 v33, v199
	v_mov_b32_e32 v34, v200
	v_mov_b32_e32 v35, v201
	v_lshlrev_b32_e32 v24, 16, v28
	v_lshlrev_b32_e32 v37, 16, v32
	v_and_b32_e32 v25, 0xffff0000, v28
	v_lshlrev_b32_e32 v28, 16, v30
	v_and_b32_e32 v32, 0xffff0000, v32
	v_lshlrev_b32_e32 v41, 16, v34
	v_fmac_f32_e32 v37, v20, v24
	v_fmac_f32_e32 v32, v21, v25
	v_fmac_f32_e32 v41, v16, v28
	v_cvt_pk_bf16_f32 v16, v37, v32
	v_ashrrev_i32_e32 v37, 31, v36
	v_lshlrev_b64 v[24:25], 11, v[36:37]
	v_lshlrev_b32_e32 v26, 16, v29
	v_and_b32_e32 v27, 0xffff0000, v29
	v_and_b32_e32 v29, 0xffff0000, v30
	v_and_b32_e32 v34, 0xffff0000, v34
	v_lshl_add_u64 v[24:25], s[0:1], 0, v[24:25]
	v_lshlrev_b32_e32 v30, 16, v31
	v_and_b32_e32 v31, 0xffff0000, v31
	v_lshlrev_b32_e32 v40, 16, v33
	v_and_b32_e32 v33, 0xffff0000, v33
	v_lshlrev_b32_e32 v42, 16, v35
	v_and_b32_e32 v35, 0xffff0000, v35
	v_fmac_f32_e32 v34, v17, v29
	v_lshl_add_u64 v[28:29], v[24:25], 0, v[144:145]
	v_fmac_f32_e32 v40, v22, v26
	v_fmac_f32_e32 v33, v23, v27
	v_fmac_f32_e32 v42, v18, v30
	v_fmac_f32_e32 v35, v19, v31
	v_cvt_pk_bf16_f32 v17, v40, v33
	v_cvt_pk_bf16_f32 v18, v41, v34
	v_cvt_pk_bf16_f32 v19, v42, v35
	s_waitcnt vmcnt(6)
	v_mov_b32_e32 v20, v202
	v_mov_b32_e32 v21, v203
	v_mov_b32_e32 v22, v204
	v_mov_b32_e32 v23, v205
	v_mov_b32_e32 v24, v206
	v_mov_b32_e32 v25, v207
	v_mov_b32_e32 v26, v208
	v_mov_b32_e32 v27, v209
	v_lshlrev_b32_e32 v30, 16, v24
	global_store_dwordx4 v[44:45], v[16:19], off offset:256
	v_and_b32_e32 v24, 0xffff0000, v24
	v_lshlrev_b32_e32 v31, 16, v25
	v_lshlrev_b32_e32 v16, 16, v20
	v_and_b32_e32 v17, 0xffff0000, v20
	v_lshlrev_b32_e32 v18, 16, v21
	v_and_b32_e32 v19, 0xffff0000, v21
	v_lshlrev_b32_e32 v20, 16, v22
	v_and_b32_e32 v21, 0xffff0000, v22
	v_lshlrev_b32_e32 v22, 16, v23
	v_and_b32_e32 v23, 0xffff0000, v23
	v_and_b32_e32 v25, 0xffff0000, v25
	v_lshlrev_b32_e32 v32, 16, v26
	v_and_b32_e32 v26, 0xffff0000, v26
	v_lshlrev_b32_e32 v33, 16, v27
	v_and_b32_e32 v27, 0xffff0000, v27
	v_fmac_f32_e32 v30, v12, v16
	v_fmac_f32_e32 v24, v13, v17
	v_fmac_f32_e32 v31, v14, v18
	v_fmac_f32_e32 v25, v15, v19
	v_fmac_f32_e32 v32, v8, v20
	v_fmac_f32_e32 v26, v9, v21
	v_fmac_f32_e32 v33, v10, v22
	v_fmac_f32_e32 v27, v11, v23
	v_cvt_pk_bf16_f32 v8, v30, v24
	v_cvt_pk_bf16_f32 v9, v31, v25
	v_cvt_pk_bf16_f32 v10, v32, v26
	v_cvt_pk_bf16_f32 v11, v33, v27
	s_waitcnt vmcnt(3)
	v_mov_b32_e32 v12, v210
	v_mov_b32_e32 v13, v211
	v_mov_b32_e32 v14, v212
	v_mov_b32_e32 v15, v213
	v_mov_b32_e32 v16, v214
	v_mov_b32_e32 v17, v215
	v_mov_b32_e32 v18, v216
	v_mov_b32_e32 v19, v217
	v_lshlrev_b32_e32 v20, 16, v16
	global_store_dwordx4 v[28:29], v[8:11], off
	v_and_b32_e32 v16, 0xffff0000, v16
	v_lshlrev_b32_e32 v21, 16, v17
	v_lshlrev_b32_e32 v8, 16, v12
	v_and_b32_e32 v9, 0xffff0000, v12
	v_lshlrev_b32_e32 v10, 16, v13
	v_and_b32_e32 v11, 0xffff0000, v13
	v_lshlrev_b32_e32 v12, 16, v14
	v_and_b32_e32 v13, 0xffff0000, v14
	v_lshlrev_b32_e32 v14, 16, v15
	v_and_b32_e32 v15, 0xffff0000, v15
	v_and_b32_e32 v17, 0xffff0000, v17
	v_lshlrev_b32_e32 v22, 16, v18
	v_and_b32_e32 v18, 0xffff0000, v18
	v_lshlrev_b32_e32 v23, 16, v19
	v_and_b32_e32 v19, 0xffff0000, v19
	v_fmac_f32_e32 v20, v4, v8
	v_fmac_f32_e32 v16, v5, v9
	v_fmac_f32_e32 v21, v6, v10
	v_fmac_f32_e32 v17, v7, v11
	v_fmac_f32_e32 v22, v0, v12
	v_fmac_f32_e32 v18, v1, v13
	v_fmac_f32_e32 v23, v2, v14
	v_fmac_f32_e32 v19, v3, v15
	v_cvt_pk_bf16_f32 v0, v20, v16
	v_cvt_pk_bf16_f32 v1, v21, v17
	v_cvt_pk_bf16_f32 v2, v22, v18
	v_cvt_pk_bf16_f32 v3, v23, v19
	global_store_dwordx4 v[28:29], v[0:3], off offset:256
	s_cbranch_vccz .LBB0_1004
	s_waitcnt vmcnt(0)
	s_cmpk_gt_u32 s25, 0xff
	s_cbranch_scc1 .LBB0_1015
	s_barrier

; #define PG8_STAGE(bufoff, gbase, voff) do { _Pragma("unroll") for (int _i = 0; _i < 2; ++_i) \
;         __builtin_amdgcn_global_load_lds((const unsigned*)((const char*)(gbase) + (voff)[_i]), (PG8_LAS unsigned*)(lds + (bufoff) + ldsw + _i * 8192), 16, 0, 0); } while (0)
; #define PG8_LDA(dst, b, h) do { _Pragma("unroll") for (int m = 0; m < 4; ++m) _Pragma("unroll") for (int k = 0; k < 2; ++k) dst[m][k] = *(const PG8_LAS bf16x8*)(lds + PG8_SA(b, h) + aoff + m * 2048 + k * 1024); } while (0)
; #define PG8_LDB(dst, b, h) do { _Pragma("unroll") for (int n = 0; n < 2; ++n) _Pragma("unroll") for (int k = 0; k < 2; ++k) dst[n][k] = *(const PG8_LAS bf16x8*)(lds + PG8_SB(b, h) + boff + n * 2048 + k * 1024); } while (0)
; #define PG8_MMA(ai, bj, At, Bt) do { __builtin_amdgcn_s_setprio(1); _Pragma("unroll") for (int m = 0; m < 4; ++m) _Pragma("unroll") for (int n = 0; n < 2; ++n) _Pragma("unroll") for (int k = 0; k < 2; ++k) \
;         acc[ai][bj][m][n] = __builtin_amdgcn_mfma_f32_16x16x32_bf16(Bt[n][k], At[m][k], acc[ai][bj][m][n], 0, 0, 0); __builtin_amdgcn_s_setprio(0); } while (0)
; template <class Epi, class Sched>
; __device__ __forceinline__ void gemm_phase(PG8_LAS unsigned char* lds, const Gemm g, const Sched& S, const Epi& E) {
;     ...
;         const bool has_next = S.next(ui + 1, nxt);
;         const char* nA = has_next ? (const char*)g.A + (size_t)nxt.pm * tstep : cA; const char* nB = has_next ? (const char*)g.Bt + (size_t)nxt.pn * tstep : cB;
;         for (int t = 0; t < nt; t += 2) {
;             const bool last = (t == nt - 2);
;             const char* a1 = cA + (size_t)(t + 1) * kstep;
;             const char* a2 = last ? nA : cA + (size_t)(t + 2) * kstep; const char* b2 = last ? nB : cB + (size_t)(t + 2) * kstep;
;             const char* a3 = a2 + kstep; const char* b3 = b2 + kstep;
;             if (last && has_next) S.a_ready(nxt);
;             PG8_LDB(B0, 0, 0); PG8_SCHED; PG8_LDA(At, 0, 0); PG8_STAGE(PG8_SA(1, 1), a1 + hstep, voffA);
;             PG8_WAIT_L(8); PG8_BAR; PG8_WAIT_L(0); PG8_MMA(0, 0, At, B0); PG8_BAR; PG8_SCHED;
;             PG8_LDB(B1, 0, 1); PG8_STAGE(PG8_SB(0, 0), b2, voffB);
;             PG8_BAR; PG8_WAIT_L(0); PG8_MMA(0, 1, At, B1); PG8_BAR;
;             PG8_LDA(At, 0, 1); PG8_STAGE(PG8_SA(0, 0), a2, voffA);
;             PG8_BAR; PG8_WAIT_L(0); PG8_MMA(1, 0, At, B0); PG8_BAR; PG8_SCHED;
.LBB0_1082:
	s_ashr_i32 s17, s16, 31
	v_cmp_lt_i64_e32 vcc, s[18:19], v[140:141]
	s_lshl_b64 s[18:19], s[16:17], 19
	s_add_u32 s18, s35, s18
	s_addc_u32 s19, s36, s19
	s_and_b64 s[20:21], vcc, exec
	s_cselect_b32 s17, s19, s25
	s_cselect_b32 s52, s18, s24
	s_ashr_i32 s15, s14, 31
	s_lshl_b64 s[20:21], s[14:15], 19
	s_add_u32 s20, s72, s20
	s_addc_u32 s21, s73, s21
	s_and_b64 s[28:29], vcc, exec
	s_cselect_b32 s15, s21, s27
	s_cselect_b32 s53, s20, s26
	s_add_u32 s24, s24, 0x40080
	s_addc_u32 s25, s25, 0
	s_add_u32 s54, s26, 0x100
	s_addc_u32 s55, s27, 0
	s_mov_b32 s56, -2
	ds_read_b128 v[152:155], v149
	ds_read_b128 v[156:159], v149 offset:1024
	ds_read_b128 v[160:163], v149 offset:2048
	ds_read_b128 v[164:167], v149 offset:3072
	s_add_u32 s26, s24, 0xfffc0080
	s_addc_u32 s27, s25, -1
	s_cmp_eq_u32 s56, 12
	s_cselect_b32 s29, s17, s27
	s_cselect_b32 s28, s52, s26
	s_cselect_b32 s27, s15, s55
	s_cselect_b32 s26, s53, s54
	s_add_i32 m0, s23, 0xc000
	ds_read_b128 v[168:171], v150
	ds_read_b128 v[172:175], v150 offset:1024
	ds_read_b128 v[182:185], v150 offset:2048
	ds_read_b128 v[190:193], v150 offset:3072
	ds_read_b128 v[194:197], v150 offset:4096
	ds_read_b128 v[198:201], v150 offset:5120
	ds_read_b128 v[202:205], v150 offset:6144
	ds_read_b128 v[206:209], v150 offset:7168
	global_load_lds_dwordx4 v136, s[24:25]
	s_add_i32 m0, s23, 0xe000
	s_nop 0
	global_load_lds_dwordx4 v138, s[24:25]
	s_waitcnt lgkmcnt(8)
	ds_read_b128 v[210:213], v151
	ds_read_b128 v[214:217], v151 offset:1024
	ds_read_b128 v[218:221], v151 offset:2048
	ds_read_b128 v[222:225], v151 offset:3072
	s_waitcnt vmcnt(8) lgkmcnt(0)
	s_barrier
	v_mfma_f32_16x16x32_bf16 v[124:127], v[152:155], v[168:171], 0
	v_mfma_f32_16x16x32_bf16 v[120:123], v[160:163], v[168:171], 0
	v_mfma_f32_16x16x32_bf16 v[108:111], v[152:155], v[182:185], 0
	v_mfma_f32_16x16x32_bf16 v[104:107], v[160:163], v[182:185], 0
	v_mfma_f32_16x16x32_bf16 v[92:95], v[152:155], v[194:197], 0
	v_mfma_f32_16x16x32_bf16 v[88:91], v[160:163], v[194:197], 0
	v_mfma_f32_16x16x32_bf16 v[76:79], v[152:155], v[202:205], 0
	v_mfma_f32_16x16x32_bf16 v[72:75], v[160:163], v[202:205], 0
	v_mfma_f32_16x16x32_bf16 v[124:127], v[156:159], v[172:175], v[124:127]
	v_mfma_f32_16x16x32_bf16 v[120:123], v[164:167], v[172:175], v[120:123]
	v_mfma_f32_16x16x32_bf16 v[108:111], v[156:159], v[190:193], v[108:111]
	v_mfma_f32_16x16x32_bf16 v[104:107], v[164:167], v[190:193], v[104:107]
	v_mfma_f32_16x16x32_bf16 v[92:95], v[156:159], v[198:201], v[92:95]
	v_mfma_f32_16x16x32_bf16 v[88:91], v[164:167], v[198:201], v[88:91]
	v_mfma_f32_16x16x32_bf16 v[76:79], v[156:159], v[206:209], v[76:79]
	v_mfma_f32_16x16x32_bf16 v[72:75], v[164:167], v[206:209], v[72:75]
	v_mfma_f32_16x16x32_bf16 v[116:119], v[210:213], v[168:171], 0
	v_mfma_f32_16x16x32_bf16 v[112:115], v[218:221], v[168:171], 0
	v_mfma_f32_16x16x32_bf16 v[100:103], v[210:213], v[182:185], 0
	v_mfma_f32_16x16x32_bf16 v[96:99], v[218:221], v[182:185], 0
	v_mfma_f32_16x16x32_bf16 v[84:87], v[210:213], v[194:197], 0
	v_mfma_f32_16x16x32_bf16 v[80:83], v[218:221], v[194:197], 0
	v_mfma_f32_16x16x32_bf16 v[68:71], v[210:213], v[202:205], 0
	v_mfma_f32_16x16x32_bf16 v[64:67], v[218:221], v[202:205], 0
	v_mfma_f32_16x16x32_bf16 v[116:119], v[214:217], v[172:175], v[116:119]
	v_mfma_f32_16x16x32_bf16 v[112:115], v[222:225], v[172:175], v[112:115]
	v_mfma_f32_16x16x32_bf16 v[100:103], v[214:217], v[190:193], v[100:103]
	v_mfma_f32_16x16x32_bf16 v[96:99], v[222:225], v[190:193], v[96:99]
	v_mfma_f32_16x16x32_bf16 v[84:87], v[214:217], v[198:201], v[84:87]
	v_mfma_f32_16x16x32_bf16 v[80:83], v[222:225], v[198:201], v[80:83]
	v_mfma_f32_16x16x32_bf16 v[68:71], v[214:217], v[206:209], v[68:71]
	v_mfma_f32_16x16x32_bf16 v[64:67], v[222:225], v[206:209], v[64:67]
	s_barrier
	ds_read_b128 v[168:171], v150 offset:16384
	ds_read_b128 v[172:175], v150 offset:17408
	ds_read_b128 v[182:185], v150 offset:18432
	ds_read_b128 v[190:193], v150 offset:19456
	ds_read_b128 v[194:197], v150 offset:20480
	ds_read_b128 v[198:201], v150 offset:21504
	ds_read_b128 v[202:205], v150 offset:22528
	ds_read_b128 v[206:209], v150 offset:23552
	s_add_i32 s57, s45, s37
	s_add_u32 s98, s26, s6
	s_addc_u32 s99, s27, s7
	s_mov_b32 m0, s57
	s_nop 0
	global_load_lds_dwordx4 v130, s[26:27]
	s_add_i32 m0, s57, 0x2000
	s_nop 0
	global_load_lds_dwordx4 v134, s[26:27]
	s_mov_b32 m0, s23
	s_add_u32 s100, s28, s6
	s_addc_u32 s101, s29, s7
	global_load_lds_dwordx4 v128, s[28:29]
	s_mov_b32 m0, s38
	s_nop 0
	global_load_lds_dwordx4 v132, s[28:29]
	s_add_u32 s58, s26, 0x40000
	s_addc_u32 s59, s27, 0
	s_add_i32 s57, s46, s37
	s_mov_b32 m0, s57
	s_nop 0
	global_load_lds_dwordx4 v130, s[58:59]
	s_add_i32 m0, s57, 0x2000
	s_nop 0
	global_load_lds_dwordx4 v134, s[58:59]
	s_waitcnt vmcnt(8) lgkmcnt(0)
	s_barrier
; #define PG8_STAGE(bufoff, gbase, voff) do { _Pragma("unroll") for (int _i = 0; _i < 2; ++_i) \
;         __builtin_amdgcn_global_load_lds((const unsigned*)((const char*)(gbase) + (voff)[_i]), (PG8_LAS unsigned*)(lds + (bufoff) + ldsw + _i * 8192), 16, 0, 0); } while (0)
; #define PG8_LDA(dst, b, h) do { _Pragma("unroll") for (int m = 0; m < 4; ++m) _Pragma("unroll") for (int k = 0; k < 2; ++k) dst[m][k] = *(const PG8_LAS bf16x8*)(lds + PG8_SA(b, h) + aoff + m * 2048 + k * 1024); } while (0)
; #define PG8_LDB(dst, b, h) do { _Pragma("unroll") for (int n = 0; n < 2; ++n) _Pragma("unroll") for (int k = 0; k < 2; ++k) dst[n][k] = *(const PG8_LAS bf16x8*)(lds + PG8_SB(b, h) + boff + n * 2048 + k * 1024); } while (0)
; #define PG8_MMA(ai, bj, At, Bt) do { __builtin_amdgcn_s_setprio(1); _Pragma("unroll") for (int m = 0; m < 4; ++m) _Pragma("unroll") for (int n = 0; n < 2; ++n) _Pragma("unroll") for (int k = 0; k < 2; ++k) \
;         acc[ai][bj][m][n] = __builtin_amdgcn_mfma_f32_16x16x32_bf16(Bt[n][k], At[m][k], acc[ai][bj][m][n], 0, 0, 0); __builtin_amdgcn_s_setprio(0); } while (0)
; #define PG8_WAIT_V(n) asm volatile("s_waitcnt vmcnt(" #n ")" ::: "memory")
; #define PG8_WAIT_L(n) asm volatile("s_waitcnt lgkmcnt(" #n ")" ::: "memory")
; #define PG8_BAR __builtin_amdgcn_s_barrier()
; #define PG8_SCHED __builtin_amdgcn_sched_barrier(0)
; template <class Epi, class Sched>
; __device__ __forceinline__ void gemm_phase(PG8_LAS unsigned char* lds, const Gemm g, const Sched& S, const Epi& E) {
;     ...
;             PG8_BAR; PG8_WAIT_L(0); PG8_MMA(1, 0, At, B0); PG8_BAR; PG8_SCHED;
;             PG8_STAGE(PG8_SB(0, 1), b2 + hstep, voffB);
;             PG8_WAIT_V(6); PG8_BAR; PG8_MMA(1, 1, At, B1); PG8_BAR;
;             PG8_LDB(B0, 1, 0); PG8_SCHED; PG8_LDA(At, 1, 0); PG8_STAGE(PG8_SA(0, 1), a2 + hstep, voffA);
;             PG8_WAIT_L(8); PG8_BAR; PG8_WAIT_L(0); PG8_MMA(0, 0, At, B0); PG8_BAR; PG8_SCHED;
	v_mfma_f32_16x16x32_bf16 v[60:63], v[152:155], v[168:171], 0
	v_mfma_f32_16x16x32_bf16 v[56:59], v[160:163], v[168:171], 0
	v_mfma_f32_16x16x32_bf16 v[48:51], v[152:155], v[182:185], 0
	v_mfma_f32_16x16x32_bf16 v[40:43], v[160:163], v[182:185], 0
	v_mfma_f32_16x16x32_bf16 v[32:35], v[152:155], v[194:197], 0
	v_mfma_f32_16x16x32_bf16 v[24:27], v[160:163], v[194:197], 0
	v_mfma_f32_16x16x32_bf16 v[16:19], v[152:155], v[202:205], 0
	v_mfma_f32_16x16x32_bf16 v[8:11], v[160:163], v[202:205], 0
	v_mfma_f32_16x16x32_bf16 v[60:63], v[156:159], v[172:175], v[60:63]
	v_mfma_f32_16x16x32_bf16 v[56:59], v[164:167], v[172:175], v[56:59]
	v_mfma_f32_16x16x32_bf16 v[48:51], v[156:159], v[190:193], v[48:51]
	v_mfma_f32_16x16x32_bf16 v[40:43], v[164:167], v[190:193], v[40:43]
	v_mfma_f32_16x16x32_bf16 v[32:35], v[156:159], v[198:201], v[32:35]
	v_mfma_f32_16x16x32_bf16 v[24:27], v[164:167], v[198:201], v[24:27]
	v_mfma_f32_16x16x32_bf16 v[16:19], v[156:159], v[206:209], v[16:19]
	v_mfma_f32_16x16x32_bf16 v[8:11], v[164:167], v[206:209], v[8:11]
	v_mfma_f32_16x16x32_bf16 v[52:55], v[210:213], v[168:171], 0
	v_mfma_f32_16x16x32_bf16 v[44:47], v[218:221], v[168:171], 0
	v_mfma_f32_16x16x32_bf16 v[36:39], v[210:213], v[182:185], 0
	v_mfma_f32_16x16x32_bf16 v[28:31], v[218:221], v[182:185], 0
	v_mfma_f32_16x16x32_bf16 v[20:23], v[210:213], v[194:197], 0
	v_mfma_f32_16x16x32_bf16 v[12:15], v[218:221], v[194:197], 0
	v_mfma_f32_16x16x32_bf16 v[4:7], v[210:213], v[202:205], 0
	v_mfma_f32_16x16x32_bf16 v[0:3], v[218:221], v[202:205], 0
	v_mfma_f32_16x16x32_bf16 v[52:55], v[214:217], v[172:175], v[52:55]
	v_mfma_f32_16x16x32_bf16 v[44:47], v[222:225], v[172:175], v[44:47]
	v_mfma_f32_16x16x32_bf16 v[36:39], v[214:217], v[190:193], v[36:39]
	v_mfma_f32_16x16x32_bf16 v[28:31], v[222:225], v[190:193], v[28:31]
	v_mfma_f32_16x16x32_bf16 v[20:23], v[214:217], v[198:201], v[20:23]
	v_mfma_f32_16x16x32_bf16 v[12:15], v[222:225], v[198:201], v[12:15]
	v_mfma_f32_16x16x32_bf16 v[4:7], v[214:217], v[206:209], v[4:7]
	v_mfma_f32_16x16x32_bf16 v[0:3], v[222:225], v[206:209], v[0:3]
	s_barrier
	s_add_i32 s57, 0, 0x18000
	v_add_u32_e32 v164, s57, v147
	ds_read_b128 v[152:155], v164
	ds_read_b128 v[156:159], v164 offset:1024
	ds_read_b128 v[160:163], v164 offset:2048
	ds_read_b128 v[164:167], v164 offset:3072
	s_add_u32 s28, s28, 0x40000
	s_addc_u32 s29, s29, 0
	s_mov_b32 m0, s39
	ds_read_b128 v[168:171], v150 offset:32768
	ds_read_b128 v[172:175], v150 offset:33792
	ds_read_b128 v[182:185], v150 offset:34816
	ds_read_b128 v[190:193], v150 offset:35840
	ds_read_b128 v[194:197], v150 offset:36864
	ds_read_b128 v[198:201], v150 offset:37888
	ds_read_b128 v[202:205], v150 offset:38912
	ds_read_b128 v[206:209], v150 offset:39936
	global_load_lds_dwordx4 v128, s[28:29]
	s_mov_b32 m0, s40
	s_nop 0
	global_load_lds_dwordx4 v132, s[28:29]
	s_add_i32 s28, 0, 0x1c000
	v_add_u32_e32 v179, s28, v147
	s_waitcnt lgkmcnt(8)
	ds_read_b128 v[210:213], v179
	ds_read_b128 v[214:217], v179 offset:1024
	ds_read_b128 v[218:221], v179 offset:2048
	ds_read_b128 v[222:225], v179 offset:3072
	s_waitcnt vmcnt(8) lgkmcnt(0)
	s_barrier
	v_mfma_f32_16x16x32_bf16 v[124:127], v[152:155], v[168:171], v[124:127]
	v_mfma_f32_16x16x32_bf16 v[120:123], v[160:163], v[168:171], v[120:123]
	v_mfma_f32_16x16x32_bf16 v[108:111], v[152:155], v[182:185], v[108:111]
	v_mfma_f32_16x16x32_bf16 v[104:107], v[160:163], v[182:185], v[104:107]
	v_mfma_f32_16x16x32_bf16 v[92:95], v[152:155], v[194:197], v[92:95]
	v_mfma_f32_16x16x32_bf16 v[88:91], v[160:163], v[194:197], v[88:91]
	v_mfma_f32_16x16x32_bf16 v[76:79], v[152:155], v[202:205], v[76:79]
	v_mfma_f32_16x16x32_bf16 v[72:75], v[160:163], v[202:205], v[72:75]
	v_mfma_f32_16x16x32_bf16 v[124:127], v[156:159], v[172:175], v[124:127]
	v_mfma_f32_16x16x32_bf16 v[120:123], v[164:167], v[172:175], v[120:123]
	v_mfma_f32_16x16x32_bf16 v[108:111], v[156:159], v[190:193], v[108:111]
	v_mfma_f32_16x16x32_bf16 v[104:107], v[164:167], v[190:193], v[104:107]
	v_mfma_f32_16x16x32_bf16 v[92:95], v[156:159], v[198:201], v[92:95]
	v_mfma_f32_16x16x32_bf16 v[88:91], v[164:167], v[198:201], v[88:91]
	v_mfma_f32_16x16x32_bf16 v[76:79], v[156:159], v[206:209], v[76:79]
	v_mfma_f32_16x16x32_bf16 v[72:75], v[164:167], v[206:209], v[72:75]
	v_mfma_f32_16x16x32_bf16 v[116:119], v[210:213], v[168:171], v[116:119]
	v_mfma_f32_16x16x32_bf16 v[112:115], v[218:221], v[168:171], v[112:115]
	v_mfma_f32_16x16x32_bf16 v[100:103], v[210:213], v[182:185], v[100:103]
	v_mfma_f32_16x16x32_bf16 v[96:99], v[218:221], v[182:185], v[96:99]
	v_mfma_f32_16x16x32_bf16 v[84:87], v[210:213], v[194:197], v[84:87]
	v_mfma_f32_16x16x32_bf16 v[80:83], v[218:221], v[194:197], v[80:83]
	v_mfma_f32_16x16x32_bf16 v[68:71], v[210:213], v[202:205], v[68:71]
	v_mfma_f32_16x16x32_bf16 v[64:67], v[218:221], v[202:205], v[64:67]
	v_mfma_f32_16x16x32_bf16 v[116:119], v[214:217], v[172:175], v[116:119]
	v_mfma_f32_16x16x32_bf16 v[112:115], v[222:225], v[172:175], v[112:115]
	v_mfma_f32_16x16x32_bf16 v[100:103], v[214:217], v[190:193], v[100:103]
	v_mfma_f32_16x16x32_bf16 v[96:99], v[222:225], v[190:193], v[96:99]
	v_mfma_f32_16x16x32_bf16 v[84:87], v[214:217], v[198:201], v[84:87]
	v_mfma_f32_16x16x32_bf16 v[80:83], v[222:225], v[198:201], v[80:83]
	v_mfma_f32_16x16x32_bf16 v[68:71], v[214:217], v[206:209], v[68:71]
	v_mfma_f32_16x16x32_bf16 v[64:67], v[222:225], v[206:209], v[64:67]
	s_barrier
; #define PG8_STAGE(bufoff, gbase, voff) do { _Pragma("unroll") for (int _i = 0; _i < 2; ++_i) \
;         __builtin_amdgcn_global_load_lds((const unsigned*)((const char*)(gbase) + (voff)[_i]), (PG8_LAS unsigned*)(lds + (bufoff) + ldsw + _i * 8192), 16, 0, 0); } while (0)
; #define PG8_LDA(dst, b, h) do { _Pragma("unroll") for (int m = 0; m < 4; ++m) _Pragma("unroll") for (int k = 0; k < 2; ++k) dst[m][k] = *(const PG8_LAS bf16x8*)(lds + PG8_SA(b, h) + aoff + m * 2048 + k * 1024); } while (0)
; #define PG8_LDB(dst, b, h) do { _Pragma("unroll") for (int n = 0; n < 2; ++n) _Pragma("unroll") for (int k = 0; k < 2; ++k) dst[n][k] = *(const PG8_LAS bf16x8*)(lds + PG8_SB(b, h) + boff + n * 2048 + k * 1024); } while (0)
; #define PG8_WAIT_V(n) asm volatile("s_waitcnt vmcnt(" #n ")" ::: "memory")
; #define PG8_WAIT_L(n) asm volatile("s_waitcnt lgkmcnt(" #n ")" ::: "memory")
; #define PG8_BAR __builtin_amdgcn_s_barrier()
; #define PG8_SCHED __builtin_amdgcn_sched_barrier(0)
; template <class Epi, class Sched>
; __device__ __forceinline__ void gemm_phase(PG8_LAS unsigned char* lds, const Gemm g, const Sched& S, const Epi& E) {
;     ...
;             PG8_LDB(B0, 0, 0); PG8_SCHED; PG8_LDA(At, 0, 0); PG8_STAGE(PG8_SA(1, 1), a1 + hstep, voffA);
;             PG8_WAIT_L(8); PG8_BAR; PG8_WAIT_L(0); PG8_MMA(0, 0, At, B0); PG8_BAR; PG8_SCHED;
;             PG8_LDB(B1, 0, 1); PG8_STAGE(PG8_SB(0, 0), b2, voffB);
;             PG8_BAR; PG8_WAIT_L(0); PG8_MMA(0, 1, At, B1); PG8_BAR;
;             PG8_LDA(At, 0, 1); PG8_STAGE(PG8_SA(0, 0), a2, voffA);
;             PG8_BAR; PG8_WAIT_L(0); PG8_MMA(1, 0, At, B0); PG8_BAR; PG8_SCHED;
;             PG8_STAGE(PG8_SB(0, 1), b2 + hstep, voffB);
;             PG8_WAIT_V(6); PG8_BAR; PG8_MMA(1, 1, At, B1); PG8_BAR;
;             PG8_LDB(B0, 1, 0); PG8_SCHED; PG8_LDA(At, 1, 0); PG8_STAGE(PG8_SA(0, 1), a2 + hstep, voffA);
;             PG8_WAIT_L(8); PG8_BAR; PG8_WAIT_L(0); PG8_MMA(0, 0, At, B0); PG8_BAR; PG8_SCHED;
;             PG8_LDB(B1, 1, 1); PG8_STAGE(PG8_SB(1, 0), b3, voffB);
;             PG8_BAR; PG8_WAIT_L(0); PG8_MMA(0, 1, At, B1); PG8_BAR;
;             PG8_LDA(At, 1, 1); PG8_STAGE(PG8_SA(1, 0), a3, voffA);
;             PG8_BAR; PG8_WAIT_L(0); PG8_MMA(1, 0, At, B0); PG8_BAR; PG8_SCHED;
;             PG8_STAGE(PG8_SB(1, 1), b3 + hstep, voffB);
;             PG8_WAIT_V(6); PG8_BAR; PG8_MMA(1, 1, At, B1); PG8_BAR;
	ds_read_b128 v[168:171], v150 offset:49152
	ds_read_b128 v[172:175], v150 offset:50176
	ds_read_b128 v[182:185], v150 offset:51200
	ds_read_b128 v[190:193], v150 offset:52224
	ds_read_b128 v[194:197], v150 offset:53248
	ds_read_b128 v[198:201], v150 offset:54272
	ds_read_b128 v[202:205], v150 offset:55296
	ds_read_b128 v[206:209], v150 offset:56320
	s_add_i32 s29, s57, s37
	s_mov_b32 m0, s29
	s_nop 0
	global_load_lds_dwordx4 v130, s[98:99]
	s_add_i32 m0, s29, 0x2000
	s_nop 0
	global_load_lds_dwordx4 v134, s[98:99]
	s_mov_b32 m0, s42
	s_nop 0
	global_load_lds_dwordx4 v128, s[100:101]
	s_mov_b32 m0, s43
	s_nop 0
	global_load_lds_dwordx4 v132, s[100:101]
	s_add_u32 s26, s26, 0x40080
	s_addc_u32 s27, s27, 0
	s_add_i32 s28, s28, s37
	s_mov_b32 m0, s28
	s_nop 0
	global_load_lds_dwordx4 v130, s[26:27]
	s_add_i32 m0, s28, 0x2000
	s_nop 0
	global_load_lds_dwordx4 v134, s[26:27]
	s_waitcnt vmcnt(8) lgkmcnt(0)
	s_barrier
	v_mfma_f32_16x16x32_bf16 v[60:63], v[152:155], v[168:171], v[60:63]
	v_mfma_f32_16x16x32_bf16 v[56:59], v[160:163], v[168:171], v[56:59]
	v_mfma_f32_16x16x32_bf16 v[48:51], v[152:155], v[182:185], v[48:51]
	v_mfma_f32_16x16x32_bf16 v[40:43], v[160:163], v[182:185], v[40:43]
	v_mfma_f32_16x16x32_bf16 v[32:35], v[152:155], v[194:197], v[32:35]
	v_mfma_f32_16x16x32_bf16 v[24:27], v[160:163], v[194:197], v[24:27]
	v_mfma_f32_16x16x32_bf16 v[16:19], v[152:155], v[202:205], v[16:19]
	v_mfma_f32_16x16x32_bf16 v[8:11], v[160:163], v[202:205], v[8:11]
	v_mfma_f32_16x16x32_bf16 v[60:63], v[156:159], v[172:175], v[60:63]
	v_mfma_f32_16x16x32_bf16 v[56:59], v[164:167], v[172:175], v[56:59]
	v_mfma_f32_16x16x32_bf16 v[48:51], v[156:159], v[190:193], v[48:51]
	v_mfma_f32_16x16x32_bf16 v[40:43], v[164:167], v[190:193], v[40:43]
	v_mfma_f32_16x16x32_bf16 v[32:35], v[156:159], v[198:201], v[32:35]
	v_mfma_f32_16x16x32_bf16 v[24:27], v[164:167], v[198:201], v[24:27]
	v_mfma_f32_16x16x32_bf16 v[16:19], v[156:159], v[206:209], v[16:19]
	v_mfma_f32_16x16x32_bf16 v[8:11], v[164:167], v[206:209], v[8:11]
	v_mfma_f32_16x16x32_bf16 v[52:55], v[210:213], v[168:171], v[52:55]
	v_mfma_f32_16x16x32_bf16 v[44:47], v[218:221], v[168:171], v[44:47]
	v_mfma_f32_16x16x32_bf16 v[36:39], v[210:213], v[182:185], v[36:39]
	v_mfma_f32_16x16x32_bf16 v[28:31], v[218:221], v[182:185], v[28:31]
	v_mfma_f32_16x16x32_bf16 v[20:23], v[210:213], v[194:197], v[20:23]
	v_mfma_f32_16x16x32_bf16 v[12:15], v[218:221], v[194:197], v[12:15]
	v_mfma_f32_16x16x32_bf16 v[4:7], v[210:213], v[202:205], v[4:7]
	v_mfma_f32_16x16x32_bf16 v[0:3], v[218:221], v[202:205], v[0:3]
	v_mfma_f32_16x16x32_bf16 v[52:55], v[214:217], v[172:175], v[52:55]
	v_mfma_f32_16x16x32_bf16 v[44:47], v[222:225], v[172:175], v[44:47]
	v_mfma_f32_16x16x32_bf16 v[36:39], v[214:217], v[190:193], v[36:39]
	v_mfma_f32_16x16x32_bf16 v[28:31], v[222:225], v[190:193], v[28:31]
	v_mfma_f32_16x16x32_bf16 v[20:23], v[214:217], v[198:201], v[20:23]
	v_mfma_f32_16x16x32_bf16 v[12:15], v[222:225], v[198:201], v[12:15]
	v_mfma_f32_16x16x32_bf16 v[4:7], v[214:217], v[206:209], v[4:7]
	v_mfma_f32_16x16x32_bf16 v[0:3], v[222:225], v[206:209], v[0:3]
	s_barrier
	s_add_i32 s56, s56, 2
	s_add_u32 s24, s24, 0x100
	s_addc_u32 s25, s25, 0
	s_add_u32 s54, s54, 0x100
	s_addc_u32 s55, s55, 0
	s_cmp_gt_u32 s56, 13
.LBB0_1083:
	ds_read_b128 v[152:155], v149
	ds_read_b128 v[156:159], v149 offset:1024
	ds_read_b128 v[160:163], v149 offset:2048
	ds_read_b128 v[164:167], v149 offset:3072
	s_add_u32 s26, s24, 0xfffc0080
	s_addc_u32 s27, s25, -1
	s_cmp_eq_u32 s56, 12
	s_cselect_b32 s29, s17, s27
	s_cselect_b32 s28, s52, s26
	s_cselect_b32 s27, s15, s55
	s_cselect_b32 s26, s53, s54
	s_add_i32 m0, s23, 0xc000
	ds_read_b128 v[168:171], v150
	ds_read_b128 v[172:175], v150 offset:1024
	ds_read_b128 v[182:185], v150 offset:2048
	ds_read_b128 v[190:193], v150 offset:3072
	ds_read_b128 v[194:197], v150 offset:4096
	ds_read_b128 v[198:201], v150 offset:5120
	ds_read_b128 v[202:205], v150 offset:6144
	ds_read_b128 v[206:209], v150 offset:7168
	global_load_lds_dwordx4 v136, s[24:25]
	s_add_i32 m0, s23, 0xe000
	s_nop 0
	global_load_lds_dwordx4 v138, s[24:25]
	s_waitcnt lgkmcnt(8)
	ds_read_b128 v[210:213], v151
	ds_read_b128 v[214:217], v151 offset:1024
	ds_read_b128 v[218:221], v151 offset:2048
	ds_read_b128 v[222:225], v151 offset:3072
	s_waitcnt vmcnt(8) lgkmcnt(0)
	s_barrier
	v_mfma_f32_16x16x32_bf16 v[124:127], v[152:155], v[168:171], v[124:127]
	v_mfma_f32_16x16x32_bf16 v[120:123], v[160:163], v[168:171], v[120:123]
	v_mfma_f32_16x16x32_bf16 v[108:111], v[152:155], v[182:185], v[108:111]
	v_mfma_f32_16x16x32_bf16 v[104:107], v[160:163], v[182:185], v[104:107]
	v_mfma_f32_16x16x32_bf16 v[92:95], v[152:155], v[194:197], v[92:95]
	v_mfma_f32_16x16x32_bf16 v[88:91], v[160:163], v[194:197], v[88:91]
	v_mfma_f32_16x16x32_bf16 v[76:79], v[152:155], v[202:205], v[76:79]
	v_mfma_f32_16x16x32_bf16 v[72:75], v[160:163], v[202:205], v[72:75]
	v_mfma_f32_16x16x32_bf16 v[124:127], v[156:159], v[172:175], v[124:127]
	v_mfma_f32_16x16x32_bf16 v[120:123], v[164:167], v[172:175], v[120:123]
	v_mfma_f32_16x16x32_bf16 v[108:111], v[156:159], v[190:193], v[108:111]
	v_mfma_f32_16x16x32_bf16 v[104:107], v[164:167], v[190:193], v[104:107]
	v_mfma_f32_16x16x32_bf16 v[92:95], v[156:159], v[198:201], v[92:95]
	v_mfma_f32_16x16x32_bf16 v[88:91], v[164:167], v[198:201], v[88:91]
	v_mfma_f32_16x16x32_bf16 v[76:79], v[156:159], v[206:209], v[76:79]
	v_mfma_f32_16x16x32_bf16 v[72:75], v[164:167], v[206:209], v[72:75]
	v_mfma_f32_16x16x32_bf16 v[116:119], v[210:213], v[168:171], v[116:119]
	v_mfma_f32_16x16x32_bf16 v[112:115], v[218:221], v[168:171], v[112:115]
	v_mfma_f32_16x16x32_bf16 v[100:103], v[210:213], v[182:185], v[100:103]
	v_mfma_f32_16x16x32_bf16 v[96:99], v[218:221], v[182:185], v[96:99]
	v_mfma_f32_16x16x32_bf16 v[84:87], v[210:213], v[194:197], v[84:87]
	v_mfma_f32_16x16x32_bf16 v[80:83], v[218:221], v[194:197], v[80:83]
	v_mfma_f32_16x16x32_bf16 v[68:71], v[210:213], v[202:205], v[68:71]
	v_mfma_f32_16x16x32_bf16 v[64:67], v[218:221], v[202:205], v[64:67]
	v_mfma_f32_16x16x32_bf16 v[116:119], v[214:217], v[172:175], v[116:119]
	v_mfma_f32_16x16x32_bf16 v[112:115], v[222:225], v[172:175], v[112:115]
	v_mfma_f32_16x16x32_bf16 v[100:103], v[214:217], v[190:193], v[100:103]
	v_mfma_f32_16x16x32_bf16 v[96:99], v[222:225], v[190:193], v[96:99]
	v_mfma_f32_16x16x32_bf16 v[84:87], v[214:217], v[198:201], v[84:87]
	v_mfma_f32_16x16x32_bf16 v[80:83], v[222:225], v[198:201], v[80:83]
	v_mfma_f32_16x16x32_bf16 v[68:71], v[214:217], v[206:209], v[68:71]
	v_mfma_f32_16x16x32_bf16 v[64:67], v[222:225], v[206:209], v[64:67]
	s_barrier
; #define PG8_STAGE(bufoff, gbase, voff) do { _Pragma("unroll") for (int _i = 0; _i < 2; ++_i) \
;         __builtin_amdgcn_global_load_lds((const unsigned*)((const char*)(gbase) + (voff)[_i]), (PG8_LAS unsigned*)(lds + (bufoff) + ldsw + _i * 8192), 16, 0, 0); } while (0)
; #define PG8_LDA(dst, b, h) do { _Pragma("unroll") for (int m = 0; m < 4; ++m) _Pragma("unroll") for (int k = 0; k < 2; ++k) dst[m][k] = *(const PG8_LAS bf16x8*)(lds + PG8_SA(b, h) + aoff + m * 2048 + k * 1024); } while (0)
; #define PG8_LDB(dst, b, h) do { _Pragma("unroll") for (int n = 0; n < 2; ++n) _Pragma("unroll") for (int k = 0; k < 2; ++k) dst[n][k] = *(const PG8_LAS bf16x8*)(lds + PG8_SB(b, h) + boff + n * 2048 + k * 1024); } while (0)
; #define PG8_MMA(ai, bj, At, Bt) do { __builtin_amdgcn_s_setprio(1); _Pragma("unroll") for (int m = 0; m < 4; ++m) _Pragma("unroll") for (int n = 0; n < 2; ++n) _Pragma("unroll") for (int k = 0; k < 2; ++k) \
;         acc[ai][bj][m][n] = __builtin_amdgcn_mfma_f32_16x16x32_bf16(Bt[n][k], At[m][k], acc[ai][bj][m][n], 0, 0, 0); __builtin_amdgcn_s_setprio(0); } while (0)
; #define PG8_WAIT_V(n) asm volatile("s_waitcnt vmcnt(" #n ")" ::: "memory")
; #define PG8_WAIT_L(n) asm volatile("s_waitcnt lgkmcnt(" #n ")" ::: "memory")
; #define PG8_BAR __builtin_amdgcn_s_barrier()
; #define PG8_SCHED __builtin_amdgcn_sched_barrier(0)
; template <class Epi, class Sched>
; __device__ __forceinline__ void gemm_phase(PG8_LAS unsigned char* lds, const Gemm g, const Sched& S, const Epi& E) {
;     ...
;             PG8_LDB(B1, 0, 1); PG8_STAGE(PG8_SB(0, 0), b2, voffB);
;             PG8_BAR; PG8_WAIT_L(0); PG8_MMA(0, 1, At, B1); PG8_BAR;
;             PG8_LDA(At, 0, 1); PG8_STAGE(PG8_SA(0, 0), a2, voffA);
;             PG8_BAR; PG8_WAIT_L(0); PG8_MMA(1, 0, At, B0); PG8_BAR; PG8_SCHED;
;             PG8_STAGE(PG8_SB(0, 1), b2 + hstep, voffB);
;             PG8_WAIT_V(6); PG8_BAR; PG8_MMA(1, 1, At, B1); PG8_BAR;
;             PG8_LDB(B0, 1, 0); PG8_SCHED; PG8_LDA(At, 1, 0); PG8_STAGE(PG8_SA(0, 1), a2 + hstep, voffA);
;             PG8_WAIT_L(8); PG8_BAR; PG8_WAIT_L(0); PG8_MMA(0, 0, At, B0); PG8_BAR; PG8_SCHED;
;             PG8_LDB(B1, 1, 1); PG8_STAGE(PG8_SB(1, 0), b3, voffB);
;             PG8_BAR; PG8_WAIT_L(0); PG8_MMA(0, 1, At, B1); PG8_BAR;
	ds_read_b128 v[168:171], v150 offset:16384
	ds_read_b128 v[172:175], v150 offset:17408
	ds_read_b128 v[182:185], v150 offset:18432
	ds_read_b128 v[190:193], v150 offset:19456
	ds_read_b128 v[194:197], v150 offset:20480
	ds_read_b128 v[198:201], v150 offset:21504
	ds_read_b128 v[202:205], v150 offset:22528
	ds_read_b128 v[206:209], v150 offset:23552
	s_add_i32 s57, s45, s37
	s_add_u32 s98, s26, s6
	s_addc_u32 s99, s27, s7
	s_mov_b32 m0, s57
	s_nop 0
	global_load_lds_dwordx4 v130, s[26:27]
	s_add_i32 m0, s57, 0x2000
	s_nop 0
	global_load_lds_dwordx4 v134, s[26:27]
	s_mov_b32 m0, s23
	s_add_u32 s100, s28, s6
	s_addc_u32 s101, s29, s7
	global_load_lds_dwordx4 v128, s[28:29]
	s_mov_b32 m0, s38
	s_nop 0
	global_load_lds_dwordx4 v132, s[28:29]
	s_add_u32 s58, s26, 0x40000
	s_addc_u32 s59, s27, 0
	s_add_i32 s57, s46, s37
	s_mov_b32 m0, s57
	s_nop 0
	global_load_lds_dwordx4 v130, s[58:59]
	s_add_i32 m0, s57, 0x2000
	s_nop 0
	global_load_lds_dwordx4 v134, s[58:59]
	s_waitcnt vmcnt(8) lgkmcnt(0)
	s_barrier
	v_mfma_f32_16x16x32_bf16 v[60:63], v[152:155], v[168:171], v[60:63]
	v_mfma_f32_16x16x32_bf16 v[56:59], v[160:163], v[168:171], v[56:59]
	v_mfma_f32_16x16x32_bf16 v[48:51], v[152:155], v[182:185], v[48:51]
	v_mfma_f32_16x16x32_bf16 v[40:43], v[160:163], v[182:185], v[40:43]
	v_mfma_f32_16x16x32_bf16 v[32:35], v[152:155], v[194:197], v[32:35]
	v_mfma_f32_16x16x32_bf16 v[24:27], v[160:163], v[194:197], v[24:27]
	v_mfma_f32_16x16x32_bf16 v[16:19], v[152:155], v[202:205], v[16:19]
	v_mfma_f32_16x16x32_bf16 v[8:11], v[160:163], v[202:205], v[8:11]
	v_mfma_f32_16x16x32_bf16 v[60:63], v[156:159], v[172:175], v[60:63]
	v_mfma_f32_16x16x32_bf16 v[56:59], v[164:167], v[172:175], v[56:59]
	v_mfma_f32_16x16x32_bf16 v[48:51], v[156:159], v[190:193], v[48:51]
	v_mfma_f32_16x16x32_bf16 v[40:43], v[164:167], v[190:193], v[40:43]
	v_mfma_f32_16x16x32_bf16 v[32:35], v[156:159], v[198:201], v[32:35]
	v_mfma_f32_16x16x32_bf16 v[24:27], v[164:167], v[198:201], v[24:27]
	v_mfma_f32_16x16x32_bf16 v[16:19], v[156:159], v[206:209], v[16:19]
	v_mfma_f32_16x16x32_bf16 v[8:11], v[164:167], v[206:209], v[8:11]
	v_mfma_f32_16x16x32_bf16 v[52:55], v[210:213], v[168:171], v[52:55]
	v_mfma_f32_16x16x32_bf16 v[44:47], v[218:221], v[168:171], v[44:47]
	v_mfma_f32_16x16x32_bf16 v[36:39], v[210:213], v[182:185], v[36:39]
	v_mfma_f32_16x16x32_bf16 v[28:31], v[218:221], v[182:185], v[28:31]
	v_mfma_f32_16x16x32_bf16 v[20:23], v[210:213], v[194:197], v[20:23]
	v_mfma_f32_16x16x32_bf16 v[12:15], v[218:221], v[194:197], v[12:15]
	v_mfma_f32_16x16x32_bf16 v[4:7], v[210:213], v[202:205], v[4:7]
	v_mfma_f32_16x16x32_bf16 v[0:3], v[218:221], v[202:205], v[0:3]
	v_mfma_f32_16x16x32_bf16 v[52:55], v[214:217], v[172:175], v[52:55]
	v_mfma_f32_16x16x32_bf16 v[44:47], v[222:225], v[172:175], v[44:47]
	v_mfma_f32_16x16x32_bf16 v[36:39], v[214:217], v[190:193], v[36:39]
	v_mfma_f32_16x16x32_bf16 v[28:31], v[222:225], v[190:193], v[28:31]
	v_mfma_f32_16x16x32_bf16 v[20:23], v[214:217], v[198:201], v[20:23]
	v_mfma_f32_16x16x32_bf16 v[12:15], v[222:225], v[198:201], v[12:15]
	v_mfma_f32_16x16x32_bf16 v[4:7], v[214:217], v[206:209], v[4:7]
	v_mfma_f32_16x16x32_bf16 v[0:3], v[222:225], v[206:209], v[0:3]
	s_barrier
	s_add_i32 s57, 0, 0x18000
	v_add_u32_e32 v164, s57, v147
	ds_read_b128 v[152:155], v164
	ds_read_b128 v[156:159], v164 offset:1024
	ds_read_b128 v[160:163], v164 offset:2048
	ds_read_b128 v[164:167], v164 offset:3072
	s_add_u32 s28, s28, 0x40000
	s_addc_u32 s29, s29, 0
	s_mov_b32 m0, s39
	ds_read_b128 v[168:171], v150 offset:32768
	ds_read_b128 v[172:175], v150 offset:33792
	ds_read_b128 v[182:185], v150 offset:34816
	ds_read_b128 v[190:193], v150 offset:35840
	ds_read_b128 v[194:197], v150 offset:36864
	ds_read_b128 v[198:201], v150 offset:37888
	ds_read_b128 v[202:205], v150 offset:38912
	ds_read_b128 v[206:209], v150 offset:39936
	global_load_lds_dwordx4 v128, s[28:29]
	s_mov_b32 m0, s40
	s_nop 0
	global_load_lds_dwordx4 v132, s[28:29]
	s_add_i32 s28, 0, 0x1c000
	v_add_u32_e32 v179, s28, v147
	s_waitcnt lgkmcnt(8)
	ds_read_b128 v[210:213], v179
	ds_read_b128 v[214:217], v179 offset:1024
	ds_read_b128 v[218:221], v179 offset:2048
	ds_read_b128 v[222:225], v179 offset:3072
	s_waitcnt vmcnt(8) lgkmcnt(0)
	s_barrier
	v_mfma_f32_16x16x32_bf16 v[124:127], v[152:155], v[168:171], v[124:127]
	v_mfma_f32_16x16x32_bf16 v[120:123], v[160:163], v[168:171], v[120:123]
	v_mfma_f32_16x16x32_bf16 v[108:111], v[152:155], v[182:185], v[108:111]
	v_mfma_f32_16x16x32_bf16 v[104:107], v[160:163], v[182:185], v[104:107]
	v_mfma_f32_16x16x32_bf16 v[92:95], v[152:155], v[194:197], v[92:95]
	v_mfma_f32_16x16x32_bf16 v[88:91], v[160:163], v[194:197], v[88:91]
	v_mfma_f32_16x16x32_bf16 v[76:79], v[152:155], v[202:205], v[76:79]
	v_mfma_f32_16x16x32_bf16 v[72:75], v[160:163], v[202:205], v[72:75]
	v_mfma_f32_16x16x32_bf16 v[124:127], v[156:159], v[172:175], v[124:127]
	v_mfma_f32_16x16x32_bf16 v[120:123], v[164:167], v[172:175], v[120:123]
	v_mfma_f32_16x16x32_bf16 v[108:111], v[156:159], v[190:193], v[108:111]
	v_mfma_f32_16x16x32_bf16 v[104:107], v[164:167], v[190:193], v[104:107]
	v_mfma_f32_16x16x32_bf16 v[92:95], v[156:159], v[198:201], v[92:95]
	v_mfma_f32_16x16x32_bf16 v[88:91], v[164:167], v[198:201], v[88:91]
	v_mfma_f32_16x16x32_bf16 v[76:79], v[156:159], v[206:209], v[76:79]
	v_mfma_f32_16x16x32_bf16 v[72:75], v[164:167], v[206:209], v[72:75]
	v_mfma_f32_16x16x32_bf16 v[116:119], v[210:213], v[168:171], v[116:119]
	v_mfma_f32_16x16x32_bf16 v[112:115], v[218:221], v[168:171], v[112:115]
	v_mfma_f32_16x16x32_bf16 v[100:103], v[210:213], v[182:185], v[100:103]
	v_mfma_f32_16x16x32_bf16 v[96:99], v[218:221], v[182:185], v[96:99]
	v_mfma_f32_16x16x32_bf16 v[84:87], v[210:213], v[194:197], v[84:87]
	v_mfma_f32_16x16x32_bf16 v[80:83], v[218:221], v[194:197], v[80:83]
	v_mfma_f32_16x16x32_bf16 v[68:71], v[210:213], v[202:205], v[68:71]
	v_mfma_f32_16x16x32_bf16 v[64:67], v[218:221], v[202:205], v[64:67]
	v_mfma_f32_16x16x32_bf16 v[116:119], v[214:217], v[172:175], v[116:119]
	v_mfma_f32_16x16x32_bf16 v[112:115], v[222:225], v[172:175], v[112:115]
	v_mfma_f32_16x16x32_bf16 v[100:103], v[214:217], v[190:193], v[100:103]
	v_mfma_f32_16x16x32_bf16 v[96:99], v[222:225], v[190:193], v[96:99]
	v_mfma_f32_16x16x32_bf16 v[84:87], v[214:217], v[198:201], v[84:87]
	v_mfma_f32_16x16x32_bf16 v[80:83], v[222:225], v[198:201], v[80:83]
	v_mfma_f32_16x16x32_bf16 v[68:71], v[214:217], v[206:209], v[68:71]
	v_mfma_f32_16x16x32_bf16 v[64:67], v[222:225], v[206:209], v[64:67]
	s_barrier
; #define PG8_WAIT_V(n) asm volatile("s_waitcnt vmcnt(" #n ")" ::: "memory")
;     __device__ __forceinline__ void operator()(const f32x4 (&acc)[2][2][4][2], const Unit& u, int wr, int wc, int fr, int fq) const {
;     ...
;         const int row0 = u.pm * BM + wr * 64 + fr, col0 = u.pn * BM + wc * 32 + 8 * fq, bcol0 = wc * 32 + 8 * fq;
;         f32x4 bv[2][2];
; #pragma unroll
;         for (int bj = 0; bj < 2; ++bj)
; #pragma unroll
;             for (int n = 0; n < 2; ++n) bv[bj][n] = bias ? *(const f32x4*)(bias + bcol0 + bj * HALF + 4 * n) : (f32x4){0.f, 0.f, 0.f, 0.f};
; #pragma unroll
;         for (int ai = 0; ai < 2; ++ai)
; #pragma unroll
;             for (int m = 0; m < 4; ++m) { bf16_t* rowp = O + (size_t)(row0 + ai * HALF + m * 16) * ldc + col0;
; #pragma unroll
;                 for (int bj = 0; bj < 2; ++bj) { f32x4 v0 = acc[ai][bj][m][0] + bv[bj][0], v1 = acc[ai][bj][m][1] + bv[bj][1];
;                     if (act == 1) {
; #pragma unroll
;                         for (int j = 0; j < 1; ++j) { v0 = v0 * sigmoid4(v0); v1 = v1 * sigmoid4(v1); } }
;                     else if (act == 2) {
; #pragma unroll
;                         for (int j = 0; j < 1; ++j) { v0 = sigmoid4(v0); v1 = sigmoid4(v1); } }
;                     else if (act == 3) {
; #pragma unroll
;                         for (int j = 0; j < 4; ++j) { v0[j] = flogsig16(v0[j]); v1[j] = flogsig16(v1[j]); } }
;                     u32x4 w; w.x = cvt_pk_bf16(v0[0], v0[1]); w.y = cvt_pk_bf16(v0[2], v0[3]); w.z = cvt_pk_bf16(v1[0], v1[1]); w.w = cvt_pk_bf16(v1[2], v1[3]);
;                     *(u32x4*)(rowp + bj * HALF) = w; } }
; template <class Epi, class Sched>
; __device__ __forceinline__ void gemm_phase(PG8_LAS unsigned char* lds, const Gemm g, const Sched& S, const Epi& E) {
;     ...
;             PG8_LDB(B0, 1, 0); PG8_SCHED; PG8_LDA(At, 1, 0); PG8_STAGE(PG8_SA(0, 1), a2 + hstep, voffA);
;             PG8_WAIT_L(8); PG8_BAR; PG8_WAIT_L(0); PG8_MMA(0, 0, At, B0); PG8_BAR; PG8_SCHED;
;             PG8_LDB(B1, 1, 1); PG8_STAGE(PG8_SB(1, 0), b3, voffB);
;             PG8_BAR; PG8_WAIT_L(0); PG8_MMA(0, 1, At, B1); PG8_BAR;
;             PG8_LDA(At, 1, 1); PG8_STAGE(PG8_SA(1, 0), a3, voffA);
;             PG8_BAR; PG8_WAIT_L(0); PG8_MMA(1, 0, At, B0); PG8_BAR; PG8_SCHED;
;             PG8_STAGE(PG8_SB(1, 1), b3 + hstep, voffB);
;             PG8_WAIT_V(6); PG8_BAR; PG8_MMA(1, 1, At, B1); PG8_BAR;
	ds_read_b128 v[168:171], v150 offset:49152
	ds_read_b128 v[172:175], v150 offset:50176
	ds_read_b128 v[182:185], v150 offset:51200
	ds_read_b128 v[190:193], v150 offset:52224
	ds_read_b128 v[194:197], v150 offset:53248
	ds_read_b128 v[198:201], v150 offset:54272
	ds_read_b128 v[202:205], v150 offset:55296
	ds_read_b128 v[206:209], v150 offset:56320
	s_add_i32 s29, s57, s37
	s_mov_b32 m0, s29
	s_nop 0
	global_load_lds_dwordx4 v130, s[98:99]
	s_add_i32 m0, s29, 0x2000
	s_nop 0
	global_load_lds_dwordx4 v134, s[98:99]
	s_mov_b32 m0, s42
	s_nop 0
	global_load_lds_dwordx4 v128, s[100:101]
	s_mov_b32 m0, s43
	s_nop 0
	global_load_lds_dwordx4 v132, s[100:101]
	s_add_u32 s26, s26, 0x40080
	s_addc_u32 s27, s27, 0
	s_add_i32 s28, s28, s37
	s_mov_b32 m0, s28
	s_nop 0
	global_load_lds_dwordx4 v130, s[26:27]
	s_add_i32 m0, s28, 0x2000
	s_nop 0
	global_load_lds_dwordx4 v134, s[26:27]
	s_waitcnt vmcnt(8) lgkmcnt(0)
	s_barrier
	v_mfma_f32_16x16x32_bf16 v[60:63], v[152:155], v[168:171], v[60:63]
	v_mfma_f32_16x16x32_bf16 v[56:59], v[160:163], v[168:171], v[56:59]
	v_mfma_f32_16x16x32_bf16 v[48:51], v[152:155], v[182:185], v[48:51]
	v_mfma_f32_16x16x32_bf16 v[40:43], v[160:163], v[182:185], v[40:43]
	v_mfma_f32_16x16x32_bf16 v[32:35], v[152:155], v[194:197], v[32:35]
	v_mfma_f32_16x16x32_bf16 v[24:27], v[160:163], v[194:197], v[24:27]
	v_mfma_f32_16x16x32_bf16 v[16:19], v[152:155], v[202:205], v[16:19]
	v_mfma_f32_16x16x32_bf16 v[8:11], v[160:163], v[202:205], v[8:11]
	v_mfma_f32_16x16x32_bf16 v[60:63], v[156:159], v[172:175], v[60:63]
	v_mfma_f32_16x16x32_bf16 v[56:59], v[164:167], v[172:175], v[56:59]
	v_mfma_f32_16x16x32_bf16 v[48:51], v[156:159], v[190:193], v[48:51]
	v_mfma_f32_16x16x32_bf16 v[40:43], v[164:167], v[190:193], v[40:43]
	v_mfma_f32_16x16x32_bf16 v[32:35], v[156:159], v[198:201], v[32:35]
	v_mfma_f32_16x16x32_bf16 v[24:27], v[164:167], v[198:201], v[24:27]
	v_mfma_f32_16x16x32_bf16 v[16:19], v[156:159], v[206:209], v[16:19]
	v_mfma_f32_16x16x32_bf16 v[8:11], v[164:167], v[206:209], v[8:11]
	v_mfma_f32_16x16x32_bf16 v[52:55], v[210:213], v[168:171], v[52:55]
	v_mfma_f32_16x16x32_bf16 v[44:47], v[218:221], v[168:171], v[44:47]
	v_mfma_f32_16x16x32_bf16 v[36:39], v[210:213], v[182:185], v[36:39]
	v_mfma_f32_16x16x32_bf16 v[28:31], v[218:221], v[182:185], v[28:31]
	v_mfma_f32_16x16x32_bf16 v[20:23], v[210:213], v[194:197], v[20:23]
	v_mfma_f32_16x16x32_bf16 v[12:15], v[218:221], v[194:197], v[12:15]
	v_mfma_f32_16x16x32_bf16 v[4:7], v[210:213], v[202:205], v[4:7]
	v_mfma_f32_16x16x32_bf16 v[0:3], v[218:221], v[202:205], v[0:3]
	v_mfma_f32_16x16x32_bf16 v[52:55], v[214:217], v[172:175], v[52:55]
	v_mfma_f32_16x16x32_bf16 v[44:47], v[222:225], v[172:175], v[44:47]
	v_mfma_f32_16x16x32_bf16 v[36:39], v[214:217], v[190:193], v[36:39]
	v_mfma_f32_16x16x32_bf16 v[28:31], v[222:225], v[190:193], v[28:31]
	v_mfma_f32_16x16x32_bf16 v[20:23], v[214:217], v[198:201], v[20:23]
	v_mfma_f32_16x16x32_bf16 v[12:15], v[222:225], v[198:201], v[12:15]
	v_mfma_f32_16x16x32_bf16 v[4:7], v[214:217], v[206:209], v[4:7]
	v_mfma_f32_16x16x32_bf16 v[0:3], v[222:225], v[206:209], v[0:3]
	s_barrier
	s_add_i32 s56, s56, 2
	s_add_u32 s24, s24, 0x100
	s_addc_u32 s25, s25, 0
	s_add_u32 s54, s54, 0x100
	s_addc_u32 s55, s55, 0
	s_cmp_gt_u32 s56, 13
	s_cbranch_scc0 .LBB0_1083
	v_lshl_add_u32 v152, s22, 8, v146
	v_lshl_or_b32 v144, s51, 8, v148
	v_ashrrev_i32_e32 v153, 31, v152
	v_ashrrev_i32_e32 v145, 31, v144
	v_lshlrev_b64 v[154:155], 11, v[152:153]
	v_lshl_add_u64 v[154:155], s[4:5], 0, v[154:155]
	v_lshlrev_b64 v[156:157], 1, v[144:145]
	v_lshl_add_u64 v[144:145], v[154:155], 0, v[156:157]
	v_pk_add_f32 v[126:127], v[126:127], 0 op_sel_hi:[1,0]
	v_pk_add_f32 v[124:125], v[124:125], 0 op_sel_hi:[1,0]
	v_pk_add_f32 v[154:155], v[122:123], 0 op_sel_hi:[1,0]
	v_pk_add_f32 v[122:123], v[120:121], 0 op_sel_hi:[1,0]
	v_cvt_pk_bf16_f32 v120, v124, v125
	v_cvt_pk_bf16_f32 v121, v126, v127
	v_pk_add_f32 v[116:117], v[116:117], 0 op_sel_hi:[1,0]
	v_cvt_pk_bf16_f32 v122, v122, v123
	v_cvt_pk_bf16_f32 v123, v154, v155
	global_store_dwordx4 v[144:145], v[120:123], off
	v_pk_add_f32 v[118:119], v[118:119], 0 op_sel_hi:[1,0]
	v_pk_add_f32 v[110:111], v[110:111], 0 op_sel_hi:[1,0]
	v_pk_add_f32 v[120:121], v[114:115], 0 op_sel_hi:[1,0]
	v_pk_add_f32 v[114:115], v[112:113], 0 op_sel_hi:[1,0]
	v_cvt_pk_bf16_f32 v112, v116, v117
	v_cvt_pk_bf16_f32 v113, v118, v119
	v_pk_add_f32 v[108:109], v[108:109], 0 op_sel_hi:[1,0]
	v_cvt_pk_bf16_f32 v114, v114, v115
	v_cvt_pk_bf16_f32 v115, v120, v121
	global_store_dwordx4 v[144:145], v[112:115], off offset:256
	v_pk_add_f32 v[100:101], v[100:101], 0 op_sel_hi:[1,0]
	v_pk_add_f32 v[102:103], v[102:103], 0 op_sel_hi:[1,0]
	v_or_b32_e32 v112, 16, v152
	v_ashrrev_i32_e32 v113, 31, v112
	v_lshlrev_b64 v[112:113], 11, v[112:113]
	v_lshl_add_u64 v[112:113], s[4:5], 0, v[112:113]
	v_lshl_add_u64 v[112:113], v[112:113], 0, v[156:157]
	v_pk_add_f32 v[114:115], v[106:107], 0 op_sel_hi:[1,0]
	v_pk_add_f32 v[106:107], v[104:105], 0 op_sel_hi:[1,0]
	v_cvt_pk_bf16_f32 v104, v108, v109
	v_cvt_pk_bf16_f32 v105, v110, v111
	v_pk_add_f32 v[94:95], v[94:95], 0 op_sel_hi:[1,0]
	v_cvt_pk_bf16_f32 v106, v106, v107
	v_cvt_pk_bf16_f32 v107, v114, v115
	global_store_dwordx4 v[112:113], v[104:107], off
	v_pk_add_f32 v[92:93], v[92:93], 0 op_sel_hi:[1,0]
	v_pk_add_f32 v[84:85], v[84:85], 0 op_sel_hi:[1,0]
	v_pk_add_f32 v[104:105], v[98:99], 0 op_sel_hi:[1,0]
	v_pk_add_f32 v[98:99], v[96:97], 0 op_sel_hi:[1,0]
	v_cvt_pk_bf16_f32 v96, v100, v101
	v_cvt_pk_bf16_f32 v97, v102, v103
	v_pk_add_f32 v[86:87], v[86:87], 0 op_sel_hi:[1,0]
	v_cvt_pk_bf16_f32 v98, v98, v99
; __device__ __forceinline__ unsigned cvt_pk_bf16(float lo, float hi) { unsigned r; asm volatile("v_cvt_pk_bf16_f32 %0, %1, %2" : "=v"(r) : "v"(lo), "v"(hi)); return r; }
; __device__ __forceinline__ float flogsig16(float x) { return (fminf(x, 0.f) - __logf(1.0f + __expf(-fabsf(x)))) * 0.0625f; }
;     __device__ __forceinline__ void operator()(const f32x4 (&acc)[2][2][4][2], const Unit& u, int wr, int wc, int fr, int fq) const {
;     ...
;         const int row0 = u.pm * BM + wr * 64 + fr, col0 = u.pn * BM + wc * 32 + 8 * fq, bcol0 = wc * 32 + 8 * fq;
;         f32x4 bv[2][2];
; #pragma unroll
;         for (int bj = 0; bj < 2; ++bj)
; #pragma unroll
;             for (int n = 0; n < 2; ++n) bv[bj][n] = bias ? *(const f32x4*)(bias + bcol0 + bj * HALF + 4 * n) : (f32x4){0.f, 0.f, 0.f, 0.f};
; #pragma unroll
;         for (int ai = 0; ai < 2; ++ai)
; #pragma unroll
;             for (int m = 0; m < 4; ++m) { bf16_t* rowp = O + (size_t)(row0 + ai * HALF + m * 16) * ldc + col0;
; #pragma unroll
;                 for (int bj = 0; bj < 2; ++bj) { f32x4 v0 = acc[ai][bj][m][0] + bv[bj][0], v1 = acc[ai][bj][m][1] + bv[bj][1];
;                     if (act == 1) {
; #pragma unroll
;                         for (int j = 0; j < 1; ++j) { v0 = v0 * sigmoid4(v0); v1 = v1 * sigmoid4(v1); } }
;                     else if (act == 2) {
; #pragma unroll
;                         for (int j = 0; j < 1; ++j) { v0 = sigmoid4(v0); v1 = sigmoid4(v1); } }
;                     else if (act == 3) {
; #pragma unroll
;                         for (int j = 0; j < 4; ++j) { v0[j] = flogsig16(v0[j]); v1[j] = flogsig16(v1[j]); } }
;                     u32x4 w; w.x = cvt_pk_bf16(v0[0], v0[1]); w.y = cvt_pk_bf16(v0[2], v0[3]); w.z = cvt_pk_bf16(v1[0], v1[1]); w.w = cvt_pk_bf16(v1[2], v1[3]);
;                     *(u32x4*)(rowp + bj * HALF) = w; } }
	v_cvt_pk_bf16_f32 v99, v104, v105
	global_store_dwordx4 v[112:113], v[96:99], off offset:256
	v_pk_add_f32 v[78:79], v[78:79], 0 op_sel_hi:[1,0]
	v_pk_add_f32 v[76:77], v[76:77], 0 op_sel_hi:[1,0]
	v_or_b32_e32 v96, 32, v152
	v_ashrrev_i32_e32 v97, 31, v96
	v_lshlrev_b64 v[96:97], 11, v[96:97]
	v_lshl_add_u64 v[96:97], s[4:5], 0, v[96:97]
	v_lshl_add_u64 v[96:97], v[96:97], 0, v[156:157]
	v_pk_add_f32 v[98:99], v[90:91], 0 op_sel_hi:[1,0]
	v_pk_add_f32 v[90:91], v[88:89], 0 op_sel_hi:[1,0]
	v_cvt_pk_bf16_f32 v88, v92, v93
	v_cvt_pk_bf16_f32 v89, v94, v95
	v_pk_add_f32 v[70:71], v[70:71], 0 op_sel_hi:[1,0]
	v_cvt_pk_bf16_f32 v90, v90, v91
	v_cvt_pk_bf16_f32 v91, v98, v99
	global_store_dwordx4 v[96:97], v[88:91], off
	v_pk_add_f32 v[68:69], v[68:69], 0 op_sel_hi:[1,0]
	v_pk_add_f32 v[60:61], v[60:61], 0 op_sel_hi:[1,0]
	v_pk_add_f32 v[88:89], v[82:83], 0 op_sel_hi:[1,0]
	v_pk_add_f32 v[82:83], v[80:81], 0 op_sel_hi:[1,0]
	v_cvt_pk_bf16_f32 v80, v84, v85
	v_cvt_pk_bf16_f32 v81, v86, v87
	v_pk_add_f32 v[62:63], v[62:63], 0 op_sel_hi:[1,0]
	v_cvt_pk_bf16_f32 v82, v82, v83
	v_cvt_pk_bf16_f32 v83, v88, v89
	global_store_dwordx4 v[96:97], v[80:83], off offset:256
	v_pk_add_f32 v[54:55], v[54:55], 0 op_sel_hi:[1,0]
	v_pk_add_f32 v[52:53], v[52:53], 0 op_sel_hi:[1,0]
	v_or_b32_e32 v80, 48, v152
	v_ashrrev_i32_e32 v81, 31, v80
	v_lshlrev_b64 v[80:81], 11, v[80:81]
	v_lshl_add_u64 v[80:81], s[4:5], 0, v[80:81]
	v_lshl_add_u64 v[80:81], v[80:81], 0, v[156:157]
	v_pk_add_f32 v[82:83], v[74:75], 0 op_sel_hi:[1,0]
	v_pk_add_f32 v[74:75], v[72:73], 0 op_sel_hi:[1,0]
	v_cvt_pk_bf16_f32 v72, v76, v77
	v_cvt_pk_bf16_f32 v73, v78, v79
	v_pk_add_f32 v[48:49], v[48:49], 0 op_sel_hi:[1,0]
	v_cvt_pk_bf16_f32 v74, v74, v75
	v_cvt_pk_bf16_f32 v75, v82, v83
	global_store_dwordx4 v[80:81], v[72:75], off
	v_pk_add_f32 v[38:39], v[38:39], 0 op_sel_hi:[1,0]
	v_pk_add_f32 v[36:37], v[36:37], 0 op_sel_hi:[1,0]
	v_pk_add_f32 v[72:73], v[66:67], 0 op_sel_hi:[1,0]
	v_pk_add_f32 v[66:67], v[64:65], 0 op_sel_hi:[1,0]
	v_cvt_pk_bf16_f32 v64, v68, v69
	v_cvt_pk_bf16_f32 v65, v70, v71
	v_pk_add_f32 v[32:33], v[32:33], 0 op_sel_hi:[1,0]
	v_cvt_pk_bf16_f32 v66, v66, v67
	v_cvt_pk_bf16_f32 v67, v72, v73
	global_store_dwordx4 v[80:81], v[64:67], off offset:256
	v_pk_add_f32 v[22:23], v[22:23], 0 op_sel_hi:[1,0]
	v_pk_add_f32 v[20:21], v[20:21], 0 op_sel_hi:[1,0]
	v_pk_add_f32 v[66:67], v[58:59], 0 op_sel_hi:[1,0]
	v_pk_add_f32 v[58:59], v[56:57], 0 op_sel_hi:[1,0]
	v_cvt_pk_bf16_f32 v56, v60, v61
	v_add_co_u32_e32 v60, vcc, s47, v144
	v_cvt_pk_bf16_f32 v57, v62, v63
	v_cvt_pk_bf16_f32 v58, v58, v59
	v_cvt_pk_bf16_f32 v59, v66, v67
	v_lshl_add_u64 v[64:65], v[144:145], 0, s[0:1]
	s_nop 0
	v_addc_co_u32_e32 v61, vcc, 0, v145, vcc
	global_store_dwordx4 v[60:61], v[56:59], off
	v_pk_add_f32 v[16:17], v[16:17], 0 op_sel_hi:[1,0]
	s_mov_b32 s51, s14
	v_pk_add_f32 v[56:57], v[46:47], 0 op_sel_hi:[1,0]
	v_pk_add_f32 v[46:47], v[44:45], 0 op_sel_hi:[1,0]
	v_cvt_pk_bf16_f32 v44, v52, v53
	v_cvt_pk_bf16_f32 v45, v54, v55
	s_mov_b32 s22, s16
	v_cvt_pk_bf16_f32 v46, v46, v47
	v_cvt_pk_bf16_f32 v47, v56, v57
	global_store_dwordx4 v[64:65], v[44:47], off offset:256
	s_mov_b64 s[26:27], s[20:21]
	s_mov_b64 s[24:25], s[18:19]
	v_pk_add_f32 v[46:47], v[50:51], 0 op_sel_hi:[1,0]
	v_pk_add_f32 v[50:51], v[42:43], 0 op_sel_hi:[1,0]
	v_pk_add_f32 v[42:43], v[40:41], 0 op_sel_hi:[1,0]
	v_cvt_pk_bf16_f32 v40, v48, v49
	v_cvt_pk_bf16_f32 v41, v46, v47
	v_add_co_u32_e32 v46, vcc, s48, v144
	v_cvt_pk_bf16_f32 v42, v42, v43
	v_cvt_pk_bf16_f32 v43, v50, v51
	v_lshl_add_u64 v[44:45], v[144:145], 0, s[8:9]
	s_nop 0
	v_addc_co_u32_e32 v47, vcc, 0, v145, vcc
	global_store_dwordx4 v[46:47], v[40:43], off
	v_pk_add_f32 v[6:7], v[6:7], 0 op_sel_hi:[1,0]
	v_pk_add_f32 v[4:5], v[4:5], 0 op_sel_hi:[1,0]
	v_pk_add_f32 v[40:41], v[30:31], 0 op_sel_hi:[1,0]
	v_pk_add_f32 v[30:31], v[28:29], 0 op_sel_hi:[1,0]
	v_cvt_pk_bf16_f32 v28, v36, v37
	v_cvt_pk_bf16_f32 v29, v38, v39
	s_nop 0
	v_cvt_pk_bf16_f32 v30, v30, v31
	v_cvt_pk_bf16_f32 v31, v40, v41
	global_store_dwordx4 v[44:45], v[28:31], off offset:256
	s_nop 1
	v_pk_add_f32 v[30:31], v[34:35], 0 op_sel_hi:[1,0]
	v_pk_add_f32 v[34:35], v[26:27], 0 op_sel_hi:[1,0]
	v_pk_add_f32 v[26:27], v[24:25], 0 op_sel_hi:[1,0]
	v_cvt_pk_bf16_f32 v24, v32, v33
	v_cvt_pk_bf16_f32 v25, v30, v31
	v_add_co_u32_e32 v30, vcc, s49, v144
	v_cvt_pk_bf16_f32 v26, v26, v27
	v_cvt_pk_bf16_f32 v27, v34, v35
	v_lshl_add_u64 v[28:29], v[144:145], 0, s[10:11]
	s_nop 0
	v_addc_co_u32_e32 v31, vcc, 0, v145, vcc
	global_store_dwordx4 v[30:31], v[24:27], off
	s_nop 1
	v_pk_add_f32 v[24:25], v[14:15], 0 op_sel_hi:[1,0]
	v_pk_add_f32 v[14:15], v[12:13], 0 op_sel_hi:[1,0]
	v_cvt_pk_bf16_f32 v12, v20, v21
	v_cvt_pk_bf16_f32 v13, v22, v23
	s_nop 0
	v_cvt_pk_bf16_f32 v14, v14, v15
	v_cvt_pk_bf16_f32 v15, v24, v25
	global_store_dwordx4 v[28:29], v[12:15], off offset:256
	s_nop 1
	v_pk_add_f32 v[14:15], v[18:19], 0 op_sel_hi:[1,0]
	v_pk_add_f32 v[18:19], v[10:11], 0 op_sel_hi:[1,0]
	v_pk_add_f32 v[10:11], v[8:9], 0 op_sel_hi:[1,0]
	v_cvt_pk_bf16_f32 v8, v16, v17
	v_cvt_pk_bf16_f32 v9, v14, v15
	v_add_co_u32_e32 v14, vcc, s50, v144
	v_lshl_add_u64 v[12:13], v[144:145], 0, s[12:13]
	s_nop 0
	v_addc_co_u32_e32 v15, vcc, 0, v145, vcc
	v_cvt_pk_bf16_f32 v10, v10, v11
	v_cvt_pk_bf16_f32 v11, v18, v19
	global_store_dwordx4 v[14:15], v[8:11], off
	s_and_b64 vcc, exec, s[2:3]
	s_nop 0
	v_pk_add_f32 v[8:9], v[2:3], 0 op_sel_hi:[1,0]
	v_pk_add_f32 v[2:3], v[0:1], 0 op_sel_hi:[1,0]
	v_cvt_pk_bf16_f32 v0, v4, v5
	v_cvt_pk_bf16_f32 v1, v6, v7
	s_nop 0
	v_cvt_pk_bf16_f32 v2, v2, v3
	v_cvt_pk_bf16_f32 v3, v8, v9
	global_store_dwordx4 v[12:13], v[0:3], off offset:256
	s_cbranch_vccz .LBB0_1076
	s_waitcnt vmcnt(0)
	s_cmpk_gt_u32 s31, 0xff
	s_cbranch_scc1 .LBB0_1087
	s_barrier

; #define PG8_STAGE(bufoff, gbase, voff) do { _Pragma("unroll") for (int _i = 0; _i < 2; ++_i) \
;         __builtin_amdgcn_global_load_lds((const unsigned*)((const char*)(gbase) + (voff)[_i]), (PG8_LAS unsigned*)(lds + (bufoff) + ldsw + _i * 8192), 16, 0, 0); } while (0)
; #define PG8_LDA(dst, b, h) do { _Pragma("unroll") for (int m = 0; m < 4; ++m) _Pragma("unroll") for (int k = 0; k < 2; ++k) dst[m][k] = *(const PG8_LAS bf16x8*)(lds + PG8_SA(b, h) + aoff + m * 2048 + k * 1024); } while (0)
; #define PG8_LDB(dst, b, h) do { _Pragma("unroll") for (int n = 0; n < 2; ++n) _Pragma("unroll") for (int k = 0; k < 2; ++k) dst[n][k] = *(const PG8_LAS bf16x8*)(lds + PG8_SB(b, h) + boff + n * 2048 + k * 1024); } while (0)
; #define PG8_MMA(ai, bj, At, Bt) do { __builtin_amdgcn_s_setprio(1); _Pragma("unroll") for (int m = 0; m < 4; ++m) _Pragma("unroll") for (int n = 0; n < 2; ++n) _Pragma("unroll") for (int k = 0; k < 2; ++k) \
;         acc[ai][bj][m][n] = __builtin_amdgcn_mfma_f32_16x16x32_bf16(Bt[n][k], At[m][k], acc[ai][bj][m][n], 0, 0, 0); __builtin_amdgcn_s_setprio(0); } while (0)
; template <class Epi, class Sched>
; __device__ __forceinline__ void gemm_phase(PG8_LAS unsigned char* lds, const Gemm g, const Sched& S, const Epi& E) {
;     ...
;         const bool has_next = S.next(ui + 1, nxt);
;         const char* nA = has_next ? (const char*)g.A + (size_t)nxt.pm * tstep : cA; const char* nB = has_next ? (const char*)g.Bt + (size_t)nxt.pn * tstep : cB;
;         for (int t = 0; t < nt; t += 2) {
;             const bool last = (t == nt - 2);
;             const char* a1 = cA + (size_t)(t + 1) * kstep;
;             const char* a2 = last ? nA : cA + (size_t)(t + 2) * kstep; const char* b2 = last ? nB : cB + (size_t)(t + 2) * kstep;
;             const char* a3 = a2 + kstep; const char* b3 = b2 + kstep;
;             if (last && has_next) S.a_ready(nxt);
;             PG8_LDB(B0, 0, 0); PG8_SCHED; PG8_LDA(At, 0, 0); PG8_STAGE(PG8_SA(1, 1), a1 + hstep, voffA);
;             PG8_WAIT_L(8); PG8_BAR; PG8_WAIT_L(0); PG8_MMA(0, 0, At, B0); PG8_BAR; PG8_SCHED;
;             PG8_LDB(B1, 0, 1); PG8_STAGE(PG8_SB(0, 0), b2, voffB);
;             PG8_BAR; PG8_WAIT_L(0); PG8_MMA(0, 1, At, B1); PG8_BAR;
;             PG8_LDA(At, 0, 1); PG8_STAGE(PG8_SA(0, 0), a2, voffA);
;             PG8_BAR; PG8_WAIT_L(0); PG8_MMA(1, 0, At, B0); PG8_BAR; PG8_SCHED;
.LBB0_1201:
	s_ashr_i32 s9, s8, 31
	v_cmp_lt_i64_e32 vcc, s[10:11], v[140:141]
	s_lshl_b64 s[10:11], s[8:9], 19
	s_add_u32 s10, s24, s10
	s_addc_u32 s11, s25, s11
	s_and_b64 s[12:13], vcc, exec
	s_cselect_b32 s9, s11, s17
	s_cselect_b32 s42, s10, s16
	s_ashr_i32 s7, s6, 31
	s_lshl_b64 s[12:13], s[6:7], 19
	s_add_u32 s12, s84, s12
	s_addc_u32 s13, s85, s13
	s_and_b64 s[20:21], vcc, exec
	s_cselect_b32 s7, s13, s19
	s_cselect_b32 s43, s12, s18
	s_add_u32 s16, s16, 0x40080
	s_addc_u32 s17, s17, 0
	s_add_u32 s44, s18, 0x100
	s_addc_u32 s45, s19, 0
	s_mov_b32 s46, -2
	ds_read_b128 v[144:147], v151
	ds_read_b128 v[154:157], v151 offset:1024
	ds_read_b128 v[158:161], v151 offset:2048
	ds_read_b128 v[162:165], v151 offset:3072
	s_add_u32 s18, s16, 0xfffc0080
	s_addc_u32 s19, s17, -1
	s_cmp_eq_u32 s46, 12
	s_cselect_b32 s21, s9, s19
	s_cselect_b32 s20, s42, s18
	s_cselect_b32 s19, s7, s45
	s_cselect_b32 s18, s43, s44
	s_add_i32 m0, s15, 0xc000
	ds_read_b128 v[166:169], v152
	ds_read_b128 v[170:173], v152 offset:1024
	ds_read_b128 v[182:185], v152 offset:2048
	ds_read_b128 v[190:193], v152 offset:3072
	ds_read_b128 v[194:197], v152 offset:4096
	ds_read_b128 v[198:201], v152 offset:5120
	ds_read_b128 v[202:205], v152 offset:6144
	ds_read_b128 v[206:209], v152 offset:7168
	global_load_lds_dwordx4 v136, s[16:17]
	s_add_i32 m0, s15, 0xe000
	s_nop 0
	global_load_lds_dwordx4 v138, s[16:17]
	s_waitcnt lgkmcnt(8)
	ds_read_b128 v[210:213], v153
	ds_read_b128 v[214:217], v153 offset:1024
	ds_read_b128 v[218:221], v153 offset:2048
	ds_read_b128 v[222:225], v153 offset:3072
	s_waitcnt vmcnt(8) lgkmcnt(0)
	s_barrier
	v_mfma_f32_16x16x32_bf16 v[124:127], v[144:147], v[166:169], 0
	v_mfma_f32_16x16x32_bf16 v[120:123], v[158:161], v[166:169], 0
	v_mfma_f32_16x16x32_bf16 v[108:111], v[144:147], v[182:185], 0
	v_mfma_f32_16x16x32_bf16 v[104:107], v[158:161], v[182:185], 0
	v_mfma_f32_16x16x32_bf16 v[92:95], v[144:147], v[194:197], 0
	v_mfma_f32_16x16x32_bf16 v[88:91], v[158:161], v[194:197], 0
	v_mfma_f32_16x16x32_bf16 v[76:79], v[144:147], v[202:205], 0
	v_mfma_f32_16x16x32_bf16 v[72:75], v[158:161], v[202:205], 0
	v_mfma_f32_16x16x32_bf16 v[124:127], v[154:157], v[170:173], v[124:127]
	v_mfma_f32_16x16x32_bf16 v[120:123], v[162:165], v[170:173], v[120:123]
	v_mfma_f32_16x16x32_bf16 v[108:111], v[154:157], v[190:193], v[108:111]
	v_mfma_f32_16x16x32_bf16 v[104:107], v[162:165], v[190:193], v[104:107]
	v_mfma_f32_16x16x32_bf16 v[92:95], v[154:157], v[198:201], v[92:95]
	v_mfma_f32_16x16x32_bf16 v[88:91], v[162:165], v[198:201], v[88:91]
	v_mfma_f32_16x16x32_bf16 v[76:79], v[154:157], v[206:209], v[76:79]
	v_mfma_f32_16x16x32_bf16 v[72:75], v[162:165], v[206:209], v[72:75]
	v_mfma_f32_16x16x32_bf16 v[116:119], v[210:213], v[166:169], 0
	v_mfma_f32_16x16x32_bf16 v[112:115], v[218:221], v[166:169], 0
	v_mfma_f32_16x16x32_bf16 v[100:103], v[210:213], v[182:185], 0
	v_mfma_f32_16x16x32_bf16 v[96:99], v[218:221], v[182:185], 0
	v_mfma_f32_16x16x32_bf16 v[84:87], v[210:213], v[194:197], 0
	v_mfma_f32_16x16x32_bf16 v[80:83], v[218:221], v[194:197], 0
	v_mfma_f32_16x16x32_bf16 v[68:71], v[210:213], v[202:205], 0
	v_mfma_f32_16x16x32_bf16 v[64:67], v[218:221], v[202:205], 0
	v_mfma_f32_16x16x32_bf16 v[116:119], v[214:217], v[170:173], v[116:119]
	v_mfma_f32_16x16x32_bf16 v[112:115], v[222:225], v[170:173], v[112:115]
	v_mfma_f32_16x16x32_bf16 v[100:103], v[214:217], v[190:193], v[100:103]
	v_mfma_f32_16x16x32_bf16 v[96:99], v[222:225], v[190:193], v[96:99]
	v_mfma_f32_16x16x32_bf16 v[84:87], v[214:217], v[198:201], v[84:87]
	v_mfma_f32_16x16x32_bf16 v[80:83], v[222:225], v[198:201], v[80:83]
	v_mfma_f32_16x16x32_bf16 v[68:71], v[214:217], v[206:209], v[68:71]
	v_mfma_f32_16x16x32_bf16 v[64:67], v[222:225], v[206:209], v[64:67]
	s_barrier
	ds_read_b128 v[166:169], v152 offset:16384
	ds_read_b128 v[170:173], v152 offset:17408
	ds_read_b128 v[182:185], v152 offset:18432
	ds_read_b128 v[190:193], v152 offset:19456
	ds_read_b128 v[194:197], v152 offset:20480
	ds_read_b128 v[198:201], v152 offset:21504
	ds_read_b128 v[202:205], v152 offset:22528
	ds_read_b128 v[206:209], v152 offset:23552
	s_add_i32 s47, s38, s26
	s_add_u32 s98, s18, s4
	s_addc_u32 s99, s19, s5
	s_mov_b32 m0, s47
	s_nop 0
	global_load_lds_dwordx4 v132, s[18:19]
	s_add_i32 m0, s47, 0x2000
	s_nop 0
	global_load_lds_dwordx4 v128, s[18:19]
	s_mov_b32 m0, s15
	s_add_u32 s100, s20, s4
	s_addc_u32 s101, s21, s5
	global_load_lds_dwordx4 v134, s[20:21]
	s_mov_b32 m0, s29
	s_nop 0
	global_load_lds_dwordx4 v130, s[20:21]
	s_add_u32 s48, s18, 0x40000
	s_addc_u32 s49, s19, 0
	s_add_i32 s47, s39, s26
	s_mov_b32 m0, s47
	s_nop 0
	global_load_lds_dwordx4 v132, s[48:49]
	s_add_i32 m0, s47, 0x2000
	s_nop 0
	global_load_lds_dwordx4 v128, s[48:49]
	s_waitcnt vmcnt(8) lgkmcnt(0)
	s_barrier
; #define PG8_STAGE(bufoff, gbase, voff) do { _Pragma("unroll") for (int _i = 0; _i < 2; ++_i) \
;         __builtin_amdgcn_global_load_lds((const unsigned*)((const char*)(gbase) + (voff)[_i]), (PG8_LAS unsigned*)(lds + (bufoff) + ldsw + _i * 8192), 16, 0, 0); } while (0)
; #define PG8_LDA(dst, b, h) do { _Pragma("unroll") for (int m = 0; m < 4; ++m) _Pragma("unroll") for (int k = 0; k < 2; ++k) dst[m][k] = *(const PG8_LAS bf16x8*)(lds + PG8_SA(b, h) + aoff + m * 2048 + k * 1024); } while (0)
; #define PG8_LDB(dst, b, h) do { _Pragma("unroll") for (int n = 0; n < 2; ++n) _Pragma("unroll") for (int k = 0; k < 2; ++k) dst[n][k] = *(const PG8_LAS bf16x8*)(lds + PG8_SB(b, h) + boff + n * 2048 + k * 1024); } while (0)
; #define PG8_MMA(ai, bj, At, Bt) do { __builtin_amdgcn_s_setprio(1); _Pragma("unroll") for (int m = 0; m < 4; ++m) _Pragma("unroll") for (int n = 0; n < 2; ++n) _Pragma("unroll") for (int k = 0; k < 2; ++k) \
;         acc[ai][bj][m][n] = __builtin_amdgcn_mfma_f32_16x16x32_bf16(Bt[n][k], At[m][k], acc[ai][bj][m][n], 0, 0, 0); __builtin_amdgcn_s_setprio(0); } while (0)
; #define PG8_WAIT_V(n) asm volatile("s_waitcnt vmcnt(" #n ")" ::: "memory")
; #define PG8_WAIT_L(n) asm volatile("s_waitcnt lgkmcnt(" #n ")" ::: "memory")
; #define PG8_BAR __builtin_amdgcn_s_barrier()
; #define PG8_SCHED __builtin_amdgcn_sched_barrier(0)
; template <class Epi, class Sched>
; __device__ __forceinline__ void gemm_phase(PG8_LAS unsigned char* lds, const Gemm g, const Sched& S, const Epi& E) {
;     ...
;             PG8_BAR; PG8_WAIT_L(0); PG8_MMA(0, 1, At, B1); PG8_BAR;
;             PG8_LDA(At, 0, 1); PG8_STAGE(PG8_SA(0, 0), a2, voffA);
;             PG8_BAR; PG8_WAIT_L(0); PG8_MMA(1, 0, At, B0); PG8_BAR; PG8_SCHED;
;             PG8_STAGE(PG8_SB(0, 1), b2 + hstep, voffB);
;             PG8_WAIT_V(6); PG8_BAR; PG8_MMA(1, 1, At, B1); PG8_BAR;
;             PG8_LDB(B0, 1, 0); PG8_SCHED; PG8_LDA(At, 1, 0); PG8_STAGE(PG8_SA(0, 1), a2 + hstep, voffA);
;             PG8_WAIT_L(8); PG8_BAR; PG8_WAIT_L(0); PG8_MMA(0, 0, At, B0); PG8_BAR; PG8_SCHED;
;             PG8_LDB(B1, 1, 1); PG8_STAGE(PG8_SB(1, 0), b3, voffB);
;             PG8_BAR; PG8_WAIT_L(0); PG8_MMA(0, 1, At, B1); PG8_BAR;
	v_mfma_f32_16x16x32_bf16 v[60:63], v[144:147], v[166:169], 0
	v_mfma_f32_16x16x32_bf16 v[56:59], v[158:161], v[166:169], 0
	v_mfma_f32_16x16x32_bf16 v[44:47], v[144:147], v[182:185], 0
	v_mfma_f32_16x16x32_bf16 v[40:43], v[158:161], v[182:185], 0
	v_mfma_f32_16x16x32_bf16 v[28:31], v[144:147], v[194:197], 0
	v_mfma_f32_16x16x32_bf16 v[24:27], v[158:161], v[194:197], 0
	v_mfma_f32_16x16x32_bf16 v[12:15], v[144:147], v[202:205], 0
	v_mfma_f32_16x16x32_bf16 v[8:11], v[158:161], v[202:205], 0
	v_mfma_f32_16x16x32_bf16 v[60:63], v[154:157], v[170:173], v[60:63]
	v_mfma_f32_16x16x32_bf16 v[56:59], v[162:165], v[170:173], v[56:59]
	v_mfma_f32_16x16x32_bf16 v[44:47], v[154:157], v[190:193], v[44:47]
	v_mfma_f32_16x16x32_bf16 v[40:43], v[162:165], v[190:193], v[40:43]
	v_mfma_f32_16x16x32_bf16 v[28:31], v[154:157], v[198:201], v[28:31]
	v_mfma_f32_16x16x32_bf16 v[24:27], v[162:165], v[198:201], v[24:27]
	v_mfma_f32_16x16x32_bf16 v[12:15], v[154:157], v[206:209], v[12:15]
	v_mfma_f32_16x16x32_bf16 v[8:11], v[162:165], v[206:209], v[8:11]
	v_mfma_f32_16x16x32_bf16 v[52:55], v[210:213], v[166:169], 0
	v_mfma_f32_16x16x32_bf16 v[48:51], v[218:221], v[166:169], 0
	v_mfma_f32_16x16x32_bf16 v[36:39], v[210:213], v[182:185], 0
	v_mfma_f32_16x16x32_bf16 v[32:35], v[218:221], v[182:185], 0
	v_mfma_f32_16x16x32_bf16 v[20:23], v[210:213], v[194:197], 0
	v_mfma_f32_16x16x32_bf16 v[16:19], v[218:221], v[194:197], 0
	v_mfma_f32_16x16x32_bf16 v[4:7], v[210:213], v[202:205], 0
	v_mfma_f32_16x16x32_bf16 v[0:3], v[218:221], v[202:205], 0
	v_mfma_f32_16x16x32_bf16 v[52:55], v[214:217], v[170:173], v[52:55]
	v_mfma_f32_16x16x32_bf16 v[48:51], v[222:225], v[170:173], v[48:51]
	v_mfma_f32_16x16x32_bf16 v[36:39], v[214:217], v[190:193], v[36:39]
	v_mfma_f32_16x16x32_bf16 v[32:35], v[222:225], v[190:193], v[32:35]
	v_mfma_f32_16x16x32_bf16 v[20:23], v[214:217], v[198:201], v[20:23]
	v_mfma_f32_16x16x32_bf16 v[16:19], v[222:225], v[198:201], v[16:19]
	v_mfma_f32_16x16x32_bf16 v[4:7], v[214:217], v[206:209], v[4:7]
	v_mfma_f32_16x16x32_bf16 v[0:3], v[222:225], v[206:209], v[0:3]
	s_barrier
	s_add_i32 s47, 0, 0x18000
	v_add_u32_e32 v162, s47, v149
	ds_read_b128 v[144:147], v162
	ds_read_b128 v[154:157], v162 offset:1024
	ds_read_b128 v[158:161], v162 offset:2048
	ds_read_b128 v[162:165], v162 offset:3072
	s_add_u32 s20, s20, 0x40000
	s_addc_u32 s21, s21, 0
	s_mov_b32 m0, s30
	ds_read_b128 v[166:169], v152 offset:32768
	ds_read_b128 v[170:173], v152 offset:33792
	ds_read_b128 v[182:185], v152 offset:34816
	ds_read_b128 v[190:193], v152 offset:35840
	ds_read_b128 v[194:197], v152 offset:36864
	ds_read_b128 v[198:201], v152 offset:37888
	ds_read_b128 v[202:205], v152 offset:38912
	ds_read_b128 v[206:209], v152 offset:39936
	global_load_lds_dwordx4 v134, s[20:21]
	s_mov_b32 m0, s31
	s_nop 0
	global_load_lds_dwordx4 v130, s[20:21]
	s_add_i32 s20, 0, 0x1c000
	v_add_u32_e32 v179, s20, v149
	s_waitcnt lgkmcnt(8)
	ds_read_b128 v[210:213], v179
	ds_read_b128 v[214:217], v179 offset:1024
	ds_read_b128 v[218:221], v179 offset:2048
	ds_read_b128 v[222:225], v179 offset:3072
	s_waitcnt vmcnt(8) lgkmcnt(0)
	s_barrier
	v_mfma_f32_16x16x32_bf16 v[124:127], v[144:147], v[166:169], v[124:127]
	v_mfma_f32_16x16x32_bf16 v[120:123], v[158:161], v[166:169], v[120:123]
	v_mfma_f32_16x16x32_bf16 v[108:111], v[144:147], v[182:185], v[108:111]
	v_mfma_f32_16x16x32_bf16 v[104:107], v[158:161], v[182:185], v[104:107]
	v_mfma_f32_16x16x32_bf16 v[92:95], v[144:147], v[194:197], v[92:95]
	v_mfma_f32_16x16x32_bf16 v[88:91], v[158:161], v[194:197], v[88:91]
	v_mfma_f32_16x16x32_bf16 v[76:79], v[144:147], v[202:205], v[76:79]
	v_mfma_f32_16x16x32_bf16 v[72:75], v[158:161], v[202:205], v[72:75]
	v_mfma_f32_16x16x32_bf16 v[124:127], v[154:157], v[170:173], v[124:127]
	v_mfma_f32_16x16x32_bf16 v[120:123], v[162:165], v[170:173], v[120:123]
	v_mfma_f32_16x16x32_bf16 v[108:111], v[154:157], v[190:193], v[108:111]
	v_mfma_f32_16x16x32_bf16 v[104:107], v[162:165], v[190:193], v[104:107]
	v_mfma_f32_16x16x32_bf16 v[92:95], v[154:157], v[198:201], v[92:95]
	v_mfma_f32_16x16x32_bf16 v[88:91], v[162:165], v[198:201], v[88:91]
	v_mfma_f32_16x16x32_bf16 v[76:79], v[154:157], v[206:209], v[76:79]
	v_mfma_f32_16x16x32_bf16 v[72:75], v[162:165], v[206:209], v[72:75]
	v_mfma_f32_16x16x32_bf16 v[116:119], v[210:213], v[166:169], v[116:119]
	v_mfma_f32_16x16x32_bf16 v[112:115], v[218:221], v[166:169], v[112:115]
	v_mfma_f32_16x16x32_bf16 v[100:103], v[210:213], v[182:185], v[100:103]
	v_mfma_f32_16x16x32_bf16 v[96:99], v[218:221], v[182:185], v[96:99]
	v_mfma_f32_16x16x32_bf16 v[84:87], v[210:213], v[194:197], v[84:87]
	v_mfma_f32_16x16x32_bf16 v[80:83], v[218:221], v[194:197], v[80:83]
	v_mfma_f32_16x16x32_bf16 v[68:71], v[210:213], v[202:205], v[68:71]
	v_mfma_f32_16x16x32_bf16 v[64:67], v[218:221], v[202:205], v[64:67]
	v_mfma_f32_16x16x32_bf16 v[116:119], v[214:217], v[170:173], v[116:119]
	v_mfma_f32_16x16x32_bf16 v[112:115], v[222:225], v[170:173], v[112:115]
	v_mfma_f32_16x16x32_bf16 v[100:103], v[214:217], v[190:193], v[100:103]
	v_mfma_f32_16x16x32_bf16 v[96:99], v[222:225], v[190:193], v[96:99]
	v_mfma_f32_16x16x32_bf16 v[84:87], v[214:217], v[198:201], v[84:87]
	v_mfma_f32_16x16x32_bf16 v[80:83], v[222:225], v[198:201], v[80:83]
	v_mfma_f32_16x16x32_bf16 v[68:71], v[214:217], v[206:209], v[68:71]
	v_mfma_f32_16x16x32_bf16 v[64:67], v[222:225], v[206:209], v[64:67]
	s_barrier
; #define PG8_STAGE(bufoff, gbase, voff) do { _Pragma("unroll") for (int _i = 0; _i < 2; ++_i) \
;         __builtin_amdgcn_global_load_lds((const unsigned*)((const char*)(gbase) + (voff)[_i]), (PG8_LAS unsigned*)(lds + (bufoff) + ldsw + _i * 8192), 16, 0, 0); } while (0)
; #define PG8_LDA(dst, b, h) do { _Pragma("unroll") for (int m = 0; m < 4; ++m) _Pragma("unroll") for (int k = 0; k < 2; ++k) dst[m][k] = *(const PG8_LAS bf16x8*)(lds + PG8_SA(b, h) + aoff + m * 2048 + k * 1024); } while (0)
; #define PG8_LDB(dst, b, h) do { _Pragma("unroll") for (int n = 0; n < 2; ++n) _Pragma("unroll") for (int k = 0; k < 2; ++k) dst[n][k] = *(const PG8_LAS bf16x8*)(lds + PG8_SB(b, h) + boff + n * 2048 + k * 1024); } while (0)
; #define PG8_WAIT_V(n) asm volatile("s_waitcnt vmcnt(" #n ")" ::: "memory")
; #define PG8_WAIT_L(n) asm volatile("s_waitcnt lgkmcnt(" #n ")" ::: "memory")
; #define PG8_BAR __builtin_amdgcn_s_barrier()
; #define PG8_SCHED __builtin_amdgcn_sched_barrier(0)
; template <class Epi, class Sched>
; __device__ __forceinline__ void gemm_phase(PG8_LAS unsigned char* lds, const Gemm g, const Sched& S, const Epi& E) {
;     ...
;             PG8_LDB(B0, 0, 0); PG8_SCHED; PG8_LDA(At, 0, 0); PG8_STAGE(PG8_SA(1, 1), a1 + hstep, voffA);
;             PG8_WAIT_L(8); PG8_BAR; PG8_WAIT_L(0); PG8_MMA(0, 0, At, B0); PG8_BAR; PG8_SCHED;
;             PG8_LDB(B1, 0, 1); PG8_STAGE(PG8_SB(0, 0), b2, voffB);
;             PG8_BAR; PG8_WAIT_L(0); PG8_MMA(0, 1, At, B1); PG8_BAR;
;             PG8_LDA(At, 0, 1); PG8_STAGE(PG8_SA(0, 0), a2, voffA);
;             PG8_BAR; PG8_WAIT_L(0); PG8_MMA(1, 0, At, B0); PG8_BAR; PG8_SCHED;
;             PG8_STAGE(PG8_SB(0, 1), b2 + hstep, voffB);
;             PG8_WAIT_V(6); PG8_BAR; PG8_MMA(1, 1, At, B1); PG8_BAR;
;             PG8_LDB(B0, 1, 0); PG8_SCHED; PG8_LDA(At, 1, 0); PG8_STAGE(PG8_SA(0, 1), a2 + hstep, voffA);
;             PG8_WAIT_L(8); PG8_BAR; PG8_WAIT_L(0); PG8_MMA(0, 0, At, B0); PG8_BAR; PG8_SCHED;
;             PG8_LDB(B1, 1, 1); PG8_STAGE(PG8_SB(1, 0), b3, voffB);
;             PG8_BAR; PG8_WAIT_L(0); PG8_MMA(0, 1, At, B1); PG8_BAR;
;             PG8_LDA(At, 1, 1); PG8_STAGE(PG8_SA(1, 0), a3, voffA);
;             PG8_BAR; PG8_WAIT_L(0); PG8_MMA(1, 0, At, B0); PG8_BAR; PG8_SCHED;
;             PG8_STAGE(PG8_SB(1, 1), b3 + hstep, voffB);
;             PG8_WAIT_V(6); PG8_BAR; PG8_MMA(1, 1, At, B1); PG8_BAR;
	ds_read_b128 v[166:169], v152 offset:49152
	ds_read_b128 v[170:173], v152 offset:50176
	ds_read_b128 v[182:185], v152 offset:51200
	ds_read_b128 v[190:193], v152 offset:52224
	ds_read_b128 v[194:197], v152 offset:53248
	ds_read_b128 v[198:201], v152 offset:54272
	ds_read_b128 v[202:205], v152 offset:55296
	ds_read_b128 v[206:209], v152 offset:56320
	s_add_i32 s21, s47, s26
	s_mov_b32 m0, s21
	s_nop 0
	global_load_lds_dwordx4 v132, s[98:99]
	s_add_i32 m0, s21, 0x2000
	s_nop 0
	global_load_lds_dwordx4 v128, s[98:99]
	s_mov_b32 m0, s35
	s_nop 0
	global_load_lds_dwordx4 v134, s[100:101]
	s_mov_b32 m0, s36
	s_nop 0
	global_load_lds_dwordx4 v130, s[100:101]
	s_add_u32 s18, s18, 0x40080
	s_addc_u32 s19, s19, 0
	s_add_i32 s20, s20, s26
	s_mov_b32 m0, s20
	s_nop 0
	global_load_lds_dwordx4 v132, s[18:19]
	s_add_i32 m0, s20, 0x2000
	s_nop 0
	global_load_lds_dwordx4 v128, s[18:19]
	s_waitcnt vmcnt(8) lgkmcnt(0)
	s_barrier
	v_mfma_f32_16x16x32_bf16 v[60:63], v[144:147], v[166:169], v[60:63]
	v_mfma_f32_16x16x32_bf16 v[56:59], v[158:161], v[166:169], v[56:59]
	v_mfma_f32_16x16x32_bf16 v[44:47], v[144:147], v[182:185], v[44:47]
	v_mfma_f32_16x16x32_bf16 v[40:43], v[158:161], v[182:185], v[40:43]
	v_mfma_f32_16x16x32_bf16 v[28:31], v[144:147], v[194:197], v[28:31]
	v_mfma_f32_16x16x32_bf16 v[24:27], v[158:161], v[194:197], v[24:27]
	v_mfma_f32_16x16x32_bf16 v[12:15], v[144:147], v[202:205], v[12:15]
	v_mfma_f32_16x16x32_bf16 v[8:11], v[158:161], v[202:205], v[8:11]
	v_mfma_f32_16x16x32_bf16 v[60:63], v[154:157], v[170:173], v[60:63]
	v_mfma_f32_16x16x32_bf16 v[56:59], v[162:165], v[170:173], v[56:59]
	v_mfma_f32_16x16x32_bf16 v[44:47], v[154:157], v[190:193], v[44:47]
	v_mfma_f32_16x16x32_bf16 v[40:43], v[162:165], v[190:193], v[40:43]
	v_mfma_f32_16x16x32_bf16 v[28:31], v[154:157], v[198:201], v[28:31]
	v_mfma_f32_16x16x32_bf16 v[24:27], v[162:165], v[198:201], v[24:27]
	v_mfma_f32_16x16x32_bf16 v[12:15], v[154:157], v[206:209], v[12:15]
	v_mfma_f32_16x16x32_bf16 v[8:11], v[162:165], v[206:209], v[8:11]
	v_mfma_f32_16x16x32_bf16 v[52:55], v[210:213], v[166:169], v[52:55]
	v_mfma_f32_16x16x32_bf16 v[48:51], v[218:221], v[166:169], v[48:51]
	v_mfma_f32_16x16x32_bf16 v[36:39], v[210:213], v[182:185], v[36:39]
	v_mfma_f32_16x16x32_bf16 v[32:35], v[218:221], v[182:185], v[32:35]
	v_mfma_f32_16x16x32_bf16 v[20:23], v[210:213], v[194:197], v[20:23]
	v_mfma_f32_16x16x32_bf16 v[16:19], v[218:221], v[194:197], v[16:19]
	v_mfma_f32_16x16x32_bf16 v[4:7], v[210:213], v[202:205], v[4:7]
	v_mfma_f32_16x16x32_bf16 v[0:3], v[218:221], v[202:205], v[0:3]
	v_mfma_f32_16x16x32_bf16 v[52:55], v[214:217], v[170:173], v[52:55]
	v_mfma_f32_16x16x32_bf16 v[48:51], v[222:225], v[170:173], v[48:51]
	v_mfma_f32_16x16x32_bf16 v[36:39], v[214:217], v[190:193], v[36:39]
	v_mfma_f32_16x16x32_bf16 v[32:35], v[222:225], v[190:193], v[32:35]
	v_mfma_f32_16x16x32_bf16 v[20:23], v[214:217], v[198:201], v[20:23]
	v_mfma_f32_16x16x32_bf16 v[16:19], v[222:225], v[198:201], v[16:19]
	v_mfma_f32_16x16x32_bf16 v[4:7], v[214:217], v[206:209], v[4:7]
	v_mfma_f32_16x16x32_bf16 v[0:3], v[222:225], v[206:209], v[0:3]
	s_barrier
	s_add_i32 s46, s46, 2
	s_add_u32 s16, s16, 0x100
	s_addc_u32 s17, s17, 0
	s_add_u32 s44, s44, 0x100
	s_addc_u32 s45, s45, 0
	s_cmp_gt_u32 s46, 13
.LBB0_1202:
	ds_read_b128 v[144:147], v151
	ds_read_b128 v[154:157], v151 offset:1024
	ds_read_b128 v[158:161], v151 offset:2048
	ds_read_b128 v[162:165], v151 offset:3072
	s_add_u32 s18, s16, 0xfffc0080
	s_addc_u32 s19, s17, -1
	s_cmp_eq_u32 s46, 12
	s_cselect_b32 s21, s9, s19
	s_cselect_b32 s20, s42, s18
	s_cselect_b32 s19, s7, s45
	s_cselect_b32 s18, s43, s44
	s_add_i32 m0, s15, 0xc000
	ds_read_b128 v[166:169], v152
	ds_read_b128 v[170:173], v152 offset:1024
	ds_read_b128 v[182:185], v152 offset:2048
	ds_read_b128 v[190:193], v152 offset:3072
	ds_read_b128 v[194:197], v152 offset:4096
	ds_read_b128 v[198:201], v152 offset:5120
	ds_read_b128 v[202:205], v152 offset:6144
	ds_read_b128 v[206:209], v152 offset:7168
	global_load_lds_dwordx4 v136, s[16:17]
	s_add_i32 m0, s15, 0xe000
	s_nop 0
	global_load_lds_dwordx4 v138, s[16:17]
	s_waitcnt lgkmcnt(8)
	ds_read_b128 v[210:213], v153
	ds_read_b128 v[214:217], v153 offset:1024
	ds_read_b128 v[218:221], v153 offset:2048
	ds_read_b128 v[222:225], v153 offset:3072
	s_waitcnt vmcnt(8) lgkmcnt(0)
	s_barrier
	v_mfma_f32_16x16x32_bf16 v[124:127], v[144:147], v[166:169], v[124:127]
	v_mfma_f32_16x16x32_bf16 v[120:123], v[158:161], v[166:169], v[120:123]
	v_mfma_f32_16x16x32_bf16 v[108:111], v[144:147], v[182:185], v[108:111]
	v_mfma_f32_16x16x32_bf16 v[104:107], v[158:161], v[182:185], v[104:107]
	v_mfma_f32_16x16x32_bf16 v[92:95], v[144:147], v[194:197], v[92:95]
	v_mfma_f32_16x16x32_bf16 v[88:91], v[158:161], v[194:197], v[88:91]
	v_mfma_f32_16x16x32_bf16 v[76:79], v[144:147], v[202:205], v[76:79]
	v_mfma_f32_16x16x32_bf16 v[72:75], v[158:161], v[202:205], v[72:75]
	v_mfma_f32_16x16x32_bf16 v[124:127], v[154:157], v[170:173], v[124:127]
	v_mfma_f32_16x16x32_bf16 v[120:123], v[162:165], v[170:173], v[120:123]
	v_mfma_f32_16x16x32_bf16 v[108:111], v[154:157], v[190:193], v[108:111]
	v_mfma_f32_16x16x32_bf16 v[104:107], v[162:165], v[190:193], v[104:107]
	v_mfma_f32_16x16x32_bf16 v[92:95], v[154:157], v[198:201], v[92:95]
	v_mfma_f32_16x16x32_bf16 v[88:91], v[162:165], v[198:201], v[88:91]
	v_mfma_f32_16x16x32_bf16 v[76:79], v[154:157], v[206:209], v[76:79]
	v_mfma_f32_16x16x32_bf16 v[72:75], v[162:165], v[206:209], v[72:75]
	v_mfma_f32_16x16x32_bf16 v[116:119], v[210:213], v[166:169], v[116:119]
	v_mfma_f32_16x16x32_bf16 v[112:115], v[218:221], v[166:169], v[112:115]
	v_mfma_f32_16x16x32_bf16 v[100:103], v[210:213], v[182:185], v[100:103]
	v_mfma_f32_16x16x32_bf16 v[96:99], v[218:221], v[182:185], v[96:99]
	v_mfma_f32_16x16x32_bf16 v[84:87], v[210:213], v[194:197], v[84:87]
	v_mfma_f32_16x16x32_bf16 v[80:83], v[218:221], v[194:197], v[80:83]
	v_mfma_f32_16x16x32_bf16 v[68:71], v[210:213], v[202:205], v[68:71]
	v_mfma_f32_16x16x32_bf16 v[64:67], v[218:221], v[202:205], v[64:67]
	v_mfma_f32_16x16x32_bf16 v[116:119], v[214:217], v[170:173], v[116:119]
	v_mfma_f32_16x16x32_bf16 v[112:115], v[222:225], v[170:173], v[112:115]
	v_mfma_f32_16x16x32_bf16 v[100:103], v[214:217], v[190:193], v[100:103]
	v_mfma_f32_16x16x32_bf16 v[96:99], v[222:225], v[190:193], v[96:99]
	v_mfma_f32_16x16x32_bf16 v[84:87], v[214:217], v[198:201], v[84:87]
	v_mfma_f32_16x16x32_bf16 v[80:83], v[222:225], v[198:201], v[80:83]
	v_mfma_f32_16x16x32_bf16 v[68:71], v[214:217], v[206:209], v[68:71]
	v_mfma_f32_16x16x32_bf16 v[64:67], v[222:225], v[206:209], v[64:67]
	s_barrier
; #define PG8_STAGE(bufoff, gbase, voff) do { _Pragma("unroll") for (int _i = 0; _i < 2; ++_i) \
;         __builtin_amdgcn_global_load_lds((const unsigned*)((const char*)(gbase) + (voff)[_i]), (PG8_LAS unsigned*)(lds + (bufoff) + ldsw + _i * 8192), 16, 0, 0); } while (0)
; #define PG8_LDA(dst, b, h) do { _Pragma("unroll") for (int m = 0; m < 4; ++m) _Pragma("unroll") for (int k = 0; k < 2; ++k) dst[m][k] = *(const PG8_LAS bf16x8*)(lds + PG8_SA(b, h) + aoff + m * 2048 + k * 1024); } while (0)
; #define PG8_LDB(dst, b, h) do { _Pragma("unroll") for (int n = 0; n < 2; ++n) _Pragma("unroll") for (int k = 0; k < 2; ++k) dst[n][k] = *(const PG8_LAS bf16x8*)(lds + PG8_SB(b, h) + boff + n * 2048 + k * 1024); } while (0)
; #define PG8_MMA(ai, bj, At, Bt) do { __builtin_amdgcn_s_setprio(1); _Pragma("unroll") for (int m = 0; m < 4; ++m) _Pragma("unroll") for (int n = 0; n < 2; ++n) _Pragma("unroll") for (int k = 0; k < 2; ++k) \
;         acc[ai][bj][m][n] = __builtin_amdgcn_mfma_f32_16x16x32_bf16(Bt[n][k], At[m][k], acc[ai][bj][m][n], 0, 0, 0); __builtin_amdgcn_s_setprio(0); } while (0)
; #define PG8_WAIT_V(n) asm volatile("s_waitcnt vmcnt(" #n ")" ::: "memory")
; #define PG8_WAIT_L(n) asm volatile("s_waitcnt lgkmcnt(" #n ")" ::: "memory")
; #define PG8_BAR __builtin_amdgcn_s_barrier()
; #define PG8_SCHED __builtin_amdgcn_sched_barrier(0)
; template <class Epi, class Sched>
; __device__ __forceinline__ void gemm_phase(PG8_LAS unsigned char* lds, const Gemm g, const Sched& S, const Epi& E) {
;     ...
;             PG8_LDB(B1, 0, 1); PG8_STAGE(PG8_SB(0, 0), b2, voffB);
;             PG8_BAR; PG8_WAIT_L(0); PG8_MMA(0, 1, At, B1); PG8_BAR;
;             PG8_LDA(At, 0, 1); PG8_STAGE(PG8_SA(0, 0), a2, voffA);
;             PG8_BAR; PG8_WAIT_L(0); PG8_MMA(1, 0, At, B0); PG8_BAR; PG8_SCHED;
;             PG8_STAGE(PG8_SB(0, 1), b2 + hstep, voffB);
;             PG8_WAIT_V(6); PG8_BAR; PG8_MMA(1, 1, At, B1); PG8_BAR;
;             PG8_LDB(B0, 1, 0); PG8_SCHED; PG8_LDA(At, 1, 0); PG8_STAGE(PG8_SA(0, 1), a2 + hstep, voffA);
;             PG8_WAIT_L(8); PG8_BAR; PG8_WAIT_L(0); PG8_MMA(0, 0, At, B0); PG8_BAR; PG8_SCHED;
;             PG8_LDB(B1, 1, 1); PG8_STAGE(PG8_SB(1, 0), b3, voffB);
;             PG8_BAR; PG8_WAIT_L(0); PG8_MMA(0, 1, At, B1); PG8_BAR;
	ds_read_b128 v[166:169], v152 offset:16384
	ds_read_b128 v[170:173], v152 offset:17408
	ds_read_b128 v[182:185], v152 offset:18432
	ds_read_b128 v[190:193], v152 offset:19456
	ds_read_b128 v[194:197], v152 offset:20480
	ds_read_b128 v[198:201], v152 offset:21504
	ds_read_b128 v[202:205], v152 offset:22528
	ds_read_b128 v[206:209], v152 offset:23552
	s_add_i32 s47, s38, s26
	s_add_u32 s98, s18, s4
	s_addc_u32 s99, s19, s5
	s_mov_b32 m0, s47
	s_nop 0
	global_load_lds_dwordx4 v132, s[18:19]
	s_add_i32 m0, s47, 0x2000
	s_nop 0
	global_load_lds_dwordx4 v128, s[18:19]
	s_mov_b32 m0, s15
	s_add_u32 s100, s20, s4
	s_addc_u32 s101, s21, s5
	global_load_lds_dwordx4 v134, s[20:21]
	s_mov_b32 m0, s29
	s_nop 0
	global_load_lds_dwordx4 v130, s[20:21]
	s_add_u32 s48, s18, 0x40000
	s_addc_u32 s49, s19, 0
	s_add_i32 s47, s39, s26
	s_mov_b32 m0, s47
	s_nop 0
	global_load_lds_dwordx4 v132, s[48:49]
	s_add_i32 m0, s47, 0x2000
	s_nop 0
	global_load_lds_dwordx4 v128, s[48:49]
	s_waitcnt vmcnt(8) lgkmcnt(0)
	s_barrier
	v_mfma_f32_16x16x32_bf16 v[60:63], v[144:147], v[166:169], v[60:63]
	v_mfma_f32_16x16x32_bf16 v[56:59], v[158:161], v[166:169], v[56:59]
	v_mfma_f32_16x16x32_bf16 v[44:47], v[144:147], v[182:185], v[44:47]
	v_mfma_f32_16x16x32_bf16 v[40:43], v[158:161], v[182:185], v[40:43]
	v_mfma_f32_16x16x32_bf16 v[28:31], v[144:147], v[194:197], v[28:31]
	v_mfma_f32_16x16x32_bf16 v[24:27], v[158:161], v[194:197], v[24:27]
	v_mfma_f32_16x16x32_bf16 v[12:15], v[144:147], v[202:205], v[12:15]
	v_mfma_f32_16x16x32_bf16 v[8:11], v[158:161], v[202:205], v[8:11]
	v_mfma_f32_16x16x32_bf16 v[60:63], v[154:157], v[170:173], v[60:63]
	v_mfma_f32_16x16x32_bf16 v[56:59], v[162:165], v[170:173], v[56:59]
	v_mfma_f32_16x16x32_bf16 v[44:47], v[154:157], v[190:193], v[44:47]
	v_mfma_f32_16x16x32_bf16 v[40:43], v[162:165], v[190:193], v[40:43]
	v_mfma_f32_16x16x32_bf16 v[28:31], v[154:157], v[198:201], v[28:31]
	v_mfma_f32_16x16x32_bf16 v[24:27], v[162:165], v[198:201], v[24:27]
	v_mfma_f32_16x16x32_bf16 v[12:15], v[154:157], v[206:209], v[12:15]
	v_mfma_f32_16x16x32_bf16 v[8:11], v[162:165], v[206:209], v[8:11]
	v_mfma_f32_16x16x32_bf16 v[52:55], v[210:213], v[166:169], v[52:55]
	v_mfma_f32_16x16x32_bf16 v[48:51], v[218:221], v[166:169], v[48:51]
	v_mfma_f32_16x16x32_bf16 v[36:39], v[210:213], v[182:185], v[36:39]
	v_mfma_f32_16x16x32_bf16 v[32:35], v[218:221], v[182:185], v[32:35]
	v_mfma_f32_16x16x32_bf16 v[20:23], v[210:213], v[194:197], v[20:23]
	v_mfma_f32_16x16x32_bf16 v[16:19], v[218:221], v[194:197], v[16:19]
	v_mfma_f32_16x16x32_bf16 v[4:7], v[210:213], v[202:205], v[4:7]
	v_mfma_f32_16x16x32_bf16 v[0:3], v[218:221], v[202:205], v[0:3]
	v_mfma_f32_16x16x32_bf16 v[52:55], v[214:217], v[170:173], v[52:55]
	v_mfma_f32_16x16x32_bf16 v[48:51], v[222:225], v[170:173], v[48:51]
	v_mfma_f32_16x16x32_bf16 v[36:39], v[214:217], v[190:193], v[36:39]
	v_mfma_f32_16x16x32_bf16 v[32:35], v[222:225], v[190:193], v[32:35]
	v_mfma_f32_16x16x32_bf16 v[20:23], v[214:217], v[198:201], v[20:23]
	v_mfma_f32_16x16x32_bf16 v[16:19], v[222:225], v[198:201], v[16:19]
	v_mfma_f32_16x16x32_bf16 v[4:7], v[214:217], v[206:209], v[4:7]
	v_mfma_f32_16x16x32_bf16 v[0:3], v[222:225], v[206:209], v[0:3]
	s_barrier
	s_add_i32 s47, 0, 0x18000
	v_add_u32_e32 v162, s47, v149
	ds_read_b128 v[144:147], v162
	ds_read_b128 v[154:157], v162 offset:1024
	ds_read_b128 v[158:161], v162 offset:2048
	ds_read_b128 v[162:165], v162 offset:3072
	s_add_u32 s20, s20, 0x40000
	s_addc_u32 s21, s21, 0
	s_mov_b32 m0, s30
	ds_read_b128 v[166:169], v152 offset:32768
	ds_read_b128 v[170:173], v152 offset:33792
	ds_read_b128 v[182:185], v152 offset:34816
	ds_read_b128 v[190:193], v152 offset:35840
	ds_read_b128 v[194:197], v152 offset:36864
	ds_read_b128 v[198:201], v152 offset:37888
	ds_read_b128 v[202:205], v152 offset:38912
	ds_read_b128 v[206:209], v152 offset:39936
	global_load_lds_dwordx4 v134, s[20:21]
	s_mov_b32 m0, s31
	s_nop 0
	global_load_lds_dwordx4 v130, s[20:21]
	s_add_i32 s20, 0, 0x1c000
	v_add_u32_e32 v179, s20, v149
	s_waitcnt lgkmcnt(8)
	ds_read_b128 v[210:213], v179
	ds_read_b128 v[214:217], v179 offset:1024
	ds_read_b128 v[218:221], v179 offset:2048
	ds_read_b128 v[222:225], v179 offset:3072
	s_waitcnt vmcnt(8) lgkmcnt(0)
	s_barrier
	v_mfma_f32_16x16x32_bf16 v[124:127], v[144:147], v[166:169], v[124:127]
	v_mfma_f32_16x16x32_bf16 v[120:123], v[158:161], v[166:169], v[120:123]
	v_mfma_f32_16x16x32_bf16 v[108:111], v[144:147], v[182:185], v[108:111]
	v_mfma_f32_16x16x32_bf16 v[104:107], v[158:161], v[182:185], v[104:107]
	v_mfma_f32_16x16x32_bf16 v[92:95], v[144:147], v[194:197], v[92:95]
	v_mfma_f32_16x16x32_bf16 v[88:91], v[158:161], v[194:197], v[88:91]
	v_mfma_f32_16x16x32_bf16 v[76:79], v[144:147], v[202:205], v[76:79]
	v_mfma_f32_16x16x32_bf16 v[72:75], v[158:161], v[202:205], v[72:75]
	v_mfma_f32_16x16x32_bf16 v[124:127], v[154:157], v[170:173], v[124:127]
	v_mfma_f32_16x16x32_bf16 v[120:123], v[162:165], v[170:173], v[120:123]
	v_mfma_f32_16x16x32_bf16 v[108:111], v[154:157], v[190:193], v[108:111]
	v_mfma_f32_16x16x32_bf16 v[104:107], v[162:165], v[190:193], v[104:107]
	v_mfma_f32_16x16x32_bf16 v[92:95], v[154:157], v[198:201], v[92:95]
	v_mfma_f32_16x16x32_bf16 v[88:91], v[162:165], v[198:201], v[88:91]
	v_mfma_f32_16x16x32_bf16 v[76:79], v[154:157], v[206:209], v[76:79]
	v_mfma_f32_16x16x32_bf16 v[72:75], v[162:165], v[206:209], v[72:75]
	v_mfma_f32_16x16x32_bf16 v[116:119], v[210:213], v[166:169], v[116:119]
	v_mfma_f32_16x16x32_bf16 v[112:115], v[218:221], v[166:169], v[112:115]
	v_mfma_f32_16x16x32_bf16 v[100:103], v[210:213], v[182:185], v[100:103]
	v_mfma_f32_16x16x32_bf16 v[96:99], v[218:221], v[182:185], v[96:99]
	v_mfma_f32_16x16x32_bf16 v[84:87], v[210:213], v[194:197], v[84:87]
	v_mfma_f32_16x16x32_bf16 v[80:83], v[218:221], v[194:197], v[80:83]
	v_mfma_f32_16x16x32_bf16 v[68:71], v[210:213], v[202:205], v[68:71]
	v_mfma_f32_16x16x32_bf16 v[64:67], v[218:221], v[202:205], v[64:67]
	v_mfma_f32_16x16x32_bf16 v[116:119], v[214:217], v[170:173], v[116:119]
	v_mfma_f32_16x16x32_bf16 v[112:115], v[222:225], v[170:173], v[112:115]
	v_mfma_f32_16x16x32_bf16 v[100:103], v[214:217], v[190:193], v[100:103]
	v_mfma_f32_16x16x32_bf16 v[96:99], v[222:225], v[190:193], v[96:99]
	v_mfma_f32_16x16x32_bf16 v[84:87], v[214:217], v[198:201], v[84:87]
	v_mfma_f32_16x16x32_bf16 v[80:83], v[222:225], v[198:201], v[80:83]
	v_mfma_f32_16x16x32_bf16 v[68:71], v[214:217], v[206:209], v[68:71]
	v_mfma_f32_16x16x32_bf16 v[64:67], v[222:225], v[206:209], v[64:67]
	s_barrier
; __device__ __forceinline__ unsigned cvt_pk_bf16(float lo, float hi) { unsigned r; asm volatile("v_cvt_pk_bf16_f32 %0, %1, %2" : "=v"(r) : "v"(lo), "v"(hi)); return r; }
; #define PG8_STAGE(bufoff, gbase, voff) do { _Pragma("unroll") for (int _i = 0; _i < 2; ++_i) \
;         __builtin_amdgcn_global_load_lds((const unsigned*)((const char*)(gbase) + (voff)[_i]), (PG8_LAS unsigned*)(lds + (bufoff) + ldsw + _i * 8192), 16, 0, 0); } while (0)
; #define PG8_LDA(dst, b, h) do { _Pragma("unroll") for (int m = 0; m < 4; ++m) _Pragma("unroll") for (int k = 0; k < 2; ++k) dst[m][k] = *(const PG8_LAS bf16x8*)(lds + PG8_SA(b, h) + aoff + m * 2048 + k * 1024); } while (0)
; #define PG8_WAIT_V(n) asm volatile("s_waitcnt vmcnt(" #n ")" ::: "memory")
;     __device__ __forceinline__ void operator()(const f32x4 (&acc)[2][2][4][2], const Unit& u, int wr, int wc, int fr, int fq) const {
;         const int row0 = u.pm * BM + wr * 64 + fr, col0 = u.pn * HALF + wc * 32 + 8 * fq;
; #pragma unroll
;         for (int ai = 0; ai < 2; ++ai)
; #pragma unroll
;             for (int m = 0; m < 4; ++m) { bf16_t* rowp = O + (size_t)(row0 + ai * HALF + m * 16) * ldc + col0;
;                 f32x4 v0, v1;
; #pragma unroll
;                 for (int j = 0; j < 1; ++j) { v0 = acc[ai][0][m][0] * sigmoid4(acc[ai][0][m][0]) * acc[ai][1][m][0]; v1 = acc[ai][0][m][1] * sigmoid4(acc[ai][0][m][1]) * acc[ai][1][m][1]; }
;                 u32x4 w; w.x = cvt_pk_bf16(v0[0], v0[1]); w.y = cvt_pk_bf16(v0[2], v0[3]); w.z = cvt_pk_bf16(v1[0], v1[1]); w.w = cvt_pk_bf16(v1[2], v1[3]);
;                 *(u32x4*)rowp = w; }
; template <class Epi, class Sched>
; __device__ __forceinline__ void gemm_phase(PG8_LAS unsigned char* lds, const Gemm g, const Sched& S, const Epi& E) {
;     ...
;             PG8_LDB(B0, 1, 0); PG8_SCHED; PG8_LDA(At, 1, 0); PG8_STAGE(PG8_SA(0, 1), a2 + hstep, voffA);
;             PG8_WAIT_L(8); PG8_BAR; PG8_WAIT_L(0); PG8_MMA(0, 0, At, B0); PG8_BAR; PG8_SCHED;
;             PG8_LDB(B1, 1, 1); PG8_STAGE(PG8_SB(1, 0), b3, voffB);
;             PG8_BAR; PG8_WAIT_L(0); PG8_MMA(0, 1, At, B1); PG8_BAR;
;             PG8_LDA(At, 1, 1); PG8_STAGE(PG8_SA(1, 0), a3, voffA);
;             PG8_BAR; PG8_WAIT_L(0); PG8_MMA(1, 0, At, B0); PG8_BAR; PG8_SCHED;
;             PG8_STAGE(PG8_SB(1, 1), b3 + hstep, voffB);
;             PG8_WAIT_V(6); PG8_BAR; PG8_MMA(1, 1, At, B1); PG8_BAR;
	ds_read_b128 v[166:169], v152 offset:49152
	ds_read_b128 v[170:173], v152 offset:50176
	ds_read_b128 v[182:185], v152 offset:51200
	ds_read_b128 v[190:193], v152 offset:52224
	ds_read_b128 v[194:197], v152 offset:53248
	ds_read_b128 v[198:201], v152 offset:54272
	ds_read_b128 v[202:205], v152 offset:55296
	ds_read_b128 v[206:209], v152 offset:56320
	s_add_i32 s21, s47, s26
	s_mov_b32 m0, s21
	s_nop 0
	global_load_lds_dwordx4 v132, s[98:99]
	s_add_i32 m0, s21, 0x2000
	s_nop 0
	global_load_lds_dwordx4 v128, s[98:99]
	s_mov_b32 m0, s35
	s_nop 0
	global_load_lds_dwordx4 v134, s[100:101]
	s_mov_b32 m0, s36
	s_nop 0
	global_load_lds_dwordx4 v130, s[100:101]
	s_add_u32 s18, s18, 0x40080
	s_addc_u32 s19, s19, 0
	s_add_i32 s20, s20, s26
	s_mov_b32 m0, s20
	s_nop 0
	global_load_lds_dwordx4 v132, s[18:19]
	s_add_i32 m0, s20, 0x2000
	s_nop 0
	global_load_lds_dwordx4 v128, s[18:19]
	s_waitcnt vmcnt(8) lgkmcnt(0)
	s_barrier
	v_mfma_f32_16x16x32_bf16 v[60:63], v[144:147], v[166:169], v[60:63]
	v_mfma_f32_16x16x32_bf16 v[56:59], v[158:161], v[166:169], v[56:59]
	v_mfma_f32_16x16x32_bf16 v[44:47], v[144:147], v[182:185], v[44:47]
	v_mfma_f32_16x16x32_bf16 v[40:43], v[158:161], v[182:185], v[40:43]
	v_mfma_f32_16x16x32_bf16 v[28:31], v[144:147], v[194:197], v[28:31]
	v_mfma_f32_16x16x32_bf16 v[24:27], v[158:161], v[194:197], v[24:27]
	v_mfma_f32_16x16x32_bf16 v[12:15], v[144:147], v[202:205], v[12:15]
	v_mfma_f32_16x16x32_bf16 v[8:11], v[158:161], v[202:205], v[8:11]
	v_mfma_f32_16x16x32_bf16 v[60:63], v[154:157], v[170:173], v[60:63]
	v_mfma_f32_16x16x32_bf16 v[56:59], v[162:165], v[170:173], v[56:59]
	v_mfma_f32_16x16x32_bf16 v[44:47], v[154:157], v[190:193], v[44:47]
	v_mfma_f32_16x16x32_bf16 v[40:43], v[162:165], v[190:193], v[40:43]
	v_mfma_f32_16x16x32_bf16 v[28:31], v[154:157], v[198:201], v[28:31]
	v_mfma_f32_16x16x32_bf16 v[24:27], v[162:165], v[198:201], v[24:27]
	v_mfma_f32_16x16x32_bf16 v[12:15], v[154:157], v[206:209], v[12:15]
	v_mfma_f32_16x16x32_bf16 v[8:11], v[162:165], v[206:209], v[8:11]
	v_mfma_f32_16x16x32_bf16 v[52:55], v[210:213], v[166:169], v[52:55]
	v_mfma_f32_16x16x32_bf16 v[48:51], v[218:221], v[166:169], v[48:51]
	v_mfma_f32_16x16x32_bf16 v[36:39], v[210:213], v[182:185], v[36:39]
	v_mfma_f32_16x16x32_bf16 v[32:35], v[218:221], v[182:185], v[32:35]
	v_mfma_f32_16x16x32_bf16 v[20:23], v[210:213], v[194:197], v[20:23]
	v_mfma_f32_16x16x32_bf16 v[16:19], v[218:221], v[194:197], v[16:19]
	v_mfma_f32_16x16x32_bf16 v[4:7], v[210:213], v[202:205], v[4:7]
	v_mfma_f32_16x16x32_bf16 v[0:3], v[218:221], v[202:205], v[0:3]
	v_mfma_f32_16x16x32_bf16 v[52:55], v[214:217], v[170:173], v[52:55]
	v_mfma_f32_16x16x32_bf16 v[48:51], v[222:225], v[170:173], v[48:51]
	v_mfma_f32_16x16x32_bf16 v[36:39], v[214:217], v[190:193], v[36:39]
	v_mfma_f32_16x16x32_bf16 v[32:35], v[222:225], v[190:193], v[32:35]
	v_mfma_f32_16x16x32_bf16 v[20:23], v[214:217], v[198:201], v[20:23]
	v_mfma_f32_16x16x32_bf16 v[16:19], v[222:225], v[198:201], v[16:19]
	v_mfma_f32_16x16x32_bf16 v[4:7], v[214:217], v[206:209], v[4:7]
	v_mfma_f32_16x16x32_bf16 v[0:3], v[222:225], v[206:209], v[0:3]
	s_barrier
	s_add_i32 s46, s46, 2
	s_add_u32 s16, s16, 0x100
	s_addc_u32 s17, s17, 0
	s_add_u32 s44, s44, 0x100
	s_addc_u32 s45, s45, 0
	s_cmp_gt_u32 s46, 13
	s_cbranch_scc0 .LBB0_1202
	v_max_f32_e32 v144, 0xc1a00000, v124
	v_mul_f32_e32 v144, 0xbfb8aa3b, v144
	v_exp_f32_e32 v157, v144
	v_max_f32_e32 v144, 0xc1a00000, v125
	v_mul_f32_e32 v144, 0xbfb8aa3b, v144
	v_exp_f32_e32 v156, v144
	v_max_f32_e32 v144, 0xc1a00000, v126
	v_mul_f32_e32 v144, 0xbfb8aa3b, v144
	v_exp_f32_e32 v159, v144
	v_max_f32_e32 v144, 0xc1a00000, v127
	v_mul_f32_e32 v144, 0xbfb8aa3b, v144
	v_exp_f32_e32 v158, v144
	v_pk_add_f32 v[156:157], v[156:157], 1.0 op_sel_hi:[1,0]
	v_lshl_or_b32 v146, s41, 7, v150
	v_mov_b32_e32 v160, v157
	v_pk_add_f32 v[158:159], v[158:159], 1.0 op_sel_hi:[1,0]
	v_mov_b32_e32 v162, v156
	v_mov_b32_e32 v161, v159
	v_mov_b32_e32 v163, v158
	v_pk_mul_f32 v[160:161], v[160:161], v[162:163]
	v_lshl_add_u32 v154, s14, 8, v148
	v_mul_f32_e32 v155, v160, v161
	v_rcp_f32_e32 v155, v155
	v_ashrrev_i32_e32 v147, 31, v146
	v_mov_b64_e32 v[144:145], s[0:1]
	v_mad_i64_i32 v[162:163], s[16:17], v154, s40, v[144:145]
	v_mul_f32_e32 v164, v161, v155
	v_mul_f32_e32 v160, v160, v155
	v_max_f32_e32 v155, 0xc1a00000, v120
	v_mul_f32_e32 v155, 0xbfb8aa3b, v155
	v_pk_mul_f32 v[158:159], v[158:159], v[160:161] op_sel_hi:[1,0]
	v_exp_f32_e32 v161, v155
	v_max_f32_e32 v155, 0xc1a00000, v121
	v_mul_f32_e32 v155, 0xbfb8aa3b, v155
	v_exp_f32_e32 v160, v155
	v_max_f32_e32 v155, 0xc1a00000, v122
	v_mul_f32_e32 v155, 0xbfb8aa3b, v155
	v_exp_f32_e32 v167, v155
	v_max_f32_e32 v155, 0xc1a00000, v123
	v_mul_f32_e32 v155, 0xbfb8aa3b, v155
	v_exp_f32_e32 v166, v155
	v_pk_mul_f32 v[156:157], v[156:157], v[164:165] op_sel_hi:[1,0]
	v_pk_mul_f32 v[126:127], v[126:127], v[158:159]
	v_pk_mul_f32 v[124:125], v[124:125], v[156:157]
	v_pk_add_f32 v[156:157], v[160:161], 1.0 op_sel_hi:[1,0]
	v_pk_add_f32 v[160:161], v[166:167], 1.0 op_sel_hi:[1,0]
	v_mov_b32_e32 v164, v157
	v_mov_b32_e32 v165, v161
	v_mov_b32_e32 v166, v156
	v_mov_b32_e32 v167, v160
	v_pk_mul_f32 v[164:165], v[164:165], v[166:167]
	v_pk_mul_f32 v[118:119], v[126:127], v[118:119]
	v_mul_f32_e32 v155, v164, v165
	v_rcp_f32_e32 v155, v155
	v_pk_mul_f32 v[116:117], v[124:125], v[116:117]
	v_lshlrev_b64 v[146:147], 1, v[146:147]
	v_lshl_add_u64 v[162:163], v[162:163], 0, v[146:147]
	v_mul_f32_e32 v124, v165, v155
	v_mul_f32_e32 v126, v164, v155
	v_pk_mul_f32 v[126:127], v[160:161], v[126:127] op_sel_hi:[1,0]
	v_pk_mul_f32 v[124:125], v[156:157], v[124:125] op_sel_hi:[1,0]
; __device__ __forceinline__ unsigned cvt_pk_bf16(float lo, float hi) { unsigned r; asm volatile("v_cvt_pk_bf16_f32 %0, %1, %2" : "=v"(r) : "v"(lo), "v"(hi)); return r; }
; __device__ __forceinline__ f32x4 sigmoid4(f32x4 x) {
;     f32x4 d;
; #pragma unroll
;     for (int j = 0; j < 4; ++j) d[j] = 1.0f + __expf(-fmaxf(x[j], -20.0f));
;     const float p01 = d[0] * d[1], p23 = d[2] * d[3], r = __builtin_amdgcn_rcpf(p01 * p23), r01 = r * p23, r23 = r * p01;
;     return (f32x4){r01 * d[1], r01 * d[0], r23 * d[3], r23 * d[2]};
; }
;     __device__ __forceinline__ void operator()(const f32x4 (&acc)[2][2][4][2], const Unit& u, int wr, int wc, int fr, int fq) const {
;         const int row0 = u.pm * BM + wr * 64 + fr, col0 = u.pn * HALF + wc * 32 + 8 * fq;
; #pragma unroll
;         for (int ai = 0; ai < 2; ++ai)
; #pragma unroll
;             for (int m = 0; m < 4; ++m) { bf16_t* rowp = O + (size_t)(row0 + ai * HALF + m * 16) * ldc + col0;
;                 f32x4 v0, v1;
; #pragma unroll
;                 for (int j = 0; j < 1; ++j) { v0 = acc[ai][0][m][0] * sigmoid4(acc[ai][0][m][0]) * acc[ai][1][m][0]; v1 = acc[ai][0][m][1] * sigmoid4(acc[ai][0][m][1]) * acc[ai][1][m][1]; }
;                 u32x4 w; w.x = cvt_pk_bf16(v0[0], v0[1]); w.y = cvt_pk_bf16(v0[2], v0[3]); w.z = cvt_pk_bf16(v1[0], v1[1]); w.w = cvt_pk_bf16(v1[2], v1[3]);
;                 *(u32x4*)rowp = w; }
	v_pk_mul_f32 v[122:123], v[122:123], v[126:127]
	v_pk_mul_f32 v[120:121], v[120:121], v[124:125]
	v_pk_mul_f32 v[122:123], v[122:123], v[114:115]
	v_pk_mul_f32 v[114:115], v[120:121], v[112:113]
	v_cvt_pk_bf16_f32 v112, v116, v117
	v_cvt_pk_bf16_f32 v113, v118, v119
	v_max_f32_e32 v116, 0xc1a00000, v108
	v_max_f32_e32 v118, 0xc1a00000, v110
	v_mul_f32_e32 v116, 0xbfb8aa3b, v116
	v_mul_f32_e32 v118, 0xbfb8aa3b, v118
	v_exp_f32_e32 v117, v116
	v_exp_f32_e32 v119, v118
	v_max_f32_e32 v116, 0xc1a00000, v109
	v_max_f32_e32 v118, 0xc1a00000, v111
	v_mul_f32_e32 v116, 0xbfb8aa3b, v116
	v_mul_f32_e32 v118, 0xbfb8aa3b, v118
	v_exp_f32_e32 v116, v116
	v_exp_f32_e32 v118, v118
	v_cvt_pk_bf16_f32 v114, v114, v115
	v_cvt_pk_bf16_f32 v115, v122, v123
	global_store_dwordx4 v[162:163], v[112:115], off
	v_or_b32_e32 v120, 16, v154
	s_and_b64 vcc, exec, s[2:3]
	v_pk_add_f32 v[112:113], v[116:117], 1.0 op_sel_hi:[1,0]
	v_pk_add_f32 v[114:115], v[118:119], 1.0 op_sel_hi:[1,0]
	v_mov_b32_e32 v116, v113
	v_mov_b32_e32 v117, v115
	v_mov_b32_e32 v118, v112
	v_mov_b32_e32 v119, v114
	v_pk_mul_f32 v[116:117], v[116:117], v[118:119]
	s_mov_b32 s41, s6
	v_mul_f32_e32 v118, v116, v117
	v_rcp_f32_e32 v121, v118
	v_mad_i64_i32 v[118:119], s[16:17], v120, s40, v[144:145]
	v_lshl_add_u64 v[118:119], v[118:119], 0, v[146:147]
	v_mul_f32_e32 v116, v116, v121
	v_mul_f32_e32 v120, v117, v121
	v_pk_mul_f32 v[114:115], v[114:115], v[116:117] op_sel_hi:[1,0]
	v_max_f32_e32 v116, 0xc1a00000, v104
	v_max_f32_e32 v121, 0xc1a00000, v106
	v_mul_f32_e32 v116, 0xbfb8aa3b, v116
	v_mul_f32_e32 v121, 0xbfb8aa3b, v121
	v_exp_f32_e32 v117, v116
	v_exp_f32_e32 v123, v121
	v_max_f32_e32 v116, 0xc1a00000, v105
	v_max_f32_e32 v121, 0xc1a00000, v107
	v_mul_f32_e32 v116, 0xbfb8aa3b, v116
	v_mul_f32_e32 v121, 0xbfb8aa3b, v121
	v_exp_f32_e32 v116, v116
	v_exp_f32_e32 v122, v121
	v_pk_mul_f32 v[112:113], v[112:113], v[120:121] op_sel_hi:[1,0]
	v_pk_mul_f32 v[110:111], v[110:111], v[114:115]
	v_pk_mul_f32 v[108:109], v[108:109], v[112:113]
	v_pk_add_f32 v[112:113], v[116:117], 1.0 op_sel_hi:[1,0]
	v_pk_add_f32 v[116:117], v[122:123], 1.0 op_sel_hi:[1,0]
	v_mov_b32_e32 v120, v113
	v_mov_b32_e32 v121, v117
	v_mov_b32_e32 v122, v112
	v_mov_b32_e32 v123, v116
	v_pk_mul_f32 v[120:121], v[120:121], v[122:123]
	v_pk_mul_f32 v[102:103], v[110:111], v[102:103]
	v_mul_f32_e32 v122, v120, v121
	v_rcp_f32_e32 v122, v122
	v_pk_mul_f32 v[100:101], v[108:109], v[100:101]
	s_mov_b32 s14, s8
	s_mov_b64 s[18:19], s[12:13]
	v_mul_f32_e32 v108, v121, v122
	v_mul_f32_e32 v110, v120, v122
	v_pk_mul_f32 v[110:111], v[116:117], v[110:111] op_sel_hi:[1,0]
	v_pk_mul_f32 v[108:109], v[112:113], v[108:109] op_sel_hi:[1,0]
	v_pk_mul_f32 v[106:107], v[106:107], v[110:111]
	v_pk_mul_f32 v[104:105], v[104:105], v[108:109]
	v_pk_mul_f32 v[106:107], v[106:107], v[98:99]
	v_pk_mul_f32 v[98:99], v[104:105], v[96:97]
	v_cvt_pk_bf16_f32 v96, v100, v101
	v_cvt_pk_bf16_f32 v97, v102, v103
	v_max_f32_e32 v100, 0xc1a00000, v92
	v_max_f32_e32 v102, 0xc1a00000, v94
	v_mul_f32_e32 v100, 0xbfb8aa3b, v100
	v_mul_f32_e32 v102, 0xbfb8aa3b, v102
	v_exp_f32_e32 v101, v100
	v_exp_f32_e32 v103, v102
	v_max_f32_e32 v100, 0xc1a00000, v93
	v_max_f32_e32 v102, 0xc1a00000, v95
	v_mul_f32_e32 v100, 0xbfb8aa3b, v100
	v_mul_f32_e32 v102, 0xbfb8aa3b, v102
	v_exp_f32_e32 v100, v100
	v_exp_f32_e32 v102, v102
	v_cvt_pk_bf16_f32 v98, v98, v99
	v_cvt_pk_bf16_f32 v99, v106, v107
	global_store_dwordx4 v[118:119], v[96:99], off
	v_or_b32_e32 v104, 32, v154
	s_nop 0
	v_pk_add_f32 v[96:97], v[100:101], 1.0 op_sel_hi:[1,0]
	v_pk_add_f32 v[98:99], v[102:103], 1.0 op_sel_hi:[1,0]
	v_mov_b32_e32 v100, v97
	v_mov_b32_e32 v101, v99
	v_mov_b32_e32 v102, v96
	v_mov_b32_e32 v103, v98
	v_pk_mul_f32 v[100:101], v[100:101], v[102:103]
	s_nop 0
	v_mul_f32_e32 v102, v100, v101
	v_rcp_f32_e32 v105, v102
	v_mad_i64_i32 v[102:103], s[16:17], v104, s40, v[144:145]
	v_lshl_add_u64 v[102:103], v[102:103], 0, v[146:147]
	v_mul_f32_e32 v100, v100, v105
	v_mul_f32_e32 v104, v101, v105
	v_pk_mul_f32 v[98:99], v[98:99], v[100:101] op_sel_hi:[1,0]
	v_max_f32_e32 v100, 0xc1a00000, v88
	v_max_f32_e32 v105, 0xc1a00000, v90
	v_mul_f32_e32 v100, 0xbfb8aa3b, v100
	v_mul_f32_e32 v105, 0xbfb8aa3b, v105
	v_exp_f32_e32 v101, v100
	v_exp_f32_e32 v107, v105
	v_max_f32_e32 v100, 0xc1a00000, v89
	v_max_f32_e32 v105, 0xc1a00000, v91
	v_mul_f32_e32 v100, 0xbfb8aa3b, v100
	v_mul_f32_e32 v105, 0xbfb8aa3b, v105
	v_exp_f32_e32 v100, v100
	v_exp_f32_e32 v106, v105
	v_pk_mul_f32 v[96:97], v[96:97], v[104:105] op_sel_hi:[1,0]
	v_pk_mul_f32 v[94:95], v[94:95], v[98:99]
	v_pk_mul_f32 v[92:93], v[92:93], v[96:97]
	v_pk_add_f32 v[96:97], v[100:101], 1.0 op_sel_hi:[1,0]
	v_pk_add_f32 v[100:101], v[106:107], 1.0 op_sel_hi:[1,0]
	v_mov_b32_e32 v104, v97
	v_mov_b32_e32 v105, v101
	v_mov_b32_e32 v106, v96
	v_mov_b32_e32 v107, v100
	v_pk_mul_f32 v[104:105], v[104:105], v[106:107]
	v_pk_mul_f32 v[86:87], v[94:95], v[86:87]
	v_mul_f32_e32 v106, v104, v105
	v_rcp_f32_e32 v106, v106
	v_pk_mul_f32 v[84:85], v[92:93], v[84:85]
	v_mul_f32_e32 v92, v105, v106
	v_mul_f32_e32 v94, v104, v106
	v_pk_mul_f32 v[94:95], v[100:101], v[94:95] op_sel_hi:[1,0]
	v_pk_mul_f32 v[92:93], v[96:97], v[92:93] op_sel_hi:[1,0]
	v_pk_mul_f32 v[90:91], v[90:91], v[94:95]
	v_pk_mul_f32 v[88:89], v[88:89], v[92:93]
	v_pk_mul_f32 v[90:91], v[90:91], v[82:83]
	v_pk_mul_f32 v[82:83], v[88:89], v[80:81]
	v_cvt_pk_bf16_f32 v80, v84, v85
	v_cvt_pk_bf16_f32 v81, v86, v87
	v_max_f32_e32 v84, 0xc1a00000, v76
	v_max_f32_e32 v86, 0xc1a00000, v78
	v_mul_f32_e32 v84, 0xbfb8aa3b, v84
	v_mul_f32_e32 v86, 0xbfb8aa3b, v86
	v_exp_f32_e32 v85, v84
	v_exp_f32_e32 v87, v86
; __device__ __forceinline__ unsigned cvt_pk_bf16(float lo, float hi) { unsigned r; asm volatile("v_cvt_pk_bf16_f32 %0, %1, %2" : "=v"(r) : "v"(lo), "v"(hi)); return r; }
; __device__ __forceinline__ f32x4 sigmoid4(f32x4 x) {
;     f32x4 d;
; #pragma unroll
;     for (int j = 0; j < 4; ++j) d[j] = 1.0f + __expf(-fmaxf(x[j], -20.0f));
;     const float p01 = d[0] * d[1], p23 = d[2] * d[3], r = __builtin_amdgcn_rcpf(p01 * p23), r01 = r * p23, r23 = r * p01;
;     return (f32x4){r01 * d[1], r01 * d[0], r23 * d[3], r23 * d[2]};
; }
;     __device__ __forceinline__ void operator()(const f32x4 (&acc)[2][2][4][2], const Unit& u, int wr, int wc, int fr, int fq) const {
;         const int row0 = u.pm * BM + wr * 64 + fr, col0 = u.pn * HALF + wc * 32 + 8 * fq;
; #pragma unroll
;         for (int ai = 0; ai < 2; ++ai)
; #pragma unroll
;             for (int m = 0; m < 4; ++m) { bf16_t* rowp = O + (size_t)(row0 + ai * HALF + m * 16) * ldc + col0;
;                 f32x4 v0, v1;
; #pragma unroll
;                 for (int j = 0; j < 1; ++j) { v0 = acc[ai][0][m][0] * sigmoid4(acc[ai][0][m][0]) * acc[ai][1][m][0]; v1 = acc[ai][0][m][1] * sigmoid4(acc[ai][0][m][1]) * acc[ai][1][m][1]; }
;                 u32x4 w; w.x = cvt_pk_bf16(v0[0], v0[1]); w.y = cvt_pk_bf16(v0[2], v0[3]); w.z = cvt_pk_bf16(v1[0], v1[1]); w.w = cvt_pk_bf16(v1[2], v1[3]);
;                 *(u32x4*)rowp = w; }
	v_max_f32_e32 v84, 0xc1a00000, v77
	v_max_f32_e32 v86, 0xc1a00000, v79
	v_mul_f32_e32 v84, 0xbfb8aa3b, v84
	v_mul_f32_e32 v86, 0xbfb8aa3b, v86
	v_exp_f32_e32 v84, v84
	v_exp_f32_e32 v86, v86
	v_cvt_pk_bf16_f32 v82, v82, v83
	v_cvt_pk_bf16_f32 v83, v90, v91
	global_store_dwordx4 v[102:103], v[80:83], off
	v_or_b32_e32 v88, 48, v154
	s_nop 0
	v_pk_add_f32 v[80:81], v[84:85], 1.0 op_sel_hi:[1,0]
	v_pk_add_f32 v[82:83], v[86:87], 1.0 op_sel_hi:[1,0]
	v_mov_b32_e32 v84, v81
	v_mov_b32_e32 v85, v83
	v_mov_b32_e32 v86, v80
	v_mov_b32_e32 v87, v82
	v_pk_mul_f32 v[84:85], v[84:85], v[86:87]
	s_nop 0
	v_mul_f32_e32 v86, v84, v85
	v_rcp_f32_e32 v89, v86
	v_mad_i64_i32 v[86:87], s[16:17], v88, s40, v[144:145]
	v_lshl_add_u64 v[86:87], v[86:87], 0, v[146:147]
	v_mul_f32_e32 v84, v84, v89
	v_mul_f32_e32 v88, v85, v89
	v_pk_mul_f32 v[82:83], v[82:83], v[84:85] op_sel_hi:[1,0]
	v_max_f32_e32 v84, 0xc1a00000, v72
	v_max_f32_e32 v89, 0xc1a00000, v74
	v_mul_f32_e32 v84, 0xbfb8aa3b, v84
	v_mul_f32_e32 v89, 0xbfb8aa3b, v89
	v_exp_f32_e32 v85, v84
	v_exp_f32_e32 v91, v89
	v_max_f32_e32 v84, 0xc1a00000, v73
	v_max_f32_e32 v89, 0xc1a00000, v75
	v_mul_f32_e32 v84, 0xbfb8aa3b, v84
	v_mul_f32_e32 v89, 0xbfb8aa3b, v89
	v_exp_f32_e32 v84, v84
	v_exp_f32_e32 v90, v89
	v_pk_mul_f32 v[80:81], v[80:81], v[88:89] op_sel_hi:[1,0]
	v_pk_mul_f32 v[78:79], v[78:79], v[82:83]
	v_pk_mul_f32 v[76:77], v[76:77], v[80:81]
	v_pk_add_f32 v[80:81], v[84:85], 1.0 op_sel_hi:[1,0]
	v_pk_add_f32 v[84:85], v[90:91], 1.0 op_sel_hi:[1,0]
	v_mov_b32_e32 v88, v81
	v_mov_b32_e32 v89, v85
	v_mov_b32_e32 v90, v80
	v_mov_b32_e32 v91, v84
	v_pk_mul_f32 v[88:89], v[88:89], v[90:91]
	v_pk_mul_f32 v[70:71], v[78:79], v[70:71]
	v_mul_f32_e32 v90, v88, v89
	v_rcp_f32_e32 v90, v90
	v_pk_mul_f32 v[68:69], v[76:77], v[68:69]
	v_mul_f32_e32 v76, v89, v90
	v_mul_f32_e32 v78, v88, v90
	v_pk_mul_f32 v[78:79], v[84:85], v[78:79] op_sel_hi:[1,0]
	v_pk_mul_f32 v[76:77], v[80:81], v[76:77] op_sel_hi:[1,0]
	v_pk_mul_f32 v[74:75], v[74:75], v[78:79]
	v_pk_mul_f32 v[72:73], v[72:73], v[76:77]
	v_pk_mul_f32 v[74:75], v[74:75], v[66:67]
	v_pk_mul_f32 v[66:67], v[72:73], v[64:65]
	v_cvt_pk_bf16_f32 v64, v68, v69
	v_cvt_pk_bf16_f32 v65, v70, v71
	v_max_f32_e32 v68, 0xc1a00000, v60
	v_max_f32_e32 v70, 0xc1a00000, v62
	v_mul_f32_e32 v68, 0xbfb8aa3b, v68
	v_mul_f32_e32 v70, 0xbfb8aa3b, v70
	v_exp_f32_e32 v69, v68
	v_exp_f32_e32 v71, v70
	v_max_f32_e32 v68, 0xc1a00000, v61
	v_max_f32_e32 v70, 0xc1a00000, v63
	v_mul_f32_e32 v68, 0xbfb8aa3b, v68
	v_mul_f32_e32 v70, 0xbfb8aa3b, v70
	v_exp_f32_e32 v68, v68
	v_exp_f32_e32 v70, v70
	v_cvt_pk_bf16_f32 v66, v66, v67
	v_cvt_pk_bf16_f32 v67, v74, v75
	global_store_dwordx4 v[86:87], v[64:67], off
	v_add_u32_e32 v72, 0x80, v154
	s_nop 0
	v_pk_add_f32 v[64:65], v[68:69], 1.0 op_sel_hi:[1,0]
	v_pk_add_f32 v[66:67], v[70:71], 1.0 op_sel_hi:[1,0]
	v_mov_b32_e32 v68, v65
	v_mov_b32_e32 v69, v67
	v_mov_b32_e32 v70, v64
	v_mov_b32_e32 v71, v66
	v_pk_mul_f32 v[68:69], v[68:69], v[70:71]
	s_nop 0
	v_mul_f32_e32 v70, v68, v69
	v_rcp_f32_e32 v73, v70
	v_mad_i64_i32 v[70:71], s[16:17], v72, s40, v[144:145]
	v_lshl_add_u64 v[70:71], v[70:71], 0, v[146:147]
	v_mul_f32_e32 v68, v68, v73
	v_mul_f32_e32 v72, v69, v73
	v_pk_mul_f32 v[66:67], v[66:67], v[68:69] op_sel_hi:[1,0]
	v_max_f32_e32 v68, 0xc1a00000, v56
	v_max_f32_e32 v73, 0xc1a00000, v58
	v_mul_f32_e32 v68, 0xbfb8aa3b, v68
	v_mul_f32_e32 v73, 0xbfb8aa3b, v73
	v_exp_f32_e32 v69, v68
	v_exp_f32_e32 v75, v73
	v_max_f32_e32 v68, 0xc1a00000, v57
	v_max_f32_e32 v73, 0xc1a00000, v59
	v_mul_f32_e32 v68, 0xbfb8aa3b, v68
	v_mul_f32_e32 v73, 0xbfb8aa3b, v73
	v_exp_f32_e32 v68, v68
	v_exp_f32_e32 v74, v73
	v_pk_mul_f32 v[64:65], v[64:65], v[72:73] op_sel_hi:[1,0]
	v_pk_mul_f32 v[62:63], v[62:63], v[66:67]
	v_pk_mul_f32 v[60:61], v[60:61], v[64:65]
	v_pk_add_f32 v[64:65], v[68:69], 1.0 op_sel_hi:[1,0]
	v_pk_add_f32 v[68:69], v[74:75], 1.0 op_sel_hi:[1,0]
	v_mov_b32_e32 v72, v65
	v_mov_b32_e32 v73, v69
	v_mov_b32_e32 v74, v64
	v_mov_b32_e32 v75, v68
	v_pk_mul_f32 v[72:73], v[72:73], v[74:75]
	v_pk_mul_f32 v[54:55], v[62:63], v[54:55]
	v_mul_f32_e32 v74, v72, v73
	v_rcp_f32_e32 v74, v74
	v_pk_mul_f32 v[52:53], v[60:61], v[52:53]
	v_mul_f32_e32 v60, v73, v74
	v_mul_f32_e32 v62, v72, v74
	v_pk_mul_f32 v[62:63], v[68:69], v[62:63] op_sel_hi:[1,0]
	v_pk_mul_f32 v[60:61], v[64:65], v[60:61] op_sel_hi:[1,0]
	v_pk_mul_f32 v[58:59], v[58:59], v[62:63]
	v_pk_mul_f32 v[56:57], v[56:57], v[60:61]
	v_pk_mul_f32 v[58:59], v[58:59], v[50:51]
	v_pk_mul_f32 v[50:51], v[56:57], v[48:49]
	v_cvt_pk_bf16_f32 v48, v52, v53
	v_cvt_pk_bf16_f32 v49, v54, v55
	v_max_f32_e32 v52, 0xc1a00000, v44
	v_max_f32_e32 v54, 0xc1a00000, v46
	v_mul_f32_e32 v52, 0xbfb8aa3b, v52
	v_mul_f32_e32 v54, 0xbfb8aa3b, v54
	v_exp_f32_e32 v53, v52
	v_exp_f32_e32 v55, v54
	v_max_f32_e32 v52, 0xc1a00000, v45
	v_max_f32_e32 v54, 0xc1a00000, v47
	v_mul_f32_e32 v52, 0xbfb8aa3b, v52
	v_mul_f32_e32 v54, 0xbfb8aa3b, v54
	v_exp_f32_e32 v52, v52
	v_exp_f32_e32 v54, v54
	v_cvt_pk_bf16_f32 v50, v50, v51
	v_cvt_pk_bf16_f32 v51, v58, v59
	global_store_dwordx4 v[70:71], v[48:51], off
	v_add_u32_e32 v56, 0x90, v154
	s_nop 0
	v_pk_add_f32 v[48:49], v[52:53], 1.0 op_sel_hi:[1,0]
	v_pk_add_f32 v[50:51], v[54:55], 1.0 op_sel_hi:[1,0]
	v_mov_b32_e32 v52, v49
	v_mov_b32_e32 v53, v51
	v_mov_b32_e32 v54, v48
	v_mov_b32_e32 v55, v50
	v_pk_mul_f32 v[52:53], v[52:53], v[54:55]
	s_nop 0
	v_mul_f32_e32 v54, v52, v53
	v_rcp_f32_e32 v57, v54
	v_mad_i64_i32 v[54:55], s[16:17], v56, s40, v[144:145]
	v_lshl_add_u64 v[54:55], v[54:55], 0, v[146:147]
	v_mul_f32_e32 v52, v52, v57
	v_mul_f32_e32 v56, v53, v57
	v_pk_mul_f32 v[50:51], v[50:51], v[52:53] op_sel_hi:[1,0]
; __device__ __forceinline__ unsigned cvt_pk_bf16(float lo, float hi) { unsigned r; asm volatile("v_cvt_pk_bf16_f32 %0, %1, %2" : "=v"(r) : "v"(lo), "v"(hi)); return r; }
; __device__ __forceinline__ f32x4 sigmoid4(f32x4 x) {
;     f32x4 d;
; #pragma unroll
;     for (int j = 0; j < 4; ++j) d[j] = 1.0f + __expf(-fmaxf(x[j], -20.0f));
;     const float p01 = d[0] * d[1], p23 = d[2] * d[3], r = __builtin_amdgcn_rcpf(p01 * p23), r01 = r * p23, r23 = r * p01;
;     return (f32x4){r01 * d[1], r01 * d[0], r23 * d[3], r23 * d[2]};
; }
;     __device__ __forceinline__ void operator()(const f32x4 (&acc)[2][2][4][2], const Unit& u, int wr, int wc, int fr, int fq) const {
;         const int row0 = u.pm * BM + wr * 64 + fr, col0 = u.pn * HALF + wc * 32 + 8 * fq;
; #pragma unroll
;         for (int ai = 0; ai < 2; ++ai)
; #pragma unroll
;             for (int m = 0; m < 4; ++m) { bf16_t* rowp = O + (size_t)(row0 + ai * HALF + m * 16) * ldc + col0;
;                 f32x4 v0, v1;
; #pragma unroll
;                 for (int j = 0; j < 1; ++j) { v0 = acc[ai][0][m][0] * sigmoid4(acc[ai][0][m][0]) * acc[ai][1][m][0]; v1 = acc[ai][0][m][1] * sigmoid4(acc[ai][0][m][1]) * acc[ai][1][m][1]; }
;                 u32x4 w; w.x = cvt_pk_bf16(v0[0], v0[1]); w.y = cvt_pk_bf16(v0[2], v0[3]); w.z = cvt_pk_bf16(v1[0], v1[1]); w.w = cvt_pk_bf16(v1[2], v1[3]);
;                 *(u32x4*)rowp = w; }
	v_max_f32_e32 v52, 0xc1a00000, v40
	v_max_f32_e32 v57, 0xc1a00000, v42
	v_mul_f32_e32 v52, 0xbfb8aa3b, v52
	v_mul_f32_e32 v57, 0xbfb8aa3b, v57
	v_exp_f32_e32 v53, v52
	v_exp_f32_e32 v59, v57
	v_max_f32_e32 v52, 0xc1a00000, v41
	v_max_f32_e32 v57, 0xc1a00000, v43
	v_mul_f32_e32 v52, 0xbfb8aa3b, v52
	v_mul_f32_e32 v57, 0xbfb8aa3b, v57
	v_exp_f32_e32 v52, v52
	v_exp_f32_e32 v58, v57
	v_pk_mul_f32 v[48:49], v[48:49], v[56:57] op_sel_hi:[1,0]
	v_pk_mul_f32 v[46:47], v[46:47], v[50:51]
	v_pk_mul_f32 v[44:45], v[44:45], v[48:49]
	v_pk_add_f32 v[48:49], v[52:53], 1.0 op_sel_hi:[1,0]
	v_pk_add_f32 v[52:53], v[58:59], 1.0 op_sel_hi:[1,0]
	v_mov_b32_e32 v56, v49
	v_mov_b32_e32 v57, v53
	v_mov_b32_e32 v58, v48
	v_mov_b32_e32 v59, v52
	v_pk_mul_f32 v[56:57], v[56:57], v[58:59]
	v_pk_mul_f32 v[38:39], v[46:47], v[38:39]
	v_mul_f32_e32 v58, v56, v57
	v_rcp_f32_e32 v58, v58
	v_pk_mul_f32 v[36:37], v[44:45], v[36:37]
	v_mul_f32_e32 v44, v57, v58
	v_mul_f32_e32 v46, v56, v58
	v_pk_mul_f32 v[46:47], v[52:53], v[46:47] op_sel_hi:[1,0]
	v_pk_mul_f32 v[44:45], v[48:49], v[44:45] op_sel_hi:[1,0]
	v_pk_mul_f32 v[42:43], v[42:43], v[46:47]
	v_pk_mul_f32 v[40:41], v[40:41], v[44:45]
	v_pk_mul_f32 v[42:43], v[42:43], v[34:35]
	v_pk_mul_f32 v[34:35], v[40:41], v[32:33]
	v_cvt_pk_bf16_f32 v32, v36, v37
	v_cvt_pk_bf16_f32 v33, v38, v39
	v_max_f32_e32 v36, 0xc1a00000, v28
	v_max_f32_e32 v38, 0xc1a00000, v30
	v_mul_f32_e32 v36, 0xbfb8aa3b, v36
	v_mul_f32_e32 v38, 0xbfb8aa3b, v38
	v_exp_f32_e32 v37, v36
	v_exp_f32_e32 v39, v38
	v_max_f32_e32 v36, 0xc1a00000, v29
	v_max_f32_e32 v38, 0xc1a00000, v31
	v_mul_f32_e32 v36, 0xbfb8aa3b, v36
	v_mul_f32_e32 v38, 0xbfb8aa3b, v38
	v_exp_f32_e32 v36, v36
	v_exp_f32_e32 v38, v38
	v_cvt_pk_bf16_f32 v34, v34, v35
	v_cvt_pk_bf16_f32 v35, v42, v43
	global_store_dwordx4 v[54:55], v[32:35], off
	v_add_u32_e32 v40, 0xa0, v154
	s_nop 0
	v_pk_add_f32 v[32:33], v[36:37], 1.0 op_sel_hi:[1,0]
	v_pk_add_f32 v[34:35], v[38:39], 1.0 op_sel_hi:[1,0]
	v_mov_b32_e32 v36, v33
	v_mov_b32_e32 v37, v35
	v_mov_b32_e32 v38, v32
	v_mov_b32_e32 v39, v34
	v_pk_mul_f32 v[36:37], v[36:37], v[38:39]
	s_nop 0
	v_mul_f32_e32 v38, v36, v37
	v_rcp_f32_e32 v41, v38
	v_mad_i64_i32 v[38:39], s[16:17], v40, s40, v[144:145]
	v_lshl_add_u64 v[38:39], v[38:39], 0, v[146:147]
	v_mul_f32_e32 v36, v36, v41
	v_mul_f32_e32 v40, v37, v41
	v_pk_mul_f32 v[34:35], v[34:35], v[36:37] op_sel_hi:[1,0]
	v_max_f32_e32 v36, 0xc1a00000, v24
	v_max_f32_e32 v41, 0xc1a00000, v26
	v_mul_f32_e32 v36, 0xbfb8aa3b, v36
	v_mul_f32_e32 v41, 0xbfb8aa3b, v41
	v_exp_f32_e32 v37, v36
	v_exp_f32_e32 v43, v41
	v_max_f32_e32 v36, 0xc1a00000, v25
	v_max_f32_e32 v41, 0xc1a00000, v27
	v_mul_f32_e32 v36, 0xbfb8aa3b, v36
	v_mul_f32_e32 v41, 0xbfb8aa3b, v41
	v_exp_f32_e32 v36, v36
	v_exp_f32_e32 v42, v41
	v_pk_mul_f32 v[32:33], v[32:33], v[40:41] op_sel_hi:[1,0]
	v_pk_mul_f32 v[30:31], v[30:31], v[34:35]
	v_pk_mul_f32 v[28:29], v[28:29], v[32:33]
	v_pk_add_f32 v[32:33], v[36:37], 1.0 op_sel_hi:[1,0]
	v_pk_add_f32 v[36:37], v[42:43], 1.0 op_sel_hi:[1,0]
	v_mov_b32_e32 v40, v33
	v_mov_b32_e32 v41, v37
	v_mov_b32_e32 v42, v32
	v_mov_b32_e32 v43, v36
	v_pk_mul_f32 v[40:41], v[40:41], v[42:43]
	v_pk_mul_f32 v[22:23], v[30:31], v[22:23]
	v_mul_f32_e32 v42, v40, v41
	v_rcp_f32_e32 v42, v42
	v_pk_mul_f32 v[20:21], v[28:29], v[20:21]
	v_mul_f32_e32 v28, v41, v42
	v_mul_f32_e32 v30, v40, v42
	v_pk_mul_f32 v[30:31], v[36:37], v[30:31] op_sel_hi:[1,0]
	v_pk_mul_f32 v[28:29], v[32:33], v[28:29] op_sel_hi:[1,0]
	v_pk_mul_f32 v[26:27], v[26:27], v[30:31]
	v_pk_mul_f32 v[24:25], v[24:25], v[28:29]
	v_pk_mul_f32 v[26:27], v[26:27], v[18:19]
	v_pk_mul_f32 v[18:19], v[24:25], v[16:17]
	v_cvt_pk_bf16_f32 v16, v20, v21
	v_cvt_pk_bf16_f32 v17, v22, v23
	v_max_f32_e32 v20, 0xc1a00000, v12
	v_max_f32_e32 v22, 0xc1a00000, v14
	v_mul_f32_e32 v20, 0xbfb8aa3b, v20
	v_mul_f32_e32 v22, 0xbfb8aa3b, v22
	v_exp_f32_e32 v21, v20
	v_exp_f32_e32 v23, v22
	v_max_f32_e32 v20, 0xc1a00000, v13
	v_max_f32_e32 v22, 0xc1a00000, v15
	v_mul_f32_e32 v20, 0xbfb8aa3b, v20
	v_mul_f32_e32 v22, 0xbfb8aa3b, v22
	v_exp_f32_e32 v20, v20
	v_exp_f32_e32 v22, v22
	v_cvt_pk_bf16_f32 v18, v18, v19
	v_cvt_pk_bf16_f32 v19, v26, v27
	global_store_dwordx4 v[38:39], v[16:19], off
	v_add_u32_e32 v24, 0xb0, v154
	s_nop 0
	v_pk_add_f32 v[16:17], v[20:21], 1.0 op_sel_hi:[1,0]
	v_pk_add_f32 v[18:19], v[22:23], 1.0 op_sel_hi:[1,0]
	v_mov_b32_e32 v20, v17
	v_mov_b32_e32 v21, v19
	v_mov_b32_e32 v22, v16
	v_mov_b32_e32 v23, v18
	v_pk_mul_f32 v[20:21], v[20:21], v[22:23]
	s_nop 0
	v_mul_f32_e32 v22, v20, v21
	v_rcp_f32_e32 v25, v22
	v_mad_i64_i32 v[22:23], s[16:17], v24, s40, v[144:145]
	v_lshl_add_u64 v[22:23], v[22:23], 0, v[146:147]
	v_mul_f32_e32 v20, v20, v25
	v_mul_f32_e32 v24, v21, v25
	v_pk_mul_f32 v[18:19], v[18:19], v[20:21] op_sel_hi:[1,0]
	v_max_f32_e32 v20, 0xc1a00000, v8
	v_max_f32_e32 v25, 0xc1a00000, v10
	v_mul_f32_e32 v20, 0xbfb8aa3b, v20
	v_mul_f32_e32 v25, 0xbfb8aa3b, v25
	v_exp_f32_e32 v21, v20
	v_exp_f32_e32 v27, v25
	v_max_f32_e32 v20, 0xc1a00000, v9
	v_max_f32_e32 v25, 0xc1a00000, v11
	v_mul_f32_e32 v20, 0xbfb8aa3b, v20
	v_mul_f32_e32 v25, 0xbfb8aa3b, v25
	v_exp_f32_e32 v20, v20
	v_exp_f32_e32 v26, v25
	v_pk_mul_f32 v[16:17], v[16:17], v[24:25] op_sel_hi:[1,0]
	v_pk_mul_f32 v[14:15], v[14:15], v[18:19]
	v_pk_mul_f32 v[12:13], v[12:13], v[16:17]
	v_pk_add_f32 v[16:17], v[20:21], 1.0 op_sel_hi:[1,0]
	v_pk_add_f32 v[20:21], v[26:27], 1.0 op_sel_hi:[1,0]
	v_mov_b32_e32 v24, v17
	v_mov_b32_e32 v25, v21
	v_mov_b32_e32 v26, v16
	v_mov_b32_e32 v27, v20
	v_pk_mul_f32 v[24:25], v[24:25], v[26:27]
	v_pk_mul_f32 v[6:7], v[14:15], v[6:7]
	v_mul_f32_e32 v26, v24, v25
	v_rcp_f32_e32 v26, v26
	v_pk_mul_f32 v[4:5], v[12:13], v[4:5]
	s_mov_b64 s[16:17], s[10:11]
	v_mul_f32_e32 v12, v25, v26
	v_mul_f32_e32 v14, v24, v26
	v_pk_mul_f32 v[14:15], v[20:21], v[14:15] op_sel_hi:[1,0]
	v_pk_mul_f32 v[12:13], v[16:17], v[12:13] op_sel_hi:[1,0]
	v_pk_mul_f32 v[10:11], v[10:11], v[14:15]
	v_pk_mul_f32 v[8:9], v[8:9], v[12:13]
	v_pk_mul_f32 v[10:11], v[10:11], v[2:3]
	v_pk_mul_f32 v[2:3], v[8:9], v[0:1]
	v_cvt_pk_bf16_f32 v0, v4, v5
	v_cvt_pk_bf16_f32 v1, v6, v7
	s_nop 0
	v_cvt_pk_bf16_f32 v2, v2, v3
	v_cvt_pk_bf16_f32 v3, v10, v11
	global_store_dwordx4 v[22:23], v[0:3], off
	s_cbranch_vccz .LBB0_1199
	s_waitcnt vmcnt(0)
	s_cmpk_gt_u32 s23, 0xff
	s_cbranch_scc1 .LBB0_1206
	s_barrier

; #define PG8_STAGE(bufoff, gbase, voff) do { _Pragma("unroll") for (int _i = 0; _i < 2; ++_i) \
;         __builtin_amdgcn_global_load_lds((const unsigned*)((const char*)(gbase) + (voff)[_i]), (PG8_LAS unsigned*)(lds + (bufoff) + ldsw + _i * 8192), 16, 0, 0); } while (0)
; #define PG8_LDA(dst, b, h) do { _Pragma("unroll") for (int m = 0; m < 4; ++m) _Pragma("unroll") for (int k = 0; k < 2; ++k) dst[m][k] = *(const PG8_LAS bf16x8*)(lds + PG8_SA(b, h) + aoff + m * 2048 + k * 1024); } while (0)
; #define PG8_LDB(dst, b, h) do { _Pragma("unroll") for (int n = 0; n < 2; ++n) _Pragma("unroll") for (int k = 0; k < 2; ++k) dst[n][k] = *(const PG8_LAS bf16x8*)(lds + PG8_SB(b, h) + boff + n * 2048 + k * 1024); } while (0)
; #define PG8_MMA(ai, bj, At, Bt) do { __builtin_amdgcn_s_setprio(1); _Pragma("unroll") for (int m = 0; m < 4; ++m) _Pragma("unroll") for (int n = 0; n < 2; ++n) _Pragma("unroll") for (int k = 0; k < 2; ++k) \
;         acc[ai][bj][m][n] = __builtin_amdgcn_mfma_f32_16x16x32_bf16(Bt[n][k], At[m][k], acc[ai][bj][m][n], 0, 0, 0); __builtin_amdgcn_s_setprio(0); } while (0)
; template <class Epi, class Sched>
; __device__ __forceinline__ void gemm_phase(PG8_LAS unsigned char* lds, const Gemm g, const Sched& S, const Epi& E) {
;     ...
;         const bool has_next = S.next(ui + 1, nxt);
;         const char* nA = has_next ? (const char*)g.A + (size_t)nxt.pm * tstep : cA; const char* nB = has_next ? (const char*)g.Bt + (size_t)nxt.pn * tstep : cB;
;         for (int t = 0; t < nt; t += 2) {
;             const bool last = (t == nt - 2);
;             const char* a1 = cA + (size_t)(t + 1) * kstep;
;             const char* a2 = last ? nA : cA + (size_t)(t + 2) * kstep; const char* b2 = last ? nB : cB + (size_t)(t + 2) * kstep;
;             const char* a3 = a2 + kstep; const char* b3 = b2 + kstep;
;             if (last && has_next) S.a_ready(nxt);
;             PG8_LDB(B0, 0, 0); PG8_SCHED; PG8_LDA(At, 0, 0); PG8_STAGE(PG8_SA(1, 1), a1 + hstep, voffA);
;             PG8_WAIT_L(8); PG8_BAR; PG8_WAIT_L(0); PG8_MMA(0, 0, At, B0); PG8_BAR; PG8_SCHED;
;             PG8_LDB(B1, 0, 1); PG8_STAGE(PG8_SB(0, 0), b2, voffB);
;             PG8_BAR; PG8_WAIT_L(0); PG8_MMA(0, 1, At, B1); PG8_BAR;
;             PG8_LDA(At, 0, 1); PG8_STAGE(PG8_SA(0, 0), a2, voffA);
;             PG8_BAR; PG8_WAIT_L(0); PG8_MMA(1, 0, At, B0); PG8_BAR; PG8_SCHED;
.LBB0_1277:
	s_add_u32 s52, s20, 0x100
	s_addc_u32 s53, s21, 0
	s_mov_b32 s54, -2
	ds_read_b128 v[152:155], v149
	ds_read_b128 v[156:159], v149 offset:1024
	ds_read_b128 v[160:163], v149 offset:2048
	ds_read_b128 v[164:167], v149 offset:3072
	s_add_u32 s20, s18, 0x100
	s_addc_u32 s21, s19, 0
	s_cmp_eq_u32 s54, 40
	s_cselect_b32 s25, s1, s21
	s_cselect_b32 s24, s0, s20
	s_cselect_b32 s23, s5, s53
	s_cselect_b32 s22, s4, s52
	s_add_i32 m0, s34, 0xc000
	ds_read_b128 v[168:171], v150
	ds_read_b128 v[172:175], v150 offset:1024
	ds_read_b128 v[182:185], v150 offset:2048
	ds_read_b128 v[190:193], v150 offset:3072
	ds_read_b128 v[194:197], v150 offset:4096
	ds_read_b128 v[198:201], v150 offset:5120
	ds_read_b128 v[202:205], v150 offset:6144
	ds_read_b128 v[206:209], v150 offset:7168
	global_load_lds_dwordx4 v136, s[18:19]
	s_add_i32 m0, s34, 0xe000
	s_nop 0
	global_load_lds_dwordx4 v138, s[18:19]
	s_waitcnt lgkmcnt(8)
	ds_read_b128 v[210:213], v151
	ds_read_b128 v[214:217], v151 offset:1024
	ds_read_b128 v[218:221], v151 offset:2048
	ds_read_b128 v[222:225], v151 offset:3072
	s_waitcnt vmcnt(8) lgkmcnt(0)
	s_barrier
	v_mfma_f32_16x16x32_bf16 v[124:127], v[152:155], v[168:171], 0
	v_mfma_f32_16x16x32_bf16 v[120:123], v[160:163], v[168:171], 0
	v_mfma_f32_16x16x32_bf16 v[108:111], v[152:155], v[182:185], 0
	v_mfma_f32_16x16x32_bf16 v[104:107], v[160:163], v[182:185], 0
	v_mfma_f32_16x16x32_bf16 v[92:95], v[152:155], v[194:197], 0
	v_mfma_f32_16x16x32_bf16 v[88:91], v[160:163], v[194:197], 0
	v_mfma_f32_16x16x32_bf16 v[76:79], v[152:155], v[202:205], 0
	v_mfma_f32_16x16x32_bf16 v[72:75], v[160:163], v[202:205], 0
	v_mfma_f32_16x16x32_bf16 v[124:127], v[156:159], v[172:175], v[124:127]
	v_mfma_f32_16x16x32_bf16 v[120:123], v[164:167], v[172:175], v[120:123]
	v_mfma_f32_16x16x32_bf16 v[108:111], v[156:159], v[190:193], v[108:111]
	v_mfma_f32_16x16x32_bf16 v[104:107], v[164:167], v[190:193], v[104:107]
	v_mfma_f32_16x16x32_bf16 v[92:95], v[156:159], v[198:201], v[92:95]
	v_mfma_f32_16x16x32_bf16 v[88:91], v[164:167], v[198:201], v[88:91]
	v_mfma_f32_16x16x32_bf16 v[76:79], v[156:159], v[206:209], v[76:79]
	v_mfma_f32_16x16x32_bf16 v[72:75], v[164:167], v[206:209], v[72:75]
	v_mfma_f32_16x16x32_bf16 v[116:119], v[210:213], v[168:171], 0
	v_mfma_f32_16x16x32_bf16 v[112:115], v[218:221], v[168:171], 0
	v_mfma_f32_16x16x32_bf16 v[100:103], v[210:213], v[182:185], 0
	v_mfma_f32_16x16x32_bf16 v[96:99], v[218:221], v[182:185], 0
	v_mfma_f32_16x16x32_bf16 v[84:87], v[210:213], v[194:197], 0
	v_mfma_f32_16x16x32_bf16 v[80:83], v[218:221], v[194:197], 0
	v_mfma_f32_16x16x32_bf16 v[68:71], v[210:213], v[202:205], 0
	v_mfma_f32_16x16x32_bf16 v[64:67], v[218:221], v[202:205], 0
	v_mfma_f32_16x16x32_bf16 v[116:119], v[214:217], v[172:175], v[116:119]
	v_mfma_f32_16x16x32_bf16 v[112:115], v[222:225], v[172:175], v[112:115]
	v_mfma_f32_16x16x32_bf16 v[100:103], v[214:217], v[190:193], v[100:103]
	v_mfma_f32_16x16x32_bf16 v[96:99], v[222:225], v[190:193], v[96:99]
	v_mfma_f32_16x16x32_bf16 v[84:87], v[214:217], v[198:201], v[84:87]
	v_mfma_f32_16x16x32_bf16 v[80:83], v[222:225], v[198:201], v[80:83]
	v_mfma_f32_16x16x32_bf16 v[68:71], v[214:217], v[206:209], v[68:71]
	v_mfma_f32_16x16x32_bf16 v[64:67], v[222:225], v[206:209], v[64:67]
	s_barrier
	ds_read_b128 v[168:171], v150 offset:16384
	ds_read_b128 v[172:175], v150 offset:17408
	ds_read_b128 v[182:185], v150 offset:18432
	ds_read_b128 v[190:193], v150 offset:19456
	ds_read_b128 v[194:197], v150 offset:20480
	ds_read_b128 v[198:201], v150 offset:21504
	ds_read_b128 v[202:205], v150 offset:22528
	ds_read_b128 v[206:209], v150 offset:23552
	s_add_i32 s18, s42, s31
	s_add_u32 s98, s22, s8
	s_addc_u32 s99, s23, s9
	s_mov_b32 m0, s18
	s_nop 0
	global_load_lds_dwordx4 v130, s[22:23]
	s_add_i32 m0, s18, 0x2000
	s_nop 0
	global_load_lds_dwordx4 v134, s[22:23]
	s_mov_b32 m0, s34
	s_add_u32 s100, s24, s8
	s_addc_u32 s101, s25, s9
	global_load_lds_dwordx4 v128, s[24:25]
	s_mov_b32 m0, s35
	s_nop 0
	global_load_lds_dwordx4 v132, s[24:25]
	s_add_u32 s18, s22, 0xb0000
	s_addc_u32 s19, s23, 0
	s_add_i32 s55, s43, s31
	s_mov_b32 m0, s55
	s_nop 0
	global_load_lds_dwordx4 v130, s[18:19]
	s_add_i32 m0, s55, 0x2000
	s_nop 0
	global_load_lds_dwordx4 v134, s[18:19]
	s_waitcnt vmcnt(8) lgkmcnt(0)
	s_barrier
	v_mfma_f32_16x16x32_bf16 v[60:63], v[152:155], v[168:171], 0
	v_mfma_f32_16x16x32_bf16 v[56:59], v[160:163], v[168:171], 0
	v_mfma_f32_16x16x32_bf16 v[48:51], v[152:155], v[182:185], 0
	v_mfma_f32_16x16x32_bf16 v[40:43], v[160:163], v[182:185], 0
	v_mfma_f32_16x16x32_bf16 v[32:35], v[152:155], v[194:197], 0
	v_mfma_f32_16x16x32_bf16 v[24:27], v[160:163], v[194:197], 0
	v_mfma_f32_16x16x32_bf16 v[16:19], v[152:155], v[202:205], 0
	v_mfma_f32_16x16x32_bf16 v[8:11], v[160:163], v[202:205], 0
	v_mfma_f32_16x16x32_bf16 v[60:63], v[156:159], v[172:175], v[60:63]
	v_mfma_f32_16x16x32_bf16 v[56:59], v[164:167], v[172:175], v[56:59]
	v_mfma_f32_16x16x32_bf16 v[48:51], v[156:159], v[190:193], v[48:51]
	v_mfma_f32_16x16x32_bf16 v[40:43], v[164:167], v[190:193], v[40:43]
	v_mfma_f32_16x16x32_bf16 v[32:35], v[156:159], v[198:201], v[32:35]
	v_mfma_f32_16x16x32_bf16 v[24:27], v[164:167], v[198:201], v[24:27]
	v_mfma_f32_16x16x32_bf16 v[16:19], v[156:159], v[206:209], v[16:19]
	v_mfma_f32_16x16x32_bf16 v[8:11], v[164:167], v[206:209], v[8:11]
	v_mfma_f32_16x16x32_bf16 v[52:55], v[210:213], v[168:171], 0
	v_mfma_f32_16x16x32_bf16 v[44:47], v[218:221], v[168:171], 0
	v_mfma_f32_16x16x32_bf16 v[36:39], v[210:213], v[182:185], 0
	v_mfma_f32_16x16x32_bf16 v[28:31], v[218:221], v[182:185], 0
	v_mfma_f32_16x16x32_bf16 v[20:23], v[210:213], v[194:197], 0
	v_mfma_f32_16x16x32_bf16 v[12:15], v[218:221], v[194:197], 0
	v_mfma_f32_16x16x32_bf16 v[4:7], v[210:213], v[202:205], 0
	v_mfma_f32_16x16x32_bf16 v[0:3], v[218:221], v[202:205], 0
	v_mfma_f32_16x16x32_bf16 v[52:55], v[214:217], v[172:175], v[52:55]
	v_mfma_f32_16x16x32_bf16 v[44:47], v[222:225], v[172:175], v[44:47]
	v_mfma_f32_16x16x32_bf16 v[36:39], v[214:217], v[190:193], v[36:39]
	v_mfma_f32_16x16x32_bf16 v[28:31], v[222:225], v[190:193], v[28:31]
	v_mfma_f32_16x16x32_bf16 v[20:23], v[214:217], v[198:201], v[20:23]
	v_mfma_f32_16x16x32_bf16 v[12:15], v[222:225], v[198:201], v[12:15]
	v_mfma_f32_16x16x32_bf16 v[4:7], v[214:217], v[206:209], v[4:7]
	v_mfma_f32_16x16x32_bf16 v[0:3], v[222:225], v[206:209], v[0:3]
	s_barrier
; #define PG8_STAGE(bufoff, gbase, voff) do { _Pragma("unroll") for (int _i = 0; _i < 2; ++_i) \
;         __builtin_amdgcn_global_load_lds((const unsigned*)((const char*)(gbase) + (voff)[_i]), (PG8_LAS unsigned*)(lds + (bufoff) + ldsw + _i * 8192), 16, 0, 0); } while (0)
; #define PG8_LDA(dst, b, h) do { _Pragma("unroll") for (int m = 0; m < 4; ++m) _Pragma("unroll") for (int k = 0; k < 2; ++k) dst[m][k] = *(const PG8_LAS bf16x8*)(lds + PG8_SA(b, h) + aoff + m * 2048 + k * 1024); } while (0)
; #define PG8_LDB(dst, b, h) do { _Pragma("unroll") for (int n = 0; n < 2; ++n) _Pragma("unroll") for (int k = 0; k < 2; ++k) dst[n][k] = *(const PG8_LAS bf16x8*)(lds + PG8_SB(b, h) + boff + n * 2048 + k * 1024); } while (0)
; #define PG8_MMA(ai, bj, At, Bt) do { __builtin_amdgcn_s_setprio(1); _Pragma("unroll") for (int m = 0; m < 4; ++m) _Pragma("unroll") for (int n = 0; n < 2; ++n) _Pragma("unroll") for (int k = 0; k < 2; ++k) \
;         acc[ai][bj][m][n] = __builtin_amdgcn_mfma_f32_16x16x32_bf16(Bt[n][k], At[m][k], acc[ai][bj][m][n], 0, 0, 0); __builtin_amdgcn_s_setprio(0); } while (0)
; #define PG8_WAIT_V(n) asm volatile("s_waitcnt vmcnt(" #n ")" ::: "memory")
; #define PG8_WAIT_L(n) asm volatile("s_waitcnt lgkmcnt(" #n ")" ::: "memory")
; #define PG8_BAR __builtin_amdgcn_s_barrier()
; #define PG8_SCHED __builtin_amdgcn_sched_barrier(0)
; template <class Epi, class Sched>
; __device__ __forceinline__ void gemm_phase(PG8_LAS unsigned char* lds, const Gemm g, const Sched& S, const Epi& E) {
;     ...
;             PG8_BAR; PG8_WAIT_L(0); PG8_MMA(1, 0, At, B0); PG8_BAR; PG8_SCHED;
;             PG8_STAGE(PG8_SB(0, 1), b2 + hstep, voffB);
;             PG8_WAIT_V(6); PG8_BAR; PG8_MMA(1, 1, At, B1); PG8_BAR;
;             PG8_LDB(B0, 1, 0); PG8_SCHED; PG8_LDA(At, 1, 0); PG8_STAGE(PG8_SA(0, 1), a2 + hstep, voffA);
;             PG8_WAIT_L(8); PG8_BAR; PG8_WAIT_L(0); PG8_MMA(0, 0, At, B0); PG8_BAR; PG8_SCHED;
;             PG8_LDB(B1, 1, 1); PG8_STAGE(PG8_SB(1, 0), b3, voffB);
;             PG8_BAR; PG8_WAIT_L(0); PG8_MMA(0, 1, At, B1); PG8_BAR;
;             PG8_LDA(At, 1, 1); PG8_STAGE(PG8_SA(1, 0), a3, voffA);
;             PG8_BAR; PG8_WAIT_L(0); PG8_MMA(1, 0, At, B0); PG8_BAR; PG8_SCHED;
;             PG8_STAGE(PG8_SB(1, 1), b3 + hstep, voffB);
;             PG8_WAIT_V(6); PG8_BAR; PG8_MMA(1, 1, At, B1); PG8_BAR;
;         }
	s_add_i32 s55, 0, 0x18000
	v_add_u32_e32 v164, s55, v147
	ds_read_b128 v[152:155], v164
	ds_read_b128 v[156:159], v164 offset:1024
	ds_read_b128 v[160:163], v164 offset:2048
	ds_read_b128 v[164:167], v164 offset:3072
	s_add_u32 s18, s24, 0xb0000
	s_addc_u32 s19, s25, 0
	s_mov_b32 m0, s36
	ds_read_b128 v[168:171], v150 offset:32768
	ds_read_b128 v[172:175], v150 offset:33792
	ds_read_b128 v[182:185], v150 offset:34816
	ds_read_b128 v[190:193], v150 offset:35840
	ds_read_b128 v[194:197], v150 offset:36864
	ds_read_b128 v[198:201], v150 offset:37888
	ds_read_b128 v[202:205], v150 offset:38912
	ds_read_b128 v[206:209], v150 offset:39936
	global_load_lds_dwordx4 v128, s[18:19]
	s_mov_b32 m0, s37
	s_nop 0
	global_load_lds_dwordx4 v132, s[18:19]
	s_add_i32 s24, 0, 0x1c000
	v_add_u32_e32 v179, s24, v147
	s_waitcnt lgkmcnt(8)
	ds_read_b128 v[210:213], v179
	ds_read_b128 v[214:217], v179 offset:1024
	ds_read_b128 v[218:221], v179 offset:2048
	ds_read_b128 v[222:225], v179 offset:3072
	s_waitcnt vmcnt(8) lgkmcnt(0)
	s_barrier
	v_mfma_f32_16x16x32_bf16 v[124:127], v[152:155], v[168:171], v[124:127]
	v_mfma_f32_16x16x32_bf16 v[120:123], v[160:163], v[168:171], v[120:123]
	v_mfma_f32_16x16x32_bf16 v[108:111], v[152:155], v[182:185], v[108:111]
	v_mfma_f32_16x16x32_bf16 v[104:107], v[160:163], v[182:185], v[104:107]
	v_mfma_f32_16x16x32_bf16 v[92:95], v[152:155], v[194:197], v[92:95]
	v_mfma_f32_16x16x32_bf16 v[88:91], v[160:163], v[194:197], v[88:91]
	v_mfma_f32_16x16x32_bf16 v[76:79], v[152:155], v[202:205], v[76:79]
	v_mfma_f32_16x16x32_bf16 v[72:75], v[160:163], v[202:205], v[72:75]
	v_mfma_f32_16x16x32_bf16 v[124:127], v[156:159], v[172:175], v[124:127]
	v_mfma_f32_16x16x32_bf16 v[120:123], v[164:167], v[172:175], v[120:123]
	v_mfma_f32_16x16x32_bf16 v[108:111], v[156:159], v[190:193], v[108:111]
	v_mfma_f32_16x16x32_bf16 v[104:107], v[164:167], v[190:193], v[104:107]
	v_mfma_f32_16x16x32_bf16 v[92:95], v[156:159], v[198:201], v[92:95]
	v_mfma_f32_16x16x32_bf16 v[88:91], v[164:167], v[198:201], v[88:91]
	v_mfma_f32_16x16x32_bf16 v[76:79], v[156:159], v[206:209], v[76:79]
	v_mfma_f32_16x16x32_bf16 v[72:75], v[164:167], v[206:209], v[72:75]
	v_mfma_f32_16x16x32_bf16 v[116:119], v[210:213], v[168:171], v[116:119]
	v_mfma_f32_16x16x32_bf16 v[112:115], v[218:221], v[168:171], v[112:115]
	v_mfma_f32_16x16x32_bf16 v[100:103], v[210:213], v[182:185], v[100:103]
	v_mfma_f32_16x16x32_bf16 v[96:99], v[218:221], v[182:185], v[96:99]
	v_mfma_f32_16x16x32_bf16 v[84:87], v[210:213], v[194:197], v[84:87]
	v_mfma_f32_16x16x32_bf16 v[80:83], v[218:221], v[194:197], v[80:83]
	v_mfma_f32_16x16x32_bf16 v[68:71], v[210:213], v[202:205], v[68:71]
	v_mfma_f32_16x16x32_bf16 v[64:67], v[218:221], v[202:205], v[64:67]
	v_mfma_f32_16x16x32_bf16 v[116:119], v[214:217], v[172:175], v[116:119]
	v_mfma_f32_16x16x32_bf16 v[112:115], v[222:225], v[172:175], v[112:115]
	v_mfma_f32_16x16x32_bf16 v[100:103], v[214:217], v[190:193], v[100:103]
	v_mfma_f32_16x16x32_bf16 v[96:99], v[222:225], v[190:193], v[96:99]
	v_mfma_f32_16x16x32_bf16 v[84:87], v[214:217], v[198:201], v[84:87]
	v_mfma_f32_16x16x32_bf16 v[80:83], v[222:225], v[198:201], v[80:83]
	v_mfma_f32_16x16x32_bf16 v[68:71], v[214:217], v[206:209], v[68:71]
	v_mfma_f32_16x16x32_bf16 v[64:67], v[222:225], v[206:209], v[64:67]
	s_barrier
	ds_read_b128 v[168:171], v150 offset:49152
	ds_read_b128 v[172:175], v150 offset:50176
	ds_read_b128 v[182:185], v150 offset:51200
	ds_read_b128 v[190:193], v150 offset:52224
	ds_read_b128 v[194:197], v150 offset:53248
	ds_read_b128 v[198:201], v150 offset:54272
	ds_read_b128 v[202:205], v150 offset:55296
	ds_read_b128 v[206:209], v150 offset:56320
	s_add_i32 s18, s55, s31
	s_mov_b32 m0, s18
	s_nop 0
	global_load_lds_dwordx4 v130, s[98:99]
	s_add_i32 m0, s18, 0x2000
	s_nop 0
	global_load_lds_dwordx4 v134, s[98:99]
	s_mov_b32 m0, s39
	s_nop 0
	global_load_lds_dwordx4 v128, s[100:101]
	s_mov_b32 m0, s40
	s_nop 0
	global_load_lds_dwordx4 v132, s[100:101]
	s_add_u32 s18, s22, 0xb0080
	s_addc_u32 s19, s23, 0
	s_add_i32 s22, s24, s31
	s_mov_b32 m0, s22
	s_nop 0
	global_load_lds_dwordx4 v130, s[18:19]
	s_add_i32 m0, s22, 0x2000
	s_nop 0
	global_load_lds_dwordx4 v134, s[18:19]
	s_waitcnt vmcnt(8) lgkmcnt(0)
	s_barrier
	v_mfma_f32_16x16x32_bf16 v[60:63], v[152:155], v[168:171], v[60:63]
	v_mfma_f32_16x16x32_bf16 v[56:59], v[160:163], v[168:171], v[56:59]
	v_mfma_f32_16x16x32_bf16 v[48:51], v[152:155], v[182:185], v[48:51]
	v_mfma_f32_16x16x32_bf16 v[40:43], v[160:163], v[182:185], v[40:43]
	v_mfma_f32_16x16x32_bf16 v[32:35], v[152:155], v[194:197], v[32:35]
	v_mfma_f32_16x16x32_bf16 v[24:27], v[160:163], v[194:197], v[24:27]
	v_mfma_f32_16x16x32_bf16 v[16:19], v[152:155], v[202:205], v[16:19]
	v_mfma_f32_16x16x32_bf16 v[8:11], v[160:163], v[202:205], v[8:11]
	v_mfma_f32_16x16x32_bf16 v[60:63], v[156:159], v[172:175], v[60:63]
	v_mfma_f32_16x16x32_bf16 v[56:59], v[164:167], v[172:175], v[56:59]
	v_mfma_f32_16x16x32_bf16 v[48:51], v[156:159], v[190:193], v[48:51]
	v_mfma_f32_16x16x32_bf16 v[40:43], v[164:167], v[190:193], v[40:43]
	v_mfma_f32_16x16x32_bf16 v[32:35], v[156:159], v[198:201], v[32:35]
	v_mfma_f32_16x16x32_bf16 v[24:27], v[164:167], v[198:201], v[24:27]
	v_mfma_f32_16x16x32_bf16 v[16:19], v[156:159], v[206:209], v[16:19]
	v_mfma_f32_16x16x32_bf16 v[8:11], v[164:167], v[206:209], v[8:11]
	v_mfma_f32_16x16x32_bf16 v[52:55], v[210:213], v[168:171], v[52:55]
	v_mfma_f32_16x16x32_bf16 v[44:47], v[218:221], v[168:171], v[44:47]
	v_mfma_f32_16x16x32_bf16 v[36:39], v[210:213], v[182:185], v[36:39]
	v_mfma_f32_16x16x32_bf16 v[28:31], v[218:221], v[182:185], v[28:31]
	v_mfma_f32_16x16x32_bf16 v[20:23], v[210:213], v[194:197], v[20:23]
	v_mfma_f32_16x16x32_bf16 v[12:15], v[218:221], v[194:197], v[12:15]
	v_mfma_f32_16x16x32_bf16 v[4:7], v[210:213], v[202:205], v[4:7]
	v_mfma_f32_16x16x32_bf16 v[0:3], v[218:221], v[202:205], v[0:3]
	v_mfma_f32_16x16x32_bf16 v[52:55], v[214:217], v[172:175], v[52:55]
	v_mfma_f32_16x16x32_bf16 v[44:47], v[222:225], v[172:175], v[44:47]
	v_mfma_f32_16x16x32_bf16 v[36:39], v[214:217], v[190:193], v[36:39]
	v_mfma_f32_16x16x32_bf16 v[28:31], v[222:225], v[190:193], v[28:31]
	v_mfma_f32_16x16x32_bf16 v[20:23], v[214:217], v[198:201], v[20:23]
	v_mfma_f32_16x16x32_bf16 v[12:15], v[222:225], v[198:201], v[12:15]
	v_mfma_f32_16x16x32_bf16 v[4:7], v[214:217], v[206:209], v[4:7]
	v_mfma_f32_16x16x32_bf16 v[0:3], v[222:225], v[206:209], v[0:3]
	s_barrier
	s_add_i32 s54, s54, 2
	s_add_u32 s52, s52, 0x100
	s_addc_u32 s53, s53, 0
	s_cmp_gt_u32 s54, 41
	s_mov_b64 s[18:19], s[20:21]
; #define PG8_STAGE(bufoff, gbase, voff) do { _Pragma("unroll") for (int _i = 0; _i < 2; ++_i) \
;         __builtin_amdgcn_global_load_lds((const unsigned*)((const char*)(gbase) + (voff)[_i]), (PG8_LAS unsigned*)(lds + (bufoff) + ldsw + _i * 8192), 16, 0, 0); } while (0)
; #define PG8_LDA(dst, b, h) do { _Pragma("unroll") for (int m = 0; m < 4; ++m) _Pragma("unroll") for (int k = 0; k < 2; ++k) dst[m][k] = *(const PG8_LAS bf16x8*)(lds + PG8_SA(b, h) + aoff + m * 2048 + k * 1024); } while (0)
; #define PG8_LDB(dst, b, h) do { _Pragma("unroll") for (int n = 0; n < 2; ++n) _Pragma("unroll") for (int k = 0; k < 2; ++k) dst[n][k] = *(const PG8_LAS bf16x8*)(lds + PG8_SB(b, h) + boff + n * 2048 + k * 1024); } while (0)
; #define PG8_MMA(ai, bj, At, Bt) do { __builtin_amdgcn_s_setprio(1); _Pragma("unroll") for (int m = 0; m < 4; ++m) _Pragma("unroll") for (int n = 0; n < 2; ++n) _Pragma("unroll") for (int k = 0; k < 2; ++k) \
;         acc[ai][bj][m][n] = __builtin_amdgcn_mfma_f32_16x16x32_bf16(Bt[n][k], At[m][k], acc[ai][bj][m][n], 0, 0, 0); __builtin_amdgcn_s_setprio(0); } while (0)
; #define PG8_WAIT_V(n) asm volatile("s_waitcnt vmcnt(" #n ")" ::: "memory")
; #define PG8_WAIT_L(n) asm volatile("s_waitcnt lgkmcnt(" #n ")" ::: "memory")
; #define PG8_BAR __builtin_amdgcn_s_barrier()
; #define PG8_SCHED __builtin_amdgcn_sched_barrier(0)
; template <class Epi, class Sched>
; __device__ __forceinline__ void gemm_phase(PG8_LAS unsigned char* lds, const Gemm g, const Sched& S, const Epi& E) {
;     ...
;             PG8_LDB(B0, 0, 0); PG8_SCHED; PG8_LDA(At, 0, 0); PG8_STAGE(PG8_SA(1, 1), a1 + hstep, voffA);
;             PG8_WAIT_L(8); PG8_BAR; PG8_WAIT_L(0); PG8_MMA(0, 0, At, B0); PG8_BAR; PG8_SCHED;
;             PG8_LDB(B1, 0, 1); PG8_STAGE(PG8_SB(0, 0), b2, voffB);
;             PG8_BAR; PG8_WAIT_L(0); PG8_MMA(0, 1, At, B1); PG8_BAR;
;             PG8_LDA(At, 0, 1); PG8_STAGE(PG8_SA(0, 0), a2, voffA);
;             PG8_BAR; PG8_WAIT_L(0); PG8_MMA(1, 0, At, B0); PG8_BAR; PG8_SCHED;
;             PG8_STAGE(PG8_SB(0, 1), b2 + hstep, voffB);
;             PG8_WAIT_V(6); PG8_BAR; PG8_MMA(1, 1, At, B1); PG8_BAR;
.LBB0_1278:
	ds_read_b128 v[152:155], v149
	ds_read_b128 v[156:159], v149 offset:1024
	ds_read_b128 v[160:163], v149 offset:2048
	ds_read_b128 v[164:167], v149 offset:3072
	s_add_u32 s20, s18, 0x100
	s_addc_u32 s21, s19, 0
	s_cmp_eq_u32 s54, 40
	s_cselect_b32 s25, s1, s21
	s_cselect_b32 s24, s0, s20
	s_cselect_b32 s23, s5, s53
	s_cselect_b32 s22, s4, s52
	s_add_i32 m0, s34, 0xc000
	ds_read_b128 v[168:171], v150
	ds_read_b128 v[172:175], v150 offset:1024
	ds_read_b128 v[182:185], v150 offset:2048
	ds_read_b128 v[190:193], v150 offset:3072
	ds_read_b128 v[194:197], v150 offset:4096
	ds_read_b128 v[198:201], v150 offset:5120
	ds_read_b128 v[202:205], v150 offset:6144
	ds_read_b128 v[206:209], v150 offset:7168
	global_load_lds_dwordx4 v136, s[18:19]
	s_add_i32 m0, s34, 0xe000
	s_nop 0
	global_load_lds_dwordx4 v138, s[18:19]
	s_waitcnt lgkmcnt(8)
	ds_read_b128 v[210:213], v151
	ds_read_b128 v[214:217], v151 offset:1024
	ds_read_b128 v[218:221], v151 offset:2048
	ds_read_b128 v[222:225], v151 offset:3072
	s_waitcnt vmcnt(8) lgkmcnt(0)
	s_barrier
	v_mfma_f32_16x16x32_bf16 v[124:127], v[152:155], v[168:171], v[124:127]
	v_mfma_f32_16x16x32_bf16 v[120:123], v[160:163], v[168:171], v[120:123]
	v_mfma_f32_16x16x32_bf16 v[108:111], v[152:155], v[182:185], v[108:111]
	v_mfma_f32_16x16x32_bf16 v[104:107], v[160:163], v[182:185], v[104:107]
	v_mfma_f32_16x16x32_bf16 v[92:95], v[152:155], v[194:197], v[92:95]
	v_mfma_f32_16x16x32_bf16 v[88:91], v[160:163], v[194:197], v[88:91]
	v_mfma_f32_16x16x32_bf16 v[76:79], v[152:155], v[202:205], v[76:79]
	v_mfma_f32_16x16x32_bf16 v[72:75], v[160:163], v[202:205], v[72:75]
	v_mfma_f32_16x16x32_bf16 v[124:127], v[156:159], v[172:175], v[124:127]
	v_mfma_f32_16x16x32_bf16 v[120:123], v[164:167], v[172:175], v[120:123]
	v_mfma_f32_16x16x32_bf16 v[108:111], v[156:159], v[190:193], v[108:111]
	v_mfma_f32_16x16x32_bf16 v[104:107], v[164:167], v[190:193], v[104:107]
	v_mfma_f32_16x16x32_bf16 v[92:95], v[156:159], v[198:201], v[92:95]
	v_mfma_f32_16x16x32_bf16 v[88:91], v[164:167], v[198:201], v[88:91]
	v_mfma_f32_16x16x32_bf16 v[76:79], v[156:159], v[206:209], v[76:79]
	v_mfma_f32_16x16x32_bf16 v[72:75], v[164:167], v[206:209], v[72:75]
	v_mfma_f32_16x16x32_bf16 v[116:119], v[210:213], v[168:171], v[116:119]
	v_mfma_f32_16x16x32_bf16 v[112:115], v[218:221], v[168:171], v[112:115]
	v_mfma_f32_16x16x32_bf16 v[100:103], v[210:213], v[182:185], v[100:103]
	v_mfma_f32_16x16x32_bf16 v[96:99], v[218:221], v[182:185], v[96:99]
	v_mfma_f32_16x16x32_bf16 v[84:87], v[210:213], v[194:197], v[84:87]
	v_mfma_f32_16x16x32_bf16 v[80:83], v[218:221], v[194:197], v[80:83]
	v_mfma_f32_16x16x32_bf16 v[68:71], v[210:213], v[202:205], v[68:71]
	v_mfma_f32_16x16x32_bf16 v[64:67], v[218:221], v[202:205], v[64:67]
	v_mfma_f32_16x16x32_bf16 v[116:119], v[214:217], v[172:175], v[116:119]
	v_mfma_f32_16x16x32_bf16 v[112:115], v[222:225], v[172:175], v[112:115]
	v_mfma_f32_16x16x32_bf16 v[100:103], v[214:217], v[190:193], v[100:103]
	v_mfma_f32_16x16x32_bf16 v[96:99], v[222:225], v[190:193], v[96:99]
	v_mfma_f32_16x16x32_bf16 v[84:87], v[214:217], v[198:201], v[84:87]
	v_mfma_f32_16x16x32_bf16 v[80:83], v[222:225], v[198:201], v[80:83]
	v_mfma_f32_16x16x32_bf16 v[68:71], v[214:217], v[206:209], v[68:71]
	v_mfma_f32_16x16x32_bf16 v[64:67], v[222:225], v[206:209], v[64:67]
	s_barrier
	ds_read_b128 v[168:171], v150 offset:16384
	ds_read_b128 v[172:175], v150 offset:17408
	ds_read_b128 v[182:185], v150 offset:18432
	ds_read_b128 v[190:193], v150 offset:19456
	ds_read_b128 v[194:197], v150 offset:20480
	ds_read_b128 v[198:201], v150 offset:21504
	ds_read_b128 v[202:205], v150 offset:22528
	ds_read_b128 v[206:209], v150 offset:23552
	s_add_i32 s18, s42, s31
	s_add_u32 s98, s22, s8
	s_addc_u32 s99, s23, s9
	s_mov_b32 m0, s18
	s_nop 0
	global_load_lds_dwordx4 v130, s[22:23]
	s_add_i32 m0, s18, 0x2000
	s_nop 0
	global_load_lds_dwordx4 v134, s[22:23]
	s_mov_b32 m0, s34
	s_add_u32 s100, s24, s8
	s_addc_u32 s101, s25, s9
	global_load_lds_dwordx4 v128, s[24:25]
	s_mov_b32 m0, s35
	s_nop 0
	global_load_lds_dwordx4 v132, s[24:25]
	s_add_u32 s18, s22, 0xb0000
	s_addc_u32 s19, s23, 0
	s_add_i32 s55, s43, s31
	s_mov_b32 m0, s55
	s_nop 0
	global_load_lds_dwordx4 v130, s[18:19]
	s_add_i32 m0, s55, 0x2000
	s_nop 0
	global_load_lds_dwordx4 v134, s[18:19]
	s_waitcnt vmcnt(8) lgkmcnt(0)
	s_barrier
	v_mfma_f32_16x16x32_bf16 v[60:63], v[152:155], v[168:171], v[60:63]
	v_mfma_f32_16x16x32_bf16 v[56:59], v[160:163], v[168:171], v[56:59]
	v_mfma_f32_16x16x32_bf16 v[48:51], v[152:155], v[182:185], v[48:51]
	v_mfma_f32_16x16x32_bf16 v[40:43], v[160:163], v[182:185], v[40:43]
	v_mfma_f32_16x16x32_bf16 v[32:35], v[152:155], v[194:197], v[32:35]
	v_mfma_f32_16x16x32_bf16 v[24:27], v[160:163], v[194:197], v[24:27]
	v_mfma_f32_16x16x32_bf16 v[16:19], v[152:155], v[202:205], v[16:19]
	v_mfma_f32_16x16x32_bf16 v[8:11], v[160:163], v[202:205], v[8:11]
	v_mfma_f32_16x16x32_bf16 v[60:63], v[156:159], v[172:175], v[60:63]
	v_mfma_f32_16x16x32_bf16 v[56:59], v[164:167], v[172:175], v[56:59]
	v_mfma_f32_16x16x32_bf16 v[48:51], v[156:159], v[190:193], v[48:51]
	v_mfma_f32_16x16x32_bf16 v[40:43], v[164:167], v[190:193], v[40:43]
	v_mfma_f32_16x16x32_bf16 v[32:35], v[156:159], v[198:201], v[32:35]
	v_mfma_f32_16x16x32_bf16 v[24:27], v[164:167], v[198:201], v[24:27]
	v_mfma_f32_16x16x32_bf16 v[16:19], v[156:159], v[206:209], v[16:19]
	v_mfma_f32_16x16x32_bf16 v[8:11], v[164:167], v[206:209], v[8:11]
	v_mfma_f32_16x16x32_bf16 v[52:55], v[210:213], v[168:171], v[52:55]
	v_mfma_f32_16x16x32_bf16 v[44:47], v[218:221], v[168:171], v[44:47]
	v_mfma_f32_16x16x32_bf16 v[36:39], v[210:213], v[182:185], v[36:39]
	v_mfma_f32_16x16x32_bf16 v[28:31], v[218:221], v[182:185], v[28:31]
	v_mfma_f32_16x16x32_bf16 v[20:23], v[210:213], v[194:197], v[20:23]
	v_mfma_f32_16x16x32_bf16 v[12:15], v[218:221], v[194:197], v[12:15]
	v_mfma_f32_16x16x32_bf16 v[4:7], v[210:213], v[202:205], v[4:7]
	v_mfma_f32_16x16x32_bf16 v[0:3], v[218:221], v[202:205], v[0:3]
	v_mfma_f32_16x16x32_bf16 v[52:55], v[214:217], v[172:175], v[52:55]
	v_mfma_f32_16x16x32_bf16 v[44:47], v[222:225], v[172:175], v[44:47]
	v_mfma_f32_16x16x32_bf16 v[36:39], v[214:217], v[190:193], v[36:39]
	v_mfma_f32_16x16x32_bf16 v[28:31], v[222:225], v[190:193], v[28:31]
	v_mfma_f32_16x16x32_bf16 v[20:23], v[214:217], v[198:201], v[20:23]
	v_mfma_f32_16x16x32_bf16 v[12:15], v[222:225], v[198:201], v[12:15]
	v_mfma_f32_16x16x32_bf16 v[4:7], v[214:217], v[206:209], v[4:7]
	v_mfma_f32_16x16x32_bf16 v[0:3], v[222:225], v[206:209], v[0:3]
	s_barrier
; #define PG8_STAGE(bufoff, gbase, voff) do { _Pragma("unroll") for (int _i = 0; _i < 2; ++_i) \
;         __builtin_amdgcn_global_load_lds((const unsigned*)((const char*)(gbase) + (voff)[_i]), (PG8_LAS unsigned*)(lds + (bufoff) + ldsw + _i * 8192), 16, 0, 0); } while (0)
; #define PG8_LDA(dst, b, h) do { _Pragma("unroll") for (int m = 0; m < 4; ++m) _Pragma("unroll") for (int k = 0; k < 2; ++k) dst[m][k] = *(const PG8_LAS bf16x8*)(lds + PG8_SA(b, h) + aoff + m * 2048 + k * 1024); } while (0)
; #define PG8_LDB(dst, b, h) do { _Pragma("unroll") for (int n = 0; n < 2; ++n) _Pragma("unroll") for (int k = 0; k < 2; ++k) dst[n][k] = *(const PG8_LAS bf16x8*)(lds + PG8_SB(b, h) + boff + n * 2048 + k * 1024); } while (0)
; #define PG8_MMA(ai, bj, At, Bt) do { __builtin_amdgcn_s_setprio(1); _Pragma("unroll") for (int m = 0; m < 4; ++m) _Pragma("unroll") for (int n = 0; n < 2; ++n) _Pragma("unroll") for (int k = 0; k < 2; ++k) \
;         acc[ai][bj][m][n] = __builtin_amdgcn_mfma_f32_16x16x32_bf16(Bt[n][k], At[m][k], acc[ai][bj][m][n], 0, 0, 0); __builtin_amdgcn_s_setprio(0); } while (0)
; #define PG8_WAIT_V(n) asm volatile("s_waitcnt vmcnt(" #n ")" ::: "memory")
; #define PG8_WAIT_L(n) asm volatile("s_waitcnt lgkmcnt(" #n ")" ::: "memory")
; #define PG8_BAR __builtin_amdgcn_s_barrier()
; #define PG8_SCHED __builtin_amdgcn_sched_barrier(0)
; template <class Epi, class Sched>
; __device__ __forceinline__ void gemm_phase(PG8_LAS unsigned char* lds, const Gemm g, const Sched& S, const Epi& E) {
;     ...
;             PG8_LDB(B0, 1, 0); PG8_SCHED; PG8_LDA(At, 1, 0); PG8_STAGE(PG8_SA(0, 1), a2 + hstep, voffA);
;             PG8_WAIT_L(8); PG8_BAR; PG8_WAIT_L(0); PG8_MMA(0, 0, At, B0); PG8_BAR; PG8_SCHED;
;             PG8_LDB(B1, 1, 1); PG8_STAGE(PG8_SB(1, 0), b3, voffB);
;             PG8_BAR; PG8_WAIT_L(0); PG8_MMA(0, 1, At, B1); PG8_BAR;
;             PG8_LDA(At, 1, 1); PG8_STAGE(PG8_SA(1, 0), a3, voffA);
;             PG8_BAR; PG8_WAIT_L(0); PG8_MMA(1, 0, At, B0); PG8_BAR; PG8_SCHED;
;             PG8_STAGE(PG8_SB(1, 1), b3 + hstep, voffB);
;             PG8_WAIT_V(6); PG8_BAR; PG8_MMA(1, 1, At, B1); PG8_BAR;
;         }
	s_add_i32 s55, 0, 0x18000
	v_add_u32_e32 v164, s55, v147
	ds_read_b128 v[152:155], v164
	ds_read_b128 v[156:159], v164 offset:1024
	ds_read_b128 v[160:163], v164 offset:2048
	ds_read_b128 v[164:167], v164 offset:3072
	s_add_u32 s18, s24, 0xb0000
	s_addc_u32 s19, s25, 0
	s_mov_b32 m0, s36
	ds_read_b128 v[168:171], v150 offset:32768
	ds_read_b128 v[172:175], v150 offset:33792
	ds_read_b128 v[182:185], v150 offset:34816
	ds_read_b128 v[190:193], v150 offset:35840
	ds_read_b128 v[194:197], v150 offset:36864
	ds_read_b128 v[198:201], v150 offset:37888
	ds_read_b128 v[202:205], v150 offset:38912
	ds_read_b128 v[206:209], v150 offset:39936
	global_load_lds_dwordx4 v128, s[18:19]
	s_mov_b32 m0, s37
	s_nop 0
	global_load_lds_dwordx4 v132, s[18:19]
	s_add_i32 s24, 0, 0x1c000
	v_add_u32_e32 v179, s24, v147
	s_waitcnt lgkmcnt(8)
	ds_read_b128 v[210:213], v179
	ds_read_b128 v[214:217], v179 offset:1024
	ds_read_b128 v[218:221], v179 offset:2048
	ds_read_b128 v[222:225], v179 offset:3072
	s_waitcnt vmcnt(8) lgkmcnt(0)
	s_barrier
	v_mfma_f32_16x16x32_bf16 v[124:127], v[152:155], v[168:171], v[124:127]
	v_mfma_f32_16x16x32_bf16 v[120:123], v[160:163], v[168:171], v[120:123]
	v_mfma_f32_16x16x32_bf16 v[108:111], v[152:155], v[182:185], v[108:111]
	v_mfma_f32_16x16x32_bf16 v[104:107], v[160:163], v[182:185], v[104:107]
	v_mfma_f32_16x16x32_bf16 v[92:95], v[152:155], v[194:197], v[92:95]
	v_mfma_f32_16x16x32_bf16 v[88:91], v[160:163], v[194:197], v[88:91]
	v_mfma_f32_16x16x32_bf16 v[76:79], v[152:155], v[202:205], v[76:79]
	v_mfma_f32_16x16x32_bf16 v[72:75], v[160:163], v[202:205], v[72:75]
	v_mfma_f32_16x16x32_bf16 v[124:127], v[156:159], v[172:175], v[124:127]
	v_mfma_f32_16x16x32_bf16 v[120:123], v[164:167], v[172:175], v[120:123]
	v_mfma_f32_16x16x32_bf16 v[108:111], v[156:159], v[190:193], v[108:111]
	v_mfma_f32_16x16x32_bf16 v[104:107], v[164:167], v[190:193], v[104:107]
	v_mfma_f32_16x16x32_bf16 v[92:95], v[156:159], v[198:201], v[92:95]
	v_mfma_f32_16x16x32_bf16 v[88:91], v[164:167], v[198:201], v[88:91]
	v_mfma_f32_16x16x32_bf16 v[76:79], v[156:159], v[206:209], v[76:79]
	v_mfma_f32_16x16x32_bf16 v[72:75], v[164:167], v[206:209], v[72:75]
	v_mfma_f32_16x16x32_bf16 v[116:119], v[210:213], v[168:171], v[116:119]
	v_mfma_f32_16x16x32_bf16 v[112:115], v[218:221], v[168:171], v[112:115]
	v_mfma_f32_16x16x32_bf16 v[100:103], v[210:213], v[182:185], v[100:103]
	v_mfma_f32_16x16x32_bf16 v[96:99], v[218:221], v[182:185], v[96:99]
	v_mfma_f32_16x16x32_bf16 v[84:87], v[210:213], v[194:197], v[84:87]
	v_mfma_f32_16x16x32_bf16 v[80:83], v[218:221], v[194:197], v[80:83]
	v_mfma_f32_16x16x32_bf16 v[68:71], v[210:213], v[202:205], v[68:71]
	v_mfma_f32_16x16x32_bf16 v[64:67], v[218:221], v[202:205], v[64:67]
	v_mfma_f32_16x16x32_bf16 v[116:119], v[214:217], v[172:175], v[116:119]
	v_mfma_f32_16x16x32_bf16 v[112:115], v[222:225], v[172:175], v[112:115]
	v_mfma_f32_16x16x32_bf16 v[100:103], v[214:217], v[190:193], v[100:103]
	v_mfma_f32_16x16x32_bf16 v[96:99], v[222:225], v[190:193], v[96:99]
	v_mfma_f32_16x16x32_bf16 v[84:87], v[214:217], v[198:201], v[84:87]
	v_mfma_f32_16x16x32_bf16 v[80:83], v[222:225], v[198:201], v[80:83]
	v_mfma_f32_16x16x32_bf16 v[68:71], v[214:217], v[206:209], v[68:71]
	v_mfma_f32_16x16x32_bf16 v[64:67], v[222:225], v[206:209], v[64:67]
	s_barrier
	ds_read_b128 v[168:171], v150 offset:49152
	ds_read_b128 v[172:175], v150 offset:50176
	ds_read_b128 v[182:185], v150 offset:51200
	ds_read_b128 v[190:193], v150 offset:52224
	ds_read_b128 v[194:197], v150 offset:53248
	ds_read_b128 v[198:201], v150 offset:54272
	ds_read_b128 v[202:205], v150 offset:55296
	ds_read_b128 v[206:209], v150 offset:56320
	s_add_i32 s18, s55, s31
	s_mov_b32 m0, s18
	s_nop 0
	global_load_lds_dwordx4 v130, s[98:99]
	s_add_i32 m0, s18, 0x2000
	s_nop 0
	global_load_lds_dwordx4 v134, s[98:99]
	s_mov_b32 m0, s39
	s_nop 0
	global_load_lds_dwordx4 v128, s[100:101]
	s_mov_b32 m0, s40
	s_nop 0
	global_load_lds_dwordx4 v132, s[100:101]
	s_add_u32 s18, s22, 0xb0080
	s_addc_u32 s19, s23, 0
	s_add_i32 s22, s24, s31
	s_mov_b32 m0, s22
	s_nop 0
	global_load_lds_dwordx4 v130, s[18:19]
	s_add_i32 m0, s22, 0x2000
	s_nop 0
	global_load_lds_dwordx4 v134, s[18:19]
	s_waitcnt vmcnt(8) lgkmcnt(0)
	s_barrier
	v_mfma_f32_16x16x32_bf16 v[60:63], v[152:155], v[168:171], v[60:63]
	v_mfma_f32_16x16x32_bf16 v[56:59], v[160:163], v[168:171], v[56:59]
	v_mfma_f32_16x16x32_bf16 v[48:51], v[152:155], v[182:185], v[48:51]
	v_mfma_f32_16x16x32_bf16 v[40:43], v[160:163], v[182:185], v[40:43]
	v_mfma_f32_16x16x32_bf16 v[32:35], v[152:155], v[194:197], v[32:35]
	v_mfma_f32_16x16x32_bf16 v[24:27], v[160:163], v[194:197], v[24:27]
	v_mfma_f32_16x16x32_bf16 v[16:19], v[152:155], v[202:205], v[16:19]
	v_mfma_f32_16x16x32_bf16 v[8:11], v[160:163], v[202:205], v[8:11]
	v_mfma_f32_16x16x32_bf16 v[60:63], v[156:159], v[172:175], v[60:63]
	v_mfma_f32_16x16x32_bf16 v[56:59], v[164:167], v[172:175], v[56:59]
	v_mfma_f32_16x16x32_bf16 v[48:51], v[156:159], v[190:193], v[48:51]
	v_mfma_f32_16x16x32_bf16 v[40:43], v[164:167], v[190:193], v[40:43]
	v_mfma_f32_16x16x32_bf16 v[32:35], v[156:159], v[198:201], v[32:35]
	v_mfma_f32_16x16x32_bf16 v[24:27], v[164:167], v[198:201], v[24:27]
	v_mfma_f32_16x16x32_bf16 v[16:19], v[156:159], v[206:209], v[16:19]
	v_mfma_f32_16x16x32_bf16 v[8:11], v[164:167], v[206:209], v[8:11]
	v_mfma_f32_16x16x32_bf16 v[52:55], v[210:213], v[168:171], v[52:55]
	v_mfma_f32_16x16x32_bf16 v[44:47], v[218:221], v[168:171], v[44:47]
	v_mfma_f32_16x16x32_bf16 v[36:39], v[210:213], v[182:185], v[36:39]
	v_mfma_f32_16x16x32_bf16 v[28:31], v[218:221], v[182:185], v[28:31]
	v_mfma_f32_16x16x32_bf16 v[20:23], v[210:213], v[194:197], v[20:23]
	v_mfma_f32_16x16x32_bf16 v[12:15], v[218:221], v[194:197], v[12:15]
	v_mfma_f32_16x16x32_bf16 v[4:7], v[210:213], v[202:205], v[4:7]
	v_mfma_f32_16x16x32_bf16 v[0:3], v[218:221], v[202:205], v[0:3]
	v_mfma_f32_16x16x32_bf16 v[52:55], v[214:217], v[172:175], v[52:55]
	v_mfma_f32_16x16x32_bf16 v[44:47], v[222:225], v[172:175], v[44:47]
	v_mfma_f32_16x16x32_bf16 v[36:39], v[214:217], v[190:193], v[36:39]
	v_mfma_f32_16x16x32_bf16 v[28:31], v[222:225], v[190:193], v[28:31]
	v_mfma_f32_16x16x32_bf16 v[20:23], v[214:217], v[198:201], v[20:23]
	v_mfma_f32_16x16x32_bf16 v[12:15], v[222:225], v[198:201], v[12:15]
	v_mfma_f32_16x16x32_bf16 v[4:7], v[214:217], v[206:209], v[4:7]
	v_mfma_f32_16x16x32_bf16 v[0:3], v[222:225], v[206:209], v[0:3]
	s_barrier
; __device__ __forceinline__ unsigned cvt_pk_bf16(float lo, float hi) { unsigned r; asm volatile("v_cvt_pk_bf16_f32 %0, %1, %2" : "=v"(r) : "v"(lo), "v"(hi)); return r; }
; __device__ __forceinline__ float flogsig16(float x) { return (fminf(x, 0.f) - __logf(1.0f + __expf(-fabsf(x)))) * 0.0625f; }
; #define PG8_WAIT_V(n) asm volatile("s_waitcnt vmcnt(" #n ")" ::: "memory")
; #define PG8_BAR __builtin_amdgcn_s_barrier()
;     __device__ __forceinline__ void operator()(const f32x4 (&acc)[2][2][4][2], const Unit& u, int wr, int wc, int fr, int fq) const {
;     ...
;         const int row0 = u.pm * BM + wr * 64 + fr, col0 = u.pn * BM + wc * 32 + 8 * fq, bcol0 = wc * 32 + 8 * fq;
;         f32x4 bv[2][2];
; #pragma unroll
;         for (int bj = 0; bj < 2; ++bj)
; #pragma unroll
;             for (int n = 0; n < 2; ++n) bv[bj][n] = bias ? *(const f32x4*)(bias + bcol0 + bj * HALF + 4 * n) : (f32x4){0.f, 0.f, 0.f, 0.f};
; #pragma unroll
;         for (int ai = 0; ai < 2; ++ai)
; #pragma unroll
;             for (int m = 0; m < 4; ++m) { bf16_t* rowp = O + (size_t)(row0 + ai * HALF + m * 16) * ldc + col0;
; #pragma unroll
;                 for (int bj = 0; bj < 2; ++bj) { f32x4 v0 = acc[ai][bj][m][0] + bv[bj][0], v1 = acc[ai][bj][m][1] + bv[bj][1];
;                     if (act == 1) {
; #pragma unroll
;                         for (int j = 0; j < 1; ++j) { v0 = v0 * sigmoid4(v0); v1 = v1 * sigmoid4(v1); } }
;                     else if (act == 2) {
; #pragma unroll
;                         for (int j = 0; j < 1; ++j) { v0 = sigmoid4(v0); v1 = sigmoid4(v1); } }
;                     else if (act == 3) {
; #pragma unroll
;                         for (int j = 0; j < 4; ++j) { v0[j] = flogsig16(v0[j]); v1[j] = flogsig16(v1[j]); } }
;                     u32x4 w; w.x = cvt_pk_bf16(v0[0], v0[1]); w.y = cvt_pk_bf16(v0[2], v0[3]); w.z = cvt_pk_bf16(v1[0], v1[1]); w.w = cvt_pk_bf16(v1[2], v1[3]);
;                     *(u32x4*)(rowp + bj * HALF) = w; } }
; template <class Epi, class Sched>
; __device__ __forceinline__ void gemm_phase(PG8_LAS unsigned char* lds, const Gemm g, const Sched& S, const Epi& E) {
;     ...
;             PG8_WAIT_V(6); PG8_BAR; PG8_MMA(1, 1, At, B1); PG8_BAR;
;         }
	s_add_i32 s54, s54, 2
	s_add_u32 s52, s52, 0x100
	s_addc_u32 s53, s53, 0
	s_cmp_gt_u32 s54, 41
	s_mov_b64 s[18:19], s[20:21]
	s_cbranch_scc0 .LBB0_1278
	v_lshl_add_u32 v152, s50, 8, v146
	v_lshl_or_b32 v144, s51, 8, v148
	v_ashrrev_i32_e32 v153, 31, v152
	v_ashrrev_i32_e32 v145, 31, v144
	v_lshlrev_b64 v[154:155], 11, v[152:153]
	v_lshl_add_u64 v[154:155], s[6:7], 0, v[154:155]
	v_lshlrev_b64 v[156:157], 1, v[144:145]
	v_lshl_add_u64 v[144:145], v[154:155], 0, v[156:157]
	v_pk_add_f32 v[126:127], v[126:127], 0 op_sel_hi:[1,0]
	v_pk_add_f32 v[124:125], v[124:125], 0 op_sel_hi:[1,0]
	v_pk_add_f32 v[154:155], v[122:123], 0 op_sel_hi:[1,0]
	v_pk_add_f32 v[122:123], v[120:121], 0 op_sel_hi:[1,0]
	v_cvt_pk_bf16_f32 v120, v124, v125
	v_cvt_pk_bf16_f32 v121, v126, v127
	v_pk_add_f32 v[116:117], v[116:117], 0 op_sel_hi:[1,0]
	v_cvt_pk_bf16_f32 v122, v122, v123
	v_cvt_pk_bf16_f32 v123, v154, v155
	global_store_dwordx4 v[144:145], v[120:123], off
	v_pk_add_f32 v[118:119], v[118:119], 0 op_sel_hi:[1,0]
	v_pk_add_f32 v[110:111], v[110:111], 0 op_sel_hi:[1,0]
	v_pk_add_f32 v[120:121], v[114:115], 0 op_sel_hi:[1,0]
	v_pk_add_f32 v[114:115], v[112:113], 0 op_sel_hi:[1,0]
	v_cvt_pk_bf16_f32 v112, v116, v117
	v_cvt_pk_bf16_f32 v113, v118, v119
	v_pk_add_f32 v[108:109], v[108:109], 0 op_sel_hi:[1,0]
	v_cvt_pk_bf16_f32 v114, v114, v115
	v_cvt_pk_bf16_f32 v115, v120, v121
	global_store_dwordx4 v[144:145], v[112:115], off offset:256
	v_pk_add_f32 v[100:101], v[100:101], 0 op_sel_hi:[1,0]
	v_pk_add_f32 v[102:103], v[102:103], 0 op_sel_hi:[1,0]
	v_or_b32_e32 v112, 16, v152
	v_ashrrev_i32_e32 v113, 31, v112
	v_lshlrev_b64 v[112:113], 11, v[112:113]
	v_lshl_add_u64 v[112:113], s[6:7], 0, v[112:113]
	v_lshl_add_u64 v[112:113], v[112:113], 0, v[156:157]
	v_pk_add_f32 v[114:115], v[106:107], 0 op_sel_hi:[1,0]
	v_pk_add_f32 v[106:107], v[104:105], 0 op_sel_hi:[1,0]
	v_cvt_pk_bf16_f32 v104, v108, v109
	v_cvt_pk_bf16_f32 v105, v110, v111
	v_pk_add_f32 v[94:95], v[94:95], 0 op_sel_hi:[1,0]
	v_cvt_pk_bf16_f32 v106, v106, v107
	v_cvt_pk_bf16_f32 v107, v114, v115
	global_store_dwordx4 v[112:113], v[104:107], off
	v_pk_add_f32 v[92:93], v[92:93], 0 op_sel_hi:[1,0]
	v_pk_add_f32 v[84:85], v[84:85], 0 op_sel_hi:[1,0]
	v_pk_add_f32 v[104:105], v[98:99], 0 op_sel_hi:[1,0]
	v_pk_add_f32 v[98:99], v[96:97], 0 op_sel_hi:[1,0]
	v_cvt_pk_bf16_f32 v96, v100, v101
	v_cvt_pk_bf16_f32 v97, v102, v103
	v_pk_add_f32 v[86:87], v[86:87], 0 op_sel_hi:[1,0]
	v_cvt_pk_bf16_f32 v98, v98, v99
	v_cvt_pk_bf16_f32 v99, v104, v105
	global_store_dwordx4 v[112:113], v[96:99], off offset:256
	v_pk_add_f32 v[78:79], v[78:79], 0 op_sel_hi:[1,0]
	v_pk_add_f32 v[76:77], v[76:77], 0 op_sel_hi:[1,0]
	v_or_b32_e32 v96, 32, v152
	v_ashrrev_i32_e32 v97, 31, v96
	v_lshlrev_b64 v[96:97], 11, v[96:97]
	v_lshl_add_u64 v[96:97], s[6:7], 0, v[96:97]
	v_lshl_add_u64 v[96:97], v[96:97], 0, v[156:157]
	v_pk_add_f32 v[98:99], v[90:91], 0 op_sel_hi:[1,0]
	v_pk_add_f32 v[90:91], v[88:89], 0 op_sel_hi:[1,0]
	v_cvt_pk_bf16_f32 v88, v92, v93
	v_cvt_pk_bf16_f32 v89, v94, v95
	v_pk_add_f32 v[70:71], v[70:71], 0 op_sel_hi:[1,0]
	v_cvt_pk_bf16_f32 v90, v90, v91
	v_cvt_pk_bf16_f32 v91, v98, v99
	global_store_dwordx4 v[96:97], v[88:91], off
	v_pk_add_f32 v[68:69], v[68:69], 0 op_sel_hi:[1,0]
	v_pk_add_f32 v[60:61], v[60:61], 0 op_sel_hi:[1,0]
	v_pk_add_f32 v[88:89], v[82:83], 0 op_sel_hi:[1,0]
	v_pk_add_f32 v[82:83], v[80:81], 0 op_sel_hi:[1,0]
	v_cvt_pk_bf16_f32 v80, v84, v85
	v_cvt_pk_bf16_f32 v81, v86, v87
	v_pk_add_f32 v[62:63], v[62:63], 0 op_sel_hi:[1,0]
	v_cvt_pk_bf16_f32 v82, v82, v83
	v_cvt_pk_bf16_f32 v83, v88, v89
	global_store_dwordx4 v[96:97], v[80:83], off offset:256
	v_pk_add_f32 v[54:55], v[54:55], 0 op_sel_hi:[1,0]
	v_pk_add_f32 v[52:53], v[52:53], 0 op_sel_hi:[1,0]
	v_or_b32_e32 v80, 48, v152
	v_ashrrev_i32_e32 v81, 31, v80
	v_lshlrev_b64 v[80:81], 11, v[80:81]
	v_lshl_add_u64 v[80:81], s[6:7], 0, v[80:81]
	v_lshl_add_u64 v[80:81], v[80:81], 0, v[156:157]
	v_pk_add_f32 v[82:83], v[74:75], 0 op_sel_hi:[1,0]
	v_pk_add_f32 v[74:75], v[72:73], 0 op_sel_hi:[1,0]
	v_cvt_pk_bf16_f32 v72, v76, v77
	v_cvt_pk_bf16_f32 v73, v78, v79
; __device__ __forceinline__ unsigned cvt_pk_bf16(float lo, float hi) { unsigned r; asm volatile("v_cvt_pk_bf16_f32 %0, %1, %2" : "=v"(r) : "v"(lo), "v"(hi)); return r; }
;     __device__ __forceinline__ void operator()(const f32x4 (&acc)[2][2][4][2], const Unit& u, int wr, int wc, int fr, int fq) const {
;     ...
;         const int row0 = u.pm * BM + wr * 64 + fr, col0 = u.pn * BM + wc * 32 + 8 * fq, bcol0 = wc * 32 + 8 * fq;
;         f32x4 bv[2][2];
; #pragma unroll
;         for (int bj = 0; bj < 2; ++bj)
; #pragma unroll
;             for (int n = 0; n < 2; ++n) bv[bj][n] = bias ? *(const f32x4*)(bias + bcol0 + bj * HALF + 4 * n) : (f32x4){0.f, 0.f, 0.f, 0.f};
; #pragma unroll
;         for (int ai = 0; ai < 2; ++ai)
; #pragma unroll
;             for (int m = 0; m < 4; ++m) { bf16_t* rowp = O + (size_t)(row0 + ai * HALF + m * 16) * ldc + col0;
; #pragma unroll
;                 for (int bj = 0; bj < 2; ++bj) { f32x4 v0 = acc[ai][bj][m][0] + bv[bj][0], v1 = acc[ai][bj][m][1] + bv[bj][1];
;                     if (act == 1) {
; #pragma unroll
;                         for (int j = 0; j < 1; ++j) { v0 = v0 * sigmoid4(v0); v1 = v1 * sigmoid4(v1); } }
;                     else if (act == 2) {
; #pragma unroll
;                         for (int j = 0; j < 1; ++j) { v0 = sigmoid4(v0); v1 = sigmoid4(v1); } }
;                     else if (act == 3) {
; #pragma unroll
;                         for (int j = 0; j < 4; ++j) { v0[j] = flogsig16(v0[j]); v1[j] = flogsig16(v1[j]); } }
;                     u32x4 w; w.x = cvt_pk_bf16(v0[0], v0[1]); w.y = cvt_pk_bf16(v0[2], v0[3]); w.z = cvt_pk_bf16(v1[0], v1[1]); w.w = cvt_pk_bf16(v1[2], v1[3]);
;                     *(u32x4*)(rowp + bj * HALF) = w; } }
; template <class Epi, class Sched>
; __device__ __forceinline__ void gemm_phase(PG8_LAS unsigned char* lds, const Gemm g, const Sched& S, const Epi& E) {
;     ...
;         if constexpr (!Epi::AFTER_DRAIN) { E(acc, cur, wr, wc, fr, fq); S.done(cur); }
;         if (!has_next) break;
; #pragma unroll
;         for (int a = 0; a < 2; ++a)
; #pragma unroll
;             for (int b = 0; b < 2; ++b)
; #pragma unroll
;                 for (int m = 0; m < 4; ++m)
; #pragma unroll
;                     for (int n = 0; n < 2; ++n) acc[a][b][m][n] = (f32x4){0.f, 0.f, 0.f, 0.f};
;         cur = nxt; cA = nA; cB = nB; ++ui;
;     }
;     PG8_WAIT_V(0);
;     if (wr == 0) PG8_BAR;
;     PG8_BAR;
	v_pk_add_f32 v[48:49], v[48:49], 0 op_sel_hi:[1,0]
	v_cvt_pk_bf16_f32 v74, v74, v75
	v_cvt_pk_bf16_f32 v75, v82, v83
	global_store_dwordx4 v[80:81], v[72:75], off
	v_pk_add_f32 v[38:39], v[38:39], 0 op_sel_hi:[1,0]
	v_pk_add_f32 v[36:37], v[36:37], 0 op_sel_hi:[1,0]
	v_pk_add_f32 v[72:73], v[66:67], 0 op_sel_hi:[1,0]
	v_pk_add_f32 v[66:67], v[64:65], 0 op_sel_hi:[1,0]
	v_cvt_pk_bf16_f32 v64, v68, v69
	v_cvt_pk_bf16_f32 v65, v70, v71
	v_pk_add_f32 v[32:33], v[32:33], 0 op_sel_hi:[1,0]
	v_cvt_pk_bf16_f32 v66, v66, v67
	v_cvt_pk_bf16_f32 v67, v72, v73
	global_store_dwordx4 v[80:81], v[64:67], off offset:256
	v_pk_add_f32 v[22:23], v[22:23], 0 op_sel_hi:[1,0]
	v_pk_add_f32 v[20:21], v[20:21], 0 op_sel_hi:[1,0]
	v_pk_add_f32 v[66:67], v[58:59], 0 op_sel_hi:[1,0]
	v_pk_add_f32 v[58:59], v[56:57], 0 op_sel_hi:[1,0]
	v_cvt_pk_bf16_f32 v56, v60, v61
	v_add_co_u32_e32 v60, vcc, s44, v144
	v_cvt_pk_bf16_f32 v57, v62, v63
	v_cvt_pk_bf16_f32 v58, v58, v59
	v_cvt_pk_bf16_f32 v59, v66, v67
	v_lshl_add_u64 v[64:65], v[144:145], 0, s[10:11]
	s_nop 0
	v_addc_co_u32_e32 v61, vcc, 0, v145, vcc
	global_store_dwordx4 v[60:61], v[56:59], off
	v_pk_add_f32 v[16:17], v[16:17], 0 op_sel_hi:[1,0]
	s_mov_b32 s51, s48
	v_pk_add_f32 v[56:57], v[46:47], 0 op_sel_hi:[1,0]
	v_pk_add_f32 v[46:47], v[44:45], 0 op_sel_hi:[1,0]
	v_cvt_pk_bf16_f32 v44, v52, v53
	v_cvt_pk_bf16_f32 v45, v54, v55
	s_mov_b32 s50, s49
	v_cvt_pk_bf16_f32 v46, v46, v47
	v_cvt_pk_bf16_f32 v47, v56, v57
	global_store_dwordx4 v[64:65], v[44:47], off offset:256
	s_mov_b64 s[20:21], s[4:5]
	s_mov_b64 s[18:19], s[0:1]
	v_pk_add_f32 v[46:47], v[50:51], 0 op_sel_hi:[1,0]
	v_pk_add_f32 v[50:51], v[42:43], 0 op_sel_hi:[1,0]
	v_pk_add_f32 v[42:43], v[40:41], 0 op_sel_hi:[1,0]
	v_cvt_pk_bf16_f32 v40, v48, v49
	v_cvt_pk_bf16_f32 v41, v46, v47
	v_add_co_u32_e32 v46, vcc, s45, v144
	v_cvt_pk_bf16_f32 v42, v42, v43
	v_cvt_pk_bf16_f32 v43, v50, v51
	v_lshl_add_u64 v[44:45], v[144:145], 0, s[12:13]
	s_nop 0
	v_addc_co_u32_e32 v47, vcc, 0, v145, vcc
	global_store_dwordx4 v[46:47], v[40:43], off
	v_pk_add_f32 v[6:7], v[6:7], 0 op_sel_hi:[1,0]
	v_pk_add_f32 v[4:5], v[4:5], 0 op_sel_hi:[1,0]
	v_pk_add_f32 v[40:41], v[30:31], 0 op_sel_hi:[1,0]
	v_pk_add_f32 v[30:31], v[28:29], 0 op_sel_hi:[1,0]
	v_cvt_pk_bf16_f32 v28, v36, v37
	v_cvt_pk_bf16_f32 v29, v38, v39
	s_nop 0
	v_cvt_pk_bf16_f32 v30, v30, v31
	v_cvt_pk_bf16_f32 v31, v40, v41
	global_store_dwordx4 v[44:45], v[28:31], off offset:256
	s_nop 1
	v_pk_add_f32 v[30:31], v[34:35], 0 op_sel_hi:[1,0]
	v_pk_add_f32 v[34:35], v[26:27], 0 op_sel_hi:[1,0]
	v_pk_add_f32 v[26:27], v[24:25], 0 op_sel_hi:[1,0]
	v_cvt_pk_bf16_f32 v24, v32, v33
	v_cvt_pk_bf16_f32 v25, v30, v31
	v_add_co_u32_e32 v30, vcc, s46, v144
	v_cvt_pk_bf16_f32 v26, v26, v27
	v_cvt_pk_bf16_f32 v27, v34, v35
	v_lshl_add_u64 v[28:29], v[144:145], 0, s[14:15]
	s_nop 0
	v_addc_co_u32_e32 v31, vcc, 0, v145, vcc
	global_store_dwordx4 v[30:31], v[24:27], off
	s_nop 1
	v_pk_add_f32 v[24:25], v[14:15], 0 op_sel_hi:[1,0]
	v_pk_add_f32 v[14:15], v[12:13], 0 op_sel_hi:[1,0]
	v_cvt_pk_bf16_f32 v12, v20, v21
	v_cvt_pk_bf16_f32 v13, v22, v23
	s_nop 0
	v_cvt_pk_bf16_f32 v14, v14, v15
	v_cvt_pk_bf16_f32 v15, v24, v25
	global_store_dwordx4 v[28:29], v[12:15], off offset:256
	s_nop 1
	v_pk_add_f32 v[14:15], v[18:19], 0 op_sel_hi:[1,0]
	v_pk_add_f32 v[18:19], v[10:11], 0 op_sel_hi:[1,0]
	v_pk_add_f32 v[10:11], v[8:9], 0 op_sel_hi:[1,0]
	v_cvt_pk_bf16_f32 v8, v16, v17
	v_cvt_pk_bf16_f32 v9, v14, v15
	v_add_co_u32_e32 v14, vcc, s47, v144
	v_lshl_add_u64 v[12:13], v[144:145], 0, s[16:17]
	s_nop 0
	v_addc_co_u32_e32 v15, vcc, 0, v145, vcc
	v_cvt_pk_bf16_f32 v10, v10, v11
	v_cvt_pk_bf16_f32 v11, v18, v19
	global_store_dwordx4 v[14:15], v[8:11], off
	s_and_b64 vcc, exec, s[2:3]
	s_nop 0
	v_pk_add_f32 v[8:9], v[2:3], 0 op_sel_hi:[1,0]
	v_pk_add_f32 v[2:3], v[0:1], 0 op_sel_hi:[1,0]
	v_cvt_pk_bf16_f32 v0, v4, v5
	v_cvt_pk_bf16_f32 v1, v6, v7
	s_nop 0
	v_cvt_pk_bf16_f32 v2, v2, v3
	v_cvt_pk_bf16_f32 v3, v8, v9
	global_store_dwordx4 v[12:13], v[0:3], off offset:256
	s_cbranch_vccz .LBB0_1267
	s_waitcnt vmcnt(0)
	s_cmpk_gt_u32 s27, 0xff
	s_cbranch_scc1 .LBB0_1282
	s_barrier
